# v60 + K-loop: the scalar/address preparation opening each LOAD segment (and the loop-counter increments) hoisted into the preceding MMA segment after its 2nd MFMA
# speedup vs baseline: 1.0009x; 1.0009x over previous
.LBB0_297:
	s_add_u32 s47, s38, s46
	s_addc_u32 s66, s39, 0
	s_add_u32 s64, s47, 0x100
	s_addc_u32 s65, s66, 0
	s_and_b64 s[48:49], s[44:45], exec
	s_cselect_b32 s49, s70, s65
	s_cselect_b32 s48, s71, s64
	s_add_u32 s46, s36, s46
	s_addc_u32 s64, s37, 0
	s_add_u32 s46, s46, 0x100
	s_addc_u32 s64, s64, 0
	s_and_b64 s[44:45], s[44:45], exec
	s_cselect_b32 s65, s72, s64
	s_cselect_b32 s64, s73, s46
	s_add_u32 s68, s47, 0x10080
	ds_read_b128 v[150:153], v146
	ds_read_b128 v[154:157], v146 offset:1024
	ds_read_b128 v[158:161], v146 offset:2048
	ds_read_b128 v[162:165], v146 offset:3072
	ds_read_b128 v[166:169], v147
	ds_read_b128 v[170:173], v147 offset:1024
	ds_read_b128 v[174:177], v147 offset:2048
	ds_read_b128 v[178:181], v147 offset:3072
	s_addc_u32 s69, s66, 0
	s_add_i32 s83, s30, s2
	s_add_i32 m0, s16, 0xc000
	s_add_i32 s84, s16, 0xe000
	s_add_i32 s80, s83, 0x2000
	s_add_u32 s66, s64, 0x40000
	s_addc_u32 s67, s65, 0
	s_add_i32 s82, s31, s2
	s_add_i32 s81, s82, 0x2000
	s_add_i32 s79, 0, 0x18000
	s_add_i32 s78, 0, 0x1c000
	s_add_u32 s46, s48, 0x10000
	s_addc_u32 s47, s49, 0
	s_add_i32 s77, s79, s2
	s_add_i32 s75, s77, 0x2000
	s_add_u32 s44, s64, 0x40080
	s_addc_u32 s45, s65, 0
	s_add_i32 s76, s78, s2
	s_add_i32 s74, s76, 0x2000
	v_lshl_add_u64 v[202:203], s[68:69], 0, v[130:131]
	ds_read_b128 v[182:185], v148
	ds_read_b128 v[186:189], v148 offset:1024
	ds_read_b128 v[190:193], v148 offset:2048
	ds_read_b128 v[194:197], v148 offset:3072
	ds_read_b128 v[198:201], v148 offset:4096
	ds_read_b128 v[206:209], v148 offset:5120
	ds_read_b128 v[210:213], v148 offset:6144
	ds_read_b128 v[214:217], v148 offset:7168
	global_load_lds_dwordx4 v[202:203], off
	v_lshl_add_u64 v[202:203], s[68:69], 0, v[132:133]
	s_mov_b32 m0, s84
	s_nop 0
	global_load_lds_dwordx4 v[202:203], off
	s_waitcnt vmcnt(8)
	s_waitcnt lgkmcnt(0)
	s_setprio 1
	s_barrier
	v_mfma_f32_16x16x32_bf16 v[126:129], v[150:153], v[182:185], v[126:129]
	v_mfma_f32_16x16x32_bf16 v[122:125], v[158:161], v[182:185], v[122:125]
	s_mov_b32 m0, s83
	v_lshl_add_u64 v[202:203], s[64:65], 0, v[136:137]
	v_mfma_f32_16x16x32_bf16 v[118:121], v[150:153], v[190:193], v[118:121]
	v_mfma_f32_16x16x32_bf16 v[114:117], v[158:161], v[190:193], v[114:117]
	v_mfma_f32_16x16x32_bf16 v[102:105], v[150:153], v[198:201], v[102:105]
	v_mfma_f32_16x16x32_bf16 v[98:101], v[158:161], v[198:201], v[98:101]
	v_mfma_f32_16x16x32_bf16 v[86:89], v[150:153], v[210:213], v[86:89]
	v_mfma_f32_16x16x32_bf16 v[82:85], v[158:161], v[210:213], v[82:85]
	v_mfma_f32_16x16x32_bf16 v[126:129], v[154:157], v[186:189], v[126:129]
	v_mfma_f32_16x16x32_bf16 v[122:125], v[162:165], v[186:189], v[122:125]
	v_mfma_f32_16x16x32_bf16 v[118:121], v[154:157], v[194:197], v[118:121]
	v_mfma_f32_16x16x32_bf16 v[114:117], v[162:165], v[194:197], v[114:117]
	v_mfma_f32_16x16x32_bf16 v[102:105], v[154:157], v[206:209], v[102:105]
	v_mfma_f32_16x16x32_bf16 v[98:101], v[162:165], v[206:209], v[98:101]
	v_mfma_f32_16x16x32_bf16 v[86:89], v[154:157], v[214:217], v[86:89]
	v_mfma_f32_16x16x32_bf16 v[82:85], v[162:165], v[214:217], v[82:85]
	v_mfma_f32_16x16x32_bf16 v[110:113], v[166:169], v[182:185], v[110:113]
	v_mfma_f32_16x16x32_bf16 v[106:109], v[174:177], v[182:185], v[106:109]
	v_mfma_f32_16x16x32_bf16 v[94:97], v[166:169], v[190:193], v[94:97]
	v_mfma_f32_16x16x32_bf16 v[90:93], v[174:177], v[190:193], v[90:93]
	v_mfma_f32_16x16x32_bf16 v[78:81], v[166:169], v[198:201], v[78:81]
	v_mfma_f32_16x16x32_bf16 v[74:77], v[174:177], v[198:201], v[74:77]
	v_mfma_f32_16x16x32_bf16 v[70:73], v[166:169], v[210:213], v[70:73]
	v_mfma_f32_16x16x32_bf16 v[66:69], v[174:177], v[210:213], v[66:69]
	v_mfma_f32_16x16x32_bf16 v[110:113], v[170:173], v[186:189], v[110:113]
	v_mfma_f32_16x16x32_bf16 v[106:109], v[178:181], v[186:189], v[106:109]
	v_mfma_f32_16x16x32_bf16 v[94:97], v[170:173], v[194:197], v[94:97]
	v_mfma_f32_16x16x32_bf16 v[90:93], v[178:181], v[194:197], v[90:93]
	v_mfma_f32_16x16x32_bf16 v[78:81], v[170:173], v[206:209], v[78:81]
	v_mfma_f32_16x16x32_bf16 v[74:77], v[178:181], v[206:209], v[74:77]
	v_mfma_f32_16x16x32_bf16 v[70:73], v[170:173], v[214:217], v[70:73]
	v_mfma_f32_16x16x32_bf16 v[66:69], v[178:181], v[214:217], v[66:69]
	s_setprio 0
	s_barrier
	ds_read_b128 v[182:185], v148 offset:16384
	ds_read_b128 v[186:189], v148 offset:17408
	ds_read_b128 v[190:193], v148 offset:18432
	ds_read_b128 v[194:197], v148 offset:19456
	ds_read_b128 v[198:201], v148 offset:20480
	ds_read_b128 v[206:209], v148 offset:21504
	ds_read_b128 v[210:213], v148 offset:22528
	ds_read_b128 v[214:217], v148 offset:23552
	global_load_lds_dwordx4 v[202:203], off
	v_lshl_add_u64 v[218:219], s[64:65], 0, v[134:135]
	s_mov_b32 m0, s80
	v_lshl_add_u64 v[220:221], s[66:67], 0, v[136:137]
	global_load_lds_dwordx4 v[218:219], off
	s_mov_b32 m0, s82
	v_lshl_add_u64 v[222:223], s[48:49], 0, v[132:133]
	global_load_lds_dwordx4 v[220:221], off
	v_lshl_add_u64 v[220:221], s[66:67], 0, v[134:135]
	s_mov_b32 m0, s81
	s_nop 0
	global_load_lds_dwordx4 v[220:221], off
	v_lshl_add_u64 v[220:221], s[48:49], 0, v[130:131]
	s_mov_b32 m0, s16
	s_nop 0
	global_load_lds_dwordx4 v[220:221], off
	s_mov_b32 m0, s17
	s_nop 0
	global_load_lds_dwordx4 v[222:223], off
	s_waitcnt vmcnt(8)
	s_waitcnt lgkmcnt(0)
	s_setprio 1
	s_barrier
	v_mfma_f32_16x16x32_bf16 v[62:65], v[150:153], v[182:185], v[62:65]
	v_mfma_f32_16x16x32_bf16 v[58:61], v[158:161], v[182:185], v[58:61]
	v_add_u32_e32 v149, s79, v145
	v_mfma_f32_16x16x32_bf16 v[54:57], v[150:153], v[190:193], v[54:57]
	v_mfma_f32_16x16x32_bf16 v[50:53], v[158:161], v[190:193], v[50:53]
	v_mfma_f32_16x16x32_bf16 v[38:41], v[150:153], v[198:201], v[38:41]
	v_mfma_f32_16x16x32_bf16 v[34:37], v[158:161], v[198:201], v[34:37]
	v_mfma_f32_16x16x32_bf16 v[22:25], v[150:153], v[210:213], v[22:25]
	v_mfma_f32_16x16x32_bf16 v[18:21], v[158:161], v[210:213], v[18:21]
	v_mfma_f32_16x16x32_bf16 v[62:65], v[154:157], v[186:189], v[62:65]
	v_mfma_f32_16x16x32_bf16 v[58:61], v[162:165], v[186:189], v[58:61]
	v_mfma_f32_16x16x32_bf16 v[54:57], v[154:157], v[194:197], v[54:57]
	v_mfma_f32_16x16x32_bf16 v[50:53], v[162:165], v[194:197], v[50:53]
	v_mfma_f32_16x16x32_bf16 v[38:41], v[154:157], v[206:209], v[38:41]
	v_mfma_f32_16x16x32_bf16 v[34:37], v[162:165], v[206:209], v[34:37]
	v_mfma_f32_16x16x32_bf16 v[22:25], v[154:157], v[214:217], v[22:25]
	v_mfma_f32_16x16x32_bf16 v[18:21], v[162:165], v[214:217], v[18:21]
	v_mfma_f32_16x16x32_bf16 v[46:49], v[166:169], v[182:185], v[46:49]
	v_mfma_f32_16x16x32_bf16 v[42:45], v[174:177], v[182:185], v[42:45]
	v_mfma_f32_16x16x32_bf16 v[30:33], v[166:169], v[190:193], v[30:33]
	v_mfma_f32_16x16x32_bf16 v[26:29], v[174:177], v[190:193], v[26:29]
	v_mfma_f32_16x16x32_bf16 v[14:17], v[166:169], v[198:201], v[14:17]
	v_mfma_f32_16x16x32_bf16 v[10:13], v[174:177], v[198:201], v[10:13]
	v_mfma_f32_16x16x32_bf16 v[6:9], v[166:169], v[210:213], v[6:9]
	v_mfma_f32_16x16x32_bf16 v[2:5], v[174:177], v[210:213], v[2:5]
	v_mfma_f32_16x16x32_bf16 v[46:49], v[170:173], v[186:189], v[46:49]
	v_mfma_f32_16x16x32_bf16 v[42:45], v[178:181], v[186:189], v[42:45]
	v_mfma_f32_16x16x32_bf16 v[30:33], v[170:173], v[194:197], v[30:33]
	v_mfma_f32_16x16x32_bf16 v[26:29], v[178:181], v[194:197], v[26:29]
	v_mfma_f32_16x16x32_bf16 v[14:17], v[170:173], v[206:209], v[14:17]
	v_mfma_f32_16x16x32_bf16 v[10:13], v[178:181], v[206:209], v[10:13]
	v_mfma_f32_16x16x32_bf16 v[6:9], v[170:173], v[214:217], v[6:9]
	v_mfma_f32_16x16x32_bf16 v[2:5], v[178:181], v[214:217], v[2:5]
	s_setprio 0
	s_barrier
	ds_read_b128 v[150:153], v149
	ds_read_b128 v[154:157], v149 offset:1024
	ds_read_b128 v[158:161], v149 offset:2048
	ds_read_b128 v[162:165], v149 offset:3072
	v_add_u32_e32 v149, s78, v145
	ds_read_b128 v[166:169], v149
	ds_read_b128 v[170:173], v149 offset:1024
	ds_read_b128 v[174:177], v149 offset:2048
	ds_read_b128 v[178:181], v149 offset:3072
	s_mov_b32 m0, s18
	v_lshl_add_u64 v[224:225], s[46:47], 0, v[130:131]
	ds_read_b128 v[182:185], v148 offset:32768
	ds_read_b128 v[186:189], v148 offset:33792
	ds_read_b128 v[190:193], v148 offset:34816
	ds_read_b128 v[194:197], v148 offset:35840
	ds_read_b128 v[198:201], v148 offset:36864
	ds_read_b128 v[206:209], v148 offset:37888
	ds_read_b128 v[210:213], v148 offset:38912
	ds_read_b128 v[214:217], v148 offset:39936
	global_load_lds_dwordx4 v[224:225], off
	v_lshl_add_u64 v[224:225], s[46:47], 0, v[132:133]
	s_mov_b32 m0, s19
	s_nop 0
	global_load_lds_dwordx4 v[224:225], off
	s_waitcnt vmcnt(8)
	s_waitcnt lgkmcnt(0)
	s_setprio 1
	s_barrier
	v_mfma_f32_16x16x32_bf16 v[126:129], v[150:153], v[182:185], v[126:129]
	v_mfma_f32_16x16x32_bf16 v[122:125], v[158:161], v[182:185], v[122:125]
	s_mov_b32 m0, s77
	v_lshl_add_u64 v[202:203], v[202:203], 0, s[8:9]
	v_mfma_f32_16x16x32_bf16 v[118:121], v[150:153], v[190:193], v[118:121]
	v_mfma_f32_16x16x32_bf16 v[114:117], v[158:161], v[190:193], v[114:117]
	v_mfma_f32_16x16x32_bf16 v[102:105], v[150:153], v[198:201], v[102:105]
	v_mfma_f32_16x16x32_bf16 v[98:101], v[158:161], v[198:201], v[98:101]
	v_mfma_f32_16x16x32_bf16 v[86:89], v[150:153], v[210:213], v[86:89]
	v_mfma_f32_16x16x32_bf16 v[82:85], v[158:161], v[210:213], v[82:85]
	v_mfma_f32_16x16x32_bf16 v[126:129], v[154:157], v[186:189], v[126:129]
	v_mfma_f32_16x16x32_bf16 v[122:125], v[162:165], v[186:189], v[122:125]
	v_mfma_f32_16x16x32_bf16 v[118:121], v[154:157], v[194:197], v[118:121]
	v_mfma_f32_16x16x32_bf16 v[114:117], v[162:165], v[194:197], v[114:117]
	v_mfma_f32_16x16x32_bf16 v[102:105], v[154:157], v[206:209], v[102:105]
	v_mfma_f32_16x16x32_bf16 v[98:101], v[162:165], v[206:209], v[98:101]
	v_mfma_f32_16x16x32_bf16 v[86:89], v[154:157], v[214:217], v[86:89]
	v_mfma_f32_16x16x32_bf16 v[82:85], v[162:165], v[214:217], v[82:85]
	v_mfma_f32_16x16x32_bf16 v[110:113], v[166:169], v[182:185], v[110:113]
	v_mfma_f32_16x16x32_bf16 v[106:109], v[174:177], v[182:185], v[106:109]
	v_mfma_f32_16x16x32_bf16 v[94:97], v[166:169], v[190:193], v[94:97]
	v_mfma_f32_16x16x32_bf16 v[90:93], v[174:177], v[190:193], v[90:93]
	v_mfma_f32_16x16x32_bf16 v[78:81], v[166:169], v[198:201], v[78:81]
	v_mfma_f32_16x16x32_bf16 v[74:77], v[174:177], v[198:201], v[74:77]
	v_mfma_f32_16x16x32_bf16 v[70:73], v[166:169], v[210:213], v[70:73]
	v_mfma_f32_16x16x32_bf16 v[66:69], v[174:177], v[210:213], v[66:69]
	v_mfma_f32_16x16x32_bf16 v[110:113], v[170:173], v[186:189], v[110:113]
	v_mfma_f32_16x16x32_bf16 v[106:109], v[178:181], v[186:189], v[106:109]
	v_mfma_f32_16x16x32_bf16 v[94:97], v[170:173], v[194:197], v[94:97]
	v_mfma_f32_16x16x32_bf16 v[90:93], v[178:181], v[194:197], v[90:93]
	v_mfma_f32_16x16x32_bf16 v[78:81], v[170:173], v[206:209], v[78:81]
	v_mfma_f32_16x16x32_bf16 v[74:77], v[178:181], v[206:209], v[74:77]
	v_mfma_f32_16x16x32_bf16 v[70:73], v[170:173], v[214:217], v[70:73]
	v_mfma_f32_16x16x32_bf16 v[66:69], v[178:181], v[214:217], v[66:69]
	s_setprio 0
	s_barrier
	ds_read_b128 v[182:185], v148 offset:49152
	ds_read_b128 v[186:189], v148 offset:50176
	ds_read_b128 v[190:193], v148 offset:51200
	ds_read_b128 v[194:197], v148 offset:52224
	ds_read_b128 v[198:201], v148 offset:53248
	ds_read_b128 v[206:209], v148 offset:54272
	ds_read_b128 v[210:213], v148 offset:55296
	ds_read_b128 v[214:217], v148 offset:56320
	global_load_lds_dwordx4 v[202:203], off
	v_lshl_add_u64 v[202:203], v[218:219], 0, s[8:9]
	s_mov_b32 m0, s75
	s_nop 0
	global_load_lds_dwordx4 v[202:203], off
	v_lshl_add_u64 v[202:203], s[44:45], 0, v[136:137]
	s_mov_b32 m0, s76
	s_nop 0
	global_load_lds_dwordx4 v[202:203], off
	v_lshl_add_u64 v[202:203], s[44:45], 0, v[134:135]
	s_mov_b32 m0, s74
	s_nop 0
	global_load_lds_dwordx4 v[202:203], off
	v_lshl_add_u64 v[202:203], v[220:221], 0, s[8:9]
	s_mov_b32 m0, s28
	s_nop 0
	global_load_lds_dwordx4 v[202:203], off
	v_lshl_add_u64 v[202:203], v[222:223], 0, s[8:9]
	s_mov_b32 m0, s29
	s_nop 0
	global_load_lds_dwordx4 v[202:203], off
	s_waitcnt vmcnt(8)
	s_waitcnt lgkmcnt(0)
	s_setprio 1
	s_barrier
	v_mfma_f32_16x16x32_bf16 v[62:65], v[150:153], v[182:185], v[62:65]
	v_mfma_f32_16x16x32_bf16 v[58:61], v[158:161], v[182:185], v[58:61]
	v_mfma_f32_16x16x32_bf16 v[54:57], v[150:153], v[190:193], v[54:57]
	v_mfma_f32_16x16x32_bf16 v[50:53], v[158:161], v[190:193], v[50:53]
	v_mfma_f32_16x16x32_bf16 v[38:41], v[150:153], v[198:201], v[38:41]
	v_mfma_f32_16x16x32_bf16 v[34:37], v[158:161], v[198:201], v[34:37]
	v_mfma_f32_16x16x32_bf16 v[22:25], v[150:153], v[210:213], v[22:25]
	v_mfma_f32_16x16x32_bf16 v[18:21], v[158:161], v[210:213], v[18:21]
	v_mfma_f32_16x16x32_bf16 v[62:65], v[154:157], v[186:189], v[62:65]
	v_mfma_f32_16x16x32_bf16 v[58:61], v[162:165], v[186:189], v[58:61]
	v_mfma_f32_16x16x32_bf16 v[54:57], v[154:157], v[194:197], v[54:57]
	v_mfma_f32_16x16x32_bf16 v[50:53], v[162:165], v[194:197], v[50:53]
	v_mfma_f32_16x16x32_bf16 v[38:41], v[154:157], v[206:209], v[38:41]
	v_mfma_f32_16x16x32_bf16 v[34:37], v[162:165], v[206:209], v[34:37]
	v_mfma_f32_16x16x32_bf16 v[22:25], v[154:157], v[214:217], v[22:25]
	v_mfma_f32_16x16x32_bf16 v[18:21], v[162:165], v[214:217], v[18:21]
	v_mfma_f32_16x16x32_bf16 v[46:49], v[166:169], v[182:185], v[46:49]
	v_mfma_f32_16x16x32_bf16 v[42:45], v[174:177], v[182:185], v[42:45]
	v_mfma_f32_16x16x32_bf16 v[30:33], v[166:169], v[190:193], v[30:33]
	v_mfma_f32_16x16x32_bf16 v[26:29], v[174:177], v[190:193], v[26:29]
	v_mfma_f32_16x16x32_bf16 v[14:17], v[166:169], v[198:201], v[14:17]
	v_mfma_f32_16x16x32_bf16 v[10:13], v[174:177], v[198:201], v[10:13]
	v_mfma_f32_16x16x32_bf16 v[6:9], v[166:169], v[210:213], v[6:9]
	v_mfma_f32_16x16x32_bf16 v[2:5], v[174:177], v[210:213], v[2:5]
	v_mfma_f32_16x16x32_bf16 v[46:49], v[170:173], v[186:189], v[46:49]
	v_mfma_f32_16x16x32_bf16 v[42:45], v[178:181], v[186:189], v[42:45]
	v_mfma_f32_16x16x32_bf16 v[30:33], v[170:173], v[194:197], v[30:33]
	v_mfma_f32_16x16x32_bf16 v[26:29], v[178:181], v[194:197], v[26:29]
	v_mfma_f32_16x16x32_bf16 v[14:17], v[170:173], v[206:209], v[14:17]
	v_mfma_f32_16x16x32_bf16 v[10:13], v[178:181], v[206:209], v[10:13]
	v_mfma_f32_16x16x32_bf16 v[6:9], v[170:173], v[214:217], v[6:9]
	v_mfma_f32_16x16x32_bf16 v[2:5], v[178:181], v[214:217], v[2:5]
	s_setprio 0
	s_barrier
	s_movk_i32 s46, 0x100
	s_andn2_b64 vcc, exec, s[42:43]
	s_mov_b64 s[44:45], -1
	s_mov_b64 s[42:43], 0
	s_cbranch_vccz .LBB0_297
	s_and_b64 vcc, exec, s[10:11]
	s_cbranch_vccz .LBB0_300
	s_barrier

.LBB0_313:
	s_add_u32 s49, s38, s48
	s_addc_u32 s68, s39, 0
	s_add_u32 s66, s49, 0x100
	s_addc_u32 s67, s68, 0
	s_and_b64 s[64:65], s[46:47], exec
	s_cselect_b32 s65, s43, s67
	s_cselect_b32 s64, s75, s66
	s_add_u32 s48, s36, s48
	s_addc_u32 s66, s37, 0
	s_add_u32 s48, s48, 0x100
	s_addc_u32 s66, s66, 0
	s_and_b64 s[46:47], s[46:47], exec
	s_cselect_b32 s67, s76, s66
	s_cselect_b32 s66, s77, s48
	s_add_u32 s70, s49, 0x10080
	ds_read_b128 v[144:147], v140
	ds_read_b128 v[148:151], v140 offset:1024
	ds_read_b128 v[152:155], v140 offset:2048
	ds_read_b128 v[156:159], v140 offset:3072
	ds_read_b128 v[160:163], v141
	ds_read_b128 v[164:167], v141 offset:1024
	ds_read_b128 v[168:171], v141 offset:2048
	ds_read_b128 v[172:175], v141 offset:3072
	s_addc_u32 s71, s68, 0
	s_add_i32 s87, s33, s2
	s_add_i32 m0, s16, 0xc000
	s_add_i32 s88, s16, 0xe000
	s_add_i32 s84, s87, 0x2000
	s_add_u32 s68, s66, 0x1000
	s_addc_u32 s69, s67, 0
	s_add_i32 s86, s34, s2
	s_add_i32 s85, s86, 0x2000
	s_add_i32 s83, 0, 0x18000
	s_add_i32 s82, 0, 0x1c000
	s_add_u32 s48, s64, 0x10000
	s_addc_u32 s49, s65, 0
	s_add_i32 s81, s83, s2
	s_add_i32 s79, s81, 0x2000
	s_add_u32 s46, s66, 0x1080
	s_addc_u32 s47, s67, 0
	s_add_i32 s80, s82, s2
	s_add_i32 s78, s80, 0x2000
	v_lshl_add_u64 v[210:211], s[70:71], 0, v[130:131]
	ds_read_b128 v[176:179], v142
	ds_read_b128 v[180:183], v142 offset:1024
	ds_read_b128 v[184:187], v142 offset:2048
	ds_read_b128 v[188:191], v142 offset:3072
	ds_read_b128 v[192:195], v142 offset:4096
	ds_read_b128 v[196:199], v142 offset:5120
	ds_read_b128 v[200:203], v142 offset:6144
	ds_read_b128 v[206:209], v142 offset:7168
	global_load_lds_dwordx4 v[210:211], off
	v_lshl_add_u64 v[210:211], s[70:71], 0, v[132:133]
	s_mov_b32 m0, s88
	s_nop 0
	global_load_lds_dwordx4 v[210:211], off
	s_waitcnt vmcnt(8)
	s_waitcnt lgkmcnt(0)
	s_setprio 1
	s_barrier
	v_mfma_f32_16x16x32_bf16 v[126:129], v[144:147], v[176:179], v[126:129]
	v_mfma_f32_16x16x32_bf16 v[122:125], v[152:155], v[176:179], v[122:125]
	s_mov_b32 m0, s87
	v_lshl_add_u64 v[210:211], s[66:67], 0, v[136:137]
	v_mfma_f32_16x16x32_bf16 v[118:121], v[144:147], v[184:187], v[118:121]
	v_mfma_f32_16x16x32_bf16 v[114:117], v[152:155], v[184:187], v[114:117]
	v_mfma_f32_16x16x32_bf16 v[102:105], v[144:147], v[192:195], v[102:105]
	v_mfma_f32_16x16x32_bf16 v[98:101], v[152:155], v[192:195], v[98:101]
	v_mfma_f32_16x16x32_bf16 v[86:89], v[144:147], v[200:203], v[86:89]
	v_mfma_f32_16x16x32_bf16 v[82:85], v[152:155], v[200:203], v[82:85]
	v_mfma_f32_16x16x32_bf16 v[126:129], v[148:151], v[180:183], v[126:129]
	v_mfma_f32_16x16x32_bf16 v[122:125], v[156:159], v[180:183], v[122:125]
	v_mfma_f32_16x16x32_bf16 v[118:121], v[148:151], v[188:191], v[118:121]
	v_mfma_f32_16x16x32_bf16 v[114:117], v[156:159], v[188:191], v[114:117]
	v_mfma_f32_16x16x32_bf16 v[102:105], v[148:151], v[196:199], v[102:105]
	v_mfma_f32_16x16x32_bf16 v[98:101], v[156:159], v[196:199], v[98:101]
	v_mfma_f32_16x16x32_bf16 v[86:89], v[148:151], v[206:209], v[86:89]
	v_mfma_f32_16x16x32_bf16 v[82:85], v[156:159], v[206:209], v[82:85]
	v_mfma_f32_16x16x32_bf16 v[110:113], v[160:163], v[176:179], v[110:113]
	v_mfma_f32_16x16x32_bf16 v[106:109], v[168:171], v[176:179], v[106:109]
	v_mfma_f32_16x16x32_bf16 v[94:97], v[160:163], v[184:187], v[94:97]
	v_mfma_f32_16x16x32_bf16 v[90:93], v[168:171], v[184:187], v[90:93]
	v_mfma_f32_16x16x32_bf16 v[78:81], v[160:163], v[192:195], v[78:81]
	v_mfma_f32_16x16x32_bf16 v[74:77], v[168:171], v[192:195], v[74:77]
	v_mfma_f32_16x16x32_bf16 v[70:73], v[160:163], v[200:203], v[70:73]
	v_mfma_f32_16x16x32_bf16 v[66:69], v[168:171], v[200:203], v[66:69]
	v_mfma_f32_16x16x32_bf16 v[110:113], v[164:167], v[180:183], v[110:113]
	v_mfma_f32_16x16x32_bf16 v[106:109], v[172:175], v[180:183], v[106:109]
	v_mfma_f32_16x16x32_bf16 v[94:97], v[164:167], v[188:191], v[94:97]
	v_mfma_f32_16x16x32_bf16 v[90:93], v[172:175], v[188:191], v[90:93]
	v_mfma_f32_16x16x32_bf16 v[78:81], v[164:167], v[196:199], v[78:81]
	v_mfma_f32_16x16x32_bf16 v[74:77], v[172:175], v[196:199], v[74:77]
	v_mfma_f32_16x16x32_bf16 v[70:73], v[164:167], v[206:209], v[70:73]
	v_mfma_f32_16x16x32_bf16 v[66:69], v[172:175], v[206:209], v[66:69]
	s_setprio 0
	s_barrier
	ds_read_b128 v[176:179], v142 offset:16384
	ds_read_b128 v[180:183], v142 offset:17408
	ds_read_b128 v[184:187], v142 offset:18432
	ds_read_b128 v[188:191], v142 offset:19456
	ds_read_b128 v[192:195], v142 offset:20480
	ds_read_b128 v[196:199], v142 offset:21504
	ds_read_b128 v[200:203], v142 offset:22528
	ds_read_b128 v[206:209], v142 offset:23552
	global_load_lds_dwordx4 v[210:211], off
	v_lshl_add_u64 v[212:213], s[66:67], 0, v[134:135]
	s_mov_b32 m0, s84
	v_lshl_add_u64 v[214:215], s[68:69], 0, v[136:137]
	global_load_lds_dwordx4 v[212:213], off
	s_mov_b32 m0, s86
	v_lshl_add_u64 v[216:217], s[64:65], 0, v[132:133]
	global_load_lds_dwordx4 v[214:215], off
	v_lshl_add_u64 v[214:215], s[68:69], 0, v[134:135]
	s_mov_b32 m0, s85
	s_nop 0
	global_load_lds_dwordx4 v[214:215], off
	v_lshl_add_u64 v[214:215], s[64:65], 0, v[130:131]
	s_mov_b32 m0, s16
	s_nop 0
	global_load_lds_dwordx4 v[214:215], off
	s_mov_b32 m0, s17
	s_nop 0
	global_load_lds_dwordx4 v[216:217], off
	s_waitcnt vmcnt(8)
	s_waitcnt lgkmcnt(0)
	s_setprio 1
	s_barrier
	v_mfma_f32_16x16x32_bf16 v[62:65], v[144:147], v[176:179], v[62:65]
	v_mfma_f32_16x16x32_bf16 v[58:61], v[152:155], v[176:179], v[58:61]
	v_add_u32_e32 v143, s83, v139
	v_mfma_f32_16x16x32_bf16 v[54:57], v[144:147], v[184:187], v[54:57]
	v_mfma_f32_16x16x32_bf16 v[50:53], v[152:155], v[184:187], v[50:53]
	v_mfma_f32_16x16x32_bf16 v[38:41], v[144:147], v[192:195], v[38:41]
	v_mfma_f32_16x16x32_bf16 v[34:37], v[152:155], v[192:195], v[34:37]
	v_mfma_f32_16x16x32_bf16 v[22:25], v[144:147], v[200:203], v[22:25]
	v_mfma_f32_16x16x32_bf16 v[18:21], v[152:155], v[200:203], v[18:21]
	v_mfma_f32_16x16x32_bf16 v[62:65], v[148:151], v[180:183], v[62:65]
	v_mfma_f32_16x16x32_bf16 v[58:61], v[156:159], v[180:183], v[58:61]
	v_mfma_f32_16x16x32_bf16 v[54:57], v[148:151], v[188:191], v[54:57]
	v_mfma_f32_16x16x32_bf16 v[50:53], v[156:159], v[188:191], v[50:53]
	v_mfma_f32_16x16x32_bf16 v[38:41], v[148:151], v[196:199], v[38:41]
	v_mfma_f32_16x16x32_bf16 v[34:37], v[156:159], v[196:199], v[34:37]
	v_mfma_f32_16x16x32_bf16 v[22:25], v[148:151], v[206:209], v[22:25]
	v_mfma_f32_16x16x32_bf16 v[18:21], v[156:159], v[206:209], v[18:21]
	v_mfma_f32_16x16x32_bf16 v[46:49], v[160:163], v[176:179], v[46:49]
	v_mfma_f32_16x16x32_bf16 v[42:45], v[168:171], v[176:179], v[42:45]
	v_mfma_f32_16x16x32_bf16 v[30:33], v[160:163], v[184:187], v[30:33]
	v_mfma_f32_16x16x32_bf16 v[26:29], v[168:171], v[184:187], v[26:29]
	v_mfma_f32_16x16x32_bf16 v[14:17], v[160:163], v[192:195], v[14:17]
	v_mfma_f32_16x16x32_bf16 v[10:13], v[168:171], v[192:195], v[10:13]
	v_mfma_f32_16x16x32_bf16 v[6:9], v[160:163], v[200:203], v[6:9]
	v_mfma_f32_16x16x32_bf16 v[2:5], v[168:171], v[200:203], v[2:5]
	v_mfma_f32_16x16x32_bf16 v[46:49], v[164:167], v[180:183], v[46:49]
	v_mfma_f32_16x16x32_bf16 v[42:45], v[172:175], v[180:183], v[42:45]
	v_mfma_f32_16x16x32_bf16 v[30:33], v[164:167], v[188:191], v[30:33]
	v_mfma_f32_16x16x32_bf16 v[26:29], v[172:175], v[188:191], v[26:29]
	v_mfma_f32_16x16x32_bf16 v[14:17], v[164:167], v[196:199], v[14:17]
	v_mfma_f32_16x16x32_bf16 v[10:13], v[172:175], v[196:199], v[10:13]
	v_mfma_f32_16x16x32_bf16 v[6:9], v[164:167], v[206:209], v[6:9]
	v_mfma_f32_16x16x32_bf16 v[2:5], v[172:175], v[206:209], v[2:5]
	s_setprio 0
	s_barrier
	ds_read_b128 v[144:147], v143
	ds_read_b128 v[148:151], v143 offset:1024
	ds_read_b128 v[152:155], v143 offset:2048
	ds_read_b128 v[156:159], v143 offset:3072
	v_add_u32_e32 v143, s82, v139
	ds_read_b128 v[160:163], v143
	ds_read_b128 v[164:167], v143 offset:1024
	ds_read_b128 v[168:171], v143 offset:2048
	ds_read_b128 v[172:175], v143 offset:3072
	s_mov_b32 m0, s18
	v_lshl_add_u64 v[218:219], s[48:49], 0, v[130:131]
	ds_read_b128 v[176:179], v142 offset:32768
	ds_read_b128 v[180:183], v142 offset:33792
	ds_read_b128 v[184:187], v142 offset:34816
	ds_read_b128 v[188:191], v142 offset:35840
	ds_read_b128 v[192:195], v142 offset:36864
	ds_read_b128 v[196:199], v142 offset:37888
	ds_read_b128 v[200:203], v142 offset:38912
	ds_read_b128 v[206:209], v142 offset:39936
	global_load_lds_dwordx4 v[218:219], off
	v_lshl_add_u64 v[218:219], s[48:49], 0, v[132:133]
	s_mov_b32 m0, s19
	s_nop 0
	global_load_lds_dwordx4 v[218:219], off
	s_waitcnt vmcnt(8)
	s_waitcnt lgkmcnt(0)
	s_setprio 1
	s_barrier
	v_mfma_f32_16x16x32_bf16 v[126:129], v[144:147], v[176:179], v[126:129]
	v_mfma_f32_16x16x32_bf16 v[122:125], v[152:155], v[176:179], v[122:125]
	s_mov_b32 m0, s81
	v_lshl_add_u64 v[210:211], v[210:211], 0, s[8:9]
	v_mfma_f32_16x16x32_bf16 v[118:121], v[144:147], v[184:187], v[118:121]
	v_mfma_f32_16x16x32_bf16 v[114:117], v[152:155], v[184:187], v[114:117]
	v_mfma_f32_16x16x32_bf16 v[102:105], v[144:147], v[192:195], v[102:105]
	v_mfma_f32_16x16x32_bf16 v[98:101], v[152:155], v[192:195], v[98:101]
	v_mfma_f32_16x16x32_bf16 v[86:89], v[144:147], v[200:203], v[86:89]
	v_mfma_f32_16x16x32_bf16 v[82:85], v[152:155], v[200:203], v[82:85]
	v_mfma_f32_16x16x32_bf16 v[126:129], v[148:151], v[180:183], v[126:129]
	v_mfma_f32_16x16x32_bf16 v[122:125], v[156:159], v[180:183], v[122:125]
	v_mfma_f32_16x16x32_bf16 v[118:121], v[148:151], v[188:191], v[118:121]
	v_mfma_f32_16x16x32_bf16 v[114:117], v[156:159], v[188:191], v[114:117]
	v_mfma_f32_16x16x32_bf16 v[102:105], v[148:151], v[196:199], v[102:105]
	v_mfma_f32_16x16x32_bf16 v[98:101], v[156:159], v[196:199], v[98:101]
	v_mfma_f32_16x16x32_bf16 v[86:89], v[148:151], v[206:209], v[86:89]
	v_mfma_f32_16x16x32_bf16 v[82:85], v[156:159], v[206:209], v[82:85]
	v_mfma_f32_16x16x32_bf16 v[110:113], v[160:163], v[176:179], v[110:113]
	v_mfma_f32_16x16x32_bf16 v[106:109], v[168:171], v[176:179], v[106:109]
	v_mfma_f32_16x16x32_bf16 v[94:97], v[160:163], v[184:187], v[94:97]
	v_mfma_f32_16x16x32_bf16 v[90:93], v[168:171], v[184:187], v[90:93]
	v_mfma_f32_16x16x32_bf16 v[78:81], v[160:163], v[192:195], v[78:81]
	v_mfma_f32_16x16x32_bf16 v[74:77], v[168:171], v[192:195], v[74:77]
	v_mfma_f32_16x16x32_bf16 v[70:73], v[160:163], v[200:203], v[70:73]
	v_mfma_f32_16x16x32_bf16 v[66:69], v[168:171], v[200:203], v[66:69]
	v_mfma_f32_16x16x32_bf16 v[110:113], v[164:167], v[180:183], v[110:113]
	v_mfma_f32_16x16x32_bf16 v[106:109], v[172:175], v[180:183], v[106:109]
	v_mfma_f32_16x16x32_bf16 v[94:97], v[164:167], v[188:191], v[94:97]
	v_mfma_f32_16x16x32_bf16 v[90:93], v[172:175], v[188:191], v[90:93]
	v_mfma_f32_16x16x32_bf16 v[78:81], v[164:167], v[196:199], v[78:81]
	v_mfma_f32_16x16x32_bf16 v[74:77], v[172:175], v[196:199], v[74:77]
	v_mfma_f32_16x16x32_bf16 v[70:73], v[164:167], v[206:209], v[70:73]
	v_mfma_f32_16x16x32_bf16 v[66:69], v[172:175], v[206:209], v[66:69]
	s_setprio 0
	s_barrier
	ds_read_b128 v[176:179], v142 offset:49152
	ds_read_b128 v[180:183], v142 offset:50176
	ds_read_b128 v[184:187], v142 offset:51200
	ds_read_b128 v[188:191], v142 offset:52224
	ds_read_b128 v[192:195], v142 offset:53248
	ds_read_b128 v[196:199], v142 offset:54272
	ds_read_b128 v[200:203], v142 offset:55296
	ds_read_b128 v[206:209], v142 offset:56320
	global_load_lds_dwordx4 v[210:211], off
	v_lshl_add_u64 v[210:211], v[212:213], 0, s[8:9]
	s_mov_b32 m0, s79
	s_nop 0
	global_load_lds_dwordx4 v[210:211], off
	v_lshl_add_u64 v[210:211], s[46:47], 0, v[136:137]
	s_mov_b32 m0, s80
	s_nop 0
	global_load_lds_dwordx4 v[210:211], off
	v_lshl_add_u64 v[210:211], s[46:47], 0, v[134:135]
	s_mov_b32 m0, s78
	s_nop 0
	global_load_lds_dwordx4 v[210:211], off
	v_lshl_add_u64 v[210:211], v[214:215], 0, s[8:9]
	s_mov_b32 m0, s30
	s_nop 0
	global_load_lds_dwordx4 v[210:211], off
	v_lshl_add_u64 v[210:211], v[216:217], 0, s[8:9]
	s_mov_b32 m0, s31
	s_nop 0
	global_load_lds_dwordx4 v[210:211], off
	s_waitcnt vmcnt(8)
	s_waitcnt lgkmcnt(0)
	s_setprio 1
	s_barrier
	v_mfma_f32_16x16x32_bf16 v[62:65], v[144:147], v[176:179], v[62:65]
	v_mfma_f32_16x16x32_bf16 v[58:61], v[152:155], v[176:179], v[58:61]
	v_mfma_f32_16x16x32_bf16 v[54:57], v[144:147], v[184:187], v[54:57]
	v_mfma_f32_16x16x32_bf16 v[50:53], v[152:155], v[184:187], v[50:53]
	v_mfma_f32_16x16x32_bf16 v[38:41], v[144:147], v[192:195], v[38:41]
	v_mfma_f32_16x16x32_bf16 v[34:37], v[152:155], v[192:195], v[34:37]
	v_mfma_f32_16x16x32_bf16 v[22:25], v[144:147], v[200:203], v[22:25]
	v_mfma_f32_16x16x32_bf16 v[18:21], v[152:155], v[200:203], v[18:21]
	v_mfma_f32_16x16x32_bf16 v[62:65], v[148:151], v[180:183], v[62:65]
	v_mfma_f32_16x16x32_bf16 v[58:61], v[156:159], v[180:183], v[58:61]
	v_mfma_f32_16x16x32_bf16 v[54:57], v[148:151], v[188:191], v[54:57]
	v_mfma_f32_16x16x32_bf16 v[50:53], v[156:159], v[188:191], v[50:53]
	v_mfma_f32_16x16x32_bf16 v[38:41], v[148:151], v[196:199], v[38:41]
	v_mfma_f32_16x16x32_bf16 v[34:37], v[156:159], v[196:199], v[34:37]
	v_mfma_f32_16x16x32_bf16 v[22:25], v[148:151], v[206:209], v[22:25]
	v_mfma_f32_16x16x32_bf16 v[18:21], v[156:159], v[206:209], v[18:21]
	v_mfma_f32_16x16x32_bf16 v[46:49], v[160:163], v[176:179], v[46:49]
	v_mfma_f32_16x16x32_bf16 v[42:45], v[168:171], v[176:179], v[42:45]
	v_mfma_f32_16x16x32_bf16 v[30:33], v[160:163], v[184:187], v[30:33]
	v_mfma_f32_16x16x32_bf16 v[26:29], v[168:171], v[184:187], v[26:29]
	v_mfma_f32_16x16x32_bf16 v[14:17], v[160:163], v[192:195], v[14:17]
	v_mfma_f32_16x16x32_bf16 v[10:13], v[168:171], v[192:195], v[10:13]
	v_mfma_f32_16x16x32_bf16 v[6:9], v[160:163], v[200:203], v[6:9]
	v_mfma_f32_16x16x32_bf16 v[2:5], v[168:171], v[200:203], v[2:5]
	v_mfma_f32_16x16x32_bf16 v[46:49], v[164:167], v[180:183], v[46:49]
	v_mfma_f32_16x16x32_bf16 v[42:45], v[172:175], v[180:183], v[42:45]
	v_mfma_f32_16x16x32_bf16 v[30:33], v[164:167], v[188:191], v[30:33]
	v_mfma_f32_16x16x32_bf16 v[26:29], v[172:175], v[188:191], v[26:29]
	v_mfma_f32_16x16x32_bf16 v[14:17], v[164:167], v[196:199], v[14:17]
	v_mfma_f32_16x16x32_bf16 v[10:13], v[172:175], v[196:199], v[10:13]
	v_mfma_f32_16x16x32_bf16 v[6:9], v[164:167], v[206:209], v[6:9]
	v_mfma_f32_16x16x32_bf16 v[2:5], v[172:175], v[206:209], v[2:5]
	s_setprio 0
	s_barrier
	s_movk_i32 s48, 0x100
	s_andn2_b64 vcc, exec, s[44:45]
	s_mov_b64 s[46:47], -1
	s_mov_b64 s[44:45], 0
	s_cbranch_vccz .LBB0_313
	s_and_b64 vcc, exec, s[10:11]
	s_cbranch_vccz .LBB0_316
	s_barrier

.LBB0_383:
	s_add_u32 s26, s0, s22
	s_addc_u32 s27, s1, s23
	s_and_b64 s[44:45], s[36:37], exec
	s_cselect_b32 s15, s27, s43
	s_cselect_b32 s39, s26, s42
	s_add_u32 s66, s42, 0x100
	s_addc_u32 s67, s43, 0
	s_mov_b32 s68, -2
	s_mov_b64 s[42:43], 0
	ds_read_b128 v[152:155], v146
	ds_read_b128 v[156:159], v146 offset:1024
	ds_read_b128 v[160:163], v146 offset:2048
	ds_read_b128 v[164:167], v146 offset:3072
	ds_read_b128 v[168:171], v147
	ds_read_b128 v[172:175], v147 offset:1024
	ds_read_b128 v[176:179], v147 offset:2048
	ds_read_b128 v[180:183], v147 offset:3072
	s_add_u32 s44, s42, 0x100
	s_addc_u32 s45, s43, 0
	s_add_u32 s46, s66, s42
	s_addc_u32 s47, s67, s43
	s_cmp_eq_u32 s68, 4
	s_cselect_b32 s48, 0, s44
	s_cselect_b32 s49, 0, s45
	s_cselect_b32 s46, s39, s46
	s_cselect_b32 s47, s15, s47
	s_add_u32 s48, s6, s48
	s_addc_u32 s49, s7, s49
	s_mov_b32 m0, s29
	v_lshl_add_u64 v[218:219], v[138:139], 0, s[42:43]
	ds_read_b128 v[184:187], v148
	ds_read_b128 v[188:191], v148 offset:1024
	ds_read_b128 v[192:195], v148 offset:2048
	ds_read_b128 v[196:199], v148 offset:3072
	ds_read_b128 v[200:203], v148 offset:4096
	ds_read_b128 v[206:209], v148 offset:5120
	ds_read_b128 v[210:213], v148 offset:6144
	ds_read_b128 v[214:217], v148 offset:7168
	global_load_lds_dwordx4 v[218:219], off
	v_lshl_add_u64 v[218:219], v[140:141], 0, s[42:43]
	s_mov_b32 m0, s30
	s_nop 0
	global_load_lds_dwordx4 v[218:219], off
	s_waitcnt vmcnt(8)
	s_waitcnt lgkmcnt(0)
	s_setprio 1
	s_barrier
	v_mfma_f32_16x16x32_bf16 v[126:129], v[152:155], v[184:187], 0
	v_mfma_f32_16x16x32_bf16 v[122:125], v[160:163], v[184:187], 0
	s_mov_b32 m0, s31
	v_lshl_add_u64 v[218:219], s[46:47], 0, v[134:135]
	s_add_u32 s42, s46, 0x20000
	v_mfma_f32_16x16x32_bf16 v[118:121], v[152:155], v[192:195], 0
	v_mfma_f32_16x16x32_bf16 v[114:117], v[160:163], v[192:195], 0
	v_mfma_f32_16x16x32_bf16 v[102:105], v[152:155], v[200:203], 0
	v_mfma_f32_16x16x32_bf16 v[98:101], v[160:163], v[200:203], 0
	v_mfma_f32_16x16x32_bf16 v[86:89], v[152:155], v[210:213], 0
	v_mfma_f32_16x16x32_bf16 v[82:85], v[160:163], v[210:213], 0
	v_mfma_f32_16x16x32_bf16 v[126:129], v[156:159], v[188:191], v[126:129]
	v_mfma_f32_16x16x32_bf16 v[122:125], v[164:167], v[188:191], v[122:125]
	v_mfma_f32_16x16x32_bf16 v[118:121], v[156:159], v[196:199], v[118:121]
	v_mfma_f32_16x16x32_bf16 v[114:117], v[164:167], v[196:199], v[114:117]
	v_mfma_f32_16x16x32_bf16 v[102:105], v[156:159], v[206:209], v[102:105]
	v_mfma_f32_16x16x32_bf16 v[98:101], v[164:167], v[206:209], v[98:101]
	v_mfma_f32_16x16x32_bf16 v[86:89], v[156:159], v[214:217], v[86:89]
	v_mfma_f32_16x16x32_bf16 v[82:85], v[164:167], v[214:217], v[82:85]
	v_mfma_f32_16x16x32_bf16 v[110:113], v[168:171], v[184:187], 0
	v_mfma_f32_16x16x32_bf16 v[106:109], v[176:179], v[184:187], 0
	v_mfma_f32_16x16x32_bf16 v[94:97], v[168:171], v[192:195], 0
	v_mfma_f32_16x16x32_bf16 v[90:93], v[176:179], v[192:195], 0
	v_mfma_f32_16x16x32_bf16 v[78:81], v[168:171], v[200:203], 0
	v_mfma_f32_16x16x32_bf16 v[74:77], v[176:179], v[200:203], 0
	v_mfma_f32_16x16x32_bf16 v[70:73], v[168:171], v[210:213], 0
	v_mfma_f32_16x16x32_bf16 v[66:69], v[176:179], v[210:213], 0
	v_mfma_f32_16x16x32_bf16 v[110:113], v[172:175], v[188:191], v[110:113]
	v_mfma_f32_16x16x32_bf16 v[106:109], v[180:183], v[188:191], v[106:109]
	v_mfma_f32_16x16x32_bf16 v[94:97], v[172:175], v[196:199], v[94:97]
	v_mfma_f32_16x16x32_bf16 v[90:93], v[180:183], v[196:199], v[90:93]
	v_mfma_f32_16x16x32_bf16 v[78:81], v[172:175], v[206:209], v[78:81]
	v_mfma_f32_16x16x32_bf16 v[74:77], v[180:183], v[206:209], v[74:77]
	v_mfma_f32_16x16x32_bf16 v[70:73], v[172:175], v[214:217], v[70:73]
	v_mfma_f32_16x16x32_bf16 v[66:69], v[180:183], v[214:217], v[66:69]
	s_setprio 0
	s_barrier
	ds_read_b128 v[184:187], v148 offset:16384
	ds_read_b128 v[188:191], v148 offset:17408
	ds_read_b128 v[192:195], v148 offset:18432
	ds_read_b128 v[196:199], v148 offset:19456
	ds_read_b128 v[200:203], v148 offset:20480
	ds_read_b128 v[206:209], v148 offset:21504
	ds_read_b128 v[210:213], v148 offset:22528
	ds_read_b128 v[214:217], v148 offset:23552
	global_load_lds_dwordx4 v[218:219], off
	v_lshl_add_u64 v[220:221], s[46:47], 0, v[130:131]
	s_mov_b32 m0, s33
	s_addc_u32 s43, s47, 0
	global_load_lds_dwordx4 v[220:221], off
	v_lshl_add_u64 v[222:223], s[42:43], 0, v[134:135]
	s_mov_b32 m0, s34
	v_lshl_add_u64 v[224:225], s[48:49], 0, v[132:133]
	global_load_lds_dwordx4 v[222:223], off
	v_lshl_add_u64 v[222:223], s[42:43], 0, v[130:131]
	s_mov_b32 m0, s35
	s_nop 0
	global_load_lds_dwordx4 v[222:223], off
	v_lshl_add_u64 v[222:223], s[48:49], 0, v[136:137]
	s_mov_b32 m0, s2
	s_nop 0
	global_load_lds_dwordx4 v[222:223], off
	s_mov_b32 m0, s3
	s_nop 0
	global_load_lds_dwordx4 v[224:225], off
	s_waitcnt vmcnt(8)
	s_waitcnt lgkmcnt(0)
	s_setprio 1
	s_barrier
	v_mfma_f32_16x16x32_bf16 v[62:65], v[152:155], v[184:187], 0
	v_mfma_f32_16x16x32_bf16 v[58:61], v[160:163], v[184:187], 0
	v_mfma_f32_16x16x32_bf16 v[54:57], v[152:155], v[192:195], 0
	v_mfma_f32_16x16x32_bf16 v[50:53], v[160:163], v[192:195], 0
	v_mfma_f32_16x16x32_bf16 v[38:41], v[152:155], v[200:203], 0
	v_mfma_f32_16x16x32_bf16 v[34:37], v[160:163], v[200:203], 0
	v_mfma_f32_16x16x32_bf16 v[22:25], v[152:155], v[210:213], 0
	v_mfma_f32_16x16x32_bf16 v[18:21], v[160:163], v[210:213], 0
	v_mfma_f32_16x16x32_bf16 v[62:65], v[156:159], v[188:191], v[62:65]
	v_mfma_f32_16x16x32_bf16 v[58:61], v[164:167], v[188:191], v[58:61]
	v_mfma_f32_16x16x32_bf16 v[54:57], v[156:159], v[196:199], v[54:57]
	v_mfma_f32_16x16x32_bf16 v[50:53], v[164:167], v[196:199], v[50:53]
	v_mfma_f32_16x16x32_bf16 v[38:41], v[156:159], v[206:209], v[38:41]
	v_mfma_f32_16x16x32_bf16 v[34:37], v[164:167], v[206:209], v[34:37]
	v_mfma_f32_16x16x32_bf16 v[22:25], v[156:159], v[214:217], v[22:25]
	v_mfma_f32_16x16x32_bf16 v[18:21], v[164:167], v[214:217], v[18:21]
	v_mfma_f32_16x16x32_bf16 v[46:49], v[168:171], v[184:187], 0
	v_mfma_f32_16x16x32_bf16 v[42:45], v[176:179], v[184:187], 0
	v_mfma_f32_16x16x32_bf16 v[30:33], v[168:171], v[192:195], 0
	v_mfma_f32_16x16x32_bf16 v[26:29], v[176:179], v[192:195], 0
	v_mfma_f32_16x16x32_bf16 v[14:17], v[168:171], v[200:203], 0
	v_mfma_f32_16x16x32_bf16 v[10:13], v[176:179], v[200:203], 0
	v_mfma_f32_16x16x32_bf16 v[6:9], v[168:171], v[210:213], 0
	v_mfma_f32_16x16x32_bf16 v[2:5], v[176:179], v[210:213], 0
	v_mfma_f32_16x16x32_bf16 v[46:49], v[172:175], v[188:191], v[46:49]
	v_mfma_f32_16x16x32_bf16 v[42:45], v[180:183], v[188:191], v[42:45]
	v_mfma_f32_16x16x32_bf16 v[30:33], v[172:175], v[196:199], v[30:33]
	v_mfma_f32_16x16x32_bf16 v[26:29], v[180:183], v[196:199], v[26:29]
	v_mfma_f32_16x16x32_bf16 v[14:17], v[172:175], v[206:209], v[14:17]
	v_mfma_f32_16x16x32_bf16 v[10:13], v[180:183], v[206:209], v[10:13]
	v_mfma_f32_16x16x32_bf16 v[6:9], v[172:175], v[214:217], v[6:9]
	v_mfma_f32_16x16x32_bf16 v[2:5], v[180:183], v[214:217], v[2:5]
	s_setprio 0
	s_barrier
	ds_read_b128 v[152:155], v149
	ds_read_b128 v[156:159], v149 offset:1024
	ds_read_b128 v[160:163], v149 offset:2048
	ds_read_b128 v[164:167], v149 offset:3072
	ds_read_b128 v[168:171], v150
	ds_read_b128 v[172:175], v150 offset:1024
	ds_read_b128 v[176:179], v150 offset:2048
	ds_read_b128 v[180:183], v150 offset:3072
	s_add_u32 s42, s48, 0x20000
	s_addc_u32 s43, s49, 0
	s_mov_b32 m0, s16
	v_lshl_add_u64 v[226:227], s[42:43], 0, v[136:137]
	ds_read_b128 v[184:187], v148 offset:32768
	ds_read_b128 v[188:191], v148 offset:33792
	ds_read_b128 v[192:195], v148 offset:34816
	ds_read_b128 v[196:199], v148 offset:35840
	ds_read_b128 v[200:203], v148 offset:36864
	ds_read_b128 v[206:209], v148 offset:37888
	ds_read_b128 v[210:213], v148 offset:38912
	ds_read_b128 v[214:217], v148 offset:39936
	global_load_lds_dwordx4 v[226:227], off
	v_lshl_add_u64 v[226:227], s[42:43], 0, v[132:133]
	s_mov_b32 m0, s17
	s_nop 0
	global_load_lds_dwordx4 v[226:227], off
	s_waitcnt vmcnt(8)
	s_waitcnt lgkmcnt(0)
	s_setprio 1
	s_barrier
	v_mfma_f32_16x16x32_bf16 v[126:129], v[152:155], v[184:187], v[126:129]
	v_mfma_f32_16x16x32_bf16 v[122:125], v[160:163], v[184:187], v[122:125]
	s_mov_b32 m0, s62
	v_lshl_add_u64 v[218:219], v[218:219], 0, s[10:11]
	s_add_u32 s42, s46, 0x20080
	v_mfma_f32_16x16x32_bf16 v[118:121], v[152:155], v[192:195], v[118:121]
	v_mfma_f32_16x16x32_bf16 v[114:117], v[160:163], v[192:195], v[114:117]
	v_mfma_f32_16x16x32_bf16 v[102:105], v[152:155], v[200:203], v[102:105]
	v_mfma_f32_16x16x32_bf16 v[98:101], v[160:163], v[200:203], v[98:101]
	v_mfma_f32_16x16x32_bf16 v[86:89], v[152:155], v[210:213], v[86:89]
	v_mfma_f32_16x16x32_bf16 v[82:85], v[160:163], v[210:213], v[82:85]
	v_mfma_f32_16x16x32_bf16 v[126:129], v[156:159], v[188:191], v[126:129]
	v_mfma_f32_16x16x32_bf16 v[122:125], v[164:167], v[188:191], v[122:125]
	v_mfma_f32_16x16x32_bf16 v[118:121], v[156:159], v[196:199], v[118:121]
	v_mfma_f32_16x16x32_bf16 v[114:117], v[164:167], v[196:199], v[114:117]
	v_mfma_f32_16x16x32_bf16 v[102:105], v[156:159], v[206:209], v[102:105]
	v_mfma_f32_16x16x32_bf16 v[98:101], v[164:167], v[206:209], v[98:101]
	v_mfma_f32_16x16x32_bf16 v[86:89], v[156:159], v[214:217], v[86:89]
	v_mfma_f32_16x16x32_bf16 v[82:85], v[164:167], v[214:217], v[82:85]
	v_mfma_f32_16x16x32_bf16 v[110:113], v[168:171], v[184:187], v[110:113]
	v_mfma_f32_16x16x32_bf16 v[106:109], v[176:179], v[184:187], v[106:109]
	v_mfma_f32_16x16x32_bf16 v[94:97], v[168:171], v[192:195], v[94:97]
	v_mfma_f32_16x16x32_bf16 v[90:93], v[176:179], v[192:195], v[90:93]
	v_mfma_f32_16x16x32_bf16 v[78:81], v[168:171], v[200:203], v[78:81]
	v_mfma_f32_16x16x32_bf16 v[74:77], v[176:179], v[200:203], v[74:77]
	v_mfma_f32_16x16x32_bf16 v[70:73], v[168:171], v[210:213], v[70:73]
	v_mfma_f32_16x16x32_bf16 v[66:69], v[176:179], v[210:213], v[66:69]
	v_mfma_f32_16x16x32_bf16 v[110:113], v[172:175], v[188:191], v[110:113]
	v_mfma_f32_16x16x32_bf16 v[106:109], v[180:183], v[188:191], v[106:109]
	v_mfma_f32_16x16x32_bf16 v[94:97], v[172:175], v[196:199], v[94:97]
	v_mfma_f32_16x16x32_bf16 v[90:93], v[180:183], v[196:199], v[90:93]
	v_mfma_f32_16x16x32_bf16 v[78:81], v[172:175], v[206:209], v[78:81]
	v_mfma_f32_16x16x32_bf16 v[74:77], v[180:183], v[206:209], v[74:77]
	v_mfma_f32_16x16x32_bf16 v[70:73], v[172:175], v[214:217], v[70:73]
	v_mfma_f32_16x16x32_bf16 v[66:69], v[180:183], v[214:217], v[66:69]
	s_setprio 0
	s_barrier
	ds_read_b128 v[184:187], v148 offset:49152
	ds_read_b128 v[188:191], v148 offset:50176
	ds_read_b128 v[192:195], v148 offset:51200
	ds_read_b128 v[196:199], v148 offset:52224
	ds_read_b128 v[200:203], v148 offset:53248
	ds_read_b128 v[206:209], v148 offset:54272
	ds_read_b128 v[210:213], v148 offset:55296
	ds_read_b128 v[214:217], v148 offset:56320
	global_load_lds_dwordx4 v[218:219], off
	v_lshl_add_u64 v[218:219], v[220:221], 0, s[10:11]
	s_mov_b32 m0, s63
	s_addc_u32 s43, s47, 0
	global_load_lds_dwordx4 v[218:219], off
	v_lshl_add_u64 v[218:219], s[42:43], 0, v[134:135]
	s_mov_b32 m0, s64
	s_nop 0
	global_load_lds_dwordx4 v[218:219], off
	v_lshl_add_u64 v[218:219], s[42:43], 0, v[130:131]
	s_mov_b32 m0, s65
	s_nop 0
	global_load_lds_dwordx4 v[218:219], off
	v_lshl_add_u64 v[218:219], v[222:223], 0, s[10:11]
	s_mov_b32 m0, s25
	s_nop 0
	global_load_lds_dwordx4 v[218:219], off
	v_lshl_add_u64 v[218:219], v[224:225], 0, s[10:11]
	s_mov_b32 m0, s28
	s_nop 0
	global_load_lds_dwordx4 v[218:219], off
	s_waitcnt vmcnt(8)
	s_waitcnt lgkmcnt(0)
	s_setprio 1
	s_barrier
	v_mfma_f32_16x16x32_bf16 v[62:65], v[152:155], v[184:187], v[62:65]
	v_mfma_f32_16x16x32_bf16 v[58:61], v[160:163], v[184:187], v[58:61]
	s_add_i32 s68, s68, 2
	s_cmp_gt_u32 s68, 5
	s_mov_b64 s[42:43], s[44:45]
	v_mfma_f32_16x16x32_bf16 v[54:57], v[152:155], v[192:195], v[54:57]
	v_mfma_f32_16x16x32_bf16 v[50:53], v[160:163], v[192:195], v[50:53]
	v_mfma_f32_16x16x32_bf16 v[38:41], v[152:155], v[200:203], v[38:41]
	v_mfma_f32_16x16x32_bf16 v[34:37], v[160:163], v[200:203], v[34:37]
	v_mfma_f32_16x16x32_bf16 v[22:25], v[152:155], v[210:213], v[22:25]
	v_mfma_f32_16x16x32_bf16 v[18:21], v[160:163], v[210:213], v[18:21]
	v_mfma_f32_16x16x32_bf16 v[62:65], v[156:159], v[188:191], v[62:65]
	v_mfma_f32_16x16x32_bf16 v[58:61], v[164:167], v[188:191], v[58:61]
	v_mfma_f32_16x16x32_bf16 v[54:57], v[156:159], v[196:199], v[54:57]
	v_mfma_f32_16x16x32_bf16 v[50:53], v[164:167], v[196:199], v[50:53]
	v_mfma_f32_16x16x32_bf16 v[38:41], v[156:159], v[206:209], v[38:41]
	v_mfma_f32_16x16x32_bf16 v[34:37], v[164:167], v[206:209], v[34:37]
	v_mfma_f32_16x16x32_bf16 v[22:25], v[156:159], v[214:217], v[22:25]
	v_mfma_f32_16x16x32_bf16 v[18:21], v[164:167], v[214:217], v[18:21]
	v_mfma_f32_16x16x32_bf16 v[46:49], v[168:171], v[184:187], v[46:49]
	v_mfma_f32_16x16x32_bf16 v[42:45], v[176:179], v[184:187], v[42:45]
	v_mfma_f32_16x16x32_bf16 v[30:33], v[168:171], v[192:195], v[30:33]
	v_mfma_f32_16x16x32_bf16 v[26:29], v[176:179], v[192:195], v[26:29]
	v_mfma_f32_16x16x32_bf16 v[14:17], v[168:171], v[200:203], v[14:17]
	v_mfma_f32_16x16x32_bf16 v[10:13], v[176:179], v[200:203], v[10:13]
	v_mfma_f32_16x16x32_bf16 v[6:9], v[168:171], v[210:213], v[6:9]
	v_mfma_f32_16x16x32_bf16 v[2:5], v[176:179], v[210:213], v[2:5]
	v_mfma_f32_16x16x32_bf16 v[46:49], v[172:175], v[188:191], v[46:49]
	v_mfma_f32_16x16x32_bf16 v[42:45], v[180:183], v[188:191], v[42:45]
	v_mfma_f32_16x16x32_bf16 v[30:33], v[172:175], v[196:199], v[30:33]
	v_mfma_f32_16x16x32_bf16 v[26:29], v[180:183], v[196:199], v[26:29]
	v_mfma_f32_16x16x32_bf16 v[14:17], v[172:175], v[206:209], v[14:17]
	v_mfma_f32_16x16x32_bf16 v[10:13], v[180:183], v[206:209], v[10:13]
	v_mfma_f32_16x16x32_bf16 v[6:9], v[172:175], v[214:217], v[6:9]
	v_mfma_f32_16x16x32_bf16 v[2:5], v[180:183], v[214:217], v[2:5]
	s_setprio 0
	s_barrier
.LBB0_384:
	ds_read_b128 v[152:155], v146
	ds_read_b128 v[156:159], v146 offset:1024
	ds_read_b128 v[160:163], v146 offset:2048
	ds_read_b128 v[164:167], v146 offset:3072
	ds_read_b128 v[168:171], v147
	ds_read_b128 v[172:175], v147 offset:1024
	ds_read_b128 v[176:179], v147 offset:2048
	ds_read_b128 v[180:183], v147 offset:3072
	s_add_u32 s44, s42, 0x100
	s_addc_u32 s45, s43, 0
	s_add_u32 s46, s66, s42
	s_addc_u32 s47, s67, s43
	s_cmp_eq_u32 s68, 4
	s_cselect_b32 s48, 0, s44
	s_cselect_b32 s49, 0, s45
	s_cselect_b32 s46, s39, s46
	s_cselect_b32 s47, s15, s47
	s_add_u32 s48, s6, s48
	s_addc_u32 s49, s7, s49
	s_mov_b32 m0, s29
	v_lshl_add_u64 v[218:219], v[138:139], 0, s[42:43]
	ds_read_b128 v[184:187], v148
	ds_read_b128 v[188:191], v148 offset:1024
	ds_read_b128 v[192:195], v148 offset:2048
	ds_read_b128 v[196:199], v148 offset:3072
	ds_read_b128 v[200:203], v148 offset:4096
	ds_read_b128 v[206:209], v148 offset:5120
	ds_read_b128 v[210:213], v148 offset:6144
	ds_read_b128 v[214:217], v148 offset:7168
	global_load_lds_dwordx4 v[218:219], off
	v_lshl_add_u64 v[218:219], v[140:141], 0, s[42:43]
	s_mov_b32 m0, s30
	s_nop 0
	global_load_lds_dwordx4 v[218:219], off
	s_waitcnt vmcnt(8)
	s_waitcnt lgkmcnt(0)
	s_setprio 1
	s_barrier
	v_mfma_f32_16x16x32_bf16 v[126:129], v[152:155], v[184:187], v[126:129]
	v_mfma_f32_16x16x32_bf16 v[122:125], v[160:163], v[184:187], v[122:125]
	s_mov_b32 m0, s31
	v_lshl_add_u64 v[218:219], s[46:47], 0, v[134:135]
	s_add_u32 s42, s46, 0x20000
	v_mfma_f32_16x16x32_bf16 v[118:121], v[152:155], v[192:195], v[118:121]
	v_mfma_f32_16x16x32_bf16 v[114:117], v[160:163], v[192:195], v[114:117]
	v_mfma_f32_16x16x32_bf16 v[102:105], v[152:155], v[200:203], v[102:105]
	v_mfma_f32_16x16x32_bf16 v[98:101], v[160:163], v[200:203], v[98:101]
	v_mfma_f32_16x16x32_bf16 v[86:89], v[152:155], v[210:213], v[86:89]
	v_mfma_f32_16x16x32_bf16 v[82:85], v[160:163], v[210:213], v[82:85]
	v_mfma_f32_16x16x32_bf16 v[126:129], v[156:159], v[188:191], v[126:129]
	v_mfma_f32_16x16x32_bf16 v[122:125], v[164:167], v[188:191], v[122:125]
	v_mfma_f32_16x16x32_bf16 v[118:121], v[156:159], v[196:199], v[118:121]
	v_mfma_f32_16x16x32_bf16 v[114:117], v[164:167], v[196:199], v[114:117]
	v_mfma_f32_16x16x32_bf16 v[102:105], v[156:159], v[206:209], v[102:105]
	v_mfma_f32_16x16x32_bf16 v[98:101], v[164:167], v[206:209], v[98:101]
	v_mfma_f32_16x16x32_bf16 v[86:89], v[156:159], v[214:217], v[86:89]
	v_mfma_f32_16x16x32_bf16 v[82:85], v[164:167], v[214:217], v[82:85]
	v_mfma_f32_16x16x32_bf16 v[110:113], v[168:171], v[184:187], v[110:113]
	v_mfma_f32_16x16x32_bf16 v[106:109], v[176:179], v[184:187], v[106:109]
	v_mfma_f32_16x16x32_bf16 v[94:97], v[168:171], v[192:195], v[94:97]
	v_mfma_f32_16x16x32_bf16 v[90:93], v[176:179], v[192:195], v[90:93]
	v_mfma_f32_16x16x32_bf16 v[78:81], v[168:171], v[200:203], v[78:81]
	v_mfma_f32_16x16x32_bf16 v[74:77], v[176:179], v[200:203], v[74:77]
	v_mfma_f32_16x16x32_bf16 v[70:73], v[168:171], v[210:213], v[70:73]
	v_mfma_f32_16x16x32_bf16 v[66:69], v[176:179], v[210:213], v[66:69]
	v_mfma_f32_16x16x32_bf16 v[110:113], v[172:175], v[188:191], v[110:113]
	v_mfma_f32_16x16x32_bf16 v[106:109], v[180:183], v[188:191], v[106:109]
	v_mfma_f32_16x16x32_bf16 v[94:97], v[172:175], v[196:199], v[94:97]
	v_mfma_f32_16x16x32_bf16 v[90:93], v[180:183], v[196:199], v[90:93]
	v_mfma_f32_16x16x32_bf16 v[78:81], v[172:175], v[206:209], v[78:81]
	v_mfma_f32_16x16x32_bf16 v[74:77], v[180:183], v[206:209], v[74:77]
	v_mfma_f32_16x16x32_bf16 v[70:73], v[172:175], v[214:217], v[70:73]
	v_mfma_f32_16x16x32_bf16 v[66:69], v[180:183], v[214:217], v[66:69]
	s_setprio 0
	s_barrier
	ds_read_b128 v[184:187], v148 offset:16384
	ds_read_b128 v[188:191], v148 offset:17408
	ds_read_b128 v[192:195], v148 offset:18432
	ds_read_b128 v[196:199], v148 offset:19456
	ds_read_b128 v[200:203], v148 offset:20480
	ds_read_b128 v[206:209], v148 offset:21504
	ds_read_b128 v[210:213], v148 offset:22528
	ds_read_b128 v[214:217], v148 offset:23552
	global_load_lds_dwordx4 v[218:219], off
	v_lshl_add_u64 v[220:221], s[46:47], 0, v[130:131]
	s_mov_b32 m0, s33
	s_addc_u32 s43, s47, 0
	global_load_lds_dwordx4 v[220:221], off
	v_lshl_add_u64 v[222:223], s[42:43], 0, v[134:135]
	s_mov_b32 m0, s34
	v_lshl_add_u64 v[224:225], s[48:49], 0, v[132:133]
	global_load_lds_dwordx4 v[222:223], off
	v_lshl_add_u64 v[222:223], s[42:43], 0, v[130:131]
	s_mov_b32 m0, s35
	s_nop 0
	global_load_lds_dwordx4 v[222:223], off
	v_lshl_add_u64 v[222:223], s[48:49], 0, v[136:137]
	s_mov_b32 m0, s2
	s_nop 0
	global_load_lds_dwordx4 v[222:223], off
	s_mov_b32 m0, s3
	s_nop 0
	global_load_lds_dwordx4 v[224:225], off
	s_waitcnt vmcnt(8)
	s_waitcnt lgkmcnt(0)
	s_setprio 1
	s_barrier
	v_mfma_f32_16x16x32_bf16 v[62:65], v[152:155], v[184:187], v[62:65]
	v_mfma_f32_16x16x32_bf16 v[58:61], v[160:163], v[184:187], v[58:61]
	v_mfma_f32_16x16x32_bf16 v[54:57], v[152:155], v[192:195], v[54:57]
	v_mfma_f32_16x16x32_bf16 v[50:53], v[160:163], v[192:195], v[50:53]
	v_mfma_f32_16x16x32_bf16 v[38:41], v[152:155], v[200:203], v[38:41]
	v_mfma_f32_16x16x32_bf16 v[34:37], v[160:163], v[200:203], v[34:37]
	v_mfma_f32_16x16x32_bf16 v[22:25], v[152:155], v[210:213], v[22:25]
	v_mfma_f32_16x16x32_bf16 v[18:21], v[160:163], v[210:213], v[18:21]
	v_mfma_f32_16x16x32_bf16 v[62:65], v[156:159], v[188:191], v[62:65]
	v_mfma_f32_16x16x32_bf16 v[58:61], v[164:167], v[188:191], v[58:61]
	v_mfma_f32_16x16x32_bf16 v[54:57], v[156:159], v[196:199], v[54:57]
	v_mfma_f32_16x16x32_bf16 v[50:53], v[164:167], v[196:199], v[50:53]
	v_mfma_f32_16x16x32_bf16 v[38:41], v[156:159], v[206:209], v[38:41]
	v_mfma_f32_16x16x32_bf16 v[34:37], v[164:167], v[206:209], v[34:37]
	v_mfma_f32_16x16x32_bf16 v[22:25], v[156:159], v[214:217], v[22:25]
	v_mfma_f32_16x16x32_bf16 v[18:21], v[164:167], v[214:217], v[18:21]
	v_mfma_f32_16x16x32_bf16 v[46:49], v[168:171], v[184:187], v[46:49]
	v_mfma_f32_16x16x32_bf16 v[42:45], v[176:179], v[184:187], v[42:45]
	v_mfma_f32_16x16x32_bf16 v[30:33], v[168:171], v[192:195], v[30:33]
	v_mfma_f32_16x16x32_bf16 v[26:29], v[176:179], v[192:195], v[26:29]
	v_mfma_f32_16x16x32_bf16 v[14:17], v[168:171], v[200:203], v[14:17]
	v_mfma_f32_16x16x32_bf16 v[10:13], v[176:179], v[200:203], v[10:13]
	v_mfma_f32_16x16x32_bf16 v[6:9], v[168:171], v[210:213], v[6:9]
	v_mfma_f32_16x16x32_bf16 v[2:5], v[176:179], v[210:213], v[2:5]
	v_mfma_f32_16x16x32_bf16 v[46:49], v[172:175], v[188:191], v[46:49]
	v_mfma_f32_16x16x32_bf16 v[42:45], v[180:183], v[188:191], v[42:45]
	v_mfma_f32_16x16x32_bf16 v[30:33], v[172:175], v[196:199], v[30:33]
	v_mfma_f32_16x16x32_bf16 v[26:29], v[180:183], v[196:199], v[26:29]
	v_mfma_f32_16x16x32_bf16 v[14:17], v[172:175], v[206:209], v[14:17]
	v_mfma_f32_16x16x32_bf16 v[10:13], v[180:183], v[206:209], v[10:13]
	v_mfma_f32_16x16x32_bf16 v[6:9], v[172:175], v[214:217], v[6:9]
	v_mfma_f32_16x16x32_bf16 v[2:5], v[180:183], v[214:217], v[2:5]
	s_setprio 0
	s_barrier
	ds_read_b128 v[152:155], v149
	ds_read_b128 v[156:159], v149 offset:1024
	ds_read_b128 v[160:163], v149 offset:2048
	ds_read_b128 v[164:167], v149 offset:3072
	ds_read_b128 v[168:171], v150
	ds_read_b128 v[172:175], v150 offset:1024
	ds_read_b128 v[176:179], v150 offset:2048
	ds_read_b128 v[180:183], v150 offset:3072
	s_add_u32 s42, s48, 0x20000
	s_addc_u32 s43, s49, 0
	s_mov_b32 m0, s16
	v_lshl_add_u64 v[226:227], s[42:43], 0, v[136:137]
	ds_read_b128 v[184:187], v148 offset:32768
	ds_read_b128 v[188:191], v148 offset:33792
	ds_read_b128 v[192:195], v148 offset:34816
	ds_read_b128 v[196:199], v148 offset:35840
	ds_read_b128 v[200:203], v148 offset:36864
	ds_read_b128 v[206:209], v148 offset:37888
	ds_read_b128 v[210:213], v148 offset:38912
	ds_read_b128 v[214:217], v148 offset:39936
	global_load_lds_dwordx4 v[226:227], off
	v_lshl_add_u64 v[226:227], s[42:43], 0, v[132:133]
	s_mov_b32 m0, s17
	s_nop 0
	global_load_lds_dwordx4 v[226:227], off
	s_waitcnt vmcnt(8)
	s_waitcnt lgkmcnt(0)
	s_setprio 1
	s_barrier
	v_mfma_f32_16x16x32_bf16 v[126:129], v[152:155], v[184:187], v[126:129]
	v_mfma_f32_16x16x32_bf16 v[122:125], v[160:163], v[184:187], v[122:125]
	s_mov_b32 m0, s62
	v_lshl_add_u64 v[218:219], v[218:219], 0, s[10:11]
	s_add_u32 s42, s46, 0x20080
	v_mfma_f32_16x16x32_bf16 v[118:121], v[152:155], v[192:195], v[118:121]
	v_mfma_f32_16x16x32_bf16 v[114:117], v[160:163], v[192:195], v[114:117]
	v_mfma_f32_16x16x32_bf16 v[102:105], v[152:155], v[200:203], v[102:105]
	v_mfma_f32_16x16x32_bf16 v[98:101], v[160:163], v[200:203], v[98:101]
	v_mfma_f32_16x16x32_bf16 v[86:89], v[152:155], v[210:213], v[86:89]
	v_mfma_f32_16x16x32_bf16 v[82:85], v[160:163], v[210:213], v[82:85]
	v_mfma_f32_16x16x32_bf16 v[126:129], v[156:159], v[188:191], v[126:129]
	v_mfma_f32_16x16x32_bf16 v[122:125], v[164:167], v[188:191], v[122:125]
	v_mfma_f32_16x16x32_bf16 v[118:121], v[156:159], v[196:199], v[118:121]
	v_mfma_f32_16x16x32_bf16 v[114:117], v[164:167], v[196:199], v[114:117]
	v_mfma_f32_16x16x32_bf16 v[102:105], v[156:159], v[206:209], v[102:105]
	v_mfma_f32_16x16x32_bf16 v[98:101], v[164:167], v[206:209], v[98:101]
	v_mfma_f32_16x16x32_bf16 v[86:89], v[156:159], v[214:217], v[86:89]
	v_mfma_f32_16x16x32_bf16 v[82:85], v[164:167], v[214:217], v[82:85]
	v_mfma_f32_16x16x32_bf16 v[110:113], v[168:171], v[184:187], v[110:113]
	v_mfma_f32_16x16x32_bf16 v[106:109], v[176:179], v[184:187], v[106:109]
	v_mfma_f32_16x16x32_bf16 v[94:97], v[168:171], v[192:195], v[94:97]
	v_mfma_f32_16x16x32_bf16 v[90:93], v[176:179], v[192:195], v[90:93]
	v_mfma_f32_16x16x32_bf16 v[78:81], v[168:171], v[200:203], v[78:81]
	v_mfma_f32_16x16x32_bf16 v[74:77], v[176:179], v[200:203], v[74:77]
	v_mfma_f32_16x16x32_bf16 v[70:73], v[168:171], v[210:213], v[70:73]
	v_mfma_f32_16x16x32_bf16 v[66:69], v[176:179], v[210:213], v[66:69]
	v_mfma_f32_16x16x32_bf16 v[110:113], v[172:175], v[188:191], v[110:113]
	v_mfma_f32_16x16x32_bf16 v[106:109], v[180:183], v[188:191], v[106:109]
	v_mfma_f32_16x16x32_bf16 v[94:97], v[172:175], v[196:199], v[94:97]
	v_mfma_f32_16x16x32_bf16 v[90:93], v[180:183], v[196:199], v[90:93]
	v_mfma_f32_16x16x32_bf16 v[78:81], v[172:175], v[206:209], v[78:81]
	v_mfma_f32_16x16x32_bf16 v[74:77], v[180:183], v[206:209], v[74:77]
	v_mfma_f32_16x16x32_bf16 v[70:73], v[172:175], v[214:217], v[70:73]
	v_mfma_f32_16x16x32_bf16 v[66:69], v[180:183], v[214:217], v[66:69]
	s_setprio 0
	s_barrier
	ds_read_b128 v[184:187], v148 offset:49152
	ds_read_b128 v[188:191], v148 offset:50176
	ds_read_b128 v[192:195], v148 offset:51200
	ds_read_b128 v[196:199], v148 offset:52224
	ds_read_b128 v[200:203], v148 offset:53248
	ds_read_b128 v[206:209], v148 offset:54272
	ds_read_b128 v[210:213], v148 offset:55296
	ds_read_b128 v[214:217], v148 offset:56320
	global_load_lds_dwordx4 v[218:219], off
	v_lshl_add_u64 v[218:219], v[220:221], 0, s[10:11]
	s_mov_b32 m0, s63
	s_addc_u32 s43, s47, 0
	global_load_lds_dwordx4 v[218:219], off
	v_lshl_add_u64 v[218:219], s[42:43], 0, v[134:135]
	s_mov_b32 m0, s64
	s_nop 0
	global_load_lds_dwordx4 v[218:219], off
	v_lshl_add_u64 v[218:219], s[42:43], 0, v[130:131]
	s_mov_b32 m0, s65
	s_nop 0
	global_load_lds_dwordx4 v[218:219], off
	v_lshl_add_u64 v[218:219], v[222:223], 0, s[10:11]
	s_mov_b32 m0, s25
	s_nop 0
	global_load_lds_dwordx4 v[218:219], off
	v_lshl_add_u64 v[218:219], v[224:225], 0, s[10:11]
	s_mov_b32 m0, s28
	s_nop 0
	global_load_lds_dwordx4 v[218:219], off
	s_waitcnt vmcnt(8)
	s_waitcnt lgkmcnt(0)
	s_setprio 1
	s_barrier
	v_mfma_f32_16x16x32_bf16 v[62:65], v[152:155], v[184:187], v[62:65]
	v_mfma_f32_16x16x32_bf16 v[58:61], v[160:163], v[184:187], v[58:61]
	s_add_i32 s68, s68, 2
	s_cmp_gt_u32 s68, 5
	s_mov_b64 s[42:43], s[44:45]
	v_mfma_f32_16x16x32_bf16 v[54:57], v[152:155], v[192:195], v[54:57]
	v_mfma_f32_16x16x32_bf16 v[50:53], v[160:163], v[192:195], v[50:53]
	v_mfma_f32_16x16x32_bf16 v[38:41], v[152:155], v[200:203], v[38:41]
	v_mfma_f32_16x16x32_bf16 v[34:37], v[160:163], v[200:203], v[34:37]
	v_mfma_f32_16x16x32_bf16 v[22:25], v[152:155], v[210:213], v[22:25]
	v_mfma_f32_16x16x32_bf16 v[18:21], v[160:163], v[210:213], v[18:21]
	v_mfma_f32_16x16x32_bf16 v[62:65], v[156:159], v[188:191], v[62:65]
	v_mfma_f32_16x16x32_bf16 v[58:61], v[164:167], v[188:191], v[58:61]
	v_mfma_f32_16x16x32_bf16 v[54:57], v[156:159], v[196:199], v[54:57]
	v_mfma_f32_16x16x32_bf16 v[50:53], v[164:167], v[196:199], v[50:53]
	v_mfma_f32_16x16x32_bf16 v[38:41], v[156:159], v[206:209], v[38:41]
	v_mfma_f32_16x16x32_bf16 v[34:37], v[164:167], v[206:209], v[34:37]
	v_mfma_f32_16x16x32_bf16 v[22:25], v[156:159], v[214:217], v[22:25]
	v_mfma_f32_16x16x32_bf16 v[18:21], v[164:167], v[214:217], v[18:21]
	v_mfma_f32_16x16x32_bf16 v[46:49], v[168:171], v[184:187], v[46:49]
	v_mfma_f32_16x16x32_bf16 v[42:45], v[176:179], v[184:187], v[42:45]
	v_mfma_f32_16x16x32_bf16 v[30:33], v[168:171], v[192:195], v[30:33]
	v_mfma_f32_16x16x32_bf16 v[26:29], v[176:179], v[192:195], v[26:29]
	v_mfma_f32_16x16x32_bf16 v[14:17], v[168:171], v[200:203], v[14:17]
	v_mfma_f32_16x16x32_bf16 v[10:13], v[176:179], v[200:203], v[10:13]
	v_mfma_f32_16x16x32_bf16 v[6:9], v[168:171], v[210:213], v[6:9]
	v_mfma_f32_16x16x32_bf16 v[2:5], v[176:179], v[210:213], v[2:5]
	v_mfma_f32_16x16x32_bf16 v[46:49], v[172:175], v[188:191], v[46:49]
	v_mfma_f32_16x16x32_bf16 v[42:45], v[180:183], v[188:191], v[42:45]
	v_mfma_f32_16x16x32_bf16 v[30:33], v[172:175], v[196:199], v[30:33]
	v_mfma_f32_16x16x32_bf16 v[26:29], v[180:183], v[196:199], v[26:29]
	v_mfma_f32_16x16x32_bf16 v[14:17], v[172:175], v[206:209], v[14:17]
	v_mfma_f32_16x16x32_bf16 v[10:13], v[180:183], v[206:209], v[10:13]
	v_mfma_f32_16x16x32_bf16 v[6:9], v[172:175], v[214:217], v[6:9]
	v_mfma_f32_16x16x32_bf16 v[2:5], v[180:183], v[214:217], v[2:5]
	s_setprio 0
	s_barrier
	s_cbranch_scc0 .LBB0_384
	s_and_b64 vcc, exec, s[12:13]
	s_cbranch_vccz .LBB0_387
	s_barrier

.LBB0_406:
	s_lshl_b32 s74, s12, 7
	s_add_i32 s12, s12, 2
	v_cndmask_b32_e64 v138, 0, 1, s[66:67]
	s_lshl_b64 s[66:67], s[12:13], 7
	s_and_b64 s[68:69], s[64:65], exec
	s_cselect_b32 s66, 0, s66
	s_cselect_b32 s67, 0, s67
	s_add_u32 s70, s8, s66
	s_addc_u32 s71, s9, s67
	s_lshl_b64 s[66:67], s[12:13], 12
	s_add_u32 s12, s48, s66
	s_addc_u32 s66, s49, s67
	s_and_b64 s[64:65], s[64:65], exec
	s_cselect_b32 s73, s14, s66
	s_cselect_b32 s72, s15, s12
	s_add_u32 s76, s10, s74
	s_addc_u32 s77, s11, 0
	s_add_i32 s91, s62, s16
	s_add_i32 m0, s17, 0xc000
	s_add_i32 s92, s17, 0xe000
	s_add_i32 s88, s91, 0x2000
	s_add_u32 s74, s72, 0x10000
	ds_read_b128 v[146:149], v141
	ds_read_b128 v[150:153], v141 offset:1024
	ds_read_b128 v[154:157], v141 offset:2048
	ds_read_b128 v[158:161], v141 offset:3072
	ds_read_b128 v[162:165], v143
	ds_read_b128 v[166:169], v143 offset:1024
	ds_read_b128 v[170:173], v143 offset:2048
	ds_read_b128 v[174:177], v143 offset:3072
	s_addc_u32 s75, s73, 0
	s_add_i32 s90, s63, s16
	s_add_i32 s89, s90, 0x2000
	s_add_i32 s87, 0, 0x18000
	s_add_i32 s86, 0, 0x1c000
	s_add_u32 s68, s70, 0x10000
	s_addc_u32 s69, s71, 0
	s_add_u32 s64, s72, 0x1000
	s_addc_u32 s65, s73, 0
	s_add_i32 s85, s87, s16
	s_add_i32 s83, s85, 0x2000
	s_add_u32 s66, s72, 0x11000
	s_addc_u32 s67, s73, 0
	s_add_i32 s84, s86, s16
	s_add_i32 s12, s84, 0x2000
	v_cmp_ne_u32_e32 vcc, 1, v138
	v_lshl_add_u64 v[202:203], s[76:77], 0, v[136:137]
	v_lshl_add_u64 v[202:203], v[202:203], 0, s[36:37]
	ds_read_b128 v[178:181], v144
	ds_read_b128 v[182:185], v144 offset:1024
	ds_read_b128 v[186:189], v144 offset:2048
	ds_read_b128 v[190:193], v144 offset:3072
	ds_read_b128 v[194:197], v144 offset:4096
	ds_read_b128 v[198:201], v144 offset:5120
	ds_read_b128 v[206:209], v144 offset:6144
	ds_read_b128 v[210:213], v144 offset:7168
	global_load_lds_dwordx4 v[202:203], off
	v_lshl_add_u64 v[202:203], s[76:77], 0, v[132:133]
	v_lshl_add_u64 v[202:203], v[202:203], 0, s[36:37]
	s_mov_b32 m0, s92
	s_nop 0
	global_load_lds_dwordx4 v[202:203], off
	s_waitcnt vmcnt(8)
	s_waitcnt lgkmcnt(0)
	s_setprio 1
	s_barrier
	v_mfma_f32_16x16x32_bf16 v[126:129], v[146:149], v[178:181], v[126:129]
	v_mfma_f32_16x16x32_bf16 v[122:125], v[154:157], v[178:181], v[122:125]
	s_mov_b32 m0, s91
	v_lshl_add_u64 v[202:203], s[72:73], 0, v[134:135]
	v_mfma_f32_16x16x32_bf16 v[118:121], v[146:149], v[186:189], v[118:121]
	v_mfma_f32_16x16x32_bf16 v[110:113], v[154:157], v[186:189], v[110:113]
	v_mfma_f32_16x16x32_bf16 v[102:105], v[146:149], v[194:197], v[102:105]
	v_mfma_f32_16x16x32_bf16 v[98:101], v[154:157], v[194:197], v[98:101]
	v_mfma_f32_16x16x32_bf16 v[86:89], v[146:149], v[206:209], v[86:89]
	v_mfma_f32_16x16x32_bf16 v[82:85], v[154:157], v[206:209], v[82:85]
	v_mfma_f32_16x16x32_bf16 v[126:129], v[150:153], v[182:185], v[126:129]
	v_mfma_f32_16x16x32_bf16 v[122:125], v[158:161], v[182:185], v[122:125]
	v_mfma_f32_16x16x32_bf16 v[118:121], v[150:153], v[190:193], v[118:121]
	v_mfma_f32_16x16x32_bf16 v[110:113], v[158:161], v[190:193], v[110:113]
	v_mfma_f32_16x16x32_bf16 v[102:105], v[150:153], v[198:201], v[102:105]
	v_mfma_f32_16x16x32_bf16 v[98:101], v[158:161], v[198:201], v[98:101]
	v_mfma_f32_16x16x32_bf16 v[86:89], v[150:153], v[210:213], v[86:89]
	v_mfma_f32_16x16x32_bf16 v[82:85], v[158:161], v[210:213], v[82:85]
	v_mfma_f32_16x16x32_bf16 v[114:117], v[162:165], v[178:181], v[114:117]
	v_mfma_f32_16x16x32_bf16 v[106:109], v[170:173], v[178:181], v[106:109]
	v_mfma_f32_16x16x32_bf16 v[94:97], v[162:165], v[186:189], v[94:97]
	v_mfma_f32_16x16x32_bf16 v[90:93], v[170:173], v[186:189], v[90:93]
	v_mfma_f32_16x16x32_bf16 v[78:81], v[162:165], v[194:197], v[78:81]
	v_mfma_f32_16x16x32_bf16 v[74:77], v[170:173], v[194:197], v[74:77]
	v_mfma_f32_16x16x32_bf16 v[70:73], v[162:165], v[206:209], v[70:73]
	v_mfma_f32_16x16x32_bf16 v[66:69], v[170:173], v[206:209], v[66:69]
	v_mfma_f32_16x16x32_bf16 v[114:117], v[166:169], v[182:185], v[114:117]
	v_mfma_f32_16x16x32_bf16 v[106:109], v[174:177], v[182:185], v[106:109]
	v_mfma_f32_16x16x32_bf16 v[94:97], v[166:169], v[190:193], v[94:97]
	v_mfma_f32_16x16x32_bf16 v[90:93], v[174:177], v[190:193], v[90:93]
	v_mfma_f32_16x16x32_bf16 v[78:81], v[166:169], v[198:201], v[78:81]
	v_mfma_f32_16x16x32_bf16 v[74:77], v[174:177], v[198:201], v[74:77]
	v_mfma_f32_16x16x32_bf16 v[70:73], v[166:169], v[210:213], v[70:73]
	v_mfma_f32_16x16x32_bf16 v[66:69], v[174:177], v[210:213], v[66:69]
	s_setprio 0
	s_barrier
	ds_read_b128 v[178:181], v144 offset:16384
	ds_read_b128 v[182:185], v144 offset:17408
	ds_read_b128 v[186:189], v144 offset:18432
	ds_read_b128 v[190:193], v144 offset:19456
	ds_read_b128 v[194:197], v144 offset:20480
	ds_read_b128 v[198:201], v144 offset:21504
	ds_read_b128 v[206:209], v144 offset:22528
	ds_read_b128 v[210:213], v144 offset:23552
	global_load_lds_dwordx4 v[202:203], off
	v_lshl_add_u64 v[202:203], s[72:73], 0, v[130:131]
	s_mov_b32 m0, s88
	v_lshl_add_u64 v[214:215], s[70:71], 0, v[132:133]
	global_load_lds_dwordx4 v[202:203], off
	v_lshl_add_u64 v[202:203], s[74:75], 0, v[134:135]
	s_mov_b32 m0, s90
	s_nop 0
	global_load_lds_dwordx4 v[202:203], off
	v_lshl_add_u64 v[202:203], s[74:75], 0, v[130:131]
	s_mov_b32 m0, s89
	s_nop 0
	global_load_lds_dwordx4 v[202:203], off
	v_lshl_add_u64 v[202:203], s[70:71], 0, v[136:137]
	s_mov_b32 m0, s17
	s_nop 0
	global_load_lds_dwordx4 v[202:203], off
	s_mov_b32 m0, s18
	s_nop 0
	global_load_lds_dwordx4 v[214:215], off
	s_waitcnt vmcnt(8)
	s_waitcnt lgkmcnt(0)
	s_setprio 1
	s_barrier
	v_mfma_f32_16x16x32_bf16 v[62:65], v[146:149], v[178:181], v[62:65]
	v_mfma_f32_16x16x32_bf16 v[58:61], v[154:157], v[178:181], v[58:61]
	v_add_u32_e32 v138, s87, v140
	v_mfma_f32_16x16x32_bf16 v[54:57], v[146:149], v[186:189], v[54:57]
	v_mfma_f32_16x16x32_bf16 v[50:53], v[154:157], v[186:189], v[50:53]
	v_mfma_f32_16x16x32_bf16 v[38:41], v[146:149], v[194:197], v[38:41]
	v_mfma_f32_16x16x32_bf16 v[34:37], v[154:157], v[194:197], v[34:37]
	v_mfma_f32_16x16x32_bf16 v[22:25], v[146:149], v[206:209], v[22:25]
	v_mfma_f32_16x16x32_bf16 v[18:21], v[154:157], v[206:209], v[18:21]
	v_mfma_f32_16x16x32_bf16 v[62:65], v[150:153], v[182:185], v[62:65]
	v_mfma_f32_16x16x32_bf16 v[58:61], v[158:161], v[182:185], v[58:61]
	v_mfma_f32_16x16x32_bf16 v[54:57], v[150:153], v[190:193], v[54:57]
	v_mfma_f32_16x16x32_bf16 v[50:53], v[158:161], v[190:193], v[50:53]
	v_mfma_f32_16x16x32_bf16 v[38:41], v[150:153], v[198:201], v[38:41]
	v_mfma_f32_16x16x32_bf16 v[34:37], v[158:161], v[198:201], v[34:37]
	v_mfma_f32_16x16x32_bf16 v[22:25], v[150:153], v[210:213], v[22:25]
	v_mfma_f32_16x16x32_bf16 v[18:21], v[158:161], v[210:213], v[18:21]
	v_mfma_f32_16x16x32_bf16 v[46:49], v[162:165], v[178:181], v[46:49]
	v_mfma_f32_16x16x32_bf16 v[42:45], v[170:173], v[178:181], v[42:45]
	v_mfma_f32_16x16x32_bf16 v[30:33], v[162:165], v[186:189], v[30:33]
	v_mfma_f32_16x16x32_bf16 v[26:29], v[170:173], v[186:189], v[26:29]
	v_mfma_f32_16x16x32_bf16 v[14:17], v[162:165], v[194:197], v[14:17]
	v_mfma_f32_16x16x32_bf16 v[10:13], v[170:173], v[194:197], v[10:13]
	v_mfma_f32_16x16x32_bf16 v[6:9], v[162:165], v[206:209], v[6:9]
	v_mfma_f32_16x16x32_bf16 v[2:5], v[170:173], v[206:209], v[2:5]
	v_mfma_f32_16x16x32_bf16 v[46:49], v[166:169], v[182:185], v[46:49]
	v_mfma_f32_16x16x32_bf16 v[42:45], v[174:177], v[182:185], v[42:45]
	v_mfma_f32_16x16x32_bf16 v[30:33], v[166:169], v[190:193], v[30:33]
	v_mfma_f32_16x16x32_bf16 v[26:29], v[174:177], v[190:193], v[26:29]
	v_mfma_f32_16x16x32_bf16 v[14:17], v[166:169], v[198:201], v[14:17]
	v_mfma_f32_16x16x32_bf16 v[10:13], v[174:177], v[198:201], v[10:13]
	v_mfma_f32_16x16x32_bf16 v[6:9], v[166:169], v[210:213], v[6:9]
	v_mfma_f32_16x16x32_bf16 v[2:5], v[174:177], v[210:213], v[2:5]
	s_setprio 0
	s_barrier
	ds_read_b128 v[146:149], v138
	ds_read_b128 v[150:153], v138 offset:1024
	ds_read_b128 v[154:157], v138 offset:2048
	ds_read_b128 v[158:161], v138 offset:3072
	v_add_u32_e32 v138, s86, v140
	ds_read_b128 v[162:165], v138
	ds_read_b128 v[166:169], v138 offset:1024
	ds_read_b128 v[170:173], v138 offset:2048
	ds_read_b128 v[174:177], v138 offset:3072
	s_mov_b32 m0, s19
	v_lshl_add_u64 v[216:217], s[68:69], 0, v[136:137]
	ds_read_b128 v[178:181], v144 offset:32768
	ds_read_b128 v[182:185], v144 offset:33792
	ds_read_b128 v[186:189], v144 offset:34816
	ds_read_b128 v[190:193], v144 offset:35840
	ds_read_b128 v[194:197], v144 offset:36864
	ds_read_b128 v[198:201], v144 offset:37888
	ds_read_b128 v[206:209], v144 offset:38912
	ds_read_b128 v[210:213], v144 offset:39936
	global_load_lds_dwordx4 v[216:217], off
	v_lshl_add_u64 v[216:217], s[68:69], 0, v[132:133]
	s_mov_b32 m0, s24
	s_nop 0
	global_load_lds_dwordx4 v[216:217], off
	s_waitcnt vmcnt(8)
	s_waitcnt lgkmcnt(0)
	s_setprio 1
	s_barrier
	v_mfma_f32_16x16x32_bf16 v[126:129], v[146:149], v[178:181], v[126:129]
	v_mfma_f32_16x16x32_bf16 v[122:125], v[154:157], v[178:181], v[122:125]
	s_mov_b32 m0, s85
	v_lshl_add_u64 v[216:217], s[64:65], 0, v[134:135]
	v_mfma_f32_16x16x32_bf16 v[118:121], v[146:149], v[186:189], v[118:121]
	v_mfma_f32_16x16x32_bf16 v[110:113], v[154:157], v[186:189], v[110:113]
	v_mfma_f32_16x16x32_bf16 v[102:105], v[146:149], v[194:197], v[102:105]
	v_mfma_f32_16x16x32_bf16 v[98:101], v[154:157], v[194:197], v[98:101]
	v_mfma_f32_16x16x32_bf16 v[86:89], v[146:149], v[206:209], v[86:89]
	v_mfma_f32_16x16x32_bf16 v[82:85], v[154:157], v[206:209], v[82:85]
	v_mfma_f32_16x16x32_bf16 v[126:129], v[150:153], v[182:185], v[126:129]
	v_mfma_f32_16x16x32_bf16 v[122:125], v[158:161], v[182:185], v[122:125]
	v_mfma_f32_16x16x32_bf16 v[118:121], v[150:153], v[190:193], v[118:121]
	v_mfma_f32_16x16x32_bf16 v[110:113], v[158:161], v[190:193], v[110:113]
	v_mfma_f32_16x16x32_bf16 v[102:105], v[150:153], v[198:201], v[102:105]
	v_mfma_f32_16x16x32_bf16 v[98:101], v[158:161], v[198:201], v[98:101]
	v_mfma_f32_16x16x32_bf16 v[86:89], v[150:153], v[210:213], v[86:89]
	v_mfma_f32_16x16x32_bf16 v[82:85], v[158:161], v[210:213], v[82:85]
	v_mfma_f32_16x16x32_bf16 v[114:117], v[162:165], v[178:181], v[114:117]
	v_mfma_f32_16x16x32_bf16 v[106:109], v[170:173], v[178:181], v[106:109]
	v_mfma_f32_16x16x32_bf16 v[94:97], v[162:165], v[186:189], v[94:97]
	v_mfma_f32_16x16x32_bf16 v[90:93], v[170:173], v[186:189], v[90:93]
	v_mfma_f32_16x16x32_bf16 v[78:81], v[162:165], v[194:197], v[78:81]
	v_mfma_f32_16x16x32_bf16 v[74:77], v[170:173], v[194:197], v[74:77]
	v_mfma_f32_16x16x32_bf16 v[70:73], v[162:165], v[206:209], v[70:73]
	v_mfma_f32_16x16x32_bf16 v[66:69], v[170:173], v[206:209], v[66:69]
	v_mfma_f32_16x16x32_bf16 v[114:117], v[166:169], v[182:185], v[114:117]
	v_mfma_f32_16x16x32_bf16 v[106:109], v[174:177], v[182:185], v[106:109]
	v_mfma_f32_16x16x32_bf16 v[94:97], v[166:169], v[190:193], v[94:97]
	v_mfma_f32_16x16x32_bf16 v[90:93], v[174:177], v[190:193], v[90:93]
	v_mfma_f32_16x16x32_bf16 v[78:81], v[166:169], v[198:201], v[78:81]
	v_mfma_f32_16x16x32_bf16 v[74:77], v[174:177], v[198:201], v[74:77]
	v_mfma_f32_16x16x32_bf16 v[70:73], v[166:169], v[210:213], v[70:73]
	v_mfma_f32_16x16x32_bf16 v[66:69], v[174:177], v[210:213], v[66:69]
	s_setprio 0
	s_barrier
	ds_read_b128 v[178:181], v144 offset:49152
	ds_read_b128 v[182:185], v144 offset:50176
	ds_read_b128 v[186:189], v144 offset:51200
	ds_read_b128 v[190:193], v144 offset:52224
	ds_read_b128 v[194:197], v144 offset:53248
	ds_read_b128 v[198:201], v144 offset:54272
	ds_read_b128 v[206:209], v144 offset:55296
	ds_read_b128 v[210:213], v144 offset:56320
	global_load_lds_dwordx4 v[216:217], off
	v_lshl_add_u64 v[216:217], s[64:65], 0, v[130:131]
	s_mov_b32 m0, s83
	v_lshl_add_u64 v[202:203], v[202:203], 0, s[36:37]
	global_load_lds_dwordx4 v[216:217], off
	v_lshl_add_u64 v[216:217], s[66:67], 0, v[134:135]
	s_mov_b32 m0, s84
	s_nop 0
	global_load_lds_dwordx4 v[216:217], off
	v_lshl_add_u64 v[216:217], s[66:67], 0, v[130:131]
	s_mov_b32 m0, s12
	s_nop 0
	global_load_lds_dwordx4 v[216:217], off
	s_mov_b32 m0, s31
	s_nop 0
	global_load_lds_dwordx4 v[202:203], off
	v_lshl_add_u64 v[202:203], v[214:215], 0, s[36:37]
	s_mov_b32 m0, s33
	s_nop 0
	global_load_lds_dwordx4 v[202:203], off
	s_waitcnt vmcnt(8)
	s_waitcnt lgkmcnt(0)
	s_setprio 1
	s_barrier
	v_mfma_f32_16x16x32_bf16 v[62:65], v[146:149], v[178:181], v[62:65]
	v_mfma_f32_16x16x32_bf16 v[58:61], v[154:157], v[178:181], v[58:61]
	s_mov_b64 s[66:67], 0
	s_mov_b64 s[64:65], -1
	s_mov_b32 s12, 2
	v_mfma_f32_16x16x32_bf16 v[54:57], v[146:149], v[186:189], v[54:57]
	v_mfma_f32_16x16x32_bf16 v[50:53], v[154:157], v[186:189], v[50:53]
	v_mfma_f32_16x16x32_bf16 v[38:41], v[146:149], v[194:197], v[38:41]
	v_mfma_f32_16x16x32_bf16 v[34:37], v[154:157], v[194:197], v[34:37]
	v_mfma_f32_16x16x32_bf16 v[22:25], v[146:149], v[206:209], v[22:25]
	v_mfma_f32_16x16x32_bf16 v[18:21], v[154:157], v[206:209], v[18:21]
	v_mfma_f32_16x16x32_bf16 v[62:65], v[150:153], v[182:185], v[62:65]
	v_mfma_f32_16x16x32_bf16 v[58:61], v[158:161], v[182:185], v[58:61]
	v_mfma_f32_16x16x32_bf16 v[54:57], v[150:153], v[190:193], v[54:57]
	v_mfma_f32_16x16x32_bf16 v[50:53], v[158:161], v[190:193], v[50:53]
	v_mfma_f32_16x16x32_bf16 v[38:41], v[150:153], v[198:201], v[38:41]
	v_mfma_f32_16x16x32_bf16 v[34:37], v[158:161], v[198:201], v[34:37]
	v_mfma_f32_16x16x32_bf16 v[22:25], v[150:153], v[210:213], v[22:25]
	v_mfma_f32_16x16x32_bf16 v[18:21], v[158:161], v[210:213], v[18:21]
	v_mfma_f32_16x16x32_bf16 v[46:49], v[162:165], v[178:181], v[46:49]
	v_mfma_f32_16x16x32_bf16 v[42:45], v[170:173], v[178:181], v[42:45]
	v_mfma_f32_16x16x32_bf16 v[30:33], v[162:165], v[186:189], v[30:33]
	v_mfma_f32_16x16x32_bf16 v[26:29], v[170:173], v[186:189], v[26:29]
	v_mfma_f32_16x16x32_bf16 v[14:17], v[162:165], v[194:197], v[14:17]
	v_mfma_f32_16x16x32_bf16 v[10:13], v[170:173], v[194:197], v[10:13]
	v_mfma_f32_16x16x32_bf16 v[6:9], v[162:165], v[206:209], v[6:9]
	v_mfma_f32_16x16x32_bf16 v[2:5], v[170:173], v[206:209], v[2:5]
	v_mfma_f32_16x16x32_bf16 v[46:49], v[166:169], v[182:185], v[46:49]
	v_mfma_f32_16x16x32_bf16 v[42:45], v[174:177], v[182:185], v[42:45]
	v_mfma_f32_16x16x32_bf16 v[30:33], v[166:169], v[190:193], v[30:33]
	v_mfma_f32_16x16x32_bf16 v[26:29], v[174:177], v[190:193], v[26:29]
	v_mfma_f32_16x16x32_bf16 v[14:17], v[166:169], v[198:201], v[14:17]
	v_mfma_f32_16x16x32_bf16 v[10:13], v[174:177], v[198:201], v[10:13]
	v_mfma_f32_16x16x32_bf16 v[6:9], v[166:169], v[210:213], v[6:9]
	v_mfma_f32_16x16x32_bf16 v[2:5], v[174:177], v[210:213], v[2:5]
	s_setprio 0
	s_barrier
	s_cbranch_vccz .LBB0_406
	s_and_b64 vcc, exec, s[22:23]
	s_cbranch_vccz .LBB0_409
	s_barrier

.LBB0_476:
	s_add_u32 s22, s2, s49
	s_addc_u32 s23, s3, s29
	s_and_b64 s[26:27], s[20:21], exec
	s_cselect_b32 s63, s23, s37
	s_cselect_b32 s64, s22, s36
	s_add_u32 s26, s16, s12
	s_addc_u32 s27, s17, s13
	s_and_b64 s[42:43], s[20:21], exec
	s_cselect_b32 s65, s27, s39
	s_cselect_b32 s66, s26, s38
	s_add_u32 s36, s36, 0x20080
	s_addc_u32 s37, s37, 0
	s_add_u32 s67, s38, 0x100
	s_addc_u32 s68, s39, 0
	s_mov_b32 s69, -2
	ds_read_b128 v[148:151], v144
	ds_read_b128 v[152:155], v144 offset:1024
	ds_read_b128 v[156:159], v144 offset:2048
	ds_read_b128 v[160:163], v144 offset:3072
	ds_read_b128 v[164:167], v145
	ds_read_b128 v[168:171], v145 offset:1024
	ds_read_b128 v[172:175], v145 offset:2048
	ds_read_b128 v[176:179], v145 offset:3072
	s_add_u32 s38, s36, 0xfffe0080
	s_addc_u32 s39, s37, -1
	s_cmp_eq_u32 s69, 4
	s_cselect_b32 s43, s63, s39
	s_cselect_b32 s42, s64, s38
	s_cselect_b32 s39, s65, s68
	s_cselect_b32 s38, s66, s67
	v_lshl_add_u64 v[214:215], s[36:37], 0, v[138:139]
	s_add_i32 m0, s19, 0xc000
	ds_read_b128 v[180:183], v146
	ds_read_b128 v[184:187], v146 offset:1024
	ds_read_b128 v[188:191], v146 offset:2048
	ds_read_b128 v[192:195], v146 offset:3072
	ds_read_b128 v[196:199], v146 offset:4096
	ds_read_b128 v[200:203], v146 offset:5120
	ds_read_b128 v[206:209], v146 offset:6144
	ds_read_b128 v[210:213], v146 offset:7168
	global_load_lds_dwordx4 v[214:215], off
	v_lshl_add_u64 v[214:215], s[36:37], 0, v[140:141]
	s_add_i32 m0, s19, 0xe000
	s_nop 0
	global_load_lds_dwordx4 v[214:215], off
	s_waitcnt vmcnt(8)
	s_waitcnt lgkmcnt(0)
	s_setprio 1
	s_barrier
	v_mfma_f32_16x16x32_bf16 v[126:129], v[148:151], v[180:183], 0
	v_mfma_f32_16x16x32_bf16 v[122:125], v[156:159], v[180:183], 0
	s_add_i32 s70, s35, s18
	v_lshl_add_u64 v[214:215], s[38:39], 0, v[134:135]
	s_mov_b32 m0, s70
	v_mfma_f32_16x16x32_bf16 v[118:121], v[148:151], v[188:191], 0
	v_mfma_f32_16x16x32_bf16 v[114:117], v[156:159], v[188:191], 0
	v_mfma_f32_16x16x32_bf16 v[102:105], v[148:151], v[196:199], 0
	v_mfma_f32_16x16x32_bf16 v[98:101], v[156:159], v[196:199], 0
	v_mfma_f32_16x16x32_bf16 v[86:89], v[148:151], v[206:209], 0
	v_mfma_f32_16x16x32_bf16 v[82:85], v[156:159], v[206:209], 0
	v_mfma_f32_16x16x32_bf16 v[126:129], v[152:155], v[184:187], v[126:129]
	v_mfma_f32_16x16x32_bf16 v[122:125], v[160:163], v[184:187], v[122:125]
	v_mfma_f32_16x16x32_bf16 v[118:121], v[152:155], v[192:195], v[118:121]
	v_mfma_f32_16x16x32_bf16 v[114:117], v[160:163], v[192:195], v[114:117]
	v_mfma_f32_16x16x32_bf16 v[102:105], v[152:155], v[200:203], v[102:105]
	v_mfma_f32_16x16x32_bf16 v[98:101], v[160:163], v[200:203], v[98:101]
	v_mfma_f32_16x16x32_bf16 v[86:89], v[152:155], v[210:213], v[86:89]
	v_mfma_f32_16x16x32_bf16 v[82:85], v[160:163], v[210:213], v[82:85]
	v_mfma_f32_16x16x32_bf16 v[110:113], v[164:167], v[180:183], 0
	v_mfma_f32_16x16x32_bf16 v[106:109], v[172:175], v[180:183], 0
	v_mfma_f32_16x16x32_bf16 v[94:97], v[164:167], v[188:191], 0
	v_mfma_f32_16x16x32_bf16 v[90:93], v[172:175], v[188:191], 0
	v_mfma_f32_16x16x32_bf16 v[78:81], v[164:167], v[196:199], 0
	v_mfma_f32_16x16x32_bf16 v[74:77], v[172:175], v[196:199], 0
	v_mfma_f32_16x16x32_bf16 v[70:73], v[164:167], v[206:209], 0
	v_mfma_f32_16x16x32_bf16 v[66:69], v[172:175], v[206:209], 0
	v_mfma_f32_16x16x32_bf16 v[110:113], v[168:171], v[184:187], v[110:113]
	v_mfma_f32_16x16x32_bf16 v[106:109], v[176:179], v[184:187], v[106:109]
	v_mfma_f32_16x16x32_bf16 v[94:97], v[168:171], v[192:195], v[94:97]
	v_mfma_f32_16x16x32_bf16 v[90:93], v[176:179], v[192:195], v[90:93]
	v_mfma_f32_16x16x32_bf16 v[78:81], v[168:171], v[200:203], v[78:81]
	v_mfma_f32_16x16x32_bf16 v[74:77], v[176:179], v[200:203], v[74:77]
	v_mfma_f32_16x16x32_bf16 v[70:73], v[168:171], v[210:213], v[70:73]
	v_mfma_f32_16x16x32_bf16 v[66:69], v[176:179], v[210:213], v[66:69]
	s_setprio 0
	s_barrier
	ds_read_b128 v[180:183], v146 offset:16384
	ds_read_b128 v[184:187], v146 offset:17408
	ds_read_b128 v[188:191], v146 offset:18432
	ds_read_b128 v[192:195], v146 offset:19456
	ds_read_b128 v[196:199], v146 offset:20480
	ds_read_b128 v[200:203], v146 offset:21504
	ds_read_b128 v[206:209], v146 offset:22528
	ds_read_b128 v[210:213], v146 offset:23552
	global_load_lds_dwordx4 v[214:215], off
	s_add_i32 m0, s70, 0x2000
	s_add_u32 s70, s38, 0x200000
	v_lshl_add_u64 v[216:217], s[38:39], 0, v[130:131]
	s_addc_u32 s71, s39, 0
	s_add_i32 s72, s44, s18
	global_load_lds_dwordx4 v[216:217], off
	v_lshl_add_u64 v[218:219], s[70:71], 0, v[134:135]
	s_mov_b32 m0, s72
	v_lshl_add_u64 v[220:221], s[42:43], 0, v[132:133]
	global_load_lds_dwordx4 v[218:219], off
	v_lshl_add_u64 v[218:219], s[70:71], 0, v[130:131]
	s_add_i32 m0, s72, 0x2000
	s_nop 0
	global_load_lds_dwordx4 v[218:219], off
	v_lshl_add_u64 v[218:219], s[42:43], 0, v[136:137]
	s_mov_b32 m0, s19
	s_nop 0
	global_load_lds_dwordx4 v[218:219], off
	s_mov_b32 m0, s24
	s_nop 0
	global_load_lds_dwordx4 v[220:221], off
	s_waitcnt vmcnt(8)
	s_waitcnt lgkmcnt(0)
	s_setprio 1
	s_barrier
	v_mfma_f32_16x16x32_bf16 v[62:65], v[148:151], v[180:183], 0
	v_mfma_f32_16x16x32_bf16 v[58:61], v[156:159], v[180:183], 0
	s_add_i32 s70, 0, 0x18000
	v_add_u32_e32 v147, s70, v143
	s_add_i32 s71, 0, 0x1c000
	v_mfma_f32_16x16x32_bf16 v[54:57], v[148:151], v[188:191], 0
	v_mfma_f32_16x16x32_bf16 v[50:53], v[156:159], v[188:191], 0
	v_mfma_f32_16x16x32_bf16 v[38:41], v[148:151], v[196:199], 0
	v_mfma_f32_16x16x32_bf16 v[34:37], v[156:159], v[196:199], 0
	v_mfma_f32_16x16x32_bf16 v[22:25], v[148:151], v[206:209], 0
	v_mfma_f32_16x16x32_bf16 v[18:21], v[156:159], v[206:209], 0
	v_mfma_f32_16x16x32_bf16 v[62:65], v[152:155], v[184:187], v[62:65]
	v_mfma_f32_16x16x32_bf16 v[58:61], v[160:163], v[184:187], v[58:61]
	v_mfma_f32_16x16x32_bf16 v[54:57], v[152:155], v[192:195], v[54:57]
	v_mfma_f32_16x16x32_bf16 v[50:53], v[160:163], v[192:195], v[50:53]
	v_mfma_f32_16x16x32_bf16 v[38:41], v[152:155], v[200:203], v[38:41]
	v_mfma_f32_16x16x32_bf16 v[34:37], v[160:163], v[200:203], v[34:37]
	v_mfma_f32_16x16x32_bf16 v[22:25], v[152:155], v[210:213], v[22:25]
	v_mfma_f32_16x16x32_bf16 v[18:21], v[160:163], v[210:213], v[18:21]
	v_mfma_f32_16x16x32_bf16 v[46:49], v[164:167], v[180:183], 0
	v_mfma_f32_16x16x32_bf16 v[42:45], v[172:175], v[180:183], 0
	v_mfma_f32_16x16x32_bf16 v[30:33], v[164:167], v[188:191], 0
	v_mfma_f32_16x16x32_bf16 v[26:29], v[172:175], v[188:191], 0
	v_mfma_f32_16x16x32_bf16 v[14:17], v[164:167], v[196:199], 0
	v_mfma_f32_16x16x32_bf16 v[10:13], v[172:175], v[196:199], 0
	v_mfma_f32_16x16x32_bf16 v[6:9], v[164:167], v[206:209], 0
	v_mfma_f32_16x16x32_bf16 v[2:5], v[172:175], v[206:209], 0
	v_mfma_f32_16x16x32_bf16 v[46:49], v[168:171], v[184:187], v[46:49]
	v_mfma_f32_16x16x32_bf16 v[42:45], v[176:179], v[184:187], v[42:45]
	v_mfma_f32_16x16x32_bf16 v[30:33], v[168:171], v[192:195], v[30:33]
	v_mfma_f32_16x16x32_bf16 v[26:29], v[176:179], v[192:195], v[26:29]
	v_mfma_f32_16x16x32_bf16 v[14:17], v[168:171], v[200:203], v[14:17]
	v_mfma_f32_16x16x32_bf16 v[10:13], v[176:179], v[200:203], v[10:13]
	v_mfma_f32_16x16x32_bf16 v[6:9], v[168:171], v[210:213], v[6:9]
	v_mfma_f32_16x16x32_bf16 v[2:5], v[176:179], v[210:213], v[2:5]
	s_setprio 0
	s_barrier
	ds_read_b128 v[148:151], v147
	ds_read_b128 v[152:155], v147 offset:1024
	ds_read_b128 v[156:159], v147 offset:2048
	ds_read_b128 v[160:163], v147 offset:3072
	v_add_u32_e32 v147, s71, v143
	ds_read_b128 v[164:167], v147
	ds_read_b128 v[168:171], v147 offset:1024
	ds_read_b128 v[172:175], v147 offset:2048
	ds_read_b128 v[176:179], v147 offset:3072
	s_add_u32 s42, s42, 0x20000
	s_addc_u32 s43, s43, 0
	s_mov_b32 m0, s25
	v_lshl_add_u64 v[222:223], s[42:43], 0, v[136:137]
	ds_read_b128 v[180:183], v146 offset:32768
	ds_read_b128 v[184:187], v146 offset:33792
	ds_read_b128 v[188:191], v146 offset:34816
	ds_read_b128 v[192:195], v146 offset:35840
	ds_read_b128 v[196:199], v146 offset:36864
	ds_read_b128 v[200:203], v146 offset:37888
	ds_read_b128 v[206:209], v146 offset:38912
	ds_read_b128 v[210:213], v146 offset:39936
	global_load_lds_dwordx4 v[222:223], off
	v_lshl_add_u64 v[222:223], s[42:43], 0, v[132:133]
	s_mov_b32 m0, s28
	s_nop 0
	global_load_lds_dwordx4 v[222:223], off
	s_waitcnt vmcnt(8)
	s_waitcnt lgkmcnt(0)
	s_setprio 1
	s_barrier
	v_mfma_f32_16x16x32_bf16 v[126:129], v[148:151], v[180:183], v[126:129]
	v_mfma_f32_16x16x32_bf16 v[122:125], v[156:159], v[180:183], v[122:125]
	s_add_i32 s42, s70, s18
	v_lshl_add_u64 v[214:215], v[214:215], 0, s[8:9]
	s_mov_b32 m0, s42
	v_mfma_f32_16x16x32_bf16 v[118:121], v[148:151], v[188:191], v[118:121]
	v_mfma_f32_16x16x32_bf16 v[114:117], v[156:159], v[188:191], v[114:117]
	v_mfma_f32_16x16x32_bf16 v[102:105], v[148:151], v[196:199], v[102:105]
	v_mfma_f32_16x16x32_bf16 v[98:101], v[156:159], v[196:199], v[98:101]
	v_mfma_f32_16x16x32_bf16 v[86:89], v[148:151], v[206:209], v[86:89]
	v_mfma_f32_16x16x32_bf16 v[82:85], v[156:159], v[206:209], v[82:85]
	v_mfma_f32_16x16x32_bf16 v[126:129], v[152:155], v[184:187], v[126:129]
	v_mfma_f32_16x16x32_bf16 v[122:125], v[160:163], v[184:187], v[122:125]
	v_mfma_f32_16x16x32_bf16 v[118:121], v[152:155], v[192:195], v[118:121]
	v_mfma_f32_16x16x32_bf16 v[114:117], v[160:163], v[192:195], v[114:117]
	v_mfma_f32_16x16x32_bf16 v[102:105], v[152:155], v[200:203], v[102:105]
	v_mfma_f32_16x16x32_bf16 v[98:101], v[160:163], v[200:203], v[98:101]
	v_mfma_f32_16x16x32_bf16 v[86:89], v[152:155], v[210:213], v[86:89]
	v_mfma_f32_16x16x32_bf16 v[82:85], v[160:163], v[210:213], v[82:85]
	v_mfma_f32_16x16x32_bf16 v[110:113], v[164:167], v[180:183], v[110:113]
	v_mfma_f32_16x16x32_bf16 v[106:109], v[172:175], v[180:183], v[106:109]
	v_mfma_f32_16x16x32_bf16 v[94:97], v[164:167], v[188:191], v[94:97]
	v_mfma_f32_16x16x32_bf16 v[90:93], v[172:175], v[188:191], v[90:93]
	v_mfma_f32_16x16x32_bf16 v[78:81], v[164:167], v[196:199], v[78:81]
	v_mfma_f32_16x16x32_bf16 v[74:77], v[172:175], v[196:199], v[74:77]
	v_mfma_f32_16x16x32_bf16 v[70:73], v[164:167], v[206:209], v[70:73]
	v_mfma_f32_16x16x32_bf16 v[66:69], v[172:175], v[206:209], v[66:69]
	v_mfma_f32_16x16x32_bf16 v[110:113], v[168:171], v[184:187], v[110:113]
	v_mfma_f32_16x16x32_bf16 v[106:109], v[176:179], v[184:187], v[106:109]
	v_mfma_f32_16x16x32_bf16 v[94:97], v[168:171], v[192:195], v[94:97]
	v_mfma_f32_16x16x32_bf16 v[90:93], v[176:179], v[192:195], v[90:93]
	v_mfma_f32_16x16x32_bf16 v[78:81], v[168:171], v[200:203], v[78:81]
	v_mfma_f32_16x16x32_bf16 v[74:77], v[176:179], v[200:203], v[74:77]
	v_mfma_f32_16x16x32_bf16 v[70:73], v[168:171], v[210:213], v[70:73]
	v_mfma_f32_16x16x32_bf16 v[66:69], v[176:179], v[210:213], v[66:69]
	s_setprio 0
	s_barrier
	ds_read_b128 v[180:183], v146 offset:49152
	ds_read_b128 v[184:187], v146 offset:50176
	ds_read_b128 v[188:191], v146 offset:51200
	ds_read_b128 v[192:195], v146 offset:52224
	ds_read_b128 v[196:199], v146 offset:53248
	ds_read_b128 v[200:203], v146 offset:54272
	ds_read_b128 v[206:209], v146 offset:55296
	ds_read_b128 v[210:213], v146 offset:56320
	global_load_lds_dwordx4 v[214:215], off
	s_add_i32 m0, s42, 0x2000
	s_add_u32 s38, s38, 0x200080
	v_lshl_add_u64 v[214:215], v[216:217], 0, s[8:9]
	s_addc_u32 s39, s39, 0
	s_add_i32 s42, s71, s18
	global_load_lds_dwordx4 v[214:215], off
	v_lshl_add_u64 v[214:215], s[38:39], 0, v[134:135]
	s_mov_b32 m0, s42
	s_nop 0
	global_load_lds_dwordx4 v[214:215], off
	v_lshl_add_u64 v[214:215], s[38:39], 0, v[130:131]
	s_add_i32 m0, s42, 0x2000
	s_nop 0
	global_load_lds_dwordx4 v[214:215], off
	v_lshl_add_u64 v[214:215], v[218:219], 0, s[8:9]
	s_mov_b32 m0, s33
	s_nop 0
	global_load_lds_dwordx4 v[214:215], off
	v_lshl_add_u64 v[214:215], v[220:221], 0, s[8:9]
	s_mov_b32 m0, s34
	s_nop 0
	global_load_lds_dwordx4 v[214:215], off
	s_waitcnt vmcnt(8)
	s_waitcnt lgkmcnt(0)
	s_setprio 1
	s_barrier
	v_mfma_f32_16x16x32_bf16 v[62:65], v[148:151], v[180:183], v[62:65]
	v_mfma_f32_16x16x32_bf16 v[58:61], v[156:159], v[180:183], v[58:61]
	s_add_i32 s69, s69, 2
	s_add_u32 s36, s36, 0x100
	s_addc_u32 s37, s37, 0
	s_add_u32 s67, s67, 0x100
	s_addc_u32 s68, s68, 0
	s_cmp_gt_u32 s69, 5
	v_mfma_f32_16x16x32_bf16 v[54:57], v[148:151], v[188:191], v[54:57]
	v_mfma_f32_16x16x32_bf16 v[50:53], v[156:159], v[188:191], v[50:53]
	v_mfma_f32_16x16x32_bf16 v[38:41], v[148:151], v[196:199], v[38:41]
	v_mfma_f32_16x16x32_bf16 v[34:37], v[156:159], v[196:199], v[34:37]
	v_mfma_f32_16x16x32_bf16 v[22:25], v[148:151], v[206:209], v[22:25]
	v_mfma_f32_16x16x32_bf16 v[18:21], v[156:159], v[206:209], v[18:21]
	v_mfma_f32_16x16x32_bf16 v[62:65], v[152:155], v[184:187], v[62:65]
	v_mfma_f32_16x16x32_bf16 v[58:61], v[160:163], v[184:187], v[58:61]
	v_mfma_f32_16x16x32_bf16 v[54:57], v[152:155], v[192:195], v[54:57]
	v_mfma_f32_16x16x32_bf16 v[50:53], v[160:163], v[192:195], v[50:53]
	v_mfma_f32_16x16x32_bf16 v[38:41], v[152:155], v[200:203], v[38:41]
	v_mfma_f32_16x16x32_bf16 v[34:37], v[160:163], v[200:203], v[34:37]
	v_mfma_f32_16x16x32_bf16 v[22:25], v[152:155], v[210:213], v[22:25]
	v_mfma_f32_16x16x32_bf16 v[18:21], v[160:163], v[210:213], v[18:21]
	v_mfma_f32_16x16x32_bf16 v[46:49], v[164:167], v[180:183], v[46:49]
	v_mfma_f32_16x16x32_bf16 v[42:45], v[172:175], v[180:183], v[42:45]
	v_mfma_f32_16x16x32_bf16 v[30:33], v[164:167], v[188:191], v[30:33]
	v_mfma_f32_16x16x32_bf16 v[26:29], v[172:175], v[188:191], v[26:29]
	v_mfma_f32_16x16x32_bf16 v[14:17], v[164:167], v[196:199], v[14:17]
	v_mfma_f32_16x16x32_bf16 v[10:13], v[172:175], v[196:199], v[10:13]
	v_mfma_f32_16x16x32_bf16 v[6:9], v[164:167], v[206:209], v[6:9]
	v_mfma_f32_16x16x32_bf16 v[2:5], v[172:175], v[206:209], v[2:5]
	v_mfma_f32_16x16x32_bf16 v[46:49], v[168:171], v[184:187], v[46:49]
	v_mfma_f32_16x16x32_bf16 v[42:45], v[176:179], v[184:187], v[42:45]
	v_mfma_f32_16x16x32_bf16 v[30:33], v[168:171], v[192:195], v[30:33]
	v_mfma_f32_16x16x32_bf16 v[26:29], v[176:179], v[192:195], v[26:29]
	v_mfma_f32_16x16x32_bf16 v[14:17], v[168:171], v[200:203], v[14:17]
	v_mfma_f32_16x16x32_bf16 v[10:13], v[176:179], v[200:203], v[10:13]
	v_mfma_f32_16x16x32_bf16 v[6:9], v[168:171], v[210:213], v[6:9]
	v_mfma_f32_16x16x32_bf16 v[2:5], v[176:179], v[210:213], v[2:5]
	s_setprio 0
	s_barrier
.LBB0_477:
	ds_read_b128 v[148:151], v144
	ds_read_b128 v[152:155], v144 offset:1024
	ds_read_b128 v[156:159], v144 offset:2048
	ds_read_b128 v[160:163], v144 offset:3072
	ds_read_b128 v[164:167], v145
	ds_read_b128 v[168:171], v145 offset:1024
	ds_read_b128 v[172:175], v145 offset:2048
	ds_read_b128 v[176:179], v145 offset:3072
	s_add_u32 s38, s36, 0xfffe0080
	s_addc_u32 s39, s37, -1
	s_cmp_eq_u32 s69, 4
	s_cselect_b32 s43, s63, s39
	s_cselect_b32 s42, s64, s38
	s_cselect_b32 s39, s65, s68
	s_cselect_b32 s38, s66, s67
	v_lshl_add_u64 v[214:215], s[36:37], 0, v[138:139]
	s_add_i32 m0, s19, 0xc000
	ds_read_b128 v[180:183], v146
	ds_read_b128 v[184:187], v146 offset:1024
	ds_read_b128 v[188:191], v146 offset:2048
	ds_read_b128 v[192:195], v146 offset:3072
	ds_read_b128 v[196:199], v146 offset:4096
	ds_read_b128 v[200:203], v146 offset:5120
	ds_read_b128 v[206:209], v146 offset:6144
	ds_read_b128 v[210:213], v146 offset:7168
	global_load_lds_dwordx4 v[214:215], off
	v_lshl_add_u64 v[214:215], s[36:37], 0, v[140:141]
	s_add_i32 m0, s19, 0xe000
	s_nop 0
	global_load_lds_dwordx4 v[214:215], off
	s_waitcnt vmcnt(8)
	s_waitcnt lgkmcnt(0)
	s_setprio 1
	s_barrier
	v_mfma_f32_16x16x32_bf16 v[126:129], v[148:151], v[180:183], v[126:129]
	v_mfma_f32_16x16x32_bf16 v[122:125], v[156:159], v[180:183], v[122:125]
	s_add_i32 s70, s35, s18
	v_lshl_add_u64 v[214:215], s[38:39], 0, v[134:135]
	s_mov_b32 m0, s70
	v_mfma_f32_16x16x32_bf16 v[118:121], v[148:151], v[188:191], v[118:121]
	v_mfma_f32_16x16x32_bf16 v[114:117], v[156:159], v[188:191], v[114:117]
	v_mfma_f32_16x16x32_bf16 v[102:105], v[148:151], v[196:199], v[102:105]
	v_mfma_f32_16x16x32_bf16 v[98:101], v[156:159], v[196:199], v[98:101]
	v_mfma_f32_16x16x32_bf16 v[86:89], v[148:151], v[206:209], v[86:89]
	v_mfma_f32_16x16x32_bf16 v[82:85], v[156:159], v[206:209], v[82:85]
	v_mfma_f32_16x16x32_bf16 v[126:129], v[152:155], v[184:187], v[126:129]
	v_mfma_f32_16x16x32_bf16 v[122:125], v[160:163], v[184:187], v[122:125]
	v_mfma_f32_16x16x32_bf16 v[118:121], v[152:155], v[192:195], v[118:121]
	v_mfma_f32_16x16x32_bf16 v[114:117], v[160:163], v[192:195], v[114:117]
	v_mfma_f32_16x16x32_bf16 v[102:105], v[152:155], v[200:203], v[102:105]
	v_mfma_f32_16x16x32_bf16 v[98:101], v[160:163], v[200:203], v[98:101]
	v_mfma_f32_16x16x32_bf16 v[86:89], v[152:155], v[210:213], v[86:89]
	v_mfma_f32_16x16x32_bf16 v[82:85], v[160:163], v[210:213], v[82:85]
	v_mfma_f32_16x16x32_bf16 v[110:113], v[164:167], v[180:183], v[110:113]
	v_mfma_f32_16x16x32_bf16 v[106:109], v[172:175], v[180:183], v[106:109]
	v_mfma_f32_16x16x32_bf16 v[94:97], v[164:167], v[188:191], v[94:97]
	v_mfma_f32_16x16x32_bf16 v[90:93], v[172:175], v[188:191], v[90:93]
	v_mfma_f32_16x16x32_bf16 v[78:81], v[164:167], v[196:199], v[78:81]
	v_mfma_f32_16x16x32_bf16 v[74:77], v[172:175], v[196:199], v[74:77]
	v_mfma_f32_16x16x32_bf16 v[70:73], v[164:167], v[206:209], v[70:73]
	v_mfma_f32_16x16x32_bf16 v[66:69], v[172:175], v[206:209], v[66:69]
	v_mfma_f32_16x16x32_bf16 v[110:113], v[168:171], v[184:187], v[110:113]
	v_mfma_f32_16x16x32_bf16 v[106:109], v[176:179], v[184:187], v[106:109]
	v_mfma_f32_16x16x32_bf16 v[94:97], v[168:171], v[192:195], v[94:97]
	v_mfma_f32_16x16x32_bf16 v[90:93], v[176:179], v[192:195], v[90:93]
	v_mfma_f32_16x16x32_bf16 v[78:81], v[168:171], v[200:203], v[78:81]
	v_mfma_f32_16x16x32_bf16 v[74:77], v[176:179], v[200:203], v[74:77]
	v_mfma_f32_16x16x32_bf16 v[70:73], v[168:171], v[210:213], v[70:73]
	v_mfma_f32_16x16x32_bf16 v[66:69], v[176:179], v[210:213], v[66:69]
	s_setprio 0
	s_barrier
	ds_read_b128 v[180:183], v146 offset:16384
	ds_read_b128 v[184:187], v146 offset:17408
	ds_read_b128 v[188:191], v146 offset:18432
	ds_read_b128 v[192:195], v146 offset:19456
	ds_read_b128 v[196:199], v146 offset:20480
	ds_read_b128 v[200:203], v146 offset:21504
	ds_read_b128 v[206:209], v146 offset:22528
	ds_read_b128 v[210:213], v146 offset:23552
	global_load_lds_dwordx4 v[214:215], off
	s_add_i32 m0, s70, 0x2000
	s_add_u32 s70, s38, 0x200000
	v_lshl_add_u64 v[216:217], s[38:39], 0, v[130:131]
	s_addc_u32 s71, s39, 0
	s_add_i32 s72, s44, s18
	global_load_lds_dwordx4 v[216:217], off
	v_lshl_add_u64 v[218:219], s[70:71], 0, v[134:135]
	s_mov_b32 m0, s72
	v_lshl_add_u64 v[220:221], s[42:43], 0, v[132:133]
	global_load_lds_dwordx4 v[218:219], off
	v_lshl_add_u64 v[218:219], s[70:71], 0, v[130:131]
	s_add_i32 m0, s72, 0x2000
	s_nop 0
	global_load_lds_dwordx4 v[218:219], off
	v_lshl_add_u64 v[218:219], s[42:43], 0, v[136:137]
	s_mov_b32 m0, s19
	s_nop 0
	global_load_lds_dwordx4 v[218:219], off
	s_mov_b32 m0, s24
	s_nop 0
	global_load_lds_dwordx4 v[220:221], off
	s_waitcnt vmcnt(8)
	s_waitcnt lgkmcnt(0)
	s_setprio 1
	s_barrier
	v_mfma_f32_16x16x32_bf16 v[62:65], v[148:151], v[180:183], v[62:65]
	v_mfma_f32_16x16x32_bf16 v[58:61], v[156:159], v[180:183], v[58:61]
	s_add_i32 s70, 0, 0x18000
	v_add_u32_e32 v147, s70, v143
	s_add_i32 s71, 0, 0x1c000
	v_mfma_f32_16x16x32_bf16 v[54:57], v[148:151], v[188:191], v[54:57]
	v_mfma_f32_16x16x32_bf16 v[50:53], v[156:159], v[188:191], v[50:53]
	v_mfma_f32_16x16x32_bf16 v[38:41], v[148:151], v[196:199], v[38:41]
	v_mfma_f32_16x16x32_bf16 v[34:37], v[156:159], v[196:199], v[34:37]
	v_mfma_f32_16x16x32_bf16 v[22:25], v[148:151], v[206:209], v[22:25]
	v_mfma_f32_16x16x32_bf16 v[18:21], v[156:159], v[206:209], v[18:21]
	v_mfma_f32_16x16x32_bf16 v[62:65], v[152:155], v[184:187], v[62:65]
	v_mfma_f32_16x16x32_bf16 v[58:61], v[160:163], v[184:187], v[58:61]
	v_mfma_f32_16x16x32_bf16 v[54:57], v[152:155], v[192:195], v[54:57]
	v_mfma_f32_16x16x32_bf16 v[50:53], v[160:163], v[192:195], v[50:53]
	v_mfma_f32_16x16x32_bf16 v[38:41], v[152:155], v[200:203], v[38:41]
	v_mfma_f32_16x16x32_bf16 v[34:37], v[160:163], v[200:203], v[34:37]
	v_mfma_f32_16x16x32_bf16 v[22:25], v[152:155], v[210:213], v[22:25]
	v_mfma_f32_16x16x32_bf16 v[18:21], v[160:163], v[210:213], v[18:21]
	v_mfma_f32_16x16x32_bf16 v[46:49], v[164:167], v[180:183], v[46:49]
	v_mfma_f32_16x16x32_bf16 v[42:45], v[172:175], v[180:183], v[42:45]
	v_mfma_f32_16x16x32_bf16 v[30:33], v[164:167], v[188:191], v[30:33]
	v_mfma_f32_16x16x32_bf16 v[26:29], v[172:175], v[188:191], v[26:29]
	v_mfma_f32_16x16x32_bf16 v[14:17], v[164:167], v[196:199], v[14:17]
	v_mfma_f32_16x16x32_bf16 v[10:13], v[172:175], v[196:199], v[10:13]
	v_mfma_f32_16x16x32_bf16 v[6:9], v[164:167], v[206:209], v[6:9]
	v_mfma_f32_16x16x32_bf16 v[2:5], v[172:175], v[206:209], v[2:5]
	v_mfma_f32_16x16x32_bf16 v[46:49], v[168:171], v[184:187], v[46:49]
	v_mfma_f32_16x16x32_bf16 v[42:45], v[176:179], v[184:187], v[42:45]
	v_mfma_f32_16x16x32_bf16 v[30:33], v[168:171], v[192:195], v[30:33]
	v_mfma_f32_16x16x32_bf16 v[26:29], v[176:179], v[192:195], v[26:29]
	v_mfma_f32_16x16x32_bf16 v[14:17], v[168:171], v[200:203], v[14:17]
	v_mfma_f32_16x16x32_bf16 v[10:13], v[176:179], v[200:203], v[10:13]
	v_mfma_f32_16x16x32_bf16 v[6:9], v[168:171], v[210:213], v[6:9]
	v_mfma_f32_16x16x32_bf16 v[2:5], v[176:179], v[210:213], v[2:5]
	s_setprio 0
	s_barrier
	ds_read_b128 v[148:151], v147
	ds_read_b128 v[152:155], v147 offset:1024
	ds_read_b128 v[156:159], v147 offset:2048
	ds_read_b128 v[160:163], v147 offset:3072
	v_add_u32_e32 v147, s71, v143
	ds_read_b128 v[164:167], v147
	ds_read_b128 v[168:171], v147 offset:1024
	ds_read_b128 v[172:175], v147 offset:2048
	ds_read_b128 v[176:179], v147 offset:3072
	s_add_u32 s42, s42, 0x20000
	s_addc_u32 s43, s43, 0
	s_mov_b32 m0, s25
	v_lshl_add_u64 v[222:223], s[42:43], 0, v[136:137]
	ds_read_b128 v[180:183], v146 offset:32768
	ds_read_b128 v[184:187], v146 offset:33792
	ds_read_b128 v[188:191], v146 offset:34816
	ds_read_b128 v[192:195], v146 offset:35840
	ds_read_b128 v[196:199], v146 offset:36864
	ds_read_b128 v[200:203], v146 offset:37888
	ds_read_b128 v[206:209], v146 offset:38912
	ds_read_b128 v[210:213], v146 offset:39936
	global_load_lds_dwordx4 v[222:223], off
	v_lshl_add_u64 v[222:223], s[42:43], 0, v[132:133]
	s_mov_b32 m0, s28
	s_nop 0
	global_load_lds_dwordx4 v[222:223], off
	s_waitcnt vmcnt(8)
	s_waitcnt lgkmcnt(0)
	s_setprio 1
	s_barrier
	v_mfma_f32_16x16x32_bf16 v[126:129], v[148:151], v[180:183], v[126:129]
	v_mfma_f32_16x16x32_bf16 v[122:125], v[156:159], v[180:183], v[122:125]
	s_add_i32 s42, s70, s18
	v_lshl_add_u64 v[214:215], v[214:215], 0, s[8:9]
	s_mov_b32 m0, s42
	v_mfma_f32_16x16x32_bf16 v[118:121], v[148:151], v[188:191], v[118:121]
	v_mfma_f32_16x16x32_bf16 v[114:117], v[156:159], v[188:191], v[114:117]
	v_mfma_f32_16x16x32_bf16 v[102:105], v[148:151], v[196:199], v[102:105]
	v_mfma_f32_16x16x32_bf16 v[98:101], v[156:159], v[196:199], v[98:101]
	v_mfma_f32_16x16x32_bf16 v[86:89], v[148:151], v[206:209], v[86:89]
	v_mfma_f32_16x16x32_bf16 v[82:85], v[156:159], v[206:209], v[82:85]
	v_mfma_f32_16x16x32_bf16 v[126:129], v[152:155], v[184:187], v[126:129]
	v_mfma_f32_16x16x32_bf16 v[122:125], v[160:163], v[184:187], v[122:125]
	v_mfma_f32_16x16x32_bf16 v[118:121], v[152:155], v[192:195], v[118:121]
	v_mfma_f32_16x16x32_bf16 v[114:117], v[160:163], v[192:195], v[114:117]
	v_mfma_f32_16x16x32_bf16 v[102:105], v[152:155], v[200:203], v[102:105]
	v_mfma_f32_16x16x32_bf16 v[98:101], v[160:163], v[200:203], v[98:101]
	v_mfma_f32_16x16x32_bf16 v[86:89], v[152:155], v[210:213], v[86:89]
	v_mfma_f32_16x16x32_bf16 v[82:85], v[160:163], v[210:213], v[82:85]
	v_mfma_f32_16x16x32_bf16 v[110:113], v[164:167], v[180:183], v[110:113]
	v_mfma_f32_16x16x32_bf16 v[106:109], v[172:175], v[180:183], v[106:109]
	v_mfma_f32_16x16x32_bf16 v[94:97], v[164:167], v[188:191], v[94:97]
	v_mfma_f32_16x16x32_bf16 v[90:93], v[172:175], v[188:191], v[90:93]
	v_mfma_f32_16x16x32_bf16 v[78:81], v[164:167], v[196:199], v[78:81]
	v_mfma_f32_16x16x32_bf16 v[74:77], v[172:175], v[196:199], v[74:77]
	v_mfma_f32_16x16x32_bf16 v[70:73], v[164:167], v[206:209], v[70:73]
	v_mfma_f32_16x16x32_bf16 v[66:69], v[172:175], v[206:209], v[66:69]
	v_mfma_f32_16x16x32_bf16 v[110:113], v[168:171], v[184:187], v[110:113]
	v_mfma_f32_16x16x32_bf16 v[106:109], v[176:179], v[184:187], v[106:109]
	v_mfma_f32_16x16x32_bf16 v[94:97], v[168:171], v[192:195], v[94:97]
	v_mfma_f32_16x16x32_bf16 v[90:93], v[176:179], v[192:195], v[90:93]
	v_mfma_f32_16x16x32_bf16 v[78:81], v[168:171], v[200:203], v[78:81]
	v_mfma_f32_16x16x32_bf16 v[74:77], v[176:179], v[200:203], v[74:77]
	v_mfma_f32_16x16x32_bf16 v[70:73], v[168:171], v[210:213], v[70:73]
	v_mfma_f32_16x16x32_bf16 v[66:69], v[176:179], v[210:213], v[66:69]
	s_setprio 0
	s_barrier
	ds_read_b128 v[180:183], v146 offset:49152
	ds_read_b128 v[184:187], v146 offset:50176
	ds_read_b128 v[188:191], v146 offset:51200
	ds_read_b128 v[192:195], v146 offset:52224
	ds_read_b128 v[196:199], v146 offset:53248
	ds_read_b128 v[200:203], v146 offset:54272
	ds_read_b128 v[206:209], v146 offset:55296
	ds_read_b128 v[210:213], v146 offset:56320
	global_load_lds_dwordx4 v[214:215], off
	s_add_i32 m0, s42, 0x2000
	s_add_u32 s38, s38, 0x200080
	v_lshl_add_u64 v[214:215], v[216:217], 0, s[8:9]
	s_addc_u32 s39, s39, 0
	s_add_i32 s42, s71, s18
	global_load_lds_dwordx4 v[214:215], off
	v_lshl_add_u64 v[214:215], s[38:39], 0, v[134:135]
	s_mov_b32 m0, s42
	s_nop 0
	global_load_lds_dwordx4 v[214:215], off
	v_lshl_add_u64 v[214:215], s[38:39], 0, v[130:131]
	s_add_i32 m0, s42, 0x2000
	s_nop 0
	global_load_lds_dwordx4 v[214:215], off
	v_lshl_add_u64 v[214:215], v[218:219], 0, s[8:9]
	s_mov_b32 m0, s33
	s_nop 0
	global_load_lds_dwordx4 v[214:215], off
	v_lshl_add_u64 v[214:215], v[220:221], 0, s[8:9]
	s_mov_b32 m0, s34
	s_nop 0
	global_load_lds_dwordx4 v[214:215], off
	s_waitcnt vmcnt(8)
	s_waitcnt lgkmcnt(0)
	s_setprio 1
	s_barrier
	v_mfma_f32_16x16x32_bf16 v[62:65], v[148:151], v[180:183], v[62:65]
	v_mfma_f32_16x16x32_bf16 v[58:61], v[156:159], v[180:183], v[58:61]
	s_add_i32 s69, s69, 2
	s_add_u32 s36, s36, 0x100
	s_addc_u32 s37, s37, 0
	s_add_u32 s67, s67, 0x100
	s_addc_u32 s68, s68, 0
	s_cmp_gt_u32 s69, 5
	v_mfma_f32_16x16x32_bf16 v[54:57], v[148:151], v[188:191], v[54:57]
	v_mfma_f32_16x16x32_bf16 v[50:53], v[156:159], v[188:191], v[50:53]
	v_mfma_f32_16x16x32_bf16 v[38:41], v[148:151], v[196:199], v[38:41]
	v_mfma_f32_16x16x32_bf16 v[34:37], v[156:159], v[196:199], v[34:37]
	v_mfma_f32_16x16x32_bf16 v[22:25], v[148:151], v[206:209], v[22:25]
	v_mfma_f32_16x16x32_bf16 v[18:21], v[156:159], v[206:209], v[18:21]
	v_mfma_f32_16x16x32_bf16 v[62:65], v[152:155], v[184:187], v[62:65]
	v_mfma_f32_16x16x32_bf16 v[58:61], v[160:163], v[184:187], v[58:61]
	v_mfma_f32_16x16x32_bf16 v[54:57], v[152:155], v[192:195], v[54:57]
	v_mfma_f32_16x16x32_bf16 v[50:53], v[160:163], v[192:195], v[50:53]
	v_mfma_f32_16x16x32_bf16 v[38:41], v[152:155], v[200:203], v[38:41]
	v_mfma_f32_16x16x32_bf16 v[34:37], v[160:163], v[200:203], v[34:37]
	v_mfma_f32_16x16x32_bf16 v[22:25], v[152:155], v[210:213], v[22:25]
	v_mfma_f32_16x16x32_bf16 v[18:21], v[160:163], v[210:213], v[18:21]
	v_mfma_f32_16x16x32_bf16 v[46:49], v[164:167], v[180:183], v[46:49]
	v_mfma_f32_16x16x32_bf16 v[42:45], v[172:175], v[180:183], v[42:45]
	v_mfma_f32_16x16x32_bf16 v[30:33], v[164:167], v[188:191], v[30:33]
	v_mfma_f32_16x16x32_bf16 v[26:29], v[172:175], v[188:191], v[26:29]
	v_mfma_f32_16x16x32_bf16 v[14:17], v[164:167], v[196:199], v[14:17]
	v_mfma_f32_16x16x32_bf16 v[10:13], v[172:175], v[196:199], v[10:13]
	v_mfma_f32_16x16x32_bf16 v[6:9], v[164:167], v[206:209], v[6:9]
	v_mfma_f32_16x16x32_bf16 v[2:5], v[172:175], v[206:209], v[2:5]
	v_mfma_f32_16x16x32_bf16 v[46:49], v[168:171], v[184:187], v[46:49]
	v_mfma_f32_16x16x32_bf16 v[42:45], v[176:179], v[184:187], v[42:45]
	v_mfma_f32_16x16x32_bf16 v[30:33], v[168:171], v[192:195], v[30:33]
	v_mfma_f32_16x16x32_bf16 v[26:29], v[176:179], v[192:195], v[26:29]
	v_mfma_f32_16x16x32_bf16 v[14:17], v[168:171], v[200:203], v[14:17]
	v_mfma_f32_16x16x32_bf16 v[10:13], v[176:179], v[200:203], v[10:13]
	v_mfma_f32_16x16x32_bf16 v[6:9], v[168:171], v[210:213], v[6:9]
	v_mfma_f32_16x16x32_bf16 v[2:5], v[176:179], v[210:213], v[2:5]
	s_setprio 0
	s_barrier
	s_cbranch_scc0 .LBB0_477
	s_and_b64 vcc, exec, s[10:11]
	s_cbranch_vccz .LBB0_480
	s_barrier

.LBB0_565:
	v_readlane_b32 s62, v249, 27
	v_readlane_b32 s63, v249, 28
	s_add_u32 s72, s62, s68
	s_addc_u32 s73, s63, s69
	s_and_b64 s[62:63], s[70:71], exec
	s_cselect_b32 s31, s73, s77
	s_cselect_b32 s33, s72, s76
	s_add_u32 s74, s35, s66
	s_addc_u32 s75, s85, s67
	s_and_b64 s[62:63], s[70:71], exec
	s_cselect_b32 s34, s75, s79
	s_cselect_b32 s39, s74, s78
	s_add_i32 s45, s7, -2
	s_add_u32 s76, s76, 0x40080
	s_addc_u32 s77, s77, 0
	s_add_u32 s47, s78, 0x100
	s_addc_u32 s62, s79, 0
	s_mov_b32 s63, 0
	s_waitcnt vmcnt(0)
	ds_read_b128 v[114:117], v190
	ds_read_b128 v[118:121], v190 offset:1024
	ds_read_b128 v[122:125], v190 offset:2048
	ds_read_b128 v[126:129], v190 offset:3072
	ds_read_b128 v[146:149], v191
	ds_read_b128 v[150:153], v191 offset:1024
	ds_read_b128 v[154:157], v191 offset:2048
	ds_read_b128 v[158:161], v191 offset:3072
	s_add_i32 s82, s63, 2
	s_add_u32 s78, s76, 0xfffc0080
	s_addc_u32 s79, s77, -1
	s_cmp_eq_u32 s45, s63
	s_cselect_b32 s81, s31, s79
	s_cselect_b32 s80, s33, s78
	s_cselect_b32 s79, s34, s62
	s_cselect_b32 s78, s39, s47
	v_lshl_add_u64 v[186:187], s[76:77], 0, v[180:181]
	s_add_i32 m0, s87, 0xc000
	ds_read_b128 v[162:165], v192
	ds_read_b128 v[166:169], v192 offset:1024
	ds_read_b128 v[194:197], v192 offset:2048
	ds_read_b128 v[198:201], v192 offset:3072
	ds_read_b128 v[206:209], v192 offset:4096
	ds_read_b128 v[210:213], v192 offset:5120
	ds_read_b128 v[214:217], v192 offset:6144
	ds_read_b128 v[218:221], v192 offset:7168
	global_load_lds_dwordx4 v[186:187], off
	v_lshl_add_u64 v[186:187], s[76:77], 0, v[182:183]
	s_add_i32 m0, s87, 0xe000
	s_nop 0
	global_load_lds_dwordx4 v[186:187], off
	s_waitcnt vmcnt(8)
	s_waitcnt lgkmcnt(0)
	s_setprio 1
	s_barrier
	v_mfma_f32_16x16x32_bf16 v[142:145], v[114:117], v[162:165], 0
	v_mfma_f32_16x16x32_bf16 v[138:141], v[122:125], v[162:165], 0
	s_add_i32 s63, s24, s86
	v_lshl_add_u64 v[186:187], s[78:79], 0, v[172:173]
	s_mov_b32 m0, s63
	v_mfma_f32_16x16x32_bf16 v[110:113], v[114:117], v[194:197], 0
	v_mfma_f32_16x16x32_bf16 v[106:109], v[122:125], v[194:197], 0
	v_mfma_f32_16x16x32_bf16 v[98:101], v[114:117], v[206:209], 0
	v_mfma_f32_16x16x32_bf16 v[90:93], v[122:125], v[206:209], 0
	v_mfma_f32_16x16x32_bf16 v[82:85], v[114:117], v[214:217], 0
	v_mfma_f32_16x16x32_bf16 v[74:77], v[122:125], v[214:217], 0
	v_mfma_f32_16x16x32_bf16 v[142:145], v[118:121], v[166:169], v[142:145]
	v_mfma_f32_16x16x32_bf16 v[138:141], v[126:129], v[166:169], v[138:141]
	v_mfma_f32_16x16x32_bf16 v[110:113], v[118:121], v[198:201], v[110:113]
	v_mfma_f32_16x16x32_bf16 v[106:109], v[126:129], v[198:201], v[106:109]
	v_mfma_f32_16x16x32_bf16 v[98:101], v[118:121], v[210:213], v[98:101]
	v_mfma_f32_16x16x32_bf16 v[90:93], v[126:129], v[210:213], v[90:93]
	v_mfma_f32_16x16x32_bf16 v[82:85], v[118:121], v[218:221], v[82:85]
	v_mfma_f32_16x16x32_bf16 v[74:77], v[126:129], v[218:221], v[74:77]
	v_mfma_f32_16x16x32_bf16 v[134:137], v[146:149], v[162:165], 0
	v_mfma_f32_16x16x32_bf16 v[130:133], v[154:157], v[162:165], 0
	v_mfma_f32_16x16x32_bf16 v[102:105], v[146:149], v[194:197], 0
	v_mfma_f32_16x16x32_bf16 v[94:97], v[154:157], v[194:197], 0
	v_mfma_f32_16x16x32_bf16 v[86:89], v[146:149], v[206:209], 0
	v_mfma_f32_16x16x32_bf16 v[78:81], v[154:157], v[206:209], 0
	v_mfma_f32_16x16x32_bf16 v[70:73], v[146:149], v[214:217], 0
	v_mfma_f32_16x16x32_bf16 v[66:69], v[154:157], v[214:217], 0
	v_mfma_f32_16x16x32_bf16 v[134:137], v[150:153], v[166:169], v[134:137]
	v_mfma_f32_16x16x32_bf16 v[130:133], v[158:161], v[166:169], v[130:133]
	v_mfma_f32_16x16x32_bf16 v[102:105], v[150:153], v[198:201], v[102:105]
	v_mfma_f32_16x16x32_bf16 v[94:97], v[158:161], v[198:201], v[94:97]
	v_mfma_f32_16x16x32_bf16 v[86:89], v[150:153], v[210:213], v[86:89]
	v_mfma_f32_16x16x32_bf16 v[78:81], v[158:161], v[210:213], v[78:81]
	v_mfma_f32_16x16x32_bf16 v[70:73], v[150:153], v[218:221], v[70:73]
	v_mfma_f32_16x16x32_bf16 v[66:69], v[158:161], v[218:221], v[66:69]
	s_setprio 0
	s_barrier
	ds_read_b128 v[162:165], v192 offset:16384
	ds_read_b128 v[166:169], v192 offset:17408
	ds_read_b128 v[194:197], v192 offset:18432
	ds_read_b128 v[198:201], v192 offset:19456
	ds_read_b128 v[206:209], v192 offset:20480
	ds_read_b128 v[210:213], v192 offset:21504
	ds_read_b128 v[214:217], v192 offset:22528
	ds_read_b128 v[218:221], v192 offset:23552
	global_load_lds_dwordx4 v[186:187], off
	s_add_i32 m0, s63, 0x2000
	s_add_u32 vcc_lo, s78, 0x40000
	v_lshl_add_u64 v[202:203], s[78:79], 0, v[176:177]
	s_addc_u32 vcc_hi, s79, 0
	s_add_i32 s63, s25, s86
	global_load_lds_dwordx4 v[202:203], off
	v_lshl_add_u64 v[222:223], vcc, 0, v[172:173]
	s_mov_b32 m0, s63
	v_lshl_add_u64 v[224:225], s[80:81], 0, v[174:175]
	global_load_lds_dwordx4 v[222:223], off
	v_lshl_add_u64 v[222:223], vcc, 0, v[176:177]
	s_add_i32 m0, s63, 0x2000
	s_nop 0
	global_load_lds_dwordx4 v[222:223], off
	v_lshl_add_u64 v[222:223], s[80:81], 0, v[170:171]
	s_mov_b32 m0, s87
	s_nop 0
	global_load_lds_dwordx4 v[222:223], off
	s_mov_b32 m0, s88
	s_nop 0
	global_load_lds_dwordx4 v[224:225], off
	s_waitcnt vmcnt(8)
	s_waitcnt lgkmcnt(0)
	s_setprio 1
	s_barrier
	v_mfma_f32_16x16x32_bf16 v[62:65], v[114:117], v[162:165], 0
	v_mfma_f32_16x16x32_bf16 v[58:61], v[122:125], v[162:165], 0
	v_mfma_f32_16x16x32_bf16 v[50:53], v[114:117], v[194:197], 0
	v_mfma_f32_16x16x32_bf16 v[42:45], v[122:125], v[194:197], 0
	v_mfma_f32_16x16x32_bf16 v[34:37], v[114:117], v[206:209], 0
	v_mfma_f32_16x16x32_bf16 v[26:29], v[122:125], v[206:209], 0
	v_mfma_f32_16x16x32_bf16 v[18:21], v[114:117], v[214:217], 0
	v_mfma_f32_16x16x32_bf16 v[10:13], v[122:125], v[214:217], 0
	v_mfma_f32_16x16x32_bf16 v[62:65], v[118:121], v[166:169], v[62:65]
	v_mfma_f32_16x16x32_bf16 v[58:61], v[126:129], v[166:169], v[58:61]
	v_mfma_f32_16x16x32_bf16 v[50:53], v[118:121], v[198:201], v[50:53]
	v_mfma_f32_16x16x32_bf16 v[42:45], v[126:129], v[198:201], v[42:45]
	v_mfma_f32_16x16x32_bf16 v[34:37], v[118:121], v[210:213], v[34:37]
	v_mfma_f32_16x16x32_bf16 v[26:29], v[126:129], v[210:213], v[26:29]
	v_mfma_f32_16x16x32_bf16 v[18:21], v[118:121], v[218:221], v[18:21]
	v_mfma_f32_16x16x32_bf16 v[10:13], v[126:129], v[218:221], v[10:13]
	v_mfma_f32_16x16x32_bf16 v[54:57], v[146:149], v[162:165], 0
	v_mfma_f32_16x16x32_bf16 v[46:49], v[154:157], v[162:165], 0
	v_mfma_f32_16x16x32_bf16 v[38:41], v[146:149], v[194:197], 0
	v_mfma_f32_16x16x32_bf16 v[30:33], v[154:157], v[194:197], 0
	v_mfma_f32_16x16x32_bf16 v[22:25], v[146:149], v[206:209], 0
	v_mfma_f32_16x16x32_bf16 v[14:17], v[154:157], v[206:209], 0
	v_mfma_f32_16x16x32_bf16 v[6:9], v[146:149], v[214:217], 0
	v_mfma_f32_16x16x32_bf16 v[2:5], v[154:157], v[214:217], 0
	v_mfma_f32_16x16x32_bf16 v[54:57], v[150:153], v[166:169], v[54:57]
	v_mfma_f32_16x16x32_bf16 v[46:49], v[158:161], v[166:169], v[46:49]
	v_mfma_f32_16x16x32_bf16 v[38:41], v[150:153], v[198:201], v[38:41]
	v_mfma_f32_16x16x32_bf16 v[30:33], v[158:161], v[198:201], v[30:33]
	v_mfma_f32_16x16x32_bf16 v[22:25], v[150:153], v[210:213], v[22:25]
	v_mfma_f32_16x16x32_bf16 v[14:17], v[158:161], v[210:213], v[14:17]
	v_mfma_f32_16x16x32_bf16 v[6:9], v[150:153], v[218:221], v[6:9]
	v_mfma_f32_16x16x32_bf16 v[2:5], v[158:161], v[218:221], v[2:5]
	s_setprio 0
	s_barrier
	s_add_i32 s63, 0, 0x18000
	s_add_i32 s83, 0, 0x1c000
	v_add_u32_e32 v126, s63, v189
	v_add_u32_e32 v158, s83, v189
	ds_read_b128 v[114:117], v126
	ds_read_b128 v[118:121], v126 offset:1024
	ds_read_b128 v[122:125], v126 offset:2048
	ds_read_b128 v[126:129], v126 offset:3072
	ds_read_b128 v[146:149], v158
	ds_read_b128 v[150:153], v158 offset:1024
	ds_read_b128 v[154:157], v158 offset:2048
	ds_read_b128 v[158:161], v158 offset:3072
	s_add_u32 s80, s80, 0x40000
	s_addc_u32 s81, s81, 0
	s_mov_b32 m0, s89
	v_lshl_add_u64 v[226:227], s[80:81], 0, v[170:171]
	ds_read_b128 v[162:165], v192 offset:32768
	ds_read_b128 v[166:169], v192 offset:33792
	ds_read_b128 v[194:197], v192 offset:34816
	ds_read_b128 v[198:201], v192 offset:35840
	ds_read_b128 v[206:209], v192 offset:36864
	ds_read_b128 v[210:213], v192 offset:37888
	ds_read_b128 v[214:217], v192 offset:38912
	ds_read_b128 v[218:221], v192 offset:39936
	global_load_lds_dwordx4 v[226:227], off
	v_lshl_add_u64 v[226:227], s[80:81], 0, v[174:175]
	s_mov_b32 m0, s90
	s_nop 0
	global_load_lds_dwordx4 v[226:227], off
	s_waitcnt vmcnt(8)
	s_waitcnt lgkmcnt(0)
	s_setprio 1
	s_barrier
	v_mfma_f32_16x16x32_bf16 v[142:145], v[114:117], v[162:165], v[142:145]
	v_mfma_f32_16x16x32_bf16 v[138:141], v[122:125], v[162:165], v[138:141]
	s_add_i32 s63, s63, s86
	v_lshl_add_u64 v[186:187], v[186:187], 0, s[22:23]
	s_mov_b32 m0, s63
	v_mfma_f32_16x16x32_bf16 v[110:113], v[114:117], v[194:197], v[110:113]
	v_mfma_f32_16x16x32_bf16 v[106:109], v[122:125], v[194:197], v[106:109]
	v_mfma_f32_16x16x32_bf16 v[98:101], v[114:117], v[206:209], v[98:101]
	v_mfma_f32_16x16x32_bf16 v[90:93], v[122:125], v[206:209], v[90:93]
	v_mfma_f32_16x16x32_bf16 v[82:85], v[114:117], v[214:217], v[82:85]
	v_mfma_f32_16x16x32_bf16 v[74:77], v[122:125], v[214:217], v[74:77]
	v_mfma_f32_16x16x32_bf16 v[142:145], v[118:121], v[166:169], v[142:145]
	v_mfma_f32_16x16x32_bf16 v[138:141], v[126:129], v[166:169], v[138:141]
	v_mfma_f32_16x16x32_bf16 v[110:113], v[118:121], v[198:201], v[110:113]
	v_mfma_f32_16x16x32_bf16 v[106:109], v[126:129], v[198:201], v[106:109]
	v_mfma_f32_16x16x32_bf16 v[98:101], v[118:121], v[210:213], v[98:101]
	v_mfma_f32_16x16x32_bf16 v[90:93], v[126:129], v[210:213], v[90:93]
	v_mfma_f32_16x16x32_bf16 v[82:85], v[118:121], v[218:221], v[82:85]
	v_mfma_f32_16x16x32_bf16 v[74:77], v[126:129], v[218:221], v[74:77]
	v_mfma_f32_16x16x32_bf16 v[134:137], v[146:149], v[162:165], v[134:137]
	v_mfma_f32_16x16x32_bf16 v[130:133], v[154:157], v[162:165], v[130:133]
	v_mfma_f32_16x16x32_bf16 v[102:105], v[146:149], v[194:197], v[102:105]
	v_mfma_f32_16x16x32_bf16 v[94:97], v[154:157], v[194:197], v[94:97]
	v_mfma_f32_16x16x32_bf16 v[86:89], v[146:149], v[206:209], v[86:89]
	v_mfma_f32_16x16x32_bf16 v[78:81], v[154:157], v[206:209], v[78:81]
	v_mfma_f32_16x16x32_bf16 v[70:73], v[146:149], v[214:217], v[70:73]
	v_mfma_f32_16x16x32_bf16 v[66:69], v[154:157], v[214:217], v[66:69]
	v_mfma_f32_16x16x32_bf16 v[134:137], v[150:153], v[166:169], v[134:137]
	v_mfma_f32_16x16x32_bf16 v[130:133], v[158:161], v[166:169], v[130:133]
	v_mfma_f32_16x16x32_bf16 v[102:105], v[150:153], v[198:201], v[102:105]
	v_mfma_f32_16x16x32_bf16 v[94:97], v[158:161], v[198:201], v[94:97]
	v_mfma_f32_16x16x32_bf16 v[86:89], v[150:153], v[210:213], v[86:89]
	v_mfma_f32_16x16x32_bf16 v[78:81], v[158:161], v[210:213], v[78:81]
	v_mfma_f32_16x16x32_bf16 v[70:73], v[150:153], v[218:221], v[70:73]
	v_mfma_f32_16x16x32_bf16 v[66:69], v[158:161], v[218:221], v[66:69]
	s_setprio 0
	s_barrier
	ds_read_b128 v[162:165], v192 offset:49152
	ds_read_b128 v[166:169], v192 offset:50176
	ds_read_b128 v[194:197], v192 offset:51200
	ds_read_b128 v[198:201], v192 offset:52224
	ds_read_b128 v[206:209], v192 offset:53248
	ds_read_b128 v[210:213], v192 offset:54272
	ds_read_b128 v[214:217], v192 offset:55296
	ds_read_b128 v[218:221], v192 offset:56320
	global_load_lds_dwordx4 v[186:187], off
	s_add_i32 m0, s63, 0x2000
	s_add_u32 s78, s78, 0x40080
	v_lshl_add_u64 v[186:187], v[202:203], 0, s[22:23]
	s_addc_u32 s79, s79, 0
	s_add_i32 s63, s83, s86
	global_load_lds_dwordx4 v[186:187], off
	v_lshl_add_u64 v[186:187], s[78:79], 0, v[172:173]
	s_mov_b32 m0, s63
	s_nop 0
	global_load_lds_dwordx4 v[186:187], off
	v_lshl_add_u64 v[186:187], s[78:79], 0, v[176:177]
	s_add_i32 m0, s63, 0x2000
	s_nop 0
	global_load_lds_dwordx4 v[186:187], off
	v_lshl_add_u64 v[186:187], v[222:223], 0, s[22:23]
	s_mov_b32 m0, s95
	s_nop 0
	global_load_lds_dwordx4 v[186:187], off
	v_lshl_add_u64 v[186:187], v[224:225], 0, s[22:23]
	s_mov_b32 m0, s96
	s_nop 0
	global_load_lds_dwordx4 v[186:187], off
	s_waitcnt vmcnt(8)
	s_waitcnt lgkmcnt(0)
	s_setprio 1
	s_barrier
	v_mfma_f32_16x16x32_bf16 v[62:65], v[114:117], v[162:165], v[62:65]
	v_mfma_f32_16x16x32_bf16 v[58:61], v[122:125], v[162:165], v[58:61]
	s_add_u32 s76, s76, 0x100
	s_addc_u32 s77, s77, 0
	s_add_u32 s47, s47, 0x100
	s_addc_u32 s62, s62, 0
	s_cmp_ge_i32 s82, s7
	s_mov_b32 s63, s82
	v_mfma_f32_16x16x32_bf16 v[50:53], v[114:117], v[194:197], v[50:53]
	v_mfma_f32_16x16x32_bf16 v[42:45], v[122:125], v[194:197], v[42:45]
	v_mfma_f32_16x16x32_bf16 v[34:37], v[114:117], v[206:209], v[34:37]
	v_mfma_f32_16x16x32_bf16 v[26:29], v[122:125], v[206:209], v[26:29]
	v_mfma_f32_16x16x32_bf16 v[18:21], v[114:117], v[214:217], v[18:21]
	v_mfma_f32_16x16x32_bf16 v[10:13], v[122:125], v[214:217], v[10:13]
	v_mfma_f32_16x16x32_bf16 v[62:65], v[118:121], v[166:169], v[62:65]
	v_mfma_f32_16x16x32_bf16 v[58:61], v[126:129], v[166:169], v[58:61]
	v_mfma_f32_16x16x32_bf16 v[50:53], v[118:121], v[198:201], v[50:53]
	v_mfma_f32_16x16x32_bf16 v[42:45], v[126:129], v[198:201], v[42:45]
	v_mfma_f32_16x16x32_bf16 v[34:37], v[118:121], v[210:213], v[34:37]
	v_mfma_f32_16x16x32_bf16 v[26:29], v[126:129], v[210:213], v[26:29]
	v_mfma_f32_16x16x32_bf16 v[18:21], v[118:121], v[218:221], v[18:21]
	v_mfma_f32_16x16x32_bf16 v[10:13], v[126:129], v[218:221], v[10:13]
	v_mfma_f32_16x16x32_bf16 v[54:57], v[146:149], v[162:165], v[54:57]
	v_mfma_f32_16x16x32_bf16 v[46:49], v[154:157], v[162:165], v[46:49]
	v_mfma_f32_16x16x32_bf16 v[38:41], v[146:149], v[194:197], v[38:41]
	v_mfma_f32_16x16x32_bf16 v[30:33], v[154:157], v[194:197], v[30:33]
	v_mfma_f32_16x16x32_bf16 v[22:25], v[146:149], v[206:209], v[22:25]
	v_mfma_f32_16x16x32_bf16 v[14:17], v[154:157], v[206:209], v[14:17]
	v_mfma_f32_16x16x32_bf16 v[6:9], v[146:149], v[214:217], v[6:9]
	v_mfma_f32_16x16x32_bf16 v[2:5], v[154:157], v[214:217], v[2:5]
	v_mfma_f32_16x16x32_bf16 v[54:57], v[150:153], v[166:169], v[54:57]
	v_mfma_f32_16x16x32_bf16 v[46:49], v[158:161], v[166:169], v[46:49]
	v_mfma_f32_16x16x32_bf16 v[38:41], v[150:153], v[198:201], v[38:41]
	v_mfma_f32_16x16x32_bf16 v[30:33], v[158:161], v[198:201], v[30:33]
	v_mfma_f32_16x16x32_bf16 v[22:25], v[150:153], v[210:213], v[22:25]
	v_mfma_f32_16x16x32_bf16 v[14:17], v[158:161], v[210:213], v[14:17]
	v_mfma_f32_16x16x32_bf16 v[6:9], v[150:153], v[218:221], v[6:9]
	v_mfma_f32_16x16x32_bf16 v[2:5], v[158:161], v[218:221], v[2:5]
	s_setprio 0
	s_barrier
.LBB0_566:
	s_waitcnt vmcnt(0)
	ds_read_b128 v[114:117], v190
	ds_read_b128 v[118:121], v190 offset:1024
	ds_read_b128 v[122:125], v190 offset:2048
	ds_read_b128 v[126:129], v190 offset:3072
	ds_read_b128 v[146:149], v191
	ds_read_b128 v[150:153], v191 offset:1024
	ds_read_b128 v[154:157], v191 offset:2048
	ds_read_b128 v[158:161], v191 offset:3072
	s_add_i32 s82, s63, 2
	s_add_u32 s78, s76, 0xfffc0080
	s_addc_u32 s79, s77, -1
	s_cmp_eq_u32 s45, s63
	s_cselect_b32 s81, s31, s79
	s_cselect_b32 s80, s33, s78
	s_cselect_b32 s79, s34, s62
	s_cselect_b32 s78, s39, s47
	v_lshl_add_u64 v[186:187], s[76:77], 0, v[180:181]
	s_add_i32 m0, s87, 0xc000
	ds_read_b128 v[162:165], v192
	ds_read_b128 v[166:169], v192 offset:1024
	ds_read_b128 v[194:197], v192 offset:2048
	ds_read_b128 v[198:201], v192 offset:3072
	ds_read_b128 v[206:209], v192 offset:4096
	ds_read_b128 v[210:213], v192 offset:5120
	ds_read_b128 v[214:217], v192 offset:6144
	ds_read_b128 v[218:221], v192 offset:7168
	global_load_lds_dwordx4 v[186:187], off
	v_lshl_add_u64 v[186:187], s[76:77], 0, v[182:183]
	s_add_i32 m0, s87, 0xe000
	s_nop 0
	global_load_lds_dwordx4 v[186:187], off
	s_waitcnt vmcnt(8)
	s_waitcnt lgkmcnt(0)
	s_setprio 1
	s_barrier
	v_mfma_f32_16x16x32_bf16 v[142:145], v[114:117], v[162:165], v[142:145]
	v_mfma_f32_16x16x32_bf16 v[138:141], v[122:125], v[162:165], v[138:141]
	s_add_i32 s63, s24, s86
	v_lshl_add_u64 v[186:187], s[78:79], 0, v[172:173]
	s_mov_b32 m0, s63
	v_mfma_f32_16x16x32_bf16 v[110:113], v[114:117], v[194:197], v[110:113]
	v_mfma_f32_16x16x32_bf16 v[106:109], v[122:125], v[194:197], v[106:109]
	v_mfma_f32_16x16x32_bf16 v[98:101], v[114:117], v[206:209], v[98:101]
	v_mfma_f32_16x16x32_bf16 v[90:93], v[122:125], v[206:209], v[90:93]
	v_mfma_f32_16x16x32_bf16 v[82:85], v[114:117], v[214:217], v[82:85]
	v_mfma_f32_16x16x32_bf16 v[74:77], v[122:125], v[214:217], v[74:77]
	v_mfma_f32_16x16x32_bf16 v[142:145], v[118:121], v[166:169], v[142:145]
	v_mfma_f32_16x16x32_bf16 v[138:141], v[126:129], v[166:169], v[138:141]
	v_mfma_f32_16x16x32_bf16 v[110:113], v[118:121], v[198:201], v[110:113]
	v_mfma_f32_16x16x32_bf16 v[106:109], v[126:129], v[198:201], v[106:109]
	v_mfma_f32_16x16x32_bf16 v[98:101], v[118:121], v[210:213], v[98:101]
	v_mfma_f32_16x16x32_bf16 v[90:93], v[126:129], v[210:213], v[90:93]
	v_mfma_f32_16x16x32_bf16 v[82:85], v[118:121], v[218:221], v[82:85]
	v_mfma_f32_16x16x32_bf16 v[74:77], v[126:129], v[218:221], v[74:77]
	v_mfma_f32_16x16x32_bf16 v[134:137], v[146:149], v[162:165], v[134:137]
	v_mfma_f32_16x16x32_bf16 v[130:133], v[154:157], v[162:165], v[130:133]
	v_mfma_f32_16x16x32_bf16 v[102:105], v[146:149], v[194:197], v[102:105]
	v_mfma_f32_16x16x32_bf16 v[94:97], v[154:157], v[194:197], v[94:97]
	v_mfma_f32_16x16x32_bf16 v[86:89], v[146:149], v[206:209], v[86:89]
	v_mfma_f32_16x16x32_bf16 v[78:81], v[154:157], v[206:209], v[78:81]
	v_mfma_f32_16x16x32_bf16 v[70:73], v[146:149], v[214:217], v[70:73]
	v_mfma_f32_16x16x32_bf16 v[66:69], v[154:157], v[214:217], v[66:69]
	v_mfma_f32_16x16x32_bf16 v[134:137], v[150:153], v[166:169], v[134:137]
	v_mfma_f32_16x16x32_bf16 v[130:133], v[158:161], v[166:169], v[130:133]
	v_mfma_f32_16x16x32_bf16 v[102:105], v[150:153], v[198:201], v[102:105]
	v_mfma_f32_16x16x32_bf16 v[94:97], v[158:161], v[198:201], v[94:97]
	v_mfma_f32_16x16x32_bf16 v[86:89], v[150:153], v[210:213], v[86:89]
	v_mfma_f32_16x16x32_bf16 v[78:81], v[158:161], v[210:213], v[78:81]
	v_mfma_f32_16x16x32_bf16 v[70:73], v[150:153], v[218:221], v[70:73]
	v_mfma_f32_16x16x32_bf16 v[66:69], v[158:161], v[218:221], v[66:69]
	s_setprio 0
	s_barrier
	ds_read_b128 v[162:165], v192 offset:16384
	ds_read_b128 v[166:169], v192 offset:17408
	ds_read_b128 v[194:197], v192 offset:18432
	ds_read_b128 v[198:201], v192 offset:19456
	ds_read_b128 v[206:209], v192 offset:20480
	ds_read_b128 v[210:213], v192 offset:21504
	ds_read_b128 v[214:217], v192 offset:22528
	ds_read_b128 v[218:221], v192 offset:23552
	global_load_lds_dwordx4 v[186:187], off
	s_add_i32 m0, s63, 0x2000
	s_add_u32 vcc_lo, s78, 0x40000
	v_lshl_add_u64 v[202:203], s[78:79], 0, v[176:177]
	s_addc_u32 vcc_hi, s79, 0
	s_add_i32 s63, s25, s86
	global_load_lds_dwordx4 v[202:203], off
	v_lshl_add_u64 v[222:223], vcc, 0, v[172:173]
	s_mov_b32 m0, s63
	v_lshl_add_u64 v[224:225], s[80:81], 0, v[174:175]
	global_load_lds_dwordx4 v[222:223], off
	v_lshl_add_u64 v[222:223], vcc, 0, v[176:177]
	s_add_i32 m0, s63, 0x2000
	s_nop 0
	global_load_lds_dwordx4 v[222:223], off
	v_lshl_add_u64 v[222:223], s[80:81], 0, v[170:171]
	s_mov_b32 m0, s87
	s_nop 0
	global_load_lds_dwordx4 v[222:223], off
	s_mov_b32 m0, s88
	s_nop 0
	global_load_lds_dwordx4 v[224:225], off
	s_waitcnt vmcnt(8)
	s_waitcnt lgkmcnt(0)
	s_setprio 1
	s_barrier
	v_mfma_f32_16x16x32_bf16 v[62:65], v[114:117], v[162:165], v[62:65]
	v_mfma_f32_16x16x32_bf16 v[58:61], v[122:125], v[162:165], v[58:61]
	v_mfma_f32_16x16x32_bf16 v[50:53], v[114:117], v[194:197], v[50:53]
	v_mfma_f32_16x16x32_bf16 v[42:45], v[122:125], v[194:197], v[42:45]
	v_mfma_f32_16x16x32_bf16 v[34:37], v[114:117], v[206:209], v[34:37]
	v_mfma_f32_16x16x32_bf16 v[26:29], v[122:125], v[206:209], v[26:29]
	v_mfma_f32_16x16x32_bf16 v[18:21], v[114:117], v[214:217], v[18:21]
	v_mfma_f32_16x16x32_bf16 v[10:13], v[122:125], v[214:217], v[10:13]
	v_mfma_f32_16x16x32_bf16 v[62:65], v[118:121], v[166:169], v[62:65]
	v_mfma_f32_16x16x32_bf16 v[58:61], v[126:129], v[166:169], v[58:61]
	v_mfma_f32_16x16x32_bf16 v[50:53], v[118:121], v[198:201], v[50:53]
	v_mfma_f32_16x16x32_bf16 v[42:45], v[126:129], v[198:201], v[42:45]
	v_mfma_f32_16x16x32_bf16 v[34:37], v[118:121], v[210:213], v[34:37]
	v_mfma_f32_16x16x32_bf16 v[26:29], v[126:129], v[210:213], v[26:29]
	v_mfma_f32_16x16x32_bf16 v[18:21], v[118:121], v[218:221], v[18:21]
	v_mfma_f32_16x16x32_bf16 v[10:13], v[126:129], v[218:221], v[10:13]
	v_mfma_f32_16x16x32_bf16 v[54:57], v[146:149], v[162:165], v[54:57]
	v_mfma_f32_16x16x32_bf16 v[46:49], v[154:157], v[162:165], v[46:49]
	v_mfma_f32_16x16x32_bf16 v[38:41], v[146:149], v[194:197], v[38:41]
	v_mfma_f32_16x16x32_bf16 v[30:33], v[154:157], v[194:197], v[30:33]
	v_mfma_f32_16x16x32_bf16 v[22:25], v[146:149], v[206:209], v[22:25]
	v_mfma_f32_16x16x32_bf16 v[14:17], v[154:157], v[206:209], v[14:17]
	v_mfma_f32_16x16x32_bf16 v[6:9], v[146:149], v[214:217], v[6:9]
	v_mfma_f32_16x16x32_bf16 v[2:5], v[154:157], v[214:217], v[2:5]
	v_mfma_f32_16x16x32_bf16 v[54:57], v[150:153], v[166:169], v[54:57]
	v_mfma_f32_16x16x32_bf16 v[46:49], v[158:161], v[166:169], v[46:49]
	v_mfma_f32_16x16x32_bf16 v[38:41], v[150:153], v[198:201], v[38:41]
	v_mfma_f32_16x16x32_bf16 v[30:33], v[158:161], v[198:201], v[30:33]
	v_mfma_f32_16x16x32_bf16 v[22:25], v[150:153], v[210:213], v[22:25]
	v_mfma_f32_16x16x32_bf16 v[14:17], v[158:161], v[210:213], v[14:17]
	v_mfma_f32_16x16x32_bf16 v[6:9], v[150:153], v[218:221], v[6:9]
	v_mfma_f32_16x16x32_bf16 v[2:5], v[158:161], v[218:221], v[2:5]
	s_setprio 0
	s_barrier
	s_add_i32 s63, 0, 0x18000
	s_add_i32 s83, 0, 0x1c000
	v_add_u32_e32 v126, s63, v189
	v_add_u32_e32 v158, s83, v189
	ds_read_b128 v[114:117], v126
	ds_read_b128 v[118:121], v126 offset:1024
	ds_read_b128 v[122:125], v126 offset:2048
	ds_read_b128 v[126:129], v126 offset:3072
	ds_read_b128 v[146:149], v158
	ds_read_b128 v[150:153], v158 offset:1024
	ds_read_b128 v[154:157], v158 offset:2048
	ds_read_b128 v[158:161], v158 offset:3072
	s_add_u32 s80, s80, 0x40000
	s_addc_u32 s81, s81, 0
	s_mov_b32 m0, s89
	v_lshl_add_u64 v[226:227], s[80:81], 0, v[170:171]
	ds_read_b128 v[162:165], v192 offset:32768
	ds_read_b128 v[166:169], v192 offset:33792
	ds_read_b128 v[194:197], v192 offset:34816
	ds_read_b128 v[198:201], v192 offset:35840
	ds_read_b128 v[206:209], v192 offset:36864
	ds_read_b128 v[210:213], v192 offset:37888
	ds_read_b128 v[214:217], v192 offset:38912
	ds_read_b128 v[218:221], v192 offset:39936
	global_load_lds_dwordx4 v[226:227], off
	v_lshl_add_u64 v[226:227], s[80:81], 0, v[174:175]
	s_mov_b32 m0, s90
	s_nop 0
	global_load_lds_dwordx4 v[226:227], off
	s_waitcnt vmcnt(8)
	s_waitcnt lgkmcnt(0)
	s_setprio 1
	s_barrier
	v_mfma_f32_16x16x32_bf16 v[142:145], v[114:117], v[162:165], v[142:145]
	v_mfma_f32_16x16x32_bf16 v[138:141], v[122:125], v[162:165], v[138:141]
	s_add_i32 s63, s63, s86
	v_lshl_add_u64 v[186:187], v[186:187], 0, s[22:23]
	s_mov_b32 m0, s63
	v_mfma_f32_16x16x32_bf16 v[110:113], v[114:117], v[194:197], v[110:113]
	v_mfma_f32_16x16x32_bf16 v[106:109], v[122:125], v[194:197], v[106:109]
	v_mfma_f32_16x16x32_bf16 v[98:101], v[114:117], v[206:209], v[98:101]
	v_mfma_f32_16x16x32_bf16 v[90:93], v[122:125], v[206:209], v[90:93]
	v_mfma_f32_16x16x32_bf16 v[82:85], v[114:117], v[214:217], v[82:85]
	v_mfma_f32_16x16x32_bf16 v[74:77], v[122:125], v[214:217], v[74:77]
	v_mfma_f32_16x16x32_bf16 v[142:145], v[118:121], v[166:169], v[142:145]
	v_mfma_f32_16x16x32_bf16 v[138:141], v[126:129], v[166:169], v[138:141]
	v_mfma_f32_16x16x32_bf16 v[110:113], v[118:121], v[198:201], v[110:113]
	v_mfma_f32_16x16x32_bf16 v[106:109], v[126:129], v[198:201], v[106:109]
	v_mfma_f32_16x16x32_bf16 v[98:101], v[118:121], v[210:213], v[98:101]
	v_mfma_f32_16x16x32_bf16 v[90:93], v[126:129], v[210:213], v[90:93]
	v_mfma_f32_16x16x32_bf16 v[82:85], v[118:121], v[218:221], v[82:85]
	v_mfma_f32_16x16x32_bf16 v[74:77], v[126:129], v[218:221], v[74:77]
	v_mfma_f32_16x16x32_bf16 v[134:137], v[146:149], v[162:165], v[134:137]
	v_mfma_f32_16x16x32_bf16 v[130:133], v[154:157], v[162:165], v[130:133]
	v_mfma_f32_16x16x32_bf16 v[102:105], v[146:149], v[194:197], v[102:105]
	v_mfma_f32_16x16x32_bf16 v[94:97], v[154:157], v[194:197], v[94:97]
	v_mfma_f32_16x16x32_bf16 v[86:89], v[146:149], v[206:209], v[86:89]
	v_mfma_f32_16x16x32_bf16 v[78:81], v[154:157], v[206:209], v[78:81]
	v_mfma_f32_16x16x32_bf16 v[70:73], v[146:149], v[214:217], v[70:73]
	v_mfma_f32_16x16x32_bf16 v[66:69], v[154:157], v[214:217], v[66:69]
	v_mfma_f32_16x16x32_bf16 v[134:137], v[150:153], v[166:169], v[134:137]
	v_mfma_f32_16x16x32_bf16 v[130:133], v[158:161], v[166:169], v[130:133]
	v_mfma_f32_16x16x32_bf16 v[102:105], v[150:153], v[198:201], v[102:105]
	v_mfma_f32_16x16x32_bf16 v[94:97], v[158:161], v[198:201], v[94:97]
	v_mfma_f32_16x16x32_bf16 v[86:89], v[150:153], v[210:213], v[86:89]
	v_mfma_f32_16x16x32_bf16 v[78:81], v[158:161], v[210:213], v[78:81]
	v_mfma_f32_16x16x32_bf16 v[70:73], v[150:153], v[218:221], v[70:73]
	v_mfma_f32_16x16x32_bf16 v[66:69], v[158:161], v[218:221], v[66:69]
	s_setprio 0
	s_barrier
	ds_read_b128 v[162:165], v192 offset:49152
	ds_read_b128 v[166:169], v192 offset:50176
	ds_read_b128 v[194:197], v192 offset:51200
	ds_read_b128 v[198:201], v192 offset:52224
	ds_read_b128 v[206:209], v192 offset:53248
	ds_read_b128 v[210:213], v192 offset:54272
	ds_read_b128 v[214:217], v192 offset:55296
	ds_read_b128 v[218:221], v192 offset:56320
	global_load_lds_dwordx4 v[186:187], off
	s_add_i32 m0, s63, 0x2000
	s_add_u32 s78, s78, 0x40080
	v_lshl_add_u64 v[186:187], v[202:203], 0, s[22:23]
	s_addc_u32 s79, s79, 0
	s_add_i32 s63, s83, s86
	global_load_lds_dwordx4 v[186:187], off
	v_lshl_add_u64 v[186:187], s[78:79], 0, v[172:173]
	s_mov_b32 m0, s63
	s_nop 0
	global_load_lds_dwordx4 v[186:187], off
	v_lshl_add_u64 v[186:187], s[78:79], 0, v[176:177]
	s_add_i32 m0, s63, 0x2000
	s_nop 0
	global_load_lds_dwordx4 v[186:187], off
	v_lshl_add_u64 v[186:187], v[222:223], 0, s[22:23]
	s_mov_b32 m0, s95
	s_nop 0
	global_load_lds_dwordx4 v[186:187], off
	v_lshl_add_u64 v[186:187], v[224:225], 0, s[22:23]
	s_mov_b32 m0, s96
	s_nop 0
	global_load_lds_dwordx4 v[186:187], off
	s_waitcnt vmcnt(8)
	s_waitcnt lgkmcnt(0)
	s_setprio 1
	s_barrier
	v_mfma_f32_16x16x32_bf16 v[62:65], v[114:117], v[162:165], v[62:65]
	v_mfma_f32_16x16x32_bf16 v[58:61], v[122:125], v[162:165], v[58:61]
	s_add_u32 s76, s76, 0x100
	s_addc_u32 s77, s77, 0
	s_add_u32 s47, s47, 0x100
	s_addc_u32 s62, s62, 0
	s_cmp_ge_i32 s82, s7
	s_mov_b32 s63, s82
	v_mfma_f32_16x16x32_bf16 v[50:53], v[114:117], v[194:197], v[50:53]
	v_mfma_f32_16x16x32_bf16 v[42:45], v[122:125], v[194:197], v[42:45]
	v_mfma_f32_16x16x32_bf16 v[34:37], v[114:117], v[206:209], v[34:37]
	v_mfma_f32_16x16x32_bf16 v[26:29], v[122:125], v[206:209], v[26:29]
	v_mfma_f32_16x16x32_bf16 v[18:21], v[114:117], v[214:217], v[18:21]
	v_mfma_f32_16x16x32_bf16 v[10:13], v[122:125], v[214:217], v[10:13]
	v_mfma_f32_16x16x32_bf16 v[62:65], v[118:121], v[166:169], v[62:65]
	v_mfma_f32_16x16x32_bf16 v[58:61], v[126:129], v[166:169], v[58:61]
	v_mfma_f32_16x16x32_bf16 v[50:53], v[118:121], v[198:201], v[50:53]
	v_mfma_f32_16x16x32_bf16 v[42:45], v[126:129], v[198:201], v[42:45]
	v_mfma_f32_16x16x32_bf16 v[34:37], v[118:121], v[210:213], v[34:37]
	v_mfma_f32_16x16x32_bf16 v[26:29], v[126:129], v[210:213], v[26:29]
	v_mfma_f32_16x16x32_bf16 v[18:21], v[118:121], v[218:221], v[18:21]
	v_mfma_f32_16x16x32_bf16 v[10:13], v[126:129], v[218:221], v[10:13]
	v_mfma_f32_16x16x32_bf16 v[54:57], v[146:149], v[162:165], v[54:57]
	v_mfma_f32_16x16x32_bf16 v[46:49], v[154:157], v[162:165], v[46:49]
	v_mfma_f32_16x16x32_bf16 v[38:41], v[146:149], v[194:197], v[38:41]
	v_mfma_f32_16x16x32_bf16 v[30:33], v[154:157], v[194:197], v[30:33]
	v_mfma_f32_16x16x32_bf16 v[22:25], v[146:149], v[206:209], v[22:25]
	v_mfma_f32_16x16x32_bf16 v[14:17], v[154:157], v[206:209], v[14:17]
	v_mfma_f32_16x16x32_bf16 v[6:9], v[146:149], v[214:217], v[6:9]
	v_mfma_f32_16x16x32_bf16 v[2:5], v[154:157], v[214:217], v[2:5]
	v_mfma_f32_16x16x32_bf16 v[54:57], v[150:153], v[166:169], v[54:57]
	v_mfma_f32_16x16x32_bf16 v[46:49], v[158:161], v[166:169], v[46:49]
	v_mfma_f32_16x16x32_bf16 v[38:41], v[150:153], v[198:201], v[38:41]
	v_mfma_f32_16x16x32_bf16 v[30:33], v[158:161], v[198:201], v[30:33]
	v_mfma_f32_16x16x32_bf16 v[22:25], v[150:153], v[210:213], v[22:25]
	v_mfma_f32_16x16x32_bf16 v[14:17], v[158:161], v[210:213], v[14:17]
	v_mfma_f32_16x16x32_bf16 v[6:9], v[150:153], v[218:221], v[6:9]
	v_mfma_f32_16x16x32_bf16 v[2:5], v[158:161], v[218:221], v[2:5]
	s_setprio 0
	s_barrier
	s_cbranch_scc0 .LBB0_566
	s_and_b64 vcc, exec, s[26:27]
	s_cbranch_vccz .LBB0_569
	s_barrier

.LBB0_744:
	s_add_u32 s36, s96, s22
	s_addc_u32 s37, s97, s23
	s_and_b64 s[14:15], s[4:5], exec
	s_cselect_b32 s14, s37, s43
	s_cselect_b32 s15, s36, s42
	s_add_u32 s38, s2, s26
	s_addc_u32 s39, s3, s27
	s_and_b64 s[46:47], s[4:5], exec
	s_cselect_b32 s21, s39, s45
	s_cselect_b32 s65, s38, s44
	s_add_u32 s42, s42, 0x40080
	s_addc_u32 s43, s43, 0
	s_add_u32 s66, s44, 0x100
	s_addc_u32 s67, s45, 0
	s_mov_b32 s68, -2
	ds_read_b128 v[154:157], v150
	ds_read_b128 v[158:161], v150 offset:1024
	ds_read_b128 v[162:165], v150 offset:2048
	ds_read_b128 v[166:169], v150 offset:3072
	ds_read_b128 v[170:173], v151
	ds_read_b128 v[174:177], v151 offset:1024
	ds_read_b128 v[178:181], v151 offset:2048
	ds_read_b128 v[182:185], v151 offset:3072
	s_add_u32 s44, s42, 0xfffc0080
	s_addc_u32 s45, s43, -1
	s_cmp_eq_u32 s68, 12
	s_cselect_b32 s47, s14, s45
	s_cselect_b32 s46, s15, s44
	s_cselect_b32 s45, s21, s67
	s_cselect_b32 s44, s65, s66
	v_lshl_add_u64 v[146:147], s[42:43], 0, v[138:139]
	s_add_i32 m0, s19, 0xc000
	ds_read_b128 v[186:189], v152
	ds_read_b128 v[190:193], v152 offset:1024
	ds_read_b128 v[194:197], v152 offset:2048
	ds_read_b128 v[198:201], v152 offset:3072
	ds_read_b128 v[206:209], v152 offset:4096
	ds_read_b128 v[210:213], v152 offset:5120
	ds_read_b128 v[214:217], v152 offset:6144
	ds_read_b128 v[218:221], v152 offset:7168
	global_load_lds_dwordx4 v[146:147], off
	v_lshl_add_u64 v[146:147], s[42:43], 0, v[140:141]
	s_add_i32 m0, s19, 0xe000
	s_nop 0
	global_load_lds_dwordx4 v[146:147], off
	s_waitcnt vmcnt(8)
	s_waitcnt lgkmcnt(0)
	s_setprio 1
	s_barrier
	v_mfma_f32_16x16x32_bf16 v[126:129], v[154:157], v[186:189], 0
	v_mfma_f32_16x16x32_bf16 v[122:125], v[162:165], v[186:189], 0
	s_add_i32 s69, s49, s16
	v_lshl_add_u64 v[146:147], s[44:45], 0, v[134:135]
	s_mov_b32 m0, s69
	v_mfma_f32_16x16x32_bf16 v[110:113], v[154:157], v[194:197], 0
	v_mfma_f32_16x16x32_bf16 v[106:109], v[162:165], v[194:197], 0
	v_mfma_f32_16x16x32_bf16 v[94:97], v[154:157], v[206:209], 0
	v_mfma_f32_16x16x32_bf16 v[90:93], v[162:165], v[206:209], 0
	v_mfma_f32_16x16x32_bf16 v[78:81], v[154:157], v[214:217], 0
	v_mfma_f32_16x16x32_bf16 v[74:77], v[162:165], v[214:217], 0
	v_mfma_f32_16x16x32_bf16 v[126:129], v[158:161], v[190:193], v[126:129]
	v_mfma_f32_16x16x32_bf16 v[122:125], v[166:169], v[190:193], v[122:125]
	v_mfma_f32_16x16x32_bf16 v[110:113], v[158:161], v[198:201], v[110:113]
	v_mfma_f32_16x16x32_bf16 v[106:109], v[166:169], v[198:201], v[106:109]
	v_mfma_f32_16x16x32_bf16 v[94:97], v[158:161], v[210:213], v[94:97]
	v_mfma_f32_16x16x32_bf16 v[90:93], v[166:169], v[210:213], v[90:93]
	v_mfma_f32_16x16x32_bf16 v[78:81], v[158:161], v[218:221], v[78:81]
	v_mfma_f32_16x16x32_bf16 v[74:77], v[166:169], v[218:221], v[74:77]
	v_mfma_f32_16x16x32_bf16 v[118:121], v[170:173], v[186:189], 0
	v_mfma_f32_16x16x32_bf16 v[114:117], v[178:181], v[186:189], 0
	v_mfma_f32_16x16x32_bf16 v[102:105], v[170:173], v[194:197], 0
	v_mfma_f32_16x16x32_bf16 v[98:101], v[178:181], v[194:197], 0
	v_mfma_f32_16x16x32_bf16 v[86:89], v[170:173], v[206:209], 0
	v_mfma_f32_16x16x32_bf16 v[82:85], v[178:181], v[206:209], 0
	v_mfma_f32_16x16x32_bf16 v[70:73], v[170:173], v[214:217], 0
	v_mfma_f32_16x16x32_bf16 v[66:69], v[178:181], v[214:217], 0
	v_mfma_f32_16x16x32_bf16 v[118:121], v[174:177], v[190:193], v[118:121]
	v_mfma_f32_16x16x32_bf16 v[114:117], v[182:185], v[190:193], v[114:117]
	v_mfma_f32_16x16x32_bf16 v[102:105], v[174:177], v[198:201], v[102:105]
	v_mfma_f32_16x16x32_bf16 v[98:101], v[182:185], v[198:201], v[98:101]
	v_mfma_f32_16x16x32_bf16 v[86:89], v[174:177], v[210:213], v[86:89]
	v_mfma_f32_16x16x32_bf16 v[82:85], v[182:185], v[210:213], v[82:85]
	v_mfma_f32_16x16x32_bf16 v[70:73], v[174:177], v[218:221], v[70:73]
	v_mfma_f32_16x16x32_bf16 v[66:69], v[182:185], v[218:221], v[66:69]
	s_setprio 0
	s_barrier
	ds_read_b128 v[186:189], v152 offset:16384
	ds_read_b128 v[190:193], v152 offset:17408
	ds_read_b128 v[194:197], v152 offset:18432
	ds_read_b128 v[198:201], v152 offset:19456
	ds_read_b128 v[206:209], v152 offset:20480
	ds_read_b128 v[210:213], v152 offset:21504
	ds_read_b128 v[214:217], v152 offset:22528
	ds_read_b128 v[218:221], v152 offset:23552
	global_load_lds_dwordx4 v[146:147], off
	s_add_i32 m0, s69, 0x2000
	s_add_u32 s70, s44, 0x40000
	v_lshl_add_u64 v[202:203], s[44:45], 0, v[130:131]
	s_addc_u32 s71, s45, 0
	s_add_i32 s69, s62, s16
	global_load_lds_dwordx4 v[202:203], off
	v_lshl_add_u64 v[222:223], s[70:71], 0, v[134:135]
	s_mov_b32 m0, s69
	v_lshl_add_u64 v[224:225], s[46:47], 0, v[132:133]
	global_load_lds_dwordx4 v[222:223], off
	v_lshl_add_u64 v[222:223], s[70:71], 0, v[130:131]
	s_add_i32 m0, s69, 0x2000
	s_nop 0
	global_load_lds_dwordx4 v[222:223], off
	v_lshl_add_u64 v[222:223], s[46:47], 0, v[136:137]
	s_mov_b32 m0, s19
	s_nop 0
	global_load_lds_dwordx4 v[222:223], off
	s_mov_b32 m0, s24
	s_nop 0
	global_load_lds_dwordx4 v[224:225], off
	s_waitcnt vmcnt(8)
	s_waitcnt lgkmcnt(0)
	s_setprio 1
	s_barrier
	v_mfma_f32_16x16x32_bf16 v[62:65], v[154:157], v[186:189], 0
	v_mfma_f32_16x16x32_bf16 v[58:61], v[162:165], v[186:189], 0
	s_add_i32 s69, 0, 0x18000
	v_add_u32_e32 v153, s69, v149
	s_add_i32 s70, 0, 0x1c000
	v_mfma_f32_16x16x32_bf16 v[46:49], v[154:157], v[194:197], 0
	v_mfma_f32_16x16x32_bf16 v[42:45], v[162:165], v[194:197], 0
	v_mfma_f32_16x16x32_bf16 v[30:33], v[154:157], v[206:209], 0
	v_mfma_f32_16x16x32_bf16 v[26:29], v[162:165], v[206:209], 0
	v_mfma_f32_16x16x32_bf16 v[14:17], v[154:157], v[214:217], 0
	v_mfma_f32_16x16x32_bf16 v[10:13], v[162:165], v[214:217], 0
	v_mfma_f32_16x16x32_bf16 v[62:65], v[158:161], v[190:193], v[62:65]
	v_mfma_f32_16x16x32_bf16 v[58:61], v[166:169], v[190:193], v[58:61]
	v_mfma_f32_16x16x32_bf16 v[46:49], v[158:161], v[198:201], v[46:49]
	v_mfma_f32_16x16x32_bf16 v[42:45], v[166:169], v[198:201], v[42:45]
	v_mfma_f32_16x16x32_bf16 v[30:33], v[158:161], v[210:213], v[30:33]
	v_mfma_f32_16x16x32_bf16 v[26:29], v[166:169], v[210:213], v[26:29]
	v_mfma_f32_16x16x32_bf16 v[14:17], v[158:161], v[218:221], v[14:17]
	v_mfma_f32_16x16x32_bf16 v[10:13], v[166:169], v[218:221], v[10:13]
	v_mfma_f32_16x16x32_bf16 v[54:57], v[170:173], v[186:189], 0
	v_mfma_f32_16x16x32_bf16 v[50:53], v[178:181], v[186:189], 0
	v_mfma_f32_16x16x32_bf16 v[38:41], v[170:173], v[194:197], 0
	v_mfma_f32_16x16x32_bf16 v[34:37], v[178:181], v[194:197], 0
	v_mfma_f32_16x16x32_bf16 v[22:25], v[170:173], v[206:209], 0
	v_mfma_f32_16x16x32_bf16 v[18:21], v[178:181], v[206:209], 0
	v_mfma_f32_16x16x32_bf16 v[6:9], v[170:173], v[214:217], 0
	v_mfma_f32_16x16x32_bf16 v[2:5], v[178:181], v[214:217], 0
	v_mfma_f32_16x16x32_bf16 v[54:57], v[174:177], v[190:193], v[54:57]
	v_mfma_f32_16x16x32_bf16 v[50:53], v[182:185], v[190:193], v[50:53]
	v_mfma_f32_16x16x32_bf16 v[38:41], v[174:177], v[198:201], v[38:41]
	v_mfma_f32_16x16x32_bf16 v[34:37], v[182:185], v[198:201], v[34:37]
	v_mfma_f32_16x16x32_bf16 v[22:25], v[174:177], v[210:213], v[22:25]
	v_mfma_f32_16x16x32_bf16 v[18:21], v[182:185], v[210:213], v[18:21]
	v_mfma_f32_16x16x32_bf16 v[6:9], v[174:177], v[218:221], v[6:9]
	v_mfma_f32_16x16x32_bf16 v[2:5], v[182:185], v[218:221], v[2:5]
	s_setprio 0
	s_barrier
	ds_read_b128 v[154:157], v153
	ds_read_b128 v[158:161], v153 offset:1024
	ds_read_b128 v[162:165], v153 offset:2048
	ds_read_b128 v[166:169], v153 offset:3072
	v_add_u32_e32 v153, s70, v149
	ds_read_b128 v[170:173], v153
	ds_read_b128 v[174:177], v153 offset:1024
	ds_read_b128 v[178:181], v153 offset:2048
	ds_read_b128 v[182:185], v153 offset:3072
	s_add_u32 s46, s46, 0x40000
	s_addc_u32 s47, s47, 0
	s_mov_b32 m0, s25
	v_lshl_add_u64 v[226:227], s[46:47], 0, v[136:137]
	ds_read_b128 v[186:189], v152 offset:32768
	ds_read_b128 v[190:193], v152 offset:33792
	ds_read_b128 v[194:197], v152 offset:34816
	ds_read_b128 v[198:201], v152 offset:35840
	ds_read_b128 v[206:209], v152 offset:36864
	ds_read_b128 v[210:213], v152 offset:37888
	ds_read_b128 v[214:217], v152 offset:38912
	ds_read_b128 v[218:221], v152 offset:39936
	global_load_lds_dwordx4 v[226:227], off
	v_lshl_add_u64 v[226:227], s[46:47], 0, v[132:133]
	s_mov_b32 m0, s28
	s_nop 0
	global_load_lds_dwordx4 v[226:227], off
	s_waitcnt vmcnt(8)
	s_waitcnt lgkmcnt(0)
	s_setprio 1
	s_barrier
	v_mfma_f32_16x16x32_bf16 v[126:129], v[154:157], v[186:189], v[126:129]
	v_mfma_f32_16x16x32_bf16 v[122:125], v[162:165], v[186:189], v[122:125]
	s_add_i32 s46, s69, s16
	v_lshl_add_u64 v[146:147], v[146:147], 0, s[10:11]
	s_mov_b32 m0, s46
	v_mfma_f32_16x16x32_bf16 v[110:113], v[154:157], v[194:197], v[110:113]
	v_mfma_f32_16x16x32_bf16 v[106:109], v[162:165], v[194:197], v[106:109]
	v_mfma_f32_16x16x32_bf16 v[94:97], v[154:157], v[206:209], v[94:97]
	v_mfma_f32_16x16x32_bf16 v[90:93], v[162:165], v[206:209], v[90:93]
	v_mfma_f32_16x16x32_bf16 v[78:81], v[154:157], v[214:217], v[78:81]
	v_mfma_f32_16x16x32_bf16 v[74:77], v[162:165], v[214:217], v[74:77]
	v_mfma_f32_16x16x32_bf16 v[126:129], v[158:161], v[190:193], v[126:129]
	v_mfma_f32_16x16x32_bf16 v[122:125], v[166:169], v[190:193], v[122:125]
	v_mfma_f32_16x16x32_bf16 v[110:113], v[158:161], v[198:201], v[110:113]
	v_mfma_f32_16x16x32_bf16 v[106:109], v[166:169], v[198:201], v[106:109]
	v_mfma_f32_16x16x32_bf16 v[94:97], v[158:161], v[210:213], v[94:97]
	v_mfma_f32_16x16x32_bf16 v[90:93], v[166:169], v[210:213], v[90:93]
	v_mfma_f32_16x16x32_bf16 v[78:81], v[158:161], v[218:221], v[78:81]
	v_mfma_f32_16x16x32_bf16 v[74:77], v[166:169], v[218:221], v[74:77]
	v_mfma_f32_16x16x32_bf16 v[118:121], v[170:173], v[186:189], v[118:121]
	v_mfma_f32_16x16x32_bf16 v[114:117], v[178:181], v[186:189], v[114:117]
	v_mfma_f32_16x16x32_bf16 v[102:105], v[170:173], v[194:197], v[102:105]
	v_mfma_f32_16x16x32_bf16 v[98:101], v[178:181], v[194:197], v[98:101]
	v_mfma_f32_16x16x32_bf16 v[86:89], v[170:173], v[206:209], v[86:89]
	v_mfma_f32_16x16x32_bf16 v[82:85], v[178:181], v[206:209], v[82:85]
	v_mfma_f32_16x16x32_bf16 v[70:73], v[170:173], v[214:217], v[70:73]
	v_mfma_f32_16x16x32_bf16 v[66:69], v[178:181], v[214:217], v[66:69]
	v_mfma_f32_16x16x32_bf16 v[118:121], v[174:177], v[190:193], v[118:121]
	v_mfma_f32_16x16x32_bf16 v[114:117], v[182:185], v[190:193], v[114:117]
	v_mfma_f32_16x16x32_bf16 v[102:105], v[174:177], v[198:201], v[102:105]
	v_mfma_f32_16x16x32_bf16 v[98:101], v[182:185], v[198:201], v[98:101]
	v_mfma_f32_16x16x32_bf16 v[86:89], v[174:177], v[210:213], v[86:89]
	v_mfma_f32_16x16x32_bf16 v[82:85], v[182:185], v[210:213], v[82:85]
	v_mfma_f32_16x16x32_bf16 v[70:73], v[174:177], v[218:221], v[70:73]
	v_mfma_f32_16x16x32_bf16 v[66:69], v[182:185], v[218:221], v[66:69]
	s_setprio 0
	s_barrier
	ds_read_b128 v[186:189], v152 offset:49152
	ds_read_b128 v[190:193], v152 offset:50176
	ds_read_b128 v[194:197], v152 offset:51200
	ds_read_b128 v[198:201], v152 offset:52224
	ds_read_b128 v[206:209], v152 offset:53248
	ds_read_b128 v[210:213], v152 offset:54272
	ds_read_b128 v[214:217], v152 offset:55296
	ds_read_b128 v[218:221], v152 offset:56320
	global_load_lds_dwordx4 v[146:147], off
	s_add_i32 m0, s46, 0x2000
	s_add_u32 s44, s44, 0x40080
	v_lshl_add_u64 v[146:147], v[202:203], 0, s[10:11]
	s_addc_u32 s45, s45, 0
	s_add_i32 s46, s70, s16
	global_load_lds_dwordx4 v[146:147], off
	v_lshl_add_u64 v[146:147], s[44:45], 0, v[134:135]
	s_mov_b32 m0, s46
	s_nop 0
	global_load_lds_dwordx4 v[146:147], off
	v_lshl_add_u64 v[146:147], s[44:45], 0, v[130:131]
	s_add_i32 m0, s46, 0x2000
	s_nop 0
	global_load_lds_dwordx4 v[146:147], off
	v_lshl_add_u64 v[146:147], v[222:223], 0, s[10:11]
	s_mov_b32 m0, s33
	s_nop 0
	global_load_lds_dwordx4 v[146:147], off
	v_lshl_add_u64 v[146:147], v[224:225], 0, s[10:11]
	s_mov_b32 m0, s35
	s_nop 0
	global_load_lds_dwordx4 v[146:147], off
	s_waitcnt vmcnt(8)
	s_waitcnt lgkmcnt(0)
	s_setprio 1
	s_barrier
	v_mfma_f32_16x16x32_bf16 v[62:65], v[154:157], v[186:189], v[62:65]
	v_mfma_f32_16x16x32_bf16 v[58:61], v[162:165], v[186:189], v[58:61]
	s_add_i32 s68, s68, 2
	s_add_u32 s42, s42, 0x100
	s_addc_u32 s43, s43, 0
	s_add_u32 s66, s66, 0x100
	s_addc_u32 s67, s67, 0
	s_cmp_gt_u32 s68, 13
	v_mfma_f32_16x16x32_bf16 v[46:49], v[154:157], v[194:197], v[46:49]
	v_mfma_f32_16x16x32_bf16 v[42:45], v[162:165], v[194:197], v[42:45]
	v_mfma_f32_16x16x32_bf16 v[30:33], v[154:157], v[206:209], v[30:33]
	v_mfma_f32_16x16x32_bf16 v[26:29], v[162:165], v[206:209], v[26:29]
	v_mfma_f32_16x16x32_bf16 v[14:17], v[154:157], v[214:217], v[14:17]
	v_mfma_f32_16x16x32_bf16 v[10:13], v[162:165], v[214:217], v[10:13]
	v_mfma_f32_16x16x32_bf16 v[62:65], v[158:161], v[190:193], v[62:65]
	v_mfma_f32_16x16x32_bf16 v[58:61], v[166:169], v[190:193], v[58:61]
	v_mfma_f32_16x16x32_bf16 v[46:49], v[158:161], v[198:201], v[46:49]
	v_mfma_f32_16x16x32_bf16 v[42:45], v[166:169], v[198:201], v[42:45]
	v_mfma_f32_16x16x32_bf16 v[30:33], v[158:161], v[210:213], v[30:33]
	v_mfma_f32_16x16x32_bf16 v[26:29], v[166:169], v[210:213], v[26:29]
	v_mfma_f32_16x16x32_bf16 v[14:17], v[158:161], v[218:221], v[14:17]
	v_mfma_f32_16x16x32_bf16 v[10:13], v[166:169], v[218:221], v[10:13]
	v_mfma_f32_16x16x32_bf16 v[54:57], v[170:173], v[186:189], v[54:57]
	v_mfma_f32_16x16x32_bf16 v[50:53], v[178:181], v[186:189], v[50:53]
	v_mfma_f32_16x16x32_bf16 v[38:41], v[170:173], v[194:197], v[38:41]
	v_mfma_f32_16x16x32_bf16 v[34:37], v[178:181], v[194:197], v[34:37]
	v_mfma_f32_16x16x32_bf16 v[22:25], v[170:173], v[206:209], v[22:25]
	v_mfma_f32_16x16x32_bf16 v[18:21], v[178:181], v[206:209], v[18:21]
	v_mfma_f32_16x16x32_bf16 v[6:9], v[170:173], v[214:217], v[6:9]
	v_mfma_f32_16x16x32_bf16 v[2:5], v[178:181], v[214:217], v[2:5]
	v_mfma_f32_16x16x32_bf16 v[54:57], v[174:177], v[190:193], v[54:57]
	v_mfma_f32_16x16x32_bf16 v[50:53], v[182:185], v[190:193], v[50:53]
	v_mfma_f32_16x16x32_bf16 v[38:41], v[174:177], v[198:201], v[38:41]
	v_mfma_f32_16x16x32_bf16 v[34:37], v[182:185], v[198:201], v[34:37]
	v_mfma_f32_16x16x32_bf16 v[22:25], v[174:177], v[210:213], v[22:25]
	v_mfma_f32_16x16x32_bf16 v[18:21], v[182:185], v[210:213], v[18:21]
	v_mfma_f32_16x16x32_bf16 v[6:9], v[174:177], v[218:221], v[6:9]
	v_mfma_f32_16x16x32_bf16 v[2:5], v[182:185], v[218:221], v[2:5]
	s_setprio 0
	s_barrier
.LBB0_745:
	ds_read_b128 v[154:157], v150
	ds_read_b128 v[158:161], v150 offset:1024
	ds_read_b128 v[162:165], v150 offset:2048
	ds_read_b128 v[166:169], v150 offset:3072
	ds_read_b128 v[170:173], v151
	ds_read_b128 v[174:177], v151 offset:1024
	ds_read_b128 v[178:181], v151 offset:2048
	ds_read_b128 v[182:185], v151 offset:3072
	s_add_u32 s44, s42, 0xfffc0080
	s_addc_u32 s45, s43, -1
	s_cmp_eq_u32 s68, 12
	s_cselect_b32 s47, s14, s45
	s_cselect_b32 s46, s15, s44
	s_cselect_b32 s45, s21, s67
	s_cselect_b32 s44, s65, s66
	v_lshl_add_u64 v[146:147], s[42:43], 0, v[138:139]
	s_add_i32 m0, s19, 0xc000
	ds_read_b128 v[186:189], v152
	ds_read_b128 v[190:193], v152 offset:1024
	ds_read_b128 v[194:197], v152 offset:2048
	ds_read_b128 v[198:201], v152 offset:3072
	ds_read_b128 v[206:209], v152 offset:4096
	ds_read_b128 v[210:213], v152 offset:5120
	ds_read_b128 v[214:217], v152 offset:6144
	ds_read_b128 v[218:221], v152 offset:7168
	global_load_lds_dwordx4 v[146:147], off
	v_lshl_add_u64 v[146:147], s[42:43], 0, v[140:141]
	s_add_i32 m0, s19, 0xe000
	s_nop 0
	global_load_lds_dwordx4 v[146:147], off
	s_waitcnt vmcnt(8)
	s_waitcnt lgkmcnt(0)
	s_setprio 1
	s_barrier
	v_mfma_f32_16x16x32_bf16 v[126:129], v[154:157], v[186:189], v[126:129]
	v_mfma_f32_16x16x32_bf16 v[122:125], v[162:165], v[186:189], v[122:125]
	s_add_i32 s69, s49, s16
	v_lshl_add_u64 v[146:147], s[44:45], 0, v[134:135]
	s_mov_b32 m0, s69
	v_mfma_f32_16x16x32_bf16 v[110:113], v[154:157], v[194:197], v[110:113]
	v_mfma_f32_16x16x32_bf16 v[106:109], v[162:165], v[194:197], v[106:109]
	v_mfma_f32_16x16x32_bf16 v[94:97], v[154:157], v[206:209], v[94:97]
	v_mfma_f32_16x16x32_bf16 v[90:93], v[162:165], v[206:209], v[90:93]
	v_mfma_f32_16x16x32_bf16 v[78:81], v[154:157], v[214:217], v[78:81]
	v_mfma_f32_16x16x32_bf16 v[74:77], v[162:165], v[214:217], v[74:77]
	v_mfma_f32_16x16x32_bf16 v[126:129], v[158:161], v[190:193], v[126:129]
	v_mfma_f32_16x16x32_bf16 v[122:125], v[166:169], v[190:193], v[122:125]
	v_mfma_f32_16x16x32_bf16 v[110:113], v[158:161], v[198:201], v[110:113]
	v_mfma_f32_16x16x32_bf16 v[106:109], v[166:169], v[198:201], v[106:109]
	v_mfma_f32_16x16x32_bf16 v[94:97], v[158:161], v[210:213], v[94:97]
	v_mfma_f32_16x16x32_bf16 v[90:93], v[166:169], v[210:213], v[90:93]
	v_mfma_f32_16x16x32_bf16 v[78:81], v[158:161], v[218:221], v[78:81]
	v_mfma_f32_16x16x32_bf16 v[74:77], v[166:169], v[218:221], v[74:77]
	v_mfma_f32_16x16x32_bf16 v[118:121], v[170:173], v[186:189], v[118:121]
	v_mfma_f32_16x16x32_bf16 v[114:117], v[178:181], v[186:189], v[114:117]
	v_mfma_f32_16x16x32_bf16 v[102:105], v[170:173], v[194:197], v[102:105]
	v_mfma_f32_16x16x32_bf16 v[98:101], v[178:181], v[194:197], v[98:101]
	v_mfma_f32_16x16x32_bf16 v[86:89], v[170:173], v[206:209], v[86:89]
	v_mfma_f32_16x16x32_bf16 v[82:85], v[178:181], v[206:209], v[82:85]
	v_mfma_f32_16x16x32_bf16 v[70:73], v[170:173], v[214:217], v[70:73]
	v_mfma_f32_16x16x32_bf16 v[66:69], v[178:181], v[214:217], v[66:69]
	v_mfma_f32_16x16x32_bf16 v[118:121], v[174:177], v[190:193], v[118:121]
	v_mfma_f32_16x16x32_bf16 v[114:117], v[182:185], v[190:193], v[114:117]
	v_mfma_f32_16x16x32_bf16 v[102:105], v[174:177], v[198:201], v[102:105]
	v_mfma_f32_16x16x32_bf16 v[98:101], v[182:185], v[198:201], v[98:101]
	v_mfma_f32_16x16x32_bf16 v[86:89], v[174:177], v[210:213], v[86:89]
	v_mfma_f32_16x16x32_bf16 v[82:85], v[182:185], v[210:213], v[82:85]
	v_mfma_f32_16x16x32_bf16 v[70:73], v[174:177], v[218:221], v[70:73]
	v_mfma_f32_16x16x32_bf16 v[66:69], v[182:185], v[218:221], v[66:69]
	s_setprio 0
	s_barrier
	ds_read_b128 v[186:189], v152 offset:16384
	ds_read_b128 v[190:193], v152 offset:17408
	ds_read_b128 v[194:197], v152 offset:18432
	ds_read_b128 v[198:201], v152 offset:19456
	ds_read_b128 v[206:209], v152 offset:20480
	ds_read_b128 v[210:213], v152 offset:21504
	ds_read_b128 v[214:217], v152 offset:22528
	ds_read_b128 v[218:221], v152 offset:23552
	global_load_lds_dwordx4 v[146:147], off
	s_add_i32 m0, s69, 0x2000
	s_add_u32 s70, s44, 0x40000
	v_lshl_add_u64 v[202:203], s[44:45], 0, v[130:131]
	s_addc_u32 s71, s45, 0
	s_add_i32 s69, s62, s16
	global_load_lds_dwordx4 v[202:203], off
	v_lshl_add_u64 v[222:223], s[70:71], 0, v[134:135]
	s_mov_b32 m0, s69
	v_lshl_add_u64 v[224:225], s[46:47], 0, v[132:133]
	global_load_lds_dwordx4 v[222:223], off
	v_lshl_add_u64 v[222:223], s[70:71], 0, v[130:131]
	s_add_i32 m0, s69, 0x2000
	s_nop 0
	global_load_lds_dwordx4 v[222:223], off
	v_lshl_add_u64 v[222:223], s[46:47], 0, v[136:137]
	s_mov_b32 m0, s19
	s_nop 0
	global_load_lds_dwordx4 v[222:223], off
	s_mov_b32 m0, s24
	s_nop 0
	global_load_lds_dwordx4 v[224:225], off
	s_waitcnt vmcnt(8)
	s_waitcnt lgkmcnt(0)
	s_setprio 1
	s_barrier
	v_mfma_f32_16x16x32_bf16 v[62:65], v[154:157], v[186:189], v[62:65]
	v_mfma_f32_16x16x32_bf16 v[58:61], v[162:165], v[186:189], v[58:61]
	s_add_i32 s69, 0, 0x18000
	v_add_u32_e32 v153, s69, v149
	s_add_i32 s70, 0, 0x1c000
	v_mfma_f32_16x16x32_bf16 v[46:49], v[154:157], v[194:197], v[46:49]
	v_mfma_f32_16x16x32_bf16 v[42:45], v[162:165], v[194:197], v[42:45]
	v_mfma_f32_16x16x32_bf16 v[30:33], v[154:157], v[206:209], v[30:33]
	v_mfma_f32_16x16x32_bf16 v[26:29], v[162:165], v[206:209], v[26:29]
	v_mfma_f32_16x16x32_bf16 v[14:17], v[154:157], v[214:217], v[14:17]
	v_mfma_f32_16x16x32_bf16 v[10:13], v[162:165], v[214:217], v[10:13]
	v_mfma_f32_16x16x32_bf16 v[62:65], v[158:161], v[190:193], v[62:65]
	v_mfma_f32_16x16x32_bf16 v[58:61], v[166:169], v[190:193], v[58:61]
	v_mfma_f32_16x16x32_bf16 v[46:49], v[158:161], v[198:201], v[46:49]
	v_mfma_f32_16x16x32_bf16 v[42:45], v[166:169], v[198:201], v[42:45]
	v_mfma_f32_16x16x32_bf16 v[30:33], v[158:161], v[210:213], v[30:33]
	v_mfma_f32_16x16x32_bf16 v[26:29], v[166:169], v[210:213], v[26:29]
	v_mfma_f32_16x16x32_bf16 v[14:17], v[158:161], v[218:221], v[14:17]
	v_mfma_f32_16x16x32_bf16 v[10:13], v[166:169], v[218:221], v[10:13]
	v_mfma_f32_16x16x32_bf16 v[54:57], v[170:173], v[186:189], v[54:57]
	v_mfma_f32_16x16x32_bf16 v[50:53], v[178:181], v[186:189], v[50:53]
	v_mfma_f32_16x16x32_bf16 v[38:41], v[170:173], v[194:197], v[38:41]
	v_mfma_f32_16x16x32_bf16 v[34:37], v[178:181], v[194:197], v[34:37]
	v_mfma_f32_16x16x32_bf16 v[22:25], v[170:173], v[206:209], v[22:25]
	v_mfma_f32_16x16x32_bf16 v[18:21], v[178:181], v[206:209], v[18:21]
	v_mfma_f32_16x16x32_bf16 v[6:9], v[170:173], v[214:217], v[6:9]
	v_mfma_f32_16x16x32_bf16 v[2:5], v[178:181], v[214:217], v[2:5]
	v_mfma_f32_16x16x32_bf16 v[54:57], v[174:177], v[190:193], v[54:57]
	v_mfma_f32_16x16x32_bf16 v[50:53], v[182:185], v[190:193], v[50:53]
	v_mfma_f32_16x16x32_bf16 v[38:41], v[174:177], v[198:201], v[38:41]
	v_mfma_f32_16x16x32_bf16 v[34:37], v[182:185], v[198:201], v[34:37]
	v_mfma_f32_16x16x32_bf16 v[22:25], v[174:177], v[210:213], v[22:25]
	v_mfma_f32_16x16x32_bf16 v[18:21], v[182:185], v[210:213], v[18:21]
	v_mfma_f32_16x16x32_bf16 v[6:9], v[174:177], v[218:221], v[6:9]
	v_mfma_f32_16x16x32_bf16 v[2:5], v[182:185], v[218:221], v[2:5]
	s_setprio 0
	s_barrier
	ds_read_b128 v[154:157], v153
	ds_read_b128 v[158:161], v153 offset:1024
	ds_read_b128 v[162:165], v153 offset:2048
	ds_read_b128 v[166:169], v153 offset:3072
	v_add_u32_e32 v153, s70, v149
	ds_read_b128 v[170:173], v153
	ds_read_b128 v[174:177], v153 offset:1024
	ds_read_b128 v[178:181], v153 offset:2048
	ds_read_b128 v[182:185], v153 offset:3072
	s_add_u32 s46, s46, 0x40000
	s_addc_u32 s47, s47, 0
	s_mov_b32 m0, s25
	v_lshl_add_u64 v[226:227], s[46:47], 0, v[136:137]
	ds_read_b128 v[186:189], v152 offset:32768
	ds_read_b128 v[190:193], v152 offset:33792
	ds_read_b128 v[194:197], v152 offset:34816
	ds_read_b128 v[198:201], v152 offset:35840
	ds_read_b128 v[206:209], v152 offset:36864
	ds_read_b128 v[210:213], v152 offset:37888
	ds_read_b128 v[214:217], v152 offset:38912
	ds_read_b128 v[218:221], v152 offset:39936
	global_load_lds_dwordx4 v[226:227], off
	v_lshl_add_u64 v[226:227], s[46:47], 0, v[132:133]
	s_mov_b32 m0, s28
	s_nop 0
	global_load_lds_dwordx4 v[226:227], off
	s_waitcnt vmcnt(8)
	s_waitcnt lgkmcnt(0)
	s_setprio 1
	s_barrier
	v_mfma_f32_16x16x32_bf16 v[126:129], v[154:157], v[186:189], v[126:129]
	v_mfma_f32_16x16x32_bf16 v[122:125], v[162:165], v[186:189], v[122:125]
	s_add_i32 s46, s69, s16
	v_lshl_add_u64 v[146:147], v[146:147], 0, s[10:11]
	s_mov_b32 m0, s46
	v_mfma_f32_16x16x32_bf16 v[110:113], v[154:157], v[194:197], v[110:113]
	v_mfma_f32_16x16x32_bf16 v[106:109], v[162:165], v[194:197], v[106:109]
	v_mfma_f32_16x16x32_bf16 v[94:97], v[154:157], v[206:209], v[94:97]
	v_mfma_f32_16x16x32_bf16 v[90:93], v[162:165], v[206:209], v[90:93]
	v_mfma_f32_16x16x32_bf16 v[78:81], v[154:157], v[214:217], v[78:81]
	v_mfma_f32_16x16x32_bf16 v[74:77], v[162:165], v[214:217], v[74:77]
	v_mfma_f32_16x16x32_bf16 v[126:129], v[158:161], v[190:193], v[126:129]
	v_mfma_f32_16x16x32_bf16 v[122:125], v[166:169], v[190:193], v[122:125]
	v_mfma_f32_16x16x32_bf16 v[110:113], v[158:161], v[198:201], v[110:113]
	v_mfma_f32_16x16x32_bf16 v[106:109], v[166:169], v[198:201], v[106:109]
	v_mfma_f32_16x16x32_bf16 v[94:97], v[158:161], v[210:213], v[94:97]
	v_mfma_f32_16x16x32_bf16 v[90:93], v[166:169], v[210:213], v[90:93]
	v_mfma_f32_16x16x32_bf16 v[78:81], v[158:161], v[218:221], v[78:81]
	v_mfma_f32_16x16x32_bf16 v[74:77], v[166:169], v[218:221], v[74:77]
	v_mfma_f32_16x16x32_bf16 v[118:121], v[170:173], v[186:189], v[118:121]
	v_mfma_f32_16x16x32_bf16 v[114:117], v[178:181], v[186:189], v[114:117]
	v_mfma_f32_16x16x32_bf16 v[102:105], v[170:173], v[194:197], v[102:105]
	v_mfma_f32_16x16x32_bf16 v[98:101], v[178:181], v[194:197], v[98:101]
	v_mfma_f32_16x16x32_bf16 v[86:89], v[170:173], v[206:209], v[86:89]
	v_mfma_f32_16x16x32_bf16 v[82:85], v[178:181], v[206:209], v[82:85]
	v_mfma_f32_16x16x32_bf16 v[70:73], v[170:173], v[214:217], v[70:73]
	v_mfma_f32_16x16x32_bf16 v[66:69], v[178:181], v[214:217], v[66:69]
	v_mfma_f32_16x16x32_bf16 v[118:121], v[174:177], v[190:193], v[118:121]
	v_mfma_f32_16x16x32_bf16 v[114:117], v[182:185], v[190:193], v[114:117]
	v_mfma_f32_16x16x32_bf16 v[102:105], v[174:177], v[198:201], v[102:105]
	v_mfma_f32_16x16x32_bf16 v[98:101], v[182:185], v[198:201], v[98:101]
	v_mfma_f32_16x16x32_bf16 v[86:89], v[174:177], v[210:213], v[86:89]
	v_mfma_f32_16x16x32_bf16 v[82:85], v[182:185], v[210:213], v[82:85]
	v_mfma_f32_16x16x32_bf16 v[70:73], v[174:177], v[218:221], v[70:73]
	v_mfma_f32_16x16x32_bf16 v[66:69], v[182:185], v[218:221], v[66:69]
	s_setprio 0
	s_barrier
	ds_read_b128 v[186:189], v152 offset:49152
	ds_read_b128 v[190:193], v152 offset:50176
	ds_read_b128 v[194:197], v152 offset:51200
	ds_read_b128 v[198:201], v152 offset:52224
	ds_read_b128 v[206:209], v152 offset:53248
	ds_read_b128 v[210:213], v152 offset:54272
	ds_read_b128 v[214:217], v152 offset:55296
	ds_read_b128 v[218:221], v152 offset:56320
	global_load_lds_dwordx4 v[146:147], off
	s_add_i32 m0, s46, 0x2000
	s_add_u32 s44, s44, 0x40080
	v_lshl_add_u64 v[146:147], v[202:203], 0, s[10:11]
	s_addc_u32 s45, s45, 0
	s_add_i32 s46, s70, s16
	global_load_lds_dwordx4 v[146:147], off
	v_lshl_add_u64 v[146:147], s[44:45], 0, v[134:135]
	s_mov_b32 m0, s46
	s_nop 0
	global_load_lds_dwordx4 v[146:147], off
	v_lshl_add_u64 v[146:147], s[44:45], 0, v[130:131]
	s_add_i32 m0, s46, 0x2000
	s_nop 0
	global_load_lds_dwordx4 v[146:147], off
	v_lshl_add_u64 v[146:147], v[222:223], 0, s[10:11]
	s_mov_b32 m0, s33
	s_nop 0
	global_load_lds_dwordx4 v[146:147], off
	v_lshl_add_u64 v[146:147], v[224:225], 0, s[10:11]
	s_mov_b32 m0, s35
	s_nop 0
	global_load_lds_dwordx4 v[146:147], off
	s_waitcnt vmcnt(8)
	s_waitcnt lgkmcnt(0)
	s_setprio 1
	s_barrier
	v_mfma_f32_16x16x32_bf16 v[62:65], v[154:157], v[186:189], v[62:65]
	v_mfma_f32_16x16x32_bf16 v[58:61], v[162:165], v[186:189], v[58:61]
	s_add_i32 s68, s68, 2
	s_add_u32 s42, s42, 0x100
	s_addc_u32 s43, s43, 0
	s_add_u32 s66, s66, 0x100
	s_addc_u32 s67, s67, 0
	s_cmp_gt_u32 s68, 13
	v_mfma_f32_16x16x32_bf16 v[46:49], v[154:157], v[194:197], v[46:49]
	v_mfma_f32_16x16x32_bf16 v[42:45], v[162:165], v[194:197], v[42:45]
	v_mfma_f32_16x16x32_bf16 v[30:33], v[154:157], v[206:209], v[30:33]
	v_mfma_f32_16x16x32_bf16 v[26:29], v[162:165], v[206:209], v[26:29]
	v_mfma_f32_16x16x32_bf16 v[14:17], v[154:157], v[214:217], v[14:17]
	v_mfma_f32_16x16x32_bf16 v[10:13], v[162:165], v[214:217], v[10:13]
	v_mfma_f32_16x16x32_bf16 v[62:65], v[158:161], v[190:193], v[62:65]
	v_mfma_f32_16x16x32_bf16 v[58:61], v[166:169], v[190:193], v[58:61]
	v_mfma_f32_16x16x32_bf16 v[46:49], v[158:161], v[198:201], v[46:49]
	v_mfma_f32_16x16x32_bf16 v[42:45], v[166:169], v[198:201], v[42:45]
	v_mfma_f32_16x16x32_bf16 v[30:33], v[158:161], v[210:213], v[30:33]
	v_mfma_f32_16x16x32_bf16 v[26:29], v[166:169], v[210:213], v[26:29]
	v_mfma_f32_16x16x32_bf16 v[14:17], v[158:161], v[218:221], v[14:17]
	v_mfma_f32_16x16x32_bf16 v[10:13], v[166:169], v[218:221], v[10:13]
	v_mfma_f32_16x16x32_bf16 v[54:57], v[170:173], v[186:189], v[54:57]
	v_mfma_f32_16x16x32_bf16 v[50:53], v[178:181], v[186:189], v[50:53]
	v_mfma_f32_16x16x32_bf16 v[38:41], v[170:173], v[194:197], v[38:41]
	v_mfma_f32_16x16x32_bf16 v[34:37], v[178:181], v[194:197], v[34:37]
	v_mfma_f32_16x16x32_bf16 v[22:25], v[170:173], v[206:209], v[22:25]
	v_mfma_f32_16x16x32_bf16 v[18:21], v[178:181], v[206:209], v[18:21]
	v_mfma_f32_16x16x32_bf16 v[6:9], v[170:173], v[214:217], v[6:9]
	v_mfma_f32_16x16x32_bf16 v[2:5], v[178:181], v[214:217], v[2:5]
	v_mfma_f32_16x16x32_bf16 v[54:57], v[174:177], v[190:193], v[54:57]
	v_mfma_f32_16x16x32_bf16 v[50:53], v[182:185], v[190:193], v[50:53]
	v_mfma_f32_16x16x32_bf16 v[38:41], v[174:177], v[198:201], v[38:41]
	v_mfma_f32_16x16x32_bf16 v[34:37], v[182:185], v[198:201], v[34:37]
	v_mfma_f32_16x16x32_bf16 v[22:25], v[174:177], v[210:213], v[22:25]
	v_mfma_f32_16x16x32_bf16 v[18:21], v[182:185], v[210:213], v[18:21]
	v_mfma_f32_16x16x32_bf16 v[6:9], v[174:177], v[218:221], v[6:9]
	v_mfma_f32_16x16x32_bf16 v[2:5], v[182:185], v[218:221], v[2:5]
	s_setprio 0
	s_barrier
	s_cbranch_scc0 .LBB0_745
	s_and_b64 vcc, exec, s[12:13]
	s_cbranch_vccz .LBB0_748
	s_barrier

.LBB0_833:
	s_add_u32 s72, s0, s68
	s_addc_u32 s73, s1, s69
	s_and_b64 s[62:63], s[70:71], exec
	s_cselect_b32 s15, s73, s77
	s_cselect_b32 s33, s72, s76
	s_add_u32 s74, s35, s66
	s_addc_u32 s75, s85, s67
	s_and_b64 s[62:63], s[70:71], exec
	s_cselect_b32 s34, s75, s79
	s_cselect_b32 s39, s74, s78
	s_add_i32 s45, s7, -2
	s_add_u32 s76, s76, 0x100080
	s_addc_u32 s77, s77, 0
	s_add_u32 s47, s78, 0x100
	s_addc_u32 s62, s79, 0
	s_mov_b32 s63, 0
	s_waitcnt vmcnt(0)
	ds_read_b128 v[114:117], v190
	ds_read_b128 v[118:121], v190 offset:1024
	ds_read_b128 v[122:125], v190 offset:2048
	ds_read_b128 v[126:129], v190 offset:3072
	ds_read_b128 v[146:149], v191
	ds_read_b128 v[150:153], v191 offset:1024
	ds_read_b128 v[154:157], v191 offset:2048
	ds_read_b128 v[158:161], v191 offset:3072
	s_add_i32 s82, s63, 2
	s_add_u32 s78, s76, 0xfff00080
	s_addc_u32 s79, s77, -1
	s_cmp_eq_u32 s45, s63
	s_cselect_b32 s81, s15, s79
	s_cselect_b32 s80, s33, s78
	s_cselect_b32 s79, s34, s62
	s_cselect_b32 s78, s39, s47
	v_lshl_add_u64 v[186:187], s[76:77], 0, v[180:181]
	s_add_i32 m0, s87, 0xc000
	ds_read_b128 v[162:165], v192
	ds_read_b128 v[166:169], v192 offset:1024
	ds_read_b128 v[194:197], v192 offset:2048
	ds_read_b128 v[198:201], v192 offset:3072
	ds_read_b128 v[206:209], v192 offset:4096
	ds_read_b128 v[210:213], v192 offset:5120
	ds_read_b128 v[214:217], v192 offset:6144
	ds_read_b128 v[218:221], v192 offset:7168
	global_load_lds_dwordx4 v[186:187], off
	v_lshl_add_u64 v[186:187], s[76:77], 0, v[182:183]
	s_add_i32 m0, s87, 0xe000
	s_nop 0
	global_load_lds_dwordx4 v[186:187], off
	s_waitcnt vmcnt(8)
	s_waitcnt lgkmcnt(0)
	s_setprio 1
	s_barrier
	v_mfma_f32_16x16x32_bf16 v[142:145], v[114:117], v[162:165], 0
	v_mfma_f32_16x16x32_bf16 v[138:141], v[122:125], v[162:165], 0
	s_add_i32 s63, s24, s86
	v_lshl_add_u64 v[186:187], s[78:79], 0, v[172:173]
	s_mov_b32 m0, s63
	v_mfma_f32_16x16x32_bf16 v[110:113], v[114:117], v[194:197], 0
	v_mfma_f32_16x16x32_bf16 v[106:109], v[122:125], v[194:197], 0
	v_mfma_f32_16x16x32_bf16 v[98:101], v[114:117], v[206:209], 0
	v_mfma_f32_16x16x32_bf16 v[90:93], v[122:125], v[206:209], 0
	v_mfma_f32_16x16x32_bf16 v[82:85], v[114:117], v[214:217], 0
	v_mfma_f32_16x16x32_bf16 v[74:77], v[122:125], v[214:217], 0
	v_mfma_f32_16x16x32_bf16 v[142:145], v[118:121], v[166:169], v[142:145]
	v_mfma_f32_16x16x32_bf16 v[138:141], v[126:129], v[166:169], v[138:141]
	v_mfma_f32_16x16x32_bf16 v[110:113], v[118:121], v[198:201], v[110:113]
	v_mfma_f32_16x16x32_bf16 v[106:109], v[126:129], v[198:201], v[106:109]
	v_mfma_f32_16x16x32_bf16 v[98:101], v[118:121], v[210:213], v[98:101]
	v_mfma_f32_16x16x32_bf16 v[90:93], v[126:129], v[210:213], v[90:93]
	v_mfma_f32_16x16x32_bf16 v[82:85], v[118:121], v[218:221], v[82:85]
	v_mfma_f32_16x16x32_bf16 v[74:77], v[126:129], v[218:221], v[74:77]
	v_mfma_f32_16x16x32_bf16 v[134:137], v[146:149], v[162:165], 0
	v_mfma_f32_16x16x32_bf16 v[130:133], v[154:157], v[162:165], 0
	v_mfma_f32_16x16x32_bf16 v[102:105], v[146:149], v[194:197], 0
	v_mfma_f32_16x16x32_bf16 v[94:97], v[154:157], v[194:197], 0
	v_mfma_f32_16x16x32_bf16 v[86:89], v[146:149], v[206:209], 0
	v_mfma_f32_16x16x32_bf16 v[78:81], v[154:157], v[206:209], 0
	v_mfma_f32_16x16x32_bf16 v[70:73], v[146:149], v[214:217], 0
	v_mfma_f32_16x16x32_bf16 v[66:69], v[154:157], v[214:217], 0
	v_mfma_f32_16x16x32_bf16 v[134:137], v[150:153], v[166:169], v[134:137]
	v_mfma_f32_16x16x32_bf16 v[130:133], v[158:161], v[166:169], v[130:133]
	v_mfma_f32_16x16x32_bf16 v[102:105], v[150:153], v[198:201], v[102:105]
	v_mfma_f32_16x16x32_bf16 v[94:97], v[158:161], v[198:201], v[94:97]
	v_mfma_f32_16x16x32_bf16 v[86:89], v[150:153], v[210:213], v[86:89]
	v_mfma_f32_16x16x32_bf16 v[78:81], v[158:161], v[210:213], v[78:81]
	v_mfma_f32_16x16x32_bf16 v[70:73], v[150:153], v[218:221], v[70:73]
	v_mfma_f32_16x16x32_bf16 v[66:69], v[158:161], v[218:221], v[66:69]
	s_setprio 0
	s_barrier
	ds_read_b128 v[162:165], v192 offset:16384
	ds_read_b128 v[166:169], v192 offset:17408
	ds_read_b128 v[194:197], v192 offset:18432
	ds_read_b128 v[198:201], v192 offset:19456
	ds_read_b128 v[206:209], v192 offset:20480
	ds_read_b128 v[210:213], v192 offset:21504
	ds_read_b128 v[214:217], v192 offset:22528
	ds_read_b128 v[218:221], v192 offset:23552
	global_load_lds_dwordx4 v[186:187], off
	s_add_i32 m0, s63, 0x2000
	s_add_u32 vcc_lo, s78, 0x100000
	v_lshl_add_u64 v[202:203], s[78:79], 0, v[176:177]
	s_addc_u32 vcc_hi, s79, 0
	s_add_i32 s63, s25, s86
	global_load_lds_dwordx4 v[202:203], off
	v_lshl_add_u64 v[222:223], vcc, 0, v[172:173]
	s_mov_b32 m0, s63
	v_lshl_add_u64 v[224:225], s[80:81], 0, v[174:175]
	global_load_lds_dwordx4 v[222:223], off
	v_lshl_add_u64 v[222:223], vcc, 0, v[176:177]
	s_add_i32 m0, s63, 0x2000
	s_nop 0
	global_load_lds_dwordx4 v[222:223], off
	v_lshl_add_u64 v[222:223], s[80:81], 0, v[170:171]
	s_mov_b32 m0, s87
	s_nop 0
	global_load_lds_dwordx4 v[222:223], off
	s_mov_b32 m0, s88
	s_nop 0
	global_load_lds_dwordx4 v[224:225], off
	s_waitcnt vmcnt(8)
	s_waitcnt lgkmcnt(0)
	s_setprio 1
	s_barrier
	v_mfma_f32_16x16x32_bf16 v[62:65], v[114:117], v[162:165], 0
	v_mfma_f32_16x16x32_bf16 v[58:61], v[122:125], v[162:165], 0
	v_mfma_f32_16x16x32_bf16 v[50:53], v[114:117], v[194:197], 0
	v_mfma_f32_16x16x32_bf16 v[42:45], v[122:125], v[194:197], 0
	v_mfma_f32_16x16x32_bf16 v[34:37], v[114:117], v[206:209], 0
	v_mfma_f32_16x16x32_bf16 v[26:29], v[122:125], v[206:209], 0
	v_mfma_f32_16x16x32_bf16 v[18:21], v[114:117], v[214:217], 0
	v_mfma_f32_16x16x32_bf16 v[10:13], v[122:125], v[214:217], 0
	v_mfma_f32_16x16x32_bf16 v[62:65], v[118:121], v[166:169], v[62:65]
	v_mfma_f32_16x16x32_bf16 v[58:61], v[126:129], v[166:169], v[58:61]
	v_mfma_f32_16x16x32_bf16 v[50:53], v[118:121], v[198:201], v[50:53]
	v_mfma_f32_16x16x32_bf16 v[42:45], v[126:129], v[198:201], v[42:45]
	v_mfma_f32_16x16x32_bf16 v[34:37], v[118:121], v[210:213], v[34:37]
	v_mfma_f32_16x16x32_bf16 v[26:29], v[126:129], v[210:213], v[26:29]
	v_mfma_f32_16x16x32_bf16 v[18:21], v[118:121], v[218:221], v[18:21]
	v_mfma_f32_16x16x32_bf16 v[10:13], v[126:129], v[218:221], v[10:13]
	v_mfma_f32_16x16x32_bf16 v[54:57], v[146:149], v[162:165], 0
	v_mfma_f32_16x16x32_bf16 v[46:49], v[154:157], v[162:165], 0
	v_mfma_f32_16x16x32_bf16 v[38:41], v[146:149], v[194:197], 0
	v_mfma_f32_16x16x32_bf16 v[30:33], v[154:157], v[194:197], 0
	v_mfma_f32_16x16x32_bf16 v[22:25], v[146:149], v[206:209], 0
	v_mfma_f32_16x16x32_bf16 v[14:17], v[154:157], v[206:209], 0
	v_mfma_f32_16x16x32_bf16 v[6:9], v[146:149], v[214:217], 0
	v_mfma_f32_16x16x32_bf16 v[2:5], v[154:157], v[214:217], 0
	v_mfma_f32_16x16x32_bf16 v[54:57], v[150:153], v[166:169], v[54:57]
	v_mfma_f32_16x16x32_bf16 v[46:49], v[158:161], v[166:169], v[46:49]
	v_mfma_f32_16x16x32_bf16 v[38:41], v[150:153], v[198:201], v[38:41]
	v_mfma_f32_16x16x32_bf16 v[30:33], v[158:161], v[198:201], v[30:33]
	v_mfma_f32_16x16x32_bf16 v[22:25], v[150:153], v[210:213], v[22:25]
	v_mfma_f32_16x16x32_bf16 v[14:17], v[158:161], v[210:213], v[14:17]
	v_mfma_f32_16x16x32_bf16 v[6:9], v[150:153], v[218:221], v[6:9]
	v_mfma_f32_16x16x32_bf16 v[2:5], v[158:161], v[218:221], v[2:5]
	s_setprio 0
	s_barrier
	s_add_i32 s63, 0, 0x18000
	s_add_i32 s83, 0, 0x1c000
	v_add_u32_e32 v126, s63, v189
	v_add_u32_e32 v158, s83, v189
	ds_read_b128 v[114:117], v126
	ds_read_b128 v[118:121], v126 offset:1024
	ds_read_b128 v[122:125], v126 offset:2048
	ds_read_b128 v[126:129], v126 offset:3072
	ds_read_b128 v[146:149], v158
	ds_read_b128 v[150:153], v158 offset:1024
	ds_read_b128 v[154:157], v158 offset:2048
	ds_read_b128 v[158:161], v158 offset:3072
	s_add_u32 s80, s80, 0x100000
	s_addc_u32 s81, s81, 0
	s_mov_b32 m0, s89
	v_lshl_add_u64 v[226:227], s[80:81], 0, v[170:171]
	ds_read_b128 v[162:165], v192 offset:32768
	ds_read_b128 v[166:169], v192 offset:33792
	ds_read_b128 v[194:197], v192 offset:34816
	ds_read_b128 v[198:201], v192 offset:35840
	ds_read_b128 v[206:209], v192 offset:36864
	ds_read_b128 v[210:213], v192 offset:37888
	ds_read_b128 v[214:217], v192 offset:38912
	ds_read_b128 v[218:221], v192 offset:39936
	global_load_lds_dwordx4 v[226:227], off
	v_lshl_add_u64 v[226:227], s[80:81], 0, v[174:175]
	s_mov_b32 m0, s90
	s_nop 0
	global_load_lds_dwordx4 v[226:227], off
	s_waitcnt vmcnt(8)
	s_waitcnt lgkmcnt(0)
	s_setprio 1
	s_barrier
	v_mfma_f32_16x16x32_bf16 v[142:145], v[114:117], v[162:165], v[142:145]
	v_mfma_f32_16x16x32_bf16 v[138:141], v[122:125], v[162:165], v[138:141]
	s_add_i32 s63, s63, s86
	v_lshl_add_u64 v[186:187], v[186:187], 0, s[22:23]
	s_mov_b32 m0, s63
	v_mfma_f32_16x16x32_bf16 v[110:113], v[114:117], v[194:197], v[110:113]
	v_mfma_f32_16x16x32_bf16 v[106:109], v[122:125], v[194:197], v[106:109]
	v_mfma_f32_16x16x32_bf16 v[98:101], v[114:117], v[206:209], v[98:101]
	v_mfma_f32_16x16x32_bf16 v[90:93], v[122:125], v[206:209], v[90:93]
	v_mfma_f32_16x16x32_bf16 v[82:85], v[114:117], v[214:217], v[82:85]
	v_mfma_f32_16x16x32_bf16 v[74:77], v[122:125], v[214:217], v[74:77]
	v_mfma_f32_16x16x32_bf16 v[142:145], v[118:121], v[166:169], v[142:145]
	v_mfma_f32_16x16x32_bf16 v[138:141], v[126:129], v[166:169], v[138:141]
	v_mfma_f32_16x16x32_bf16 v[110:113], v[118:121], v[198:201], v[110:113]
	v_mfma_f32_16x16x32_bf16 v[106:109], v[126:129], v[198:201], v[106:109]
	v_mfma_f32_16x16x32_bf16 v[98:101], v[118:121], v[210:213], v[98:101]
	v_mfma_f32_16x16x32_bf16 v[90:93], v[126:129], v[210:213], v[90:93]
	v_mfma_f32_16x16x32_bf16 v[82:85], v[118:121], v[218:221], v[82:85]
	v_mfma_f32_16x16x32_bf16 v[74:77], v[126:129], v[218:221], v[74:77]
	v_mfma_f32_16x16x32_bf16 v[134:137], v[146:149], v[162:165], v[134:137]
	v_mfma_f32_16x16x32_bf16 v[130:133], v[154:157], v[162:165], v[130:133]
	v_mfma_f32_16x16x32_bf16 v[102:105], v[146:149], v[194:197], v[102:105]
	v_mfma_f32_16x16x32_bf16 v[94:97], v[154:157], v[194:197], v[94:97]
	v_mfma_f32_16x16x32_bf16 v[86:89], v[146:149], v[206:209], v[86:89]
	v_mfma_f32_16x16x32_bf16 v[78:81], v[154:157], v[206:209], v[78:81]
	v_mfma_f32_16x16x32_bf16 v[70:73], v[146:149], v[214:217], v[70:73]
	v_mfma_f32_16x16x32_bf16 v[66:69], v[154:157], v[214:217], v[66:69]
	v_mfma_f32_16x16x32_bf16 v[134:137], v[150:153], v[166:169], v[134:137]
	v_mfma_f32_16x16x32_bf16 v[130:133], v[158:161], v[166:169], v[130:133]
	v_mfma_f32_16x16x32_bf16 v[102:105], v[150:153], v[198:201], v[102:105]
	v_mfma_f32_16x16x32_bf16 v[94:97], v[158:161], v[198:201], v[94:97]
	v_mfma_f32_16x16x32_bf16 v[86:89], v[150:153], v[210:213], v[86:89]
	v_mfma_f32_16x16x32_bf16 v[78:81], v[158:161], v[210:213], v[78:81]
	v_mfma_f32_16x16x32_bf16 v[70:73], v[150:153], v[218:221], v[70:73]
	v_mfma_f32_16x16x32_bf16 v[66:69], v[158:161], v[218:221], v[66:69]
	s_setprio 0
	s_barrier
	ds_read_b128 v[162:165], v192 offset:49152
	ds_read_b128 v[166:169], v192 offset:50176
	ds_read_b128 v[194:197], v192 offset:51200
	ds_read_b128 v[198:201], v192 offset:52224
	ds_read_b128 v[206:209], v192 offset:53248
	ds_read_b128 v[210:213], v192 offset:54272
	ds_read_b128 v[214:217], v192 offset:55296
	ds_read_b128 v[218:221], v192 offset:56320
	global_load_lds_dwordx4 v[186:187], off
	s_add_i32 m0, s63, 0x2000
	s_add_u32 s78, s78, 0x100080
	v_lshl_add_u64 v[186:187], v[202:203], 0, s[22:23]
	s_addc_u32 s79, s79, 0
	s_add_i32 s63, s83, s86
	global_load_lds_dwordx4 v[186:187], off
	v_lshl_add_u64 v[186:187], s[78:79], 0, v[172:173]
	s_mov_b32 m0, s63
	s_nop 0
	global_load_lds_dwordx4 v[186:187], off
	v_lshl_add_u64 v[186:187], s[78:79], 0, v[176:177]
	s_add_i32 m0, s63, 0x2000
	s_nop 0
	global_load_lds_dwordx4 v[186:187], off
	v_lshl_add_u64 v[186:187], v[222:223], 0, s[22:23]
	s_mov_b32 m0, s95
	s_nop 0
	global_load_lds_dwordx4 v[186:187], off
	v_lshl_add_u64 v[186:187], v[224:225], 0, s[22:23]
	s_mov_b32 m0, s96
	s_nop 0
	global_load_lds_dwordx4 v[186:187], off
	s_waitcnt vmcnt(8)
	s_waitcnt lgkmcnt(0)
	s_setprio 1
	s_barrier
	v_mfma_f32_16x16x32_bf16 v[62:65], v[114:117], v[162:165], v[62:65]
	v_mfma_f32_16x16x32_bf16 v[58:61], v[122:125], v[162:165], v[58:61]
	s_add_u32 s76, s76, 0x100
	s_addc_u32 s77, s77, 0
	s_add_u32 s47, s47, 0x100
	s_addc_u32 s62, s62, 0
	s_cmp_ge_i32 s82, s7
	s_mov_b32 s63, s82
	v_mfma_f32_16x16x32_bf16 v[50:53], v[114:117], v[194:197], v[50:53]
	v_mfma_f32_16x16x32_bf16 v[42:45], v[122:125], v[194:197], v[42:45]
	v_mfma_f32_16x16x32_bf16 v[34:37], v[114:117], v[206:209], v[34:37]
	v_mfma_f32_16x16x32_bf16 v[26:29], v[122:125], v[206:209], v[26:29]
	v_mfma_f32_16x16x32_bf16 v[18:21], v[114:117], v[214:217], v[18:21]
	v_mfma_f32_16x16x32_bf16 v[10:13], v[122:125], v[214:217], v[10:13]
	v_mfma_f32_16x16x32_bf16 v[62:65], v[118:121], v[166:169], v[62:65]
	v_mfma_f32_16x16x32_bf16 v[58:61], v[126:129], v[166:169], v[58:61]
	v_mfma_f32_16x16x32_bf16 v[50:53], v[118:121], v[198:201], v[50:53]
	v_mfma_f32_16x16x32_bf16 v[42:45], v[126:129], v[198:201], v[42:45]
	v_mfma_f32_16x16x32_bf16 v[34:37], v[118:121], v[210:213], v[34:37]
	v_mfma_f32_16x16x32_bf16 v[26:29], v[126:129], v[210:213], v[26:29]
	v_mfma_f32_16x16x32_bf16 v[18:21], v[118:121], v[218:221], v[18:21]
	v_mfma_f32_16x16x32_bf16 v[10:13], v[126:129], v[218:221], v[10:13]
	v_mfma_f32_16x16x32_bf16 v[54:57], v[146:149], v[162:165], v[54:57]
	v_mfma_f32_16x16x32_bf16 v[46:49], v[154:157], v[162:165], v[46:49]
	v_mfma_f32_16x16x32_bf16 v[38:41], v[146:149], v[194:197], v[38:41]
	v_mfma_f32_16x16x32_bf16 v[30:33], v[154:157], v[194:197], v[30:33]
	v_mfma_f32_16x16x32_bf16 v[22:25], v[146:149], v[206:209], v[22:25]
	v_mfma_f32_16x16x32_bf16 v[14:17], v[154:157], v[206:209], v[14:17]
	v_mfma_f32_16x16x32_bf16 v[6:9], v[146:149], v[214:217], v[6:9]
	v_mfma_f32_16x16x32_bf16 v[2:5], v[154:157], v[214:217], v[2:5]
	v_mfma_f32_16x16x32_bf16 v[54:57], v[150:153], v[166:169], v[54:57]
	v_mfma_f32_16x16x32_bf16 v[46:49], v[158:161], v[166:169], v[46:49]
	v_mfma_f32_16x16x32_bf16 v[38:41], v[150:153], v[198:201], v[38:41]
	v_mfma_f32_16x16x32_bf16 v[30:33], v[158:161], v[198:201], v[30:33]
	v_mfma_f32_16x16x32_bf16 v[22:25], v[150:153], v[210:213], v[22:25]
	v_mfma_f32_16x16x32_bf16 v[14:17], v[158:161], v[210:213], v[14:17]
	v_mfma_f32_16x16x32_bf16 v[6:9], v[150:153], v[218:221], v[6:9]
	v_mfma_f32_16x16x32_bf16 v[2:5], v[158:161], v[218:221], v[2:5]
	s_setprio 0
	s_barrier
.LBB0_834:
	ds_read_b128 v[114:117], v190
	ds_read_b128 v[118:121], v190 offset:1024
	ds_read_b128 v[122:125], v190 offset:2048
	ds_read_b128 v[126:129], v190 offset:3072
	ds_read_b128 v[146:149], v191
	ds_read_b128 v[150:153], v191 offset:1024
	ds_read_b128 v[154:157], v191 offset:2048
	ds_read_b128 v[158:161], v191 offset:3072
	s_add_i32 s82, s63, 2
	s_add_u32 s78, s76, 0xfff00080
	s_addc_u32 s79, s77, -1
	s_cmp_eq_u32 s45, s63
	s_cselect_b32 s81, s15, s79
	s_cselect_b32 s80, s33, s78
	s_cselect_b32 s79, s34, s62
	s_cselect_b32 s78, s39, s47
	v_lshl_add_u64 v[186:187], s[76:77], 0, v[180:181]
	s_add_i32 m0, s87, 0xc000
	ds_read_b128 v[162:165], v192
	ds_read_b128 v[166:169], v192 offset:1024
	ds_read_b128 v[194:197], v192 offset:2048
	ds_read_b128 v[198:201], v192 offset:3072
	ds_read_b128 v[206:209], v192 offset:4096
	ds_read_b128 v[210:213], v192 offset:5120
	ds_read_b128 v[214:217], v192 offset:6144
	ds_read_b128 v[218:221], v192 offset:7168
	global_load_lds_dwordx4 v[186:187], off
	v_lshl_add_u64 v[186:187], s[76:77], 0, v[182:183]
	s_add_i32 m0, s87, 0xe000
	s_nop 0
	global_load_lds_dwordx4 v[186:187], off
	s_waitcnt vmcnt(8)
	s_waitcnt lgkmcnt(0)
	s_setprio 1
	s_barrier
	v_mfma_f32_16x16x32_bf16 v[142:145], v[114:117], v[162:165], v[142:145]
	v_mfma_f32_16x16x32_bf16 v[138:141], v[122:125], v[162:165], v[138:141]
	s_add_i32 s63, s24, s86
	v_lshl_add_u64 v[186:187], s[78:79], 0, v[172:173]
	s_mov_b32 m0, s63
	v_mfma_f32_16x16x32_bf16 v[110:113], v[114:117], v[194:197], v[110:113]
	v_mfma_f32_16x16x32_bf16 v[106:109], v[122:125], v[194:197], v[106:109]
	v_mfma_f32_16x16x32_bf16 v[98:101], v[114:117], v[206:209], v[98:101]
	v_mfma_f32_16x16x32_bf16 v[90:93], v[122:125], v[206:209], v[90:93]
	v_mfma_f32_16x16x32_bf16 v[82:85], v[114:117], v[214:217], v[82:85]
	v_mfma_f32_16x16x32_bf16 v[74:77], v[122:125], v[214:217], v[74:77]
	v_mfma_f32_16x16x32_bf16 v[142:145], v[118:121], v[166:169], v[142:145]
	v_mfma_f32_16x16x32_bf16 v[138:141], v[126:129], v[166:169], v[138:141]
	v_mfma_f32_16x16x32_bf16 v[110:113], v[118:121], v[198:201], v[110:113]
	v_mfma_f32_16x16x32_bf16 v[106:109], v[126:129], v[198:201], v[106:109]
	v_mfma_f32_16x16x32_bf16 v[98:101], v[118:121], v[210:213], v[98:101]
	v_mfma_f32_16x16x32_bf16 v[90:93], v[126:129], v[210:213], v[90:93]
	v_mfma_f32_16x16x32_bf16 v[82:85], v[118:121], v[218:221], v[82:85]
	v_mfma_f32_16x16x32_bf16 v[74:77], v[126:129], v[218:221], v[74:77]
	v_mfma_f32_16x16x32_bf16 v[134:137], v[146:149], v[162:165], v[134:137]
	v_mfma_f32_16x16x32_bf16 v[130:133], v[154:157], v[162:165], v[130:133]
	v_mfma_f32_16x16x32_bf16 v[102:105], v[146:149], v[194:197], v[102:105]
	v_mfma_f32_16x16x32_bf16 v[94:97], v[154:157], v[194:197], v[94:97]
	v_mfma_f32_16x16x32_bf16 v[86:89], v[146:149], v[206:209], v[86:89]
	v_mfma_f32_16x16x32_bf16 v[78:81], v[154:157], v[206:209], v[78:81]
	v_mfma_f32_16x16x32_bf16 v[70:73], v[146:149], v[214:217], v[70:73]
	v_mfma_f32_16x16x32_bf16 v[66:69], v[154:157], v[214:217], v[66:69]
	v_mfma_f32_16x16x32_bf16 v[134:137], v[150:153], v[166:169], v[134:137]
	v_mfma_f32_16x16x32_bf16 v[130:133], v[158:161], v[166:169], v[130:133]
	v_mfma_f32_16x16x32_bf16 v[102:105], v[150:153], v[198:201], v[102:105]
	v_mfma_f32_16x16x32_bf16 v[94:97], v[158:161], v[198:201], v[94:97]
	v_mfma_f32_16x16x32_bf16 v[86:89], v[150:153], v[210:213], v[86:89]
	v_mfma_f32_16x16x32_bf16 v[78:81], v[158:161], v[210:213], v[78:81]
	v_mfma_f32_16x16x32_bf16 v[70:73], v[150:153], v[218:221], v[70:73]
	v_mfma_f32_16x16x32_bf16 v[66:69], v[158:161], v[218:221], v[66:69]
	s_setprio 0
	s_barrier
	ds_read_b128 v[162:165], v192 offset:16384
	ds_read_b128 v[166:169], v192 offset:17408
	ds_read_b128 v[194:197], v192 offset:18432
	ds_read_b128 v[198:201], v192 offset:19456
	ds_read_b128 v[206:209], v192 offset:20480
	ds_read_b128 v[210:213], v192 offset:21504
	ds_read_b128 v[214:217], v192 offset:22528
	ds_read_b128 v[218:221], v192 offset:23552
	global_load_lds_dwordx4 v[186:187], off
	s_add_i32 m0, s63, 0x2000
	s_add_u32 vcc_lo, s78, 0x100000
	v_lshl_add_u64 v[202:203], s[78:79], 0, v[176:177]
	s_addc_u32 vcc_hi, s79, 0
	s_add_i32 s63, s25, s86
	global_load_lds_dwordx4 v[202:203], off
	v_lshl_add_u64 v[222:223], vcc, 0, v[172:173]
	s_mov_b32 m0, s63
	v_lshl_add_u64 v[224:225], s[80:81], 0, v[174:175]
	global_load_lds_dwordx4 v[222:223], off
	v_lshl_add_u64 v[222:223], vcc, 0, v[176:177]
	s_add_i32 m0, s63, 0x2000
	s_nop 0
	global_load_lds_dwordx4 v[222:223], off
	v_lshl_add_u64 v[222:223], s[80:81], 0, v[170:171]
	s_mov_b32 m0, s87
	s_nop 0
	global_load_lds_dwordx4 v[222:223], off
	s_mov_b32 m0, s88
	s_nop 0
	global_load_lds_dwordx4 v[224:225], off
	s_waitcnt vmcnt(8)
	s_waitcnt lgkmcnt(0)
	s_setprio 1
	s_barrier
	v_mfma_f32_16x16x32_bf16 v[62:65], v[114:117], v[162:165], v[62:65]
	v_mfma_f32_16x16x32_bf16 v[58:61], v[122:125], v[162:165], v[58:61]
	v_mfma_f32_16x16x32_bf16 v[50:53], v[114:117], v[194:197], v[50:53]
	v_mfma_f32_16x16x32_bf16 v[42:45], v[122:125], v[194:197], v[42:45]
	v_mfma_f32_16x16x32_bf16 v[34:37], v[114:117], v[206:209], v[34:37]
	v_mfma_f32_16x16x32_bf16 v[26:29], v[122:125], v[206:209], v[26:29]
	v_mfma_f32_16x16x32_bf16 v[18:21], v[114:117], v[214:217], v[18:21]
	v_mfma_f32_16x16x32_bf16 v[10:13], v[122:125], v[214:217], v[10:13]
	v_mfma_f32_16x16x32_bf16 v[62:65], v[118:121], v[166:169], v[62:65]
	v_mfma_f32_16x16x32_bf16 v[58:61], v[126:129], v[166:169], v[58:61]
	v_mfma_f32_16x16x32_bf16 v[50:53], v[118:121], v[198:201], v[50:53]
	v_mfma_f32_16x16x32_bf16 v[42:45], v[126:129], v[198:201], v[42:45]
	v_mfma_f32_16x16x32_bf16 v[34:37], v[118:121], v[210:213], v[34:37]
	v_mfma_f32_16x16x32_bf16 v[26:29], v[126:129], v[210:213], v[26:29]
	v_mfma_f32_16x16x32_bf16 v[18:21], v[118:121], v[218:221], v[18:21]
	v_mfma_f32_16x16x32_bf16 v[10:13], v[126:129], v[218:221], v[10:13]
	v_mfma_f32_16x16x32_bf16 v[54:57], v[146:149], v[162:165], v[54:57]
	v_mfma_f32_16x16x32_bf16 v[46:49], v[154:157], v[162:165], v[46:49]
	v_mfma_f32_16x16x32_bf16 v[38:41], v[146:149], v[194:197], v[38:41]
	v_mfma_f32_16x16x32_bf16 v[30:33], v[154:157], v[194:197], v[30:33]
	v_mfma_f32_16x16x32_bf16 v[22:25], v[146:149], v[206:209], v[22:25]
	v_mfma_f32_16x16x32_bf16 v[14:17], v[154:157], v[206:209], v[14:17]
	v_mfma_f32_16x16x32_bf16 v[6:9], v[146:149], v[214:217], v[6:9]
	v_mfma_f32_16x16x32_bf16 v[2:5], v[154:157], v[214:217], v[2:5]
	v_mfma_f32_16x16x32_bf16 v[54:57], v[150:153], v[166:169], v[54:57]
	v_mfma_f32_16x16x32_bf16 v[46:49], v[158:161], v[166:169], v[46:49]
	v_mfma_f32_16x16x32_bf16 v[38:41], v[150:153], v[198:201], v[38:41]
	v_mfma_f32_16x16x32_bf16 v[30:33], v[158:161], v[198:201], v[30:33]
	v_mfma_f32_16x16x32_bf16 v[22:25], v[150:153], v[210:213], v[22:25]
	v_mfma_f32_16x16x32_bf16 v[14:17], v[158:161], v[210:213], v[14:17]
	v_mfma_f32_16x16x32_bf16 v[6:9], v[150:153], v[218:221], v[6:9]
	v_mfma_f32_16x16x32_bf16 v[2:5], v[158:161], v[218:221], v[2:5]
	s_setprio 0
	s_barrier
	s_add_i32 s63, 0, 0x18000
	s_add_i32 s83, 0, 0x1c000
	v_add_u32_e32 v126, s63, v189
	v_add_u32_e32 v158, s83, v189
	ds_read_b128 v[114:117], v126
	ds_read_b128 v[118:121], v126 offset:1024
	ds_read_b128 v[122:125], v126 offset:2048
	ds_read_b128 v[126:129], v126 offset:3072
	ds_read_b128 v[146:149], v158
	ds_read_b128 v[150:153], v158 offset:1024
	ds_read_b128 v[154:157], v158 offset:2048
	ds_read_b128 v[158:161], v158 offset:3072
	s_add_u32 s80, s80, 0x100000
	s_addc_u32 s81, s81, 0
	s_mov_b32 m0, s89
	v_lshl_add_u64 v[226:227], s[80:81], 0, v[170:171]
	ds_read_b128 v[162:165], v192 offset:32768
	ds_read_b128 v[166:169], v192 offset:33792
	ds_read_b128 v[194:197], v192 offset:34816
	ds_read_b128 v[198:201], v192 offset:35840
	ds_read_b128 v[206:209], v192 offset:36864
	ds_read_b128 v[210:213], v192 offset:37888
	ds_read_b128 v[214:217], v192 offset:38912
	ds_read_b128 v[218:221], v192 offset:39936
	global_load_lds_dwordx4 v[226:227], off
	v_lshl_add_u64 v[226:227], s[80:81], 0, v[174:175]
	s_mov_b32 m0, s90
	s_nop 0
	global_load_lds_dwordx4 v[226:227], off
	s_waitcnt vmcnt(8)
	s_waitcnt lgkmcnt(0)
	s_setprio 1
	s_barrier
	v_mfma_f32_16x16x32_bf16 v[142:145], v[114:117], v[162:165], v[142:145]
	v_mfma_f32_16x16x32_bf16 v[138:141], v[122:125], v[162:165], v[138:141]
	s_add_i32 s63, s63, s86
	v_lshl_add_u64 v[186:187], v[186:187], 0, s[22:23]
	s_mov_b32 m0, s63
	v_mfma_f32_16x16x32_bf16 v[110:113], v[114:117], v[194:197], v[110:113]
	v_mfma_f32_16x16x32_bf16 v[106:109], v[122:125], v[194:197], v[106:109]
	v_mfma_f32_16x16x32_bf16 v[98:101], v[114:117], v[206:209], v[98:101]
	v_mfma_f32_16x16x32_bf16 v[90:93], v[122:125], v[206:209], v[90:93]
	v_mfma_f32_16x16x32_bf16 v[82:85], v[114:117], v[214:217], v[82:85]
	v_mfma_f32_16x16x32_bf16 v[74:77], v[122:125], v[214:217], v[74:77]
	v_mfma_f32_16x16x32_bf16 v[142:145], v[118:121], v[166:169], v[142:145]
	v_mfma_f32_16x16x32_bf16 v[138:141], v[126:129], v[166:169], v[138:141]
	v_mfma_f32_16x16x32_bf16 v[110:113], v[118:121], v[198:201], v[110:113]
	v_mfma_f32_16x16x32_bf16 v[106:109], v[126:129], v[198:201], v[106:109]
	v_mfma_f32_16x16x32_bf16 v[98:101], v[118:121], v[210:213], v[98:101]
	v_mfma_f32_16x16x32_bf16 v[90:93], v[126:129], v[210:213], v[90:93]
	v_mfma_f32_16x16x32_bf16 v[82:85], v[118:121], v[218:221], v[82:85]
	v_mfma_f32_16x16x32_bf16 v[74:77], v[126:129], v[218:221], v[74:77]
	v_mfma_f32_16x16x32_bf16 v[134:137], v[146:149], v[162:165], v[134:137]
	v_mfma_f32_16x16x32_bf16 v[130:133], v[154:157], v[162:165], v[130:133]
	v_mfma_f32_16x16x32_bf16 v[102:105], v[146:149], v[194:197], v[102:105]
	v_mfma_f32_16x16x32_bf16 v[94:97], v[154:157], v[194:197], v[94:97]
	v_mfma_f32_16x16x32_bf16 v[86:89], v[146:149], v[206:209], v[86:89]
	v_mfma_f32_16x16x32_bf16 v[78:81], v[154:157], v[206:209], v[78:81]
	v_mfma_f32_16x16x32_bf16 v[70:73], v[146:149], v[214:217], v[70:73]
	v_mfma_f32_16x16x32_bf16 v[66:69], v[154:157], v[214:217], v[66:69]
	v_mfma_f32_16x16x32_bf16 v[134:137], v[150:153], v[166:169], v[134:137]
	v_mfma_f32_16x16x32_bf16 v[130:133], v[158:161], v[166:169], v[130:133]
	v_mfma_f32_16x16x32_bf16 v[102:105], v[150:153], v[198:201], v[102:105]
	v_mfma_f32_16x16x32_bf16 v[94:97], v[158:161], v[198:201], v[94:97]
	v_mfma_f32_16x16x32_bf16 v[86:89], v[150:153], v[210:213], v[86:89]
	v_mfma_f32_16x16x32_bf16 v[78:81], v[158:161], v[210:213], v[78:81]
	v_mfma_f32_16x16x32_bf16 v[70:73], v[150:153], v[218:221], v[70:73]
	v_mfma_f32_16x16x32_bf16 v[66:69], v[158:161], v[218:221], v[66:69]
	s_setprio 0
	s_barrier
	ds_read_b128 v[162:165], v192 offset:49152
	ds_read_b128 v[166:169], v192 offset:50176
	ds_read_b128 v[194:197], v192 offset:51200
	ds_read_b128 v[198:201], v192 offset:52224
	ds_read_b128 v[206:209], v192 offset:53248
	ds_read_b128 v[210:213], v192 offset:54272
	ds_read_b128 v[214:217], v192 offset:55296
	ds_read_b128 v[218:221], v192 offset:56320
	global_load_lds_dwordx4 v[186:187], off
	s_add_i32 m0, s63, 0x2000
	s_add_u32 s78, s78, 0x100080
	v_lshl_add_u64 v[186:187], v[202:203], 0, s[22:23]
	s_addc_u32 s79, s79, 0
	s_add_i32 s63, s83, s86
	global_load_lds_dwordx4 v[186:187], off
	v_lshl_add_u64 v[186:187], s[78:79], 0, v[172:173]
	s_mov_b32 m0, s63
	s_nop 0
	global_load_lds_dwordx4 v[186:187], off
	v_lshl_add_u64 v[186:187], s[78:79], 0, v[176:177]
	s_add_i32 m0, s63, 0x2000
	s_nop 0
	global_load_lds_dwordx4 v[186:187], off
	v_lshl_add_u64 v[186:187], v[222:223], 0, s[22:23]
	s_mov_b32 m0, s95
	s_nop 0
	global_load_lds_dwordx4 v[186:187], off
	v_lshl_add_u64 v[186:187], v[224:225], 0, s[22:23]
	s_mov_b32 m0, s96
	s_nop 0
	global_load_lds_dwordx4 v[186:187], off
	s_waitcnt vmcnt(8)
	s_waitcnt lgkmcnt(0)
	s_setprio 1
	s_barrier
	v_mfma_f32_16x16x32_bf16 v[62:65], v[114:117], v[162:165], v[62:65]
	v_mfma_f32_16x16x32_bf16 v[58:61], v[122:125], v[162:165], v[58:61]
	s_add_u32 s76, s76, 0x100
	s_addc_u32 s77, s77, 0
	s_add_u32 s47, s47, 0x100
	s_addc_u32 s62, s62, 0
	s_cmp_ge_i32 s82, s7
	s_mov_b32 s63, s82
	v_mfma_f32_16x16x32_bf16 v[50:53], v[114:117], v[194:197], v[50:53]
	v_mfma_f32_16x16x32_bf16 v[42:45], v[122:125], v[194:197], v[42:45]
	v_mfma_f32_16x16x32_bf16 v[34:37], v[114:117], v[206:209], v[34:37]
	v_mfma_f32_16x16x32_bf16 v[26:29], v[122:125], v[206:209], v[26:29]
	v_mfma_f32_16x16x32_bf16 v[18:21], v[114:117], v[214:217], v[18:21]
	v_mfma_f32_16x16x32_bf16 v[10:13], v[122:125], v[214:217], v[10:13]
	v_mfma_f32_16x16x32_bf16 v[62:65], v[118:121], v[166:169], v[62:65]
	v_mfma_f32_16x16x32_bf16 v[58:61], v[126:129], v[166:169], v[58:61]
	v_mfma_f32_16x16x32_bf16 v[50:53], v[118:121], v[198:201], v[50:53]
	v_mfma_f32_16x16x32_bf16 v[42:45], v[126:129], v[198:201], v[42:45]
	v_mfma_f32_16x16x32_bf16 v[34:37], v[118:121], v[210:213], v[34:37]
	v_mfma_f32_16x16x32_bf16 v[26:29], v[126:129], v[210:213], v[26:29]
	v_mfma_f32_16x16x32_bf16 v[18:21], v[118:121], v[218:221], v[18:21]
	v_mfma_f32_16x16x32_bf16 v[10:13], v[126:129], v[218:221], v[10:13]
	v_mfma_f32_16x16x32_bf16 v[54:57], v[146:149], v[162:165], v[54:57]
	v_mfma_f32_16x16x32_bf16 v[46:49], v[154:157], v[162:165], v[46:49]
	v_mfma_f32_16x16x32_bf16 v[38:41], v[146:149], v[194:197], v[38:41]
	v_mfma_f32_16x16x32_bf16 v[30:33], v[154:157], v[194:197], v[30:33]
	v_mfma_f32_16x16x32_bf16 v[22:25], v[146:149], v[206:209], v[22:25]
	v_mfma_f32_16x16x32_bf16 v[14:17], v[154:157], v[206:209], v[14:17]
	v_mfma_f32_16x16x32_bf16 v[6:9], v[146:149], v[214:217], v[6:9]
	v_mfma_f32_16x16x32_bf16 v[2:5], v[154:157], v[214:217], v[2:5]
	v_mfma_f32_16x16x32_bf16 v[54:57], v[150:153], v[166:169], v[54:57]
	v_mfma_f32_16x16x32_bf16 v[46:49], v[158:161], v[166:169], v[46:49]
	v_mfma_f32_16x16x32_bf16 v[38:41], v[150:153], v[198:201], v[38:41]
	v_mfma_f32_16x16x32_bf16 v[30:33], v[158:161], v[198:201], v[30:33]
	v_mfma_f32_16x16x32_bf16 v[22:25], v[150:153], v[210:213], v[22:25]
	v_mfma_f32_16x16x32_bf16 v[14:17], v[158:161], v[210:213], v[14:17]
	v_mfma_f32_16x16x32_bf16 v[6:9], v[150:153], v[218:221], v[6:9]
	v_mfma_f32_16x16x32_bf16 v[2:5], v[158:161], v[218:221], v[2:5]
	s_setprio 0
	s_barrier
	s_cbranch_scc0 .LBB0_834
	s_and_b64 vcc, exec, s[26:27]
	s_cbranch_vccz .LBB0_837
	s_barrier

.LBB0_1012:
	s_add_u32 s48, s96, s44
	s_addc_u32 s49, s97, s45
	s_and_b64 s[14:15], s[4:5], exec
	s_cselect_b32 s6, s49, s65
	s_cselect_b32 s14, s48, s64
	s_add_u32 s50, s3, s46
	s_addc_u32 s51, s35, s47
	s_and_b64 s[18:19], s[4:5], exec
	s_cselect_b32 s15, s51, s67
	s_cselect_b32 s17, s50, s66
	s_add_u32 s64, s64, 0x40080
	s_addc_u32 s65, s65, 0
	s_add_u32 s18, s66, 0x100
	s_addc_u32 s19, s67, 0
	s_mov_b32 s24, -2
	s_waitcnt vmcnt(0)
	ds_read_b128 v[130:133], v172
	ds_read_b128 v[134:137], v172 offset:1024
	ds_read_b128 v[138:141], v172 offset:2048
	ds_read_b128 v[142:145], v172 offset:3072
	ds_read_b128 v[164:167], v173
	ds_read_b128 v[176:179], v173 offset:1024
	ds_read_b128 v[180:183], v173 offset:2048
	ds_read_b128 v[184:187], v173 offset:3072
	s_add_u32 s25, s64, 0xfffc0080
	s_addc_u32 s28, s65, -1
	s_cmp_eq_u32 s24, 12
	s_cselect_b32 s69, s6, s28
	s_cselect_b32 s68, s14, s25
	s_cselect_b32 s67, s15, s19
	s_cselect_b32 s66, s17, s18
	v_lshl_add_u64 v[168:169], s[64:65], 0, v[156:157]
	s_add_i32 m0, s73, 0xc000
	ds_read_b128 v[188:191], v174
	ds_read_b128 v[192:195], v174 offset:1024
	ds_read_b128 v[196:199], v174 offset:2048
	ds_read_b128 v[200:203], v174 offset:3072
	ds_read_b128 v[206:209], v174 offset:4096
	ds_read_b128 v[210:213], v174 offset:5120
	ds_read_b128 v[214:217], v174 offset:6144
	ds_read_b128 v[218:221], v174 offset:7168
	global_load_lds_dwordx4 v[168:169], off
	v_lshl_add_u64 v[168:169], s[64:65], 0, v[158:159]
	s_add_i32 m0, s73, 0xe000
	s_nop 0
	global_load_lds_dwordx4 v[168:169], off
	s_waitcnt vmcnt(8)
	s_waitcnt lgkmcnt(0)
	s_setprio 1
	s_barrier
	v_mfma_f32_16x16x32_bf16 v[126:129], v[130:133], v[188:191], 0
	v_mfma_f32_16x16x32_bf16 v[122:125], v[138:141], v[188:191], 0
	s_add_i32 s25, s82, s70
	v_lshl_add_u64 v[168:169], s[66:67], 0, v[150:151]
	s_mov_b32 m0, s25
	v_mfma_f32_16x16x32_bf16 v[110:113], v[130:133], v[196:199], 0
	v_mfma_f32_16x16x32_bf16 v[106:109], v[138:141], v[196:199], 0
	v_mfma_f32_16x16x32_bf16 v[94:97], v[130:133], v[206:209], 0
	v_mfma_f32_16x16x32_bf16 v[90:93], v[138:141], v[206:209], 0
	v_mfma_f32_16x16x32_bf16 v[78:81], v[130:133], v[214:217], 0
	v_mfma_f32_16x16x32_bf16 v[74:77], v[138:141], v[214:217], 0
	v_mfma_f32_16x16x32_bf16 v[126:129], v[134:137], v[192:195], v[126:129]
	v_mfma_f32_16x16x32_bf16 v[122:125], v[142:145], v[192:195], v[122:125]
	v_mfma_f32_16x16x32_bf16 v[110:113], v[134:137], v[200:203], v[110:113]
	v_mfma_f32_16x16x32_bf16 v[106:109], v[142:145], v[200:203], v[106:109]
	v_mfma_f32_16x16x32_bf16 v[94:97], v[134:137], v[210:213], v[94:97]
	v_mfma_f32_16x16x32_bf16 v[90:93], v[142:145], v[210:213], v[90:93]
	v_mfma_f32_16x16x32_bf16 v[78:81], v[134:137], v[218:221], v[78:81]
	v_mfma_f32_16x16x32_bf16 v[74:77], v[142:145], v[218:221], v[74:77]
	v_mfma_f32_16x16x32_bf16 v[118:121], v[164:167], v[188:191], 0
	v_mfma_f32_16x16x32_bf16 v[114:117], v[180:183], v[188:191], 0
	v_mfma_f32_16x16x32_bf16 v[102:105], v[164:167], v[196:199], 0
	v_mfma_f32_16x16x32_bf16 v[98:101], v[180:183], v[196:199], 0
	v_mfma_f32_16x16x32_bf16 v[86:89], v[164:167], v[206:209], 0
	v_mfma_f32_16x16x32_bf16 v[82:85], v[180:183], v[206:209], 0
	v_mfma_f32_16x16x32_bf16 v[70:73], v[164:167], v[214:217], 0
	v_mfma_f32_16x16x32_bf16 v[66:69], v[180:183], v[214:217], 0
	v_mfma_f32_16x16x32_bf16 v[118:121], v[176:179], v[192:195], v[118:121]
	v_mfma_f32_16x16x32_bf16 v[114:117], v[184:187], v[192:195], v[114:117]
	v_mfma_f32_16x16x32_bf16 v[102:105], v[176:179], v[200:203], v[102:105]
	v_mfma_f32_16x16x32_bf16 v[98:101], v[184:187], v[200:203], v[98:101]
	v_mfma_f32_16x16x32_bf16 v[86:89], v[176:179], v[210:213], v[86:89]
	v_mfma_f32_16x16x32_bf16 v[82:85], v[184:187], v[210:213], v[82:85]
	v_mfma_f32_16x16x32_bf16 v[70:73], v[176:179], v[218:221], v[70:73]
	v_mfma_f32_16x16x32_bf16 v[66:69], v[184:187], v[218:221], v[66:69]
	s_setprio 0
	s_barrier
	ds_read_b128 v[188:191], v174 offset:16384
	ds_read_b128 v[192:195], v174 offset:17408
	ds_read_b128 v[196:199], v174 offset:18432
	ds_read_b128 v[200:203], v174 offset:19456
	ds_read_b128 v[206:209], v174 offset:20480
	ds_read_b128 v[210:213], v174 offset:21504
	ds_read_b128 v[214:217], v174 offset:22528
	ds_read_b128 v[218:221], v174 offset:23552
	global_load_lds_dwordx4 v[168:169], off
	s_add_i32 m0, s25, 0x2000
	s_add_u32 s28, s66, 0x40000
	v_lshl_add_u64 v[222:223], s[66:67], 0, v[146:147]
	s_addc_u32 s29, s67, 0
	s_add_i32 s25, s83, s70
	global_load_lds_dwordx4 v[222:223], off
	v_lshl_add_u64 v[224:225], s[28:29], 0, v[150:151]
	s_mov_b32 m0, s25
	v_lshl_add_u64 v[226:227], s[68:69], 0, v[148:149]
	global_load_lds_dwordx4 v[224:225], off
	v_lshl_add_u64 v[224:225], s[28:29], 0, v[146:147]
	s_add_i32 m0, s25, 0x2000
	s_nop 0
	global_load_lds_dwordx4 v[224:225], off
	v_lshl_add_u64 v[224:225], s[68:69], 0, v[152:153]
	s_mov_b32 m0, s73
	s_nop 0
	global_load_lds_dwordx4 v[224:225], off
	s_mov_b32 m0, s74
	s_nop 0
	global_load_lds_dwordx4 v[226:227], off
	s_waitcnt vmcnt(8)
	s_waitcnt lgkmcnt(0)
	s_setprio 1
	s_barrier
	v_mfma_f32_16x16x32_bf16 v[62:65], v[130:133], v[188:191], 0
	v_mfma_f32_16x16x32_bf16 v[58:61], v[138:141], v[188:191], 0
	v_mfma_f32_16x16x32_bf16 v[46:49], v[130:133], v[196:199], 0
	v_mfma_f32_16x16x32_bf16 v[42:45], v[138:141], v[196:199], 0
	v_mfma_f32_16x16x32_bf16 v[30:33], v[130:133], v[206:209], 0
	v_mfma_f32_16x16x32_bf16 v[26:29], v[138:141], v[206:209], 0
	v_mfma_f32_16x16x32_bf16 v[14:17], v[130:133], v[214:217], 0
	v_mfma_f32_16x16x32_bf16 v[10:13], v[138:141], v[214:217], 0
	v_mfma_f32_16x16x32_bf16 v[62:65], v[134:137], v[192:195], v[62:65]
	v_mfma_f32_16x16x32_bf16 v[58:61], v[142:145], v[192:195], v[58:61]
	v_mfma_f32_16x16x32_bf16 v[46:49], v[134:137], v[200:203], v[46:49]
	v_mfma_f32_16x16x32_bf16 v[42:45], v[142:145], v[200:203], v[42:45]
	v_mfma_f32_16x16x32_bf16 v[30:33], v[134:137], v[210:213], v[30:33]
	v_mfma_f32_16x16x32_bf16 v[26:29], v[142:145], v[210:213], v[26:29]
	v_mfma_f32_16x16x32_bf16 v[14:17], v[134:137], v[218:221], v[14:17]
	v_mfma_f32_16x16x32_bf16 v[10:13], v[142:145], v[218:221], v[10:13]
	v_mfma_f32_16x16x32_bf16 v[54:57], v[164:167], v[188:191], 0
	v_mfma_f32_16x16x32_bf16 v[50:53], v[180:183], v[188:191], 0
	v_mfma_f32_16x16x32_bf16 v[38:41], v[164:167], v[196:199], 0
	v_mfma_f32_16x16x32_bf16 v[34:37], v[180:183], v[196:199], 0
	v_mfma_f32_16x16x32_bf16 v[22:25], v[164:167], v[206:209], 0
	v_mfma_f32_16x16x32_bf16 v[18:21], v[180:183], v[206:209], 0
	v_mfma_f32_16x16x32_bf16 v[6:9], v[164:167], v[214:217], 0
	v_mfma_f32_16x16x32_bf16 v[2:5], v[180:183], v[214:217], 0
	v_mfma_f32_16x16x32_bf16 v[54:57], v[176:179], v[192:195], v[54:57]
	v_mfma_f32_16x16x32_bf16 v[50:53], v[184:187], v[192:195], v[50:53]
	v_mfma_f32_16x16x32_bf16 v[38:41], v[176:179], v[200:203], v[38:41]
	v_mfma_f32_16x16x32_bf16 v[34:37], v[184:187], v[200:203], v[34:37]
	v_mfma_f32_16x16x32_bf16 v[22:25], v[176:179], v[210:213], v[22:25]
	v_mfma_f32_16x16x32_bf16 v[18:21], v[184:187], v[210:213], v[18:21]
	v_mfma_f32_16x16x32_bf16 v[6:9], v[176:179], v[218:221], v[6:9]
	v_mfma_f32_16x16x32_bf16 v[2:5], v[184:187], v[218:221], v[2:5]
	s_setprio 0
	s_barrier
	s_add_i32 s25, 0, 0x18000
	s_add_i32 s30, 0, 0x1c000
	v_add_u32_e32 v142, s25, v171
	v_add_u32_e32 v175, s30, v171
	ds_read_b128 v[130:133], v142
	ds_read_b128 v[134:137], v142 offset:1024
	ds_read_b128 v[138:141], v142 offset:2048
	ds_read_b128 v[142:145], v142 offset:3072
	ds_read_b128 v[164:167], v175
	ds_read_b128 v[176:179], v175 offset:1024
	ds_read_b128 v[180:183], v175 offset:2048
	ds_read_b128 v[184:187], v175 offset:3072
	s_add_u32 s28, s68, 0x40000
	s_addc_u32 s29, s69, 0
	s_mov_b32 m0, s75
	v_lshl_add_u64 v[228:229], s[28:29], 0, v[152:153]
	ds_read_b128 v[188:191], v174 offset:32768
	ds_read_b128 v[192:195], v174 offset:33792
	ds_read_b128 v[196:199], v174 offset:34816
	ds_read_b128 v[200:203], v174 offset:35840
	ds_read_b128 v[206:209], v174 offset:36864
	ds_read_b128 v[210:213], v174 offset:37888
	ds_read_b128 v[214:217], v174 offset:38912
	ds_read_b128 v[218:221], v174 offset:39936
	global_load_lds_dwordx4 v[228:229], off
	v_lshl_add_u64 v[228:229], s[28:29], 0, v[148:149]
	s_mov_b32 m0, s76
	s_nop 0
	global_load_lds_dwordx4 v[228:229], off
	s_waitcnt vmcnt(8)
	s_waitcnt lgkmcnt(0)
	s_setprio 1
	s_barrier
	v_mfma_f32_16x16x32_bf16 v[126:129], v[130:133], v[188:191], v[126:129]
	v_mfma_f32_16x16x32_bf16 v[122:125], v[138:141], v[188:191], v[122:125]
	s_add_i32 s25, s25, s70
	v_lshl_add_u64 v[168:169], v[168:169], 0, s[36:37]
	s_mov_b32 m0, s25
	v_mfma_f32_16x16x32_bf16 v[110:113], v[130:133], v[196:199], v[110:113]
	v_mfma_f32_16x16x32_bf16 v[106:109], v[138:141], v[196:199], v[106:109]
	v_mfma_f32_16x16x32_bf16 v[94:97], v[130:133], v[206:209], v[94:97]
	v_mfma_f32_16x16x32_bf16 v[90:93], v[138:141], v[206:209], v[90:93]
	v_mfma_f32_16x16x32_bf16 v[78:81], v[130:133], v[214:217], v[78:81]
	v_mfma_f32_16x16x32_bf16 v[74:77], v[138:141], v[214:217], v[74:77]
	v_mfma_f32_16x16x32_bf16 v[126:129], v[134:137], v[192:195], v[126:129]
	v_mfma_f32_16x16x32_bf16 v[122:125], v[142:145], v[192:195], v[122:125]
	v_mfma_f32_16x16x32_bf16 v[110:113], v[134:137], v[200:203], v[110:113]
	v_mfma_f32_16x16x32_bf16 v[106:109], v[142:145], v[200:203], v[106:109]
	v_mfma_f32_16x16x32_bf16 v[94:97], v[134:137], v[210:213], v[94:97]
	v_mfma_f32_16x16x32_bf16 v[90:93], v[142:145], v[210:213], v[90:93]
	v_mfma_f32_16x16x32_bf16 v[78:81], v[134:137], v[218:221], v[78:81]
	v_mfma_f32_16x16x32_bf16 v[74:77], v[142:145], v[218:221], v[74:77]
	v_mfma_f32_16x16x32_bf16 v[118:121], v[164:167], v[188:191], v[118:121]
	v_mfma_f32_16x16x32_bf16 v[114:117], v[180:183], v[188:191], v[114:117]
	v_mfma_f32_16x16x32_bf16 v[102:105], v[164:167], v[196:199], v[102:105]
	v_mfma_f32_16x16x32_bf16 v[98:101], v[180:183], v[196:199], v[98:101]
	v_mfma_f32_16x16x32_bf16 v[86:89], v[164:167], v[206:209], v[86:89]
	v_mfma_f32_16x16x32_bf16 v[82:85], v[180:183], v[206:209], v[82:85]
	v_mfma_f32_16x16x32_bf16 v[70:73], v[164:167], v[214:217], v[70:73]
	v_mfma_f32_16x16x32_bf16 v[66:69], v[180:183], v[214:217], v[66:69]
	v_mfma_f32_16x16x32_bf16 v[118:121], v[176:179], v[192:195], v[118:121]
	v_mfma_f32_16x16x32_bf16 v[114:117], v[184:187], v[192:195], v[114:117]
	v_mfma_f32_16x16x32_bf16 v[102:105], v[176:179], v[200:203], v[102:105]
	v_mfma_f32_16x16x32_bf16 v[98:101], v[184:187], v[200:203], v[98:101]
	v_mfma_f32_16x16x32_bf16 v[86:89], v[176:179], v[210:213], v[86:89]
	v_mfma_f32_16x16x32_bf16 v[82:85], v[184:187], v[210:213], v[82:85]
	v_mfma_f32_16x16x32_bf16 v[70:73], v[176:179], v[218:221], v[70:73]
	v_mfma_f32_16x16x32_bf16 v[66:69], v[184:187], v[218:221], v[66:69]
	s_setprio 0
	s_barrier
	ds_read_b128 v[188:191], v174 offset:49152
	ds_read_b128 v[192:195], v174 offset:50176
	ds_read_b128 v[196:199], v174 offset:51200
	ds_read_b128 v[200:203], v174 offset:52224
	ds_read_b128 v[206:209], v174 offset:53248
	ds_read_b128 v[210:213], v174 offset:54272
	ds_read_b128 v[214:217], v174 offset:55296
	ds_read_b128 v[218:221], v174 offset:56320
	global_load_lds_dwordx4 v[168:169], off
	s_add_i32 m0, s25, 0x2000
	s_add_u32 s28, s66, 0x40080
	v_lshl_add_u64 v[168:169], v[222:223], 0, s[36:37]
	s_addc_u32 s29, s67, 0
	s_add_i32 s25, s30, s70
	global_load_lds_dwordx4 v[168:169], off
	v_lshl_add_u64 v[168:169], s[28:29], 0, v[150:151]
	s_mov_b32 m0, s25
	s_nop 0
	global_load_lds_dwordx4 v[168:169], off
	v_lshl_add_u64 v[168:169], s[28:29], 0, v[146:147]
	s_add_i32 m0, s25, 0x2000
	s_nop 0
	global_load_lds_dwordx4 v[168:169], off
	v_lshl_add_u64 v[168:169], v[224:225], 0, s[36:37]
	s_mov_b32 m0, s79
	s_nop 0
	global_load_lds_dwordx4 v[168:169], off
	v_lshl_add_u64 v[168:169], v[226:227], 0, s[36:37]
	s_mov_b32 m0, s80
	s_nop 0
	global_load_lds_dwordx4 v[168:169], off
	s_waitcnt vmcnt(8)
	s_waitcnt lgkmcnt(0)
	s_setprio 1
	s_barrier
	v_mfma_f32_16x16x32_bf16 v[62:65], v[130:133], v[188:191], v[62:65]
	v_mfma_f32_16x16x32_bf16 v[58:61], v[138:141], v[188:191], v[58:61]
	s_add_i32 s24, s24, 2
	s_add_u32 s64, s64, 0x100
	s_addc_u32 s65, s65, 0
	s_add_u32 s18, s18, 0x100
	s_addc_u32 s19, s19, 0
	s_cmp_gt_u32 s24, 13
	v_mfma_f32_16x16x32_bf16 v[46:49], v[130:133], v[196:199], v[46:49]
	v_mfma_f32_16x16x32_bf16 v[42:45], v[138:141], v[196:199], v[42:45]
	v_mfma_f32_16x16x32_bf16 v[30:33], v[130:133], v[206:209], v[30:33]
	v_mfma_f32_16x16x32_bf16 v[26:29], v[138:141], v[206:209], v[26:29]
	v_mfma_f32_16x16x32_bf16 v[14:17], v[130:133], v[214:217], v[14:17]
	v_mfma_f32_16x16x32_bf16 v[10:13], v[138:141], v[214:217], v[10:13]
	v_mfma_f32_16x16x32_bf16 v[62:65], v[134:137], v[192:195], v[62:65]
	v_mfma_f32_16x16x32_bf16 v[58:61], v[142:145], v[192:195], v[58:61]
	v_mfma_f32_16x16x32_bf16 v[46:49], v[134:137], v[200:203], v[46:49]
	v_mfma_f32_16x16x32_bf16 v[42:45], v[142:145], v[200:203], v[42:45]
	v_mfma_f32_16x16x32_bf16 v[30:33], v[134:137], v[210:213], v[30:33]
	v_mfma_f32_16x16x32_bf16 v[26:29], v[142:145], v[210:213], v[26:29]
	v_mfma_f32_16x16x32_bf16 v[14:17], v[134:137], v[218:221], v[14:17]
	v_mfma_f32_16x16x32_bf16 v[10:13], v[142:145], v[218:221], v[10:13]
	v_mfma_f32_16x16x32_bf16 v[54:57], v[164:167], v[188:191], v[54:57]
	v_mfma_f32_16x16x32_bf16 v[50:53], v[180:183], v[188:191], v[50:53]
	v_mfma_f32_16x16x32_bf16 v[38:41], v[164:167], v[196:199], v[38:41]
	v_mfma_f32_16x16x32_bf16 v[34:37], v[180:183], v[196:199], v[34:37]
	v_mfma_f32_16x16x32_bf16 v[22:25], v[164:167], v[206:209], v[22:25]
	v_mfma_f32_16x16x32_bf16 v[18:21], v[180:183], v[206:209], v[18:21]
	v_mfma_f32_16x16x32_bf16 v[6:9], v[164:167], v[214:217], v[6:9]
	v_mfma_f32_16x16x32_bf16 v[2:5], v[180:183], v[214:217], v[2:5]
	v_mfma_f32_16x16x32_bf16 v[54:57], v[176:179], v[192:195], v[54:57]
	v_mfma_f32_16x16x32_bf16 v[50:53], v[184:187], v[192:195], v[50:53]
	v_mfma_f32_16x16x32_bf16 v[38:41], v[176:179], v[200:203], v[38:41]
	v_mfma_f32_16x16x32_bf16 v[34:37], v[184:187], v[200:203], v[34:37]
	v_mfma_f32_16x16x32_bf16 v[22:25], v[176:179], v[210:213], v[22:25]
	v_mfma_f32_16x16x32_bf16 v[18:21], v[184:187], v[210:213], v[18:21]
	v_mfma_f32_16x16x32_bf16 v[6:9], v[176:179], v[218:221], v[6:9]
	v_mfma_f32_16x16x32_bf16 v[2:5], v[184:187], v[218:221], v[2:5]
	s_setprio 0
	s_barrier
.LBB0_1013:
	ds_read_b128 v[130:133], v172
	ds_read_b128 v[134:137], v172 offset:1024
	ds_read_b128 v[138:141], v172 offset:2048
	ds_read_b128 v[142:145], v172 offset:3072
	ds_read_b128 v[164:167], v173
	ds_read_b128 v[176:179], v173 offset:1024
	ds_read_b128 v[180:183], v173 offset:2048
	ds_read_b128 v[184:187], v173 offset:3072
	s_add_u32 s25, s64, 0xfffc0080
	s_addc_u32 s28, s65, -1
	s_cmp_eq_u32 s24, 12
	s_cselect_b32 s69, s6, s28
	s_cselect_b32 s68, s14, s25
	s_cselect_b32 s67, s15, s19
	s_cselect_b32 s66, s17, s18
	v_lshl_add_u64 v[168:169], s[64:65], 0, v[156:157]
	s_add_i32 m0, s73, 0xc000
	ds_read_b128 v[188:191], v174
	ds_read_b128 v[192:195], v174 offset:1024
	ds_read_b128 v[196:199], v174 offset:2048
	ds_read_b128 v[200:203], v174 offset:3072
	ds_read_b128 v[206:209], v174 offset:4096
	ds_read_b128 v[210:213], v174 offset:5120
	ds_read_b128 v[214:217], v174 offset:6144
	ds_read_b128 v[218:221], v174 offset:7168
	global_load_lds_dwordx4 v[168:169], off
	v_lshl_add_u64 v[168:169], s[64:65], 0, v[158:159]
	s_add_i32 m0, s73, 0xe000
	s_nop 0
	global_load_lds_dwordx4 v[168:169], off
	s_waitcnt vmcnt(8)
	s_waitcnt lgkmcnt(0)
	s_setprio 1
	s_barrier
	v_mfma_f32_16x16x32_bf16 v[126:129], v[130:133], v[188:191], v[126:129]
	v_mfma_f32_16x16x32_bf16 v[122:125], v[138:141], v[188:191], v[122:125]
	s_add_i32 s25, s82, s70
	v_lshl_add_u64 v[168:169], s[66:67], 0, v[150:151]
	s_mov_b32 m0, s25
	v_mfma_f32_16x16x32_bf16 v[110:113], v[130:133], v[196:199], v[110:113]
	v_mfma_f32_16x16x32_bf16 v[106:109], v[138:141], v[196:199], v[106:109]
	v_mfma_f32_16x16x32_bf16 v[94:97], v[130:133], v[206:209], v[94:97]
	v_mfma_f32_16x16x32_bf16 v[90:93], v[138:141], v[206:209], v[90:93]
	v_mfma_f32_16x16x32_bf16 v[78:81], v[130:133], v[214:217], v[78:81]
	v_mfma_f32_16x16x32_bf16 v[74:77], v[138:141], v[214:217], v[74:77]
	v_mfma_f32_16x16x32_bf16 v[126:129], v[134:137], v[192:195], v[126:129]
	v_mfma_f32_16x16x32_bf16 v[122:125], v[142:145], v[192:195], v[122:125]
	v_mfma_f32_16x16x32_bf16 v[110:113], v[134:137], v[200:203], v[110:113]
	v_mfma_f32_16x16x32_bf16 v[106:109], v[142:145], v[200:203], v[106:109]
	v_mfma_f32_16x16x32_bf16 v[94:97], v[134:137], v[210:213], v[94:97]
	v_mfma_f32_16x16x32_bf16 v[90:93], v[142:145], v[210:213], v[90:93]
	v_mfma_f32_16x16x32_bf16 v[78:81], v[134:137], v[218:221], v[78:81]
	v_mfma_f32_16x16x32_bf16 v[74:77], v[142:145], v[218:221], v[74:77]
	v_mfma_f32_16x16x32_bf16 v[118:121], v[164:167], v[188:191], v[118:121]
	v_mfma_f32_16x16x32_bf16 v[114:117], v[180:183], v[188:191], v[114:117]
	v_mfma_f32_16x16x32_bf16 v[102:105], v[164:167], v[196:199], v[102:105]
	v_mfma_f32_16x16x32_bf16 v[98:101], v[180:183], v[196:199], v[98:101]
	v_mfma_f32_16x16x32_bf16 v[86:89], v[164:167], v[206:209], v[86:89]
	v_mfma_f32_16x16x32_bf16 v[82:85], v[180:183], v[206:209], v[82:85]
	v_mfma_f32_16x16x32_bf16 v[70:73], v[164:167], v[214:217], v[70:73]
	v_mfma_f32_16x16x32_bf16 v[66:69], v[180:183], v[214:217], v[66:69]
	v_mfma_f32_16x16x32_bf16 v[118:121], v[176:179], v[192:195], v[118:121]
	v_mfma_f32_16x16x32_bf16 v[114:117], v[184:187], v[192:195], v[114:117]
	v_mfma_f32_16x16x32_bf16 v[102:105], v[176:179], v[200:203], v[102:105]
	v_mfma_f32_16x16x32_bf16 v[98:101], v[184:187], v[200:203], v[98:101]
	v_mfma_f32_16x16x32_bf16 v[86:89], v[176:179], v[210:213], v[86:89]
	v_mfma_f32_16x16x32_bf16 v[82:85], v[184:187], v[210:213], v[82:85]
	v_mfma_f32_16x16x32_bf16 v[70:73], v[176:179], v[218:221], v[70:73]
	v_mfma_f32_16x16x32_bf16 v[66:69], v[184:187], v[218:221], v[66:69]
	s_setprio 0
	s_barrier
	ds_read_b128 v[188:191], v174 offset:16384
	ds_read_b128 v[192:195], v174 offset:17408
	ds_read_b128 v[196:199], v174 offset:18432
	ds_read_b128 v[200:203], v174 offset:19456
	ds_read_b128 v[206:209], v174 offset:20480
	ds_read_b128 v[210:213], v174 offset:21504
	ds_read_b128 v[214:217], v174 offset:22528
	ds_read_b128 v[218:221], v174 offset:23552
	global_load_lds_dwordx4 v[168:169], off
	s_add_i32 m0, s25, 0x2000
	s_add_u32 s28, s66, 0x40000
	v_lshl_add_u64 v[222:223], s[66:67], 0, v[146:147]
	s_addc_u32 s29, s67, 0
	s_add_i32 s25, s83, s70
	global_load_lds_dwordx4 v[222:223], off
	v_lshl_add_u64 v[224:225], s[28:29], 0, v[150:151]
	s_mov_b32 m0, s25
	v_lshl_add_u64 v[226:227], s[68:69], 0, v[148:149]
	global_load_lds_dwordx4 v[224:225], off
	v_lshl_add_u64 v[224:225], s[28:29], 0, v[146:147]
	s_add_i32 m0, s25, 0x2000
	s_nop 0
	global_load_lds_dwordx4 v[224:225], off
	v_lshl_add_u64 v[224:225], s[68:69], 0, v[152:153]
	s_mov_b32 m0, s73
	s_nop 0
	global_load_lds_dwordx4 v[224:225], off
	s_mov_b32 m0, s74
	s_nop 0
	global_load_lds_dwordx4 v[226:227], off
	s_waitcnt vmcnt(8)
	s_waitcnt lgkmcnt(0)
	s_setprio 1
	s_barrier
	v_mfma_f32_16x16x32_bf16 v[62:65], v[130:133], v[188:191], v[62:65]
	v_mfma_f32_16x16x32_bf16 v[58:61], v[138:141], v[188:191], v[58:61]
	v_mfma_f32_16x16x32_bf16 v[46:49], v[130:133], v[196:199], v[46:49]
	v_mfma_f32_16x16x32_bf16 v[42:45], v[138:141], v[196:199], v[42:45]
	v_mfma_f32_16x16x32_bf16 v[30:33], v[130:133], v[206:209], v[30:33]
	v_mfma_f32_16x16x32_bf16 v[26:29], v[138:141], v[206:209], v[26:29]
	v_mfma_f32_16x16x32_bf16 v[14:17], v[130:133], v[214:217], v[14:17]
	v_mfma_f32_16x16x32_bf16 v[10:13], v[138:141], v[214:217], v[10:13]
	v_mfma_f32_16x16x32_bf16 v[62:65], v[134:137], v[192:195], v[62:65]
	v_mfma_f32_16x16x32_bf16 v[58:61], v[142:145], v[192:195], v[58:61]
	v_mfma_f32_16x16x32_bf16 v[46:49], v[134:137], v[200:203], v[46:49]
	v_mfma_f32_16x16x32_bf16 v[42:45], v[142:145], v[200:203], v[42:45]
	v_mfma_f32_16x16x32_bf16 v[30:33], v[134:137], v[210:213], v[30:33]
	v_mfma_f32_16x16x32_bf16 v[26:29], v[142:145], v[210:213], v[26:29]
	v_mfma_f32_16x16x32_bf16 v[14:17], v[134:137], v[218:221], v[14:17]
	v_mfma_f32_16x16x32_bf16 v[10:13], v[142:145], v[218:221], v[10:13]
	v_mfma_f32_16x16x32_bf16 v[54:57], v[164:167], v[188:191], v[54:57]
	v_mfma_f32_16x16x32_bf16 v[50:53], v[180:183], v[188:191], v[50:53]
	v_mfma_f32_16x16x32_bf16 v[38:41], v[164:167], v[196:199], v[38:41]
	v_mfma_f32_16x16x32_bf16 v[34:37], v[180:183], v[196:199], v[34:37]
	v_mfma_f32_16x16x32_bf16 v[22:25], v[164:167], v[206:209], v[22:25]
	v_mfma_f32_16x16x32_bf16 v[18:21], v[180:183], v[206:209], v[18:21]
	v_mfma_f32_16x16x32_bf16 v[6:9], v[164:167], v[214:217], v[6:9]
	v_mfma_f32_16x16x32_bf16 v[2:5], v[180:183], v[214:217], v[2:5]
	v_mfma_f32_16x16x32_bf16 v[54:57], v[176:179], v[192:195], v[54:57]
	v_mfma_f32_16x16x32_bf16 v[50:53], v[184:187], v[192:195], v[50:53]
	v_mfma_f32_16x16x32_bf16 v[38:41], v[176:179], v[200:203], v[38:41]
	v_mfma_f32_16x16x32_bf16 v[34:37], v[184:187], v[200:203], v[34:37]
	v_mfma_f32_16x16x32_bf16 v[22:25], v[176:179], v[210:213], v[22:25]
	v_mfma_f32_16x16x32_bf16 v[18:21], v[184:187], v[210:213], v[18:21]
	v_mfma_f32_16x16x32_bf16 v[6:9], v[176:179], v[218:221], v[6:9]
	v_mfma_f32_16x16x32_bf16 v[2:5], v[184:187], v[218:221], v[2:5]
	s_setprio 0
	s_barrier
	s_add_i32 s25, 0, 0x18000
	s_add_i32 s30, 0, 0x1c000
	v_add_u32_e32 v142, s25, v171
	v_add_u32_e32 v175, s30, v171
	ds_read_b128 v[130:133], v142
	ds_read_b128 v[134:137], v142 offset:1024
	ds_read_b128 v[138:141], v142 offset:2048
	ds_read_b128 v[142:145], v142 offset:3072
	ds_read_b128 v[164:167], v175
	ds_read_b128 v[176:179], v175 offset:1024
	ds_read_b128 v[180:183], v175 offset:2048
	ds_read_b128 v[184:187], v175 offset:3072
	s_add_u32 s28, s68, 0x40000
	s_addc_u32 s29, s69, 0
	s_mov_b32 m0, s75
	v_lshl_add_u64 v[228:229], s[28:29], 0, v[152:153]
	ds_read_b128 v[188:191], v174 offset:32768
	ds_read_b128 v[192:195], v174 offset:33792
	ds_read_b128 v[196:199], v174 offset:34816
	ds_read_b128 v[200:203], v174 offset:35840
	ds_read_b128 v[206:209], v174 offset:36864
	ds_read_b128 v[210:213], v174 offset:37888
	ds_read_b128 v[214:217], v174 offset:38912
	ds_read_b128 v[218:221], v174 offset:39936
	global_load_lds_dwordx4 v[228:229], off
	v_lshl_add_u64 v[228:229], s[28:29], 0, v[148:149]
	s_mov_b32 m0, s76
	s_nop 0
	global_load_lds_dwordx4 v[228:229], off
	s_waitcnt vmcnt(8)
	s_waitcnt lgkmcnt(0)
	s_setprio 1
	s_barrier
	v_mfma_f32_16x16x32_bf16 v[126:129], v[130:133], v[188:191], v[126:129]
	v_mfma_f32_16x16x32_bf16 v[122:125], v[138:141], v[188:191], v[122:125]
	s_add_i32 s25, s25, s70
	v_lshl_add_u64 v[168:169], v[168:169], 0, s[36:37]
	s_mov_b32 m0, s25
	v_mfma_f32_16x16x32_bf16 v[110:113], v[130:133], v[196:199], v[110:113]
	v_mfma_f32_16x16x32_bf16 v[106:109], v[138:141], v[196:199], v[106:109]
	v_mfma_f32_16x16x32_bf16 v[94:97], v[130:133], v[206:209], v[94:97]
	v_mfma_f32_16x16x32_bf16 v[90:93], v[138:141], v[206:209], v[90:93]
	v_mfma_f32_16x16x32_bf16 v[78:81], v[130:133], v[214:217], v[78:81]
	v_mfma_f32_16x16x32_bf16 v[74:77], v[138:141], v[214:217], v[74:77]
	v_mfma_f32_16x16x32_bf16 v[126:129], v[134:137], v[192:195], v[126:129]
	v_mfma_f32_16x16x32_bf16 v[122:125], v[142:145], v[192:195], v[122:125]
	v_mfma_f32_16x16x32_bf16 v[110:113], v[134:137], v[200:203], v[110:113]
	v_mfma_f32_16x16x32_bf16 v[106:109], v[142:145], v[200:203], v[106:109]
	v_mfma_f32_16x16x32_bf16 v[94:97], v[134:137], v[210:213], v[94:97]
	v_mfma_f32_16x16x32_bf16 v[90:93], v[142:145], v[210:213], v[90:93]
	v_mfma_f32_16x16x32_bf16 v[78:81], v[134:137], v[218:221], v[78:81]
	v_mfma_f32_16x16x32_bf16 v[74:77], v[142:145], v[218:221], v[74:77]
	v_mfma_f32_16x16x32_bf16 v[118:121], v[164:167], v[188:191], v[118:121]
	v_mfma_f32_16x16x32_bf16 v[114:117], v[180:183], v[188:191], v[114:117]
	v_mfma_f32_16x16x32_bf16 v[102:105], v[164:167], v[196:199], v[102:105]
	v_mfma_f32_16x16x32_bf16 v[98:101], v[180:183], v[196:199], v[98:101]
	v_mfma_f32_16x16x32_bf16 v[86:89], v[164:167], v[206:209], v[86:89]
	v_mfma_f32_16x16x32_bf16 v[82:85], v[180:183], v[206:209], v[82:85]
	v_mfma_f32_16x16x32_bf16 v[70:73], v[164:167], v[214:217], v[70:73]
	v_mfma_f32_16x16x32_bf16 v[66:69], v[180:183], v[214:217], v[66:69]
	v_mfma_f32_16x16x32_bf16 v[118:121], v[176:179], v[192:195], v[118:121]
	v_mfma_f32_16x16x32_bf16 v[114:117], v[184:187], v[192:195], v[114:117]
	v_mfma_f32_16x16x32_bf16 v[102:105], v[176:179], v[200:203], v[102:105]
	v_mfma_f32_16x16x32_bf16 v[98:101], v[184:187], v[200:203], v[98:101]
	v_mfma_f32_16x16x32_bf16 v[86:89], v[176:179], v[210:213], v[86:89]
	v_mfma_f32_16x16x32_bf16 v[82:85], v[184:187], v[210:213], v[82:85]
	v_mfma_f32_16x16x32_bf16 v[70:73], v[176:179], v[218:221], v[70:73]
	v_mfma_f32_16x16x32_bf16 v[66:69], v[184:187], v[218:221], v[66:69]
	s_setprio 0
	s_barrier
	ds_read_b128 v[188:191], v174 offset:49152
	ds_read_b128 v[192:195], v174 offset:50176
	ds_read_b128 v[196:199], v174 offset:51200
	ds_read_b128 v[200:203], v174 offset:52224
	ds_read_b128 v[206:209], v174 offset:53248
	ds_read_b128 v[210:213], v174 offset:54272
	ds_read_b128 v[214:217], v174 offset:55296
	ds_read_b128 v[218:221], v174 offset:56320
	global_load_lds_dwordx4 v[168:169], off
	s_add_i32 m0, s25, 0x2000
	s_add_u32 s28, s66, 0x40080
	v_lshl_add_u64 v[168:169], v[222:223], 0, s[36:37]
	s_addc_u32 s29, s67, 0
	s_add_i32 s25, s30, s70
	global_load_lds_dwordx4 v[168:169], off
	v_lshl_add_u64 v[168:169], s[28:29], 0, v[150:151]
	s_mov_b32 m0, s25
	s_nop 0
	global_load_lds_dwordx4 v[168:169], off
	v_lshl_add_u64 v[168:169], s[28:29], 0, v[146:147]
	s_add_i32 m0, s25, 0x2000
	s_nop 0
	global_load_lds_dwordx4 v[168:169], off
	v_lshl_add_u64 v[168:169], v[224:225], 0, s[36:37]
	s_mov_b32 m0, s79
	s_nop 0
	global_load_lds_dwordx4 v[168:169], off
	v_lshl_add_u64 v[168:169], v[226:227], 0, s[36:37]
	s_mov_b32 m0, s80
	s_nop 0
	global_load_lds_dwordx4 v[168:169], off
	s_waitcnt vmcnt(8)
	s_waitcnt lgkmcnt(0)
	s_setprio 1
	s_barrier
	v_mfma_f32_16x16x32_bf16 v[62:65], v[130:133], v[188:191], v[62:65]
	v_mfma_f32_16x16x32_bf16 v[58:61], v[138:141], v[188:191], v[58:61]
	s_add_i32 s24, s24, 2
	s_add_u32 s64, s64, 0x100
	s_addc_u32 s65, s65, 0
	s_add_u32 s18, s18, 0x100
	s_addc_u32 s19, s19, 0
	s_cmp_gt_u32 s24, 13
	v_mfma_f32_16x16x32_bf16 v[46:49], v[130:133], v[196:199], v[46:49]
	v_mfma_f32_16x16x32_bf16 v[42:45], v[138:141], v[196:199], v[42:45]
	v_mfma_f32_16x16x32_bf16 v[30:33], v[130:133], v[206:209], v[30:33]
	v_mfma_f32_16x16x32_bf16 v[26:29], v[138:141], v[206:209], v[26:29]
	v_mfma_f32_16x16x32_bf16 v[14:17], v[130:133], v[214:217], v[14:17]
	v_mfma_f32_16x16x32_bf16 v[10:13], v[138:141], v[214:217], v[10:13]
	v_mfma_f32_16x16x32_bf16 v[62:65], v[134:137], v[192:195], v[62:65]
	v_mfma_f32_16x16x32_bf16 v[58:61], v[142:145], v[192:195], v[58:61]
	v_mfma_f32_16x16x32_bf16 v[46:49], v[134:137], v[200:203], v[46:49]
	v_mfma_f32_16x16x32_bf16 v[42:45], v[142:145], v[200:203], v[42:45]
	v_mfma_f32_16x16x32_bf16 v[30:33], v[134:137], v[210:213], v[30:33]
	v_mfma_f32_16x16x32_bf16 v[26:29], v[142:145], v[210:213], v[26:29]
	v_mfma_f32_16x16x32_bf16 v[14:17], v[134:137], v[218:221], v[14:17]
	v_mfma_f32_16x16x32_bf16 v[10:13], v[142:145], v[218:221], v[10:13]
	v_mfma_f32_16x16x32_bf16 v[54:57], v[164:167], v[188:191], v[54:57]
	v_mfma_f32_16x16x32_bf16 v[50:53], v[180:183], v[188:191], v[50:53]
	v_mfma_f32_16x16x32_bf16 v[38:41], v[164:167], v[196:199], v[38:41]
	v_mfma_f32_16x16x32_bf16 v[34:37], v[180:183], v[196:199], v[34:37]
	v_mfma_f32_16x16x32_bf16 v[22:25], v[164:167], v[206:209], v[22:25]
	v_mfma_f32_16x16x32_bf16 v[18:21], v[180:183], v[206:209], v[18:21]
	v_mfma_f32_16x16x32_bf16 v[6:9], v[164:167], v[214:217], v[6:9]
	v_mfma_f32_16x16x32_bf16 v[2:5], v[180:183], v[214:217], v[2:5]
	v_mfma_f32_16x16x32_bf16 v[54:57], v[176:179], v[192:195], v[54:57]
	v_mfma_f32_16x16x32_bf16 v[50:53], v[184:187], v[192:195], v[50:53]
	v_mfma_f32_16x16x32_bf16 v[38:41], v[176:179], v[200:203], v[38:41]
	v_mfma_f32_16x16x32_bf16 v[34:37], v[184:187], v[200:203], v[34:37]
	v_mfma_f32_16x16x32_bf16 v[22:25], v[176:179], v[210:213], v[22:25]
	v_mfma_f32_16x16x32_bf16 v[18:21], v[184:187], v[210:213], v[18:21]
	v_mfma_f32_16x16x32_bf16 v[6:9], v[176:179], v[218:221], v[6:9]
	v_mfma_f32_16x16x32_bf16 v[2:5], v[184:187], v[218:221], v[2:5]
	s_setprio 0
	s_barrier
	s_cbranch_scc0 .LBB0_1013
	s_and_b64 vcc, exec, s[38:39]
	s_cbranch_vccz .LBB0_1016
	s_barrier

.LBB0_1427:
	s_add_u32 s90, s35, s86
	s_addc_u32 s91, s64, s87
	s_and_b64 s[14:15], s[88:89], exec
	s_cselect_b32 s14, s91, s11
	s_cselect_b32 s15, s90, s10
	s_add_u32 s92, s65, s74
	s_addc_u32 s93, s68, s75
	s_and_b64 s[66:67], s[88:89], exec
	s_cselect_b32 s51, s93, s95
	s_cselect_b32 s84, s92, s94
	s_add_i32 s85, s18, -2
	s_add_u32 s10, s10, 0x40080
	s_addc_u32 s11, s11, 0
	s_add_u32 vcc_lo, s94, 0x100
	s_addc_u32 vcc_hi, s95, 0
	s_mov_b32 s94, 0
	s_waitcnt vmcnt(0)
	s_add_i32 s66, s94, 2
	s_add_u32 s67, s10, 0xfffc0080
	s_addc_u32 s72, s11, -1
	s_cmp_eq_u32 s85, s94
	s_cselect_b32 s97, s14, s72
	s_cselect_b32 s96, s15, s67
	s_cselect_b32 s95, s51, vcc_hi
	s_cselect_b32 s94, s84, vcc_lo
	s_add_i32 s67, 0, 0x10000
	s_add_i32 s62, 0, 0x14000
	v_add_u32_e32 v126, s67, v199
	v_add_u32_e32 v158, s62, v199
	ds_read_b128 v[114:117], v126
	ds_read_b128 v[118:121], v126 offset:1024
	ds_read_b128 v[122:125], v126 offset:2048
	ds_read_b128 v[126:129], v126 offset:3072
	ds_read_b128 v[146:149], v158
	ds_read_b128 v[150:153], v158 offset:1024
	ds_read_b128 v[154:157], v158 offset:2048
	ds_read_b128 v[158:161], v158 offset:3072
	v_lshl_add_u64 v[202:203], s[10:11], 0, v[196:197]
	s_add_i32 m0, s28, 0xc000
	ds_read_b128 v[162:165], v214
	ds_read_b128 v[166:169], v214 offset:1024
	ds_read_b128 v[216:219], v214 offset:2048
	ds_read_b128 v[220:223], v214 offset:3072
	ds_read_b128 v[224:227], v214 offset:4096
	ds_read_b128 v[228:231], v214 offset:5120
	ds_read_b128 v[232:235], v214 offset:6144
	ds_read_b128 v[236:239], v214 offset:7168
	global_load_lds_dwordx4 v[202:203], off
	v_lshl_add_u64 v[202:203], s[10:11], 0, v[176:177]
	s_add_i32 m0, s28, 0xe000
	s_nop 0
	global_load_lds_dwordx4 v[202:203], off
	s_waitcnt vmcnt(8)
	s_waitcnt lgkmcnt(0)
	s_setprio 1
	s_barrier
	v_mfma_f32_16x16x32_bf16 v[142:145], v[114:117], v[162:165], 0
	v_mfma_f32_16x16x32_bf16 v[138:141], v[122:125], v[162:165], 0
	s_add_i32 s63, s67, s17
	v_lshl_add_u64 v[202:203], s[94:95], 0, v[174:175]
	s_mov_b32 m0, s63
	v_mfma_f32_16x16x32_bf16 v[110:113], v[114:117], v[216:219], 0
	v_mfma_f32_16x16x32_bf16 v[106:109], v[122:125], v[216:219], 0
	v_mfma_f32_16x16x32_bf16 v[98:101], v[114:117], v[224:227], 0
	v_mfma_f32_16x16x32_bf16 v[90:93], v[122:125], v[224:227], 0
	v_mfma_f32_16x16x32_bf16 v[82:85], v[114:117], v[232:235], 0
	v_mfma_f32_16x16x32_bf16 v[74:77], v[122:125], v[232:235], 0
	v_mfma_f32_16x16x32_bf16 v[142:145], v[118:121], v[166:169], v[142:145]
	v_mfma_f32_16x16x32_bf16 v[138:141], v[126:129], v[166:169], v[138:141]
	v_mfma_f32_16x16x32_bf16 v[110:113], v[118:121], v[220:223], v[110:113]
	v_mfma_f32_16x16x32_bf16 v[106:109], v[126:129], v[220:223], v[106:109]
	v_mfma_f32_16x16x32_bf16 v[98:101], v[118:121], v[228:231], v[98:101]
	v_mfma_f32_16x16x32_bf16 v[90:93], v[126:129], v[228:231], v[90:93]
	v_mfma_f32_16x16x32_bf16 v[82:85], v[118:121], v[236:239], v[82:85]
	v_mfma_f32_16x16x32_bf16 v[74:77], v[126:129], v[236:239], v[74:77]
	v_mfma_f32_16x16x32_bf16 v[134:137], v[146:149], v[162:165], 0
	v_mfma_f32_16x16x32_bf16 v[130:133], v[154:157], v[162:165], 0
	v_mfma_f32_16x16x32_bf16 v[102:105], v[146:149], v[216:219], 0
	v_mfma_f32_16x16x32_bf16 v[94:97], v[154:157], v[216:219], 0
	v_mfma_f32_16x16x32_bf16 v[86:89], v[146:149], v[224:227], 0
	v_mfma_f32_16x16x32_bf16 v[78:81], v[154:157], v[224:227], 0
	v_mfma_f32_16x16x32_bf16 v[70:73], v[146:149], v[232:235], 0
	v_mfma_f32_16x16x32_bf16 v[66:69], v[154:157], v[232:235], 0
	v_mfma_f32_16x16x32_bf16 v[134:137], v[150:153], v[166:169], v[134:137]
	v_mfma_f32_16x16x32_bf16 v[130:133], v[158:161], v[166:169], v[130:133]
	v_mfma_f32_16x16x32_bf16 v[102:105], v[150:153], v[220:223], v[102:105]
	v_mfma_f32_16x16x32_bf16 v[94:97], v[158:161], v[220:223], v[94:97]
	v_mfma_f32_16x16x32_bf16 v[86:89], v[150:153], v[228:231], v[86:89]
	v_mfma_f32_16x16x32_bf16 v[78:81], v[158:161], v[228:231], v[78:81]
	v_mfma_f32_16x16x32_bf16 v[70:73], v[150:153], v[236:239], v[70:73]
	v_mfma_f32_16x16x32_bf16 v[66:69], v[158:161], v[236:239], v[66:69]
	s_setprio 0
	s_barrier
	ds_read_b128 v[162:165], v214 offset:16384
	ds_read_b128 v[166:169], v214 offset:17408
	ds_read_b128 v[216:219], v214 offset:18432
	ds_read_b128 v[220:223], v214 offset:19456
	ds_read_b128 v[224:227], v214 offset:20480
	ds_read_b128 v[228:231], v214 offset:21504
	ds_read_b128 v[232:235], v214 offset:22528
	ds_read_b128 v[236:239], v214 offset:23552
	global_load_lds_dwordx4 v[202:203], off
	s_add_i32 m0, s63, 0x2000
	s_add_u32 s72, s94, 0x40000
	v_lshl_add_u64 v[240:241], s[94:95], 0, v[178:179]
	s_addc_u32 s73, s95, 0
	s_add_i32 s62, s62, s17
	global_load_lds_dwordx4 v[240:241], off
	v_lshl_add_u64 v[242:243], s[72:73], 0, v[174:175]
	s_mov_b32 m0, s62
	v_lshl_add_u64 v[244:245], s[96:97], 0, v[176:177]
	global_load_lds_dwordx4 v[242:243], off
	v_lshl_add_u64 v[242:243], s[72:73], 0, v[178:179]
	s_add_i32 m0, s62, 0x2000
	s_nop 0
	global_load_lds_dwordx4 v[242:243], off
	v_lshl_add_u64 v[242:243], s[96:97], 0, v[172:173]
	s_mov_b32 m0, s28
	s_nop 0
	global_load_lds_dwordx4 v[242:243], off
	s_mov_b32 m0, s29
	s_nop 0
	global_load_lds_dwordx4 v[244:245], off
	s_waitcnt vmcnt(8)
	s_waitcnt lgkmcnt(0)
	s_setprio 1
	s_barrier
	v_mfma_f32_16x16x32_bf16 v[62:65], v[114:117], v[162:165], 0
	v_mfma_f32_16x16x32_bf16 v[58:61], v[122:125], v[162:165], 0
	v_mfma_f32_16x16x32_bf16 v[50:53], v[114:117], v[216:219], 0
	v_mfma_f32_16x16x32_bf16 v[42:45], v[122:125], v[216:219], 0
	v_mfma_f32_16x16x32_bf16 v[34:37], v[114:117], v[224:227], 0
	v_mfma_f32_16x16x32_bf16 v[26:29], v[122:125], v[224:227], 0
	v_mfma_f32_16x16x32_bf16 v[18:21], v[114:117], v[232:235], 0
	v_mfma_f32_16x16x32_bf16 v[10:13], v[122:125], v[232:235], 0
	v_mfma_f32_16x16x32_bf16 v[62:65], v[118:121], v[166:169], v[62:65]
	v_mfma_f32_16x16x32_bf16 v[58:61], v[126:129], v[166:169], v[58:61]
	v_mfma_f32_16x16x32_bf16 v[50:53], v[118:121], v[220:223], v[50:53]
	v_mfma_f32_16x16x32_bf16 v[42:45], v[126:129], v[220:223], v[42:45]
	v_mfma_f32_16x16x32_bf16 v[34:37], v[118:121], v[228:231], v[34:37]
	v_mfma_f32_16x16x32_bf16 v[26:29], v[126:129], v[228:231], v[26:29]
	v_mfma_f32_16x16x32_bf16 v[18:21], v[118:121], v[236:239], v[18:21]
	v_mfma_f32_16x16x32_bf16 v[10:13], v[126:129], v[236:239], v[10:13]
	v_mfma_f32_16x16x32_bf16 v[54:57], v[146:149], v[162:165], 0
	v_mfma_f32_16x16x32_bf16 v[46:49], v[154:157], v[162:165], 0
	v_mfma_f32_16x16x32_bf16 v[38:41], v[146:149], v[216:219], 0
	v_mfma_f32_16x16x32_bf16 v[30:33], v[154:157], v[216:219], 0
	v_mfma_f32_16x16x32_bf16 v[22:25], v[146:149], v[224:227], 0
	v_mfma_f32_16x16x32_bf16 v[14:17], v[154:157], v[224:227], 0
	v_mfma_f32_16x16x32_bf16 v[6:9], v[146:149], v[232:235], 0
	v_mfma_f32_16x16x32_bf16 v[2:5], v[154:157], v[232:235], 0
	v_mfma_f32_16x16x32_bf16 v[54:57], v[150:153], v[166:169], v[54:57]
	v_mfma_f32_16x16x32_bf16 v[46:49], v[158:161], v[166:169], v[46:49]
	v_mfma_f32_16x16x32_bf16 v[38:41], v[150:153], v[220:223], v[38:41]
	v_mfma_f32_16x16x32_bf16 v[30:33], v[158:161], v[220:223], v[30:33]
	v_mfma_f32_16x16x32_bf16 v[22:25], v[150:153], v[228:231], v[22:25]
	v_mfma_f32_16x16x32_bf16 v[14:17], v[158:161], v[228:231], v[14:17]
	v_mfma_f32_16x16x32_bf16 v[6:9], v[150:153], v[236:239], v[6:9]
	v_mfma_f32_16x16x32_bf16 v[2:5], v[158:161], v[236:239], v[2:5]
	s_setprio 0
	s_barrier
	s_add_i32 s62, 0, 0x18000
	s_add_i32 s63, 0, 0x1c000
	v_add_u32_e32 v126, s62, v199
	v_add_u32_e32 v158, s63, v199
	ds_read_b128 v[114:117], v126
	ds_read_b128 v[118:121], v126 offset:1024
	ds_read_b128 v[122:125], v126 offset:2048
	ds_read_b128 v[126:129], v126 offset:3072
	ds_read_b128 v[146:149], v158
	ds_read_b128 v[150:153], v158 offset:1024
	ds_read_b128 v[154:157], v158 offset:2048
	ds_read_b128 v[158:161], v158 offset:3072
	s_add_u32 s72, s96, 0x40000
	s_addc_u32 s73, s97, 0
	s_mov_b32 m0, s30
	v_lshl_add_u64 v[246:247], s[72:73], 0, v[172:173]
	ds_read_b128 v[162:165], v214 offset:32768
	ds_read_b128 v[166:169], v214 offset:33792
	ds_read_b128 v[216:219], v214 offset:34816
	ds_read_b128 v[220:223], v214 offset:35840
	ds_read_b128 v[224:227], v214 offset:36864
	ds_read_b128 v[228:231], v214 offset:37888
	ds_read_b128 v[232:235], v214 offset:38912
	ds_read_b128 v[236:239], v214 offset:39936
	global_load_lds_dwordx4 v[246:247], off
	v_lshl_add_u64 v[246:247], s[72:73], 0, v[176:177]
	s_mov_b32 m0, s31
	s_nop 0
	global_load_lds_dwordx4 v[246:247], off
	s_waitcnt vmcnt(8)
	s_waitcnt lgkmcnt(0)
	s_setprio 1
	s_barrier
	v_mfma_f32_16x16x32_bf16 v[142:145], v[114:117], v[162:165], v[142:145]
	v_mfma_f32_16x16x32_bf16 v[138:141], v[122:125], v[162:165], v[138:141]
	s_add_i32 s62, s62, s17
	v_lshl_add_u64 v[202:203], v[202:203], 0, s[76:77]
	s_mov_b32 m0, s62
	v_mfma_f32_16x16x32_bf16 v[110:113], v[114:117], v[216:219], v[110:113]
	v_mfma_f32_16x16x32_bf16 v[106:109], v[122:125], v[216:219], v[106:109]
	v_mfma_f32_16x16x32_bf16 v[98:101], v[114:117], v[224:227], v[98:101]
	v_mfma_f32_16x16x32_bf16 v[90:93], v[122:125], v[224:227], v[90:93]
	v_mfma_f32_16x16x32_bf16 v[82:85], v[114:117], v[232:235], v[82:85]
	v_mfma_f32_16x16x32_bf16 v[74:77], v[122:125], v[232:235], v[74:77]
	v_mfma_f32_16x16x32_bf16 v[142:145], v[118:121], v[166:169], v[142:145]
	v_mfma_f32_16x16x32_bf16 v[138:141], v[126:129], v[166:169], v[138:141]
	v_mfma_f32_16x16x32_bf16 v[110:113], v[118:121], v[220:223], v[110:113]
	v_mfma_f32_16x16x32_bf16 v[106:109], v[126:129], v[220:223], v[106:109]
	v_mfma_f32_16x16x32_bf16 v[98:101], v[118:121], v[228:231], v[98:101]
	v_mfma_f32_16x16x32_bf16 v[90:93], v[126:129], v[228:231], v[90:93]
	v_mfma_f32_16x16x32_bf16 v[82:85], v[118:121], v[236:239], v[82:85]
	v_mfma_f32_16x16x32_bf16 v[74:77], v[126:129], v[236:239], v[74:77]
	v_mfma_f32_16x16x32_bf16 v[134:137], v[146:149], v[162:165], v[134:137]
	v_mfma_f32_16x16x32_bf16 v[130:133], v[154:157], v[162:165], v[130:133]
	v_mfma_f32_16x16x32_bf16 v[102:105], v[146:149], v[216:219], v[102:105]
	v_mfma_f32_16x16x32_bf16 v[94:97], v[154:157], v[216:219], v[94:97]
	v_mfma_f32_16x16x32_bf16 v[86:89], v[146:149], v[224:227], v[86:89]
	v_mfma_f32_16x16x32_bf16 v[78:81], v[154:157], v[224:227], v[78:81]
	v_mfma_f32_16x16x32_bf16 v[70:73], v[146:149], v[232:235], v[70:73]
	v_mfma_f32_16x16x32_bf16 v[66:69], v[154:157], v[232:235], v[66:69]
	v_mfma_f32_16x16x32_bf16 v[134:137], v[150:153], v[166:169], v[134:137]
	v_mfma_f32_16x16x32_bf16 v[130:133], v[158:161], v[166:169], v[130:133]
	v_mfma_f32_16x16x32_bf16 v[102:105], v[150:153], v[220:223], v[102:105]
	v_mfma_f32_16x16x32_bf16 v[94:97], v[158:161], v[220:223], v[94:97]
	v_mfma_f32_16x16x32_bf16 v[86:89], v[150:153], v[228:231], v[86:89]
	v_mfma_f32_16x16x32_bf16 v[78:81], v[158:161], v[228:231], v[78:81]
	v_mfma_f32_16x16x32_bf16 v[70:73], v[150:153], v[236:239], v[70:73]
	v_mfma_f32_16x16x32_bf16 v[66:69], v[158:161], v[236:239], v[66:69]
	s_setprio 0
	s_barrier
	ds_read_b128 v[162:165], v214 offset:49152
	ds_read_b128 v[166:169], v214 offset:50176
	ds_read_b128 v[216:219], v214 offset:51200
	ds_read_b128 v[220:223], v214 offset:52224
	ds_read_b128 v[224:227], v214 offset:53248
	ds_read_b128 v[228:231], v214 offset:54272
	ds_read_b128 v[232:235], v214 offset:55296
	ds_read_b128 v[236:239], v214 offset:56320
	global_load_lds_dwordx4 v[202:203], off
	s_add_i32 m0, s62, 0x2000
	s_add_u32 s72, s94, 0x40080
	v_lshl_add_u64 v[202:203], v[240:241], 0, s[76:77]
	s_addc_u32 s73, s95, 0
	s_add_i32 s62, s63, s17
	global_load_lds_dwordx4 v[202:203], off
	v_lshl_add_u64 v[202:203], s[72:73], 0, v[174:175]
	s_mov_b32 m0, s62
	s_nop 0
	global_load_lds_dwordx4 v[202:203], off
	v_lshl_add_u64 v[202:203], s[72:73], 0, v[178:179]
	s_add_i32 m0, s62, 0x2000
	s_nop 0
	global_load_lds_dwordx4 v[202:203], off
	v_lshl_add_u64 v[202:203], v[242:243], 0, s[76:77]
	s_mov_b32 m0, s44
	s_nop 0
	global_load_lds_dwordx4 v[202:203], off
	v_lshl_add_u64 v[202:203], v[244:245], 0, s[76:77]
	s_mov_b32 m0, s36
	s_nop 0
	global_load_lds_dwordx4 v[202:203], off
	s_waitcnt vmcnt(8)
	s_waitcnt lgkmcnt(0)
	s_setprio 1
	s_barrier
	v_mfma_f32_16x16x32_bf16 v[62:65], v[114:117], v[162:165], v[62:65]
	v_mfma_f32_16x16x32_bf16 v[58:61], v[122:125], v[162:165], v[58:61]
	s_add_u32 s10, s10, 0x100
	s_addc_u32 s11, s11, 0
	s_add_u32 vcc_lo, vcc_lo, 0x100
	s_addc_u32 vcc_hi, vcc_hi, 0
	s_cmp_ge_i32 s66, s18
	s_mov_b32 s94, s66
	v_mfma_f32_16x16x32_bf16 v[50:53], v[114:117], v[216:219], v[50:53]
	v_mfma_f32_16x16x32_bf16 v[42:45], v[122:125], v[216:219], v[42:45]
	v_mfma_f32_16x16x32_bf16 v[34:37], v[114:117], v[224:227], v[34:37]
	v_mfma_f32_16x16x32_bf16 v[26:29], v[122:125], v[224:227], v[26:29]
	v_mfma_f32_16x16x32_bf16 v[18:21], v[114:117], v[232:235], v[18:21]
	v_mfma_f32_16x16x32_bf16 v[10:13], v[122:125], v[232:235], v[10:13]
	v_mfma_f32_16x16x32_bf16 v[62:65], v[118:121], v[166:169], v[62:65]
	v_mfma_f32_16x16x32_bf16 v[58:61], v[126:129], v[166:169], v[58:61]
	v_mfma_f32_16x16x32_bf16 v[50:53], v[118:121], v[220:223], v[50:53]
	v_mfma_f32_16x16x32_bf16 v[42:45], v[126:129], v[220:223], v[42:45]
	v_mfma_f32_16x16x32_bf16 v[34:37], v[118:121], v[228:231], v[34:37]
	v_mfma_f32_16x16x32_bf16 v[26:29], v[126:129], v[228:231], v[26:29]
	v_mfma_f32_16x16x32_bf16 v[18:21], v[118:121], v[236:239], v[18:21]
	v_mfma_f32_16x16x32_bf16 v[10:13], v[126:129], v[236:239], v[10:13]
	v_mfma_f32_16x16x32_bf16 v[54:57], v[146:149], v[162:165], v[54:57]
	v_mfma_f32_16x16x32_bf16 v[46:49], v[154:157], v[162:165], v[46:49]
	v_mfma_f32_16x16x32_bf16 v[38:41], v[146:149], v[216:219], v[38:41]
	v_mfma_f32_16x16x32_bf16 v[30:33], v[154:157], v[216:219], v[30:33]
	v_mfma_f32_16x16x32_bf16 v[22:25], v[146:149], v[224:227], v[22:25]
	v_mfma_f32_16x16x32_bf16 v[14:17], v[154:157], v[224:227], v[14:17]
	v_mfma_f32_16x16x32_bf16 v[6:9], v[146:149], v[232:235], v[6:9]
	v_mfma_f32_16x16x32_bf16 v[2:5], v[154:157], v[232:235], v[2:5]
	v_mfma_f32_16x16x32_bf16 v[54:57], v[150:153], v[166:169], v[54:57]
	v_mfma_f32_16x16x32_bf16 v[46:49], v[158:161], v[166:169], v[46:49]
	v_mfma_f32_16x16x32_bf16 v[38:41], v[150:153], v[220:223], v[38:41]
	v_mfma_f32_16x16x32_bf16 v[30:33], v[158:161], v[220:223], v[30:33]
	v_mfma_f32_16x16x32_bf16 v[22:25], v[150:153], v[228:231], v[22:25]
	v_mfma_f32_16x16x32_bf16 v[14:17], v[158:161], v[228:231], v[14:17]
	v_mfma_f32_16x16x32_bf16 v[6:9], v[150:153], v[236:239], v[6:9]
	v_mfma_f32_16x16x32_bf16 v[2:5], v[158:161], v[236:239], v[2:5]
	s_setprio 0
	s_barrier
.LBB0_1428:
	s_add_i32 s66, s94, 2
	s_add_u32 s67, s10, 0xfffc0080
	s_addc_u32 s72, s11, -1
	s_cmp_eq_u32 s85, s94
	s_cselect_b32 s97, s14, s72
	s_cselect_b32 s96, s15, s67
	s_cselect_b32 s95, s51, vcc_hi
	s_cselect_b32 s94, s84, vcc_lo
	s_add_i32 s67, 0, 0x10000
	s_add_i32 s62, 0, 0x14000
	v_add_u32_e32 v126, s67, v199
	v_add_u32_e32 v158, s62, v199
	ds_read_b128 v[114:117], v126
	ds_read_b128 v[118:121], v126 offset:1024
	ds_read_b128 v[122:125], v126 offset:2048
	ds_read_b128 v[126:129], v126 offset:3072
	ds_read_b128 v[146:149], v158
	ds_read_b128 v[150:153], v158 offset:1024
	ds_read_b128 v[154:157], v158 offset:2048
	ds_read_b128 v[158:161], v158 offset:3072
	v_lshl_add_u64 v[202:203], s[10:11], 0, v[196:197]
	s_add_i32 m0, s28, 0xc000
	ds_read_b128 v[162:165], v214
	ds_read_b128 v[166:169], v214 offset:1024
	ds_read_b128 v[216:219], v214 offset:2048
	ds_read_b128 v[220:223], v214 offset:3072
	ds_read_b128 v[224:227], v214 offset:4096
	ds_read_b128 v[228:231], v214 offset:5120
	ds_read_b128 v[232:235], v214 offset:6144
	ds_read_b128 v[236:239], v214 offset:7168
	global_load_lds_dwordx4 v[202:203], off
	v_lshl_add_u64 v[202:203], s[10:11], 0, v[176:177]
	s_add_i32 m0, s28, 0xe000
	s_nop 0
	global_load_lds_dwordx4 v[202:203], off
	s_waitcnt vmcnt(8)
	s_waitcnt lgkmcnt(0)
	s_setprio 1
	s_barrier
	v_mfma_f32_16x16x32_bf16 v[142:145], v[114:117], v[162:165], v[142:145]
	v_mfma_f32_16x16x32_bf16 v[138:141], v[122:125], v[162:165], v[138:141]
	s_add_i32 s63, s67, s17
	v_lshl_add_u64 v[202:203], s[94:95], 0, v[174:175]
	s_mov_b32 m0, s63
	v_mfma_f32_16x16x32_bf16 v[110:113], v[114:117], v[216:219], v[110:113]
	v_mfma_f32_16x16x32_bf16 v[106:109], v[122:125], v[216:219], v[106:109]
	v_mfma_f32_16x16x32_bf16 v[98:101], v[114:117], v[224:227], v[98:101]
	v_mfma_f32_16x16x32_bf16 v[90:93], v[122:125], v[224:227], v[90:93]
	v_mfma_f32_16x16x32_bf16 v[82:85], v[114:117], v[232:235], v[82:85]
	v_mfma_f32_16x16x32_bf16 v[74:77], v[122:125], v[232:235], v[74:77]
	v_mfma_f32_16x16x32_bf16 v[142:145], v[118:121], v[166:169], v[142:145]
	v_mfma_f32_16x16x32_bf16 v[138:141], v[126:129], v[166:169], v[138:141]
	v_mfma_f32_16x16x32_bf16 v[110:113], v[118:121], v[220:223], v[110:113]
	v_mfma_f32_16x16x32_bf16 v[106:109], v[126:129], v[220:223], v[106:109]
	v_mfma_f32_16x16x32_bf16 v[98:101], v[118:121], v[228:231], v[98:101]
	v_mfma_f32_16x16x32_bf16 v[90:93], v[126:129], v[228:231], v[90:93]
	v_mfma_f32_16x16x32_bf16 v[82:85], v[118:121], v[236:239], v[82:85]
	v_mfma_f32_16x16x32_bf16 v[74:77], v[126:129], v[236:239], v[74:77]
	v_mfma_f32_16x16x32_bf16 v[134:137], v[146:149], v[162:165], v[134:137]
	v_mfma_f32_16x16x32_bf16 v[130:133], v[154:157], v[162:165], v[130:133]
	v_mfma_f32_16x16x32_bf16 v[102:105], v[146:149], v[216:219], v[102:105]
	v_mfma_f32_16x16x32_bf16 v[94:97], v[154:157], v[216:219], v[94:97]
	v_mfma_f32_16x16x32_bf16 v[86:89], v[146:149], v[224:227], v[86:89]
	v_mfma_f32_16x16x32_bf16 v[78:81], v[154:157], v[224:227], v[78:81]
	v_mfma_f32_16x16x32_bf16 v[70:73], v[146:149], v[232:235], v[70:73]
	v_mfma_f32_16x16x32_bf16 v[66:69], v[154:157], v[232:235], v[66:69]
	v_mfma_f32_16x16x32_bf16 v[134:137], v[150:153], v[166:169], v[134:137]
	v_mfma_f32_16x16x32_bf16 v[130:133], v[158:161], v[166:169], v[130:133]
	v_mfma_f32_16x16x32_bf16 v[102:105], v[150:153], v[220:223], v[102:105]
	v_mfma_f32_16x16x32_bf16 v[94:97], v[158:161], v[220:223], v[94:97]
	v_mfma_f32_16x16x32_bf16 v[86:89], v[150:153], v[228:231], v[86:89]
	v_mfma_f32_16x16x32_bf16 v[78:81], v[158:161], v[228:231], v[78:81]
	v_mfma_f32_16x16x32_bf16 v[70:73], v[150:153], v[236:239], v[70:73]
	v_mfma_f32_16x16x32_bf16 v[66:69], v[158:161], v[236:239], v[66:69]
	s_setprio 0
	s_barrier
	ds_read_b128 v[162:165], v214 offset:16384
	ds_read_b128 v[166:169], v214 offset:17408
	ds_read_b128 v[216:219], v214 offset:18432
	ds_read_b128 v[220:223], v214 offset:19456
	ds_read_b128 v[224:227], v214 offset:20480
	ds_read_b128 v[228:231], v214 offset:21504
	ds_read_b128 v[232:235], v214 offset:22528
	ds_read_b128 v[236:239], v214 offset:23552
	global_load_lds_dwordx4 v[202:203], off
	s_add_i32 m0, s63, 0x2000
	s_add_u32 s72, s94, 0x40000
	v_lshl_add_u64 v[240:241], s[94:95], 0, v[178:179]
	s_addc_u32 s73, s95, 0
	s_add_i32 s62, s62, s17
	global_load_lds_dwordx4 v[240:241], off
	v_lshl_add_u64 v[242:243], s[72:73], 0, v[174:175]
	s_mov_b32 m0, s62
	v_lshl_add_u64 v[244:245], s[96:97], 0, v[176:177]
	global_load_lds_dwordx4 v[242:243], off
	v_lshl_add_u64 v[242:243], s[72:73], 0, v[178:179]
	s_add_i32 m0, s62, 0x2000
	s_nop 0
	global_load_lds_dwordx4 v[242:243], off
	v_lshl_add_u64 v[242:243], s[96:97], 0, v[172:173]
	s_mov_b32 m0, s28
	s_nop 0
	global_load_lds_dwordx4 v[242:243], off
	s_mov_b32 m0, s29
	s_nop 0
	global_load_lds_dwordx4 v[244:245], off
	s_waitcnt vmcnt(8)
	s_waitcnt lgkmcnt(0)
	s_setprio 1
	s_barrier
	v_mfma_f32_16x16x32_bf16 v[62:65], v[114:117], v[162:165], v[62:65]
	v_mfma_f32_16x16x32_bf16 v[58:61], v[122:125], v[162:165], v[58:61]
	v_mfma_f32_16x16x32_bf16 v[50:53], v[114:117], v[216:219], v[50:53]
	v_mfma_f32_16x16x32_bf16 v[42:45], v[122:125], v[216:219], v[42:45]
	v_mfma_f32_16x16x32_bf16 v[34:37], v[114:117], v[224:227], v[34:37]
	v_mfma_f32_16x16x32_bf16 v[26:29], v[122:125], v[224:227], v[26:29]
	v_mfma_f32_16x16x32_bf16 v[18:21], v[114:117], v[232:235], v[18:21]
	v_mfma_f32_16x16x32_bf16 v[10:13], v[122:125], v[232:235], v[10:13]
	v_mfma_f32_16x16x32_bf16 v[62:65], v[118:121], v[166:169], v[62:65]
	v_mfma_f32_16x16x32_bf16 v[58:61], v[126:129], v[166:169], v[58:61]
	v_mfma_f32_16x16x32_bf16 v[50:53], v[118:121], v[220:223], v[50:53]
	v_mfma_f32_16x16x32_bf16 v[42:45], v[126:129], v[220:223], v[42:45]
	v_mfma_f32_16x16x32_bf16 v[34:37], v[118:121], v[228:231], v[34:37]
	v_mfma_f32_16x16x32_bf16 v[26:29], v[126:129], v[228:231], v[26:29]
	v_mfma_f32_16x16x32_bf16 v[18:21], v[118:121], v[236:239], v[18:21]
	v_mfma_f32_16x16x32_bf16 v[10:13], v[126:129], v[236:239], v[10:13]
	v_mfma_f32_16x16x32_bf16 v[54:57], v[146:149], v[162:165], v[54:57]
	v_mfma_f32_16x16x32_bf16 v[46:49], v[154:157], v[162:165], v[46:49]
	v_mfma_f32_16x16x32_bf16 v[38:41], v[146:149], v[216:219], v[38:41]
	v_mfma_f32_16x16x32_bf16 v[30:33], v[154:157], v[216:219], v[30:33]
	v_mfma_f32_16x16x32_bf16 v[22:25], v[146:149], v[224:227], v[22:25]
	v_mfma_f32_16x16x32_bf16 v[14:17], v[154:157], v[224:227], v[14:17]
	v_mfma_f32_16x16x32_bf16 v[6:9], v[146:149], v[232:235], v[6:9]
	v_mfma_f32_16x16x32_bf16 v[2:5], v[154:157], v[232:235], v[2:5]
	v_mfma_f32_16x16x32_bf16 v[54:57], v[150:153], v[166:169], v[54:57]
	v_mfma_f32_16x16x32_bf16 v[46:49], v[158:161], v[166:169], v[46:49]
	v_mfma_f32_16x16x32_bf16 v[38:41], v[150:153], v[220:223], v[38:41]
	v_mfma_f32_16x16x32_bf16 v[30:33], v[158:161], v[220:223], v[30:33]
	v_mfma_f32_16x16x32_bf16 v[22:25], v[150:153], v[228:231], v[22:25]
	v_mfma_f32_16x16x32_bf16 v[14:17], v[158:161], v[228:231], v[14:17]
	v_mfma_f32_16x16x32_bf16 v[6:9], v[150:153], v[236:239], v[6:9]
	v_mfma_f32_16x16x32_bf16 v[2:5], v[158:161], v[236:239], v[2:5]
	s_setprio 0
	s_barrier
	s_add_i32 s62, 0, 0x18000
	s_add_i32 s63, 0, 0x1c000
	v_add_u32_e32 v126, s62, v199
	v_add_u32_e32 v158, s63, v199
	ds_read_b128 v[114:117], v126
	ds_read_b128 v[118:121], v126 offset:1024
	ds_read_b128 v[122:125], v126 offset:2048
	ds_read_b128 v[126:129], v126 offset:3072
	ds_read_b128 v[146:149], v158
	ds_read_b128 v[150:153], v158 offset:1024
	ds_read_b128 v[154:157], v158 offset:2048
	ds_read_b128 v[158:161], v158 offset:3072
	s_add_u32 s72, s96, 0x40000
	s_addc_u32 s73, s97, 0
	s_mov_b32 m0, s30
	v_lshl_add_u64 v[246:247], s[72:73], 0, v[172:173]
	ds_read_b128 v[162:165], v214 offset:32768
	ds_read_b128 v[166:169], v214 offset:33792
	ds_read_b128 v[216:219], v214 offset:34816
	ds_read_b128 v[220:223], v214 offset:35840
	ds_read_b128 v[224:227], v214 offset:36864
	ds_read_b128 v[228:231], v214 offset:37888
	ds_read_b128 v[232:235], v214 offset:38912
	ds_read_b128 v[236:239], v214 offset:39936
	global_load_lds_dwordx4 v[246:247], off
	v_lshl_add_u64 v[246:247], s[72:73], 0, v[176:177]
	s_mov_b32 m0, s31
	s_nop 0
	global_load_lds_dwordx4 v[246:247], off
	s_waitcnt vmcnt(8)
	s_waitcnt lgkmcnt(0)
	s_setprio 1
	s_barrier
	v_mfma_f32_16x16x32_bf16 v[142:145], v[114:117], v[162:165], v[142:145]
	v_mfma_f32_16x16x32_bf16 v[138:141], v[122:125], v[162:165], v[138:141]
	s_add_i32 s62, s62, s17
	v_lshl_add_u64 v[202:203], v[202:203], 0, s[76:77]
	s_mov_b32 m0, s62
	v_mfma_f32_16x16x32_bf16 v[110:113], v[114:117], v[216:219], v[110:113]
	v_mfma_f32_16x16x32_bf16 v[106:109], v[122:125], v[216:219], v[106:109]
	v_mfma_f32_16x16x32_bf16 v[98:101], v[114:117], v[224:227], v[98:101]
	v_mfma_f32_16x16x32_bf16 v[90:93], v[122:125], v[224:227], v[90:93]
	v_mfma_f32_16x16x32_bf16 v[82:85], v[114:117], v[232:235], v[82:85]
	v_mfma_f32_16x16x32_bf16 v[74:77], v[122:125], v[232:235], v[74:77]
	v_mfma_f32_16x16x32_bf16 v[142:145], v[118:121], v[166:169], v[142:145]
	v_mfma_f32_16x16x32_bf16 v[138:141], v[126:129], v[166:169], v[138:141]
	v_mfma_f32_16x16x32_bf16 v[110:113], v[118:121], v[220:223], v[110:113]
	v_mfma_f32_16x16x32_bf16 v[106:109], v[126:129], v[220:223], v[106:109]
	v_mfma_f32_16x16x32_bf16 v[98:101], v[118:121], v[228:231], v[98:101]
	v_mfma_f32_16x16x32_bf16 v[90:93], v[126:129], v[228:231], v[90:93]
	v_mfma_f32_16x16x32_bf16 v[82:85], v[118:121], v[236:239], v[82:85]
	v_mfma_f32_16x16x32_bf16 v[74:77], v[126:129], v[236:239], v[74:77]
	v_mfma_f32_16x16x32_bf16 v[134:137], v[146:149], v[162:165], v[134:137]
	v_mfma_f32_16x16x32_bf16 v[130:133], v[154:157], v[162:165], v[130:133]
	v_mfma_f32_16x16x32_bf16 v[102:105], v[146:149], v[216:219], v[102:105]
	v_mfma_f32_16x16x32_bf16 v[94:97], v[154:157], v[216:219], v[94:97]
	v_mfma_f32_16x16x32_bf16 v[86:89], v[146:149], v[224:227], v[86:89]
	v_mfma_f32_16x16x32_bf16 v[78:81], v[154:157], v[224:227], v[78:81]
	v_mfma_f32_16x16x32_bf16 v[70:73], v[146:149], v[232:235], v[70:73]
	v_mfma_f32_16x16x32_bf16 v[66:69], v[154:157], v[232:235], v[66:69]
	v_mfma_f32_16x16x32_bf16 v[134:137], v[150:153], v[166:169], v[134:137]
	v_mfma_f32_16x16x32_bf16 v[130:133], v[158:161], v[166:169], v[130:133]
	v_mfma_f32_16x16x32_bf16 v[102:105], v[150:153], v[220:223], v[102:105]
	v_mfma_f32_16x16x32_bf16 v[94:97], v[158:161], v[220:223], v[94:97]
	v_mfma_f32_16x16x32_bf16 v[86:89], v[150:153], v[228:231], v[86:89]
	v_mfma_f32_16x16x32_bf16 v[78:81], v[158:161], v[228:231], v[78:81]
	v_mfma_f32_16x16x32_bf16 v[70:73], v[150:153], v[236:239], v[70:73]
	v_mfma_f32_16x16x32_bf16 v[66:69], v[158:161], v[236:239], v[66:69]
	s_setprio 0
	s_barrier
	ds_read_b128 v[162:165], v214 offset:49152
	ds_read_b128 v[166:169], v214 offset:50176
	ds_read_b128 v[216:219], v214 offset:51200
	ds_read_b128 v[220:223], v214 offset:52224
	ds_read_b128 v[224:227], v214 offset:53248
	ds_read_b128 v[228:231], v214 offset:54272
	ds_read_b128 v[232:235], v214 offset:55296
	ds_read_b128 v[236:239], v214 offset:56320
	global_load_lds_dwordx4 v[202:203], off
	s_add_i32 m0, s62, 0x2000
	s_add_u32 s72, s94, 0x40080
	v_lshl_add_u64 v[202:203], v[240:241], 0, s[76:77]
	s_addc_u32 s73, s95, 0
	s_add_i32 s62, s63, s17
	global_load_lds_dwordx4 v[202:203], off
	v_lshl_add_u64 v[202:203], s[72:73], 0, v[174:175]
	s_mov_b32 m0, s62
	s_nop 0
	global_load_lds_dwordx4 v[202:203], off
	v_lshl_add_u64 v[202:203], s[72:73], 0, v[178:179]
	s_add_i32 m0, s62, 0x2000
	s_nop 0
	global_load_lds_dwordx4 v[202:203], off
	v_lshl_add_u64 v[202:203], v[242:243], 0, s[76:77]
	s_mov_b32 m0, s44
	s_nop 0
	global_load_lds_dwordx4 v[202:203], off
	v_lshl_add_u64 v[202:203], v[244:245], 0, s[76:77]
	s_mov_b32 m0, s36
	s_nop 0
	global_load_lds_dwordx4 v[202:203], off
	s_waitcnt vmcnt(8)
	s_waitcnt lgkmcnt(0)
	s_setprio 1
	s_barrier
	v_mfma_f32_16x16x32_bf16 v[62:65], v[114:117], v[162:165], v[62:65]
	v_mfma_f32_16x16x32_bf16 v[58:61], v[122:125], v[162:165], v[58:61]
	s_add_u32 s10, s10, 0x100
	s_addc_u32 s11, s11, 0
	s_add_u32 vcc_lo, vcc_lo, 0x100
	s_addc_u32 vcc_hi, vcc_hi, 0
	s_cmp_ge_i32 s66, s18
	s_mov_b32 s94, s66
	v_mfma_f32_16x16x32_bf16 v[50:53], v[114:117], v[216:219], v[50:53]
	v_mfma_f32_16x16x32_bf16 v[42:45], v[122:125], v[216:219], v[42:45]
	v_mfma_f32_16x16x32_bf16 v[34:37], v[114:117], v[224:227], v[34:37]
	v_mfma_f32_16x16x32_bf16 v[26:29], v[122:125], v[224:227], v[26:29]
	v_mfma_f32_16x16x32_bf16 v[18:21], v[114:117], v[232:235], v[18:21]
	v_mfma_f32_16x16x32_bf16 v[10:13], v[122:125], v[232:235], v[10:13]
	v_mfma_f32_16x16x32_bf16 v[62:65], v[118:121], v[166:169], v[62:65]
	v_mfma_f32_16x16x32_bf16 v[58:61], v[126:129], v[166:169], v[58:61]
	v_mfma_f32_16x16x32_bf16 v[50:53], v[118:121], v[220:223], v[50:53]
	v_mfma_f32_16x16x32_bf16 v[42:45], v[126:129], v[220:223], v[42:45]
	v_mfma_f32_16x16x32_bf16 v[34:37], v[118:121], v[228:231], v[34:37]
	v_mfma_f32_16x16x32_bf16 v[26:29], v[126:129], v[228:231], v[26:29]
	v_mfma_f32_16x16x32_bf16 v[18:21], v[118:121], v[236:239], v[18:21]
	v_mfma_f32_16x16x32_bf16 v[10:13], v[126:129], v[236:239], v[10:13]
	v_mfma_f32_16x16x32_bf16 v[54:57], v[146:149], v[162:165], v[54:57]
	v_mfma_f32_16x16x32_bf16 v[46:49], v[154:157], v[162:165], v[46:49]
	v_mfma_f32_16x16x32_bf16 v[38:41], v[146:149], v[216:219], v[38:41]
	v_mfma_f32_16x16x32_bf16 v[30:33], v[154:157], v[216:219], v[30:33]
	v_mfma_f32_16x16x32_bf16 v[22:25], v[146:149], v[224:227], v[22:25]
	v_mfma_f32_16x16x32_bf16 v[14:17], v[154:157], v[224:227], v[14:17]
	v_mfma_f32_16x16x32_bf16 v[6:9], v[146:149], v[232:235], v[6:9]
	v_mfma_f32_16x16x32_bf16 v[2:5], v[154:157], v[232:235], v[2:5]
	v_mfma_f32_16x16x32_bf16 v[54:57], v[150:153], v[166:169], v[54:57]
	v_mfma_f32_16x16x32_bf16 v[46:49], v[158:161], v[166:169], v[46:49]
	v_mfma_f32_16x16x32_bf16 v[38:41], v[150:153], v[220:223], v[38:41]
	v_mfma_f32_16x16x32_bf16 v[30:33], v[158:161], v[220:223], v[30:33]
	v_mfma_f32_16x16x32_bf16 v[22:25], v[150:153], v[228:231], v[22:25]
	v_mfma_f32_16x16x32_bf16 v[14:17], v[158:161], v[228:231], v[14:17]
	v_mfma_f32_16x16x32_bf16 v[6:9], v[150:153], v[236:239], v[6:9]
	v_mfma_f32_16x16x32_bf16 v[2:5], v[158:161], v[236:239], v[2:5]
	s_setprio 0
	s_barrier
	s_cbranch_scc0 .LBB0_1428
	s_and_b64 vcc, exec, s[82:83]
	s_cbranch_vccz .LBB0_1431
	s_barrier

.LBB0_1618:
	s_add_u32 s24, s96, s20
	s_addc_u32 s25, s97, s21
	s_and_b64 s[14:15], s[4:5], exec
	s_cselect_b32 s14, s25, s29
	s_cselect_b32 s15, s24, s28
	s_add_u32 s26, s2, s22
	s_addc_u32 s27, s3, s23
	s_and_b64 s[36:37], s[4:5], exec
	s_cselect_b32 s17, s27, s31
	s_cselect_b32 s49, s26, s30
	s_add_u32 s28, s28, 0x40080
	s_addc_u32 s29, s29, 0
	s_add_u32 s50, s30, 0x100
	s_addc_u32 s51, s31, 0
	s_mov_b32 s62, -2
	ds_read_b128 v[154:157], v150
	ds_read_b128 v[158:161], v150 offset:1024
	ds_read_b128 v[162:165], v150 offset:2048
	ds_read_b128 v[166:169], v150 offset:3072
	ds_read_b128 v[170:173], v151
	ds_read_b128 v[174:177], v151 offset:1024
	ds_read_b128 v[178:181], v151 offset:2048
	ds_read_b128 v[182:185], v151 offset:3072
	s_add_u32 s30, s28, 0xfffc0080
	s_addc_u32 s31, s29, -1
	s_cmp_eq_u32 s62, 12
	s_cselect_b32 s37, s14, s31
	s_cselect_b32 s36, s15, s30
	s_cselect_b32 s31, s17, s51
	s_cselect_b32 s30, s49, s50
	v_lshl_add_u64 v[146:147], s[28:29], 0, v[138:139]
	s_add_i32 m0, s19, 0xc000
	ds_read_b128 v[186:189], v152
	ds_read_b128 v[190:193], v152 offset:1024
	ds_read_b128 v[194:197], v152 offset:2048
	ds_read_b128 v[198:201], v152 offset:3072
	ds_read_b128 v[206:209], v152 offset:4096
	ds_read_b128 v[210:213], v152 offset:5120
	ds_read_b128 v[214:217], v152 offset:6144
	ds_read_b128 v[218:221], v152 offset:7168
	global_load_lds_dwordx4 v[146:147], off
	v_lshl_add_u64 v[146:147], s[28:29], 0, v[140:141]
	s_add_i32 m0, s19, 0xe000
	s_nop 0
	global_load_lds_dwordx4 v[146:147], off
	s_waitcnt vmcnt(8)
	s_waitcnt lgkmcnt(0)
	s_setprio 1
	s_barrier
	v_mfma_f32_16x16x32_bf16 v[126:129], v[154:157], v[186:189], 0
	v_mfma_f32_16x16x32_bf16 v[122:125], v[162:165], v[186:189], 0
	s_add_i32 s63, s45, s12
	v_lshl_add_u64 v[146:147], s[30:31], 0, v[134:135]
	s_mov_b32 m0, s63
	v_mfma_f32_16x16x32_bf16 v[110:113], v[154:157], v[194:197], 0
	v_mfma_f32_16x16x32_bf16 v[106:109], v[162:165], v[194:197], 0
	v_mfma_f32_16x16x32_bf16 v[94:97], v[154:157], v[206:209], 0
	v_mfma_f32_16x16x32_bf16 v[90:93], v[162:165], v[206:209], 0
	v_mfma_f32_16x16x32_bf16 v[78:81], v[154:157], v[214:217], 0
	v_mfma_f32_16x16x32_bf16 v[74:77], v[162:165], v[214:217], 0
	v_mfma_f32_16x16x32_bf16 v[126:129], v[158:161], v[190:193], v[126:129]
	v_mfma_f32_16x16x32_bf16 v[122:125], v[166:169], v[190:193], v[122:125]
	v_mfma_f32_16x16x32_bf16 v[110:113], v[158:161], v[198:201], v[110:113]
	v_mfma_f32_16x16x32_bf16 v[106:109], v[166:169], v[198:201], v[106:109]
	v_mfma_f32_16x16x32_bf16 v[94:97], v[158:161], v[210:213], v[94:97]
	v_mfma_f32_16x16x32_bf16 v[90:93], v[166:169], v[210:213], v[90:93]
	v_mfma_f32_16x16x32_bf16 v[78:81], v[158:161], v[218:221], v[78:81]
	v_mfma_f32_16x16x32_bf16 v[74:77], v[166:169], v[218:221], v[74:77]
	v_mfma_f32_16x16x32_bf16 v[118:121], v[170:173], v[186:189], 0
	v_mfma_f32_16x16x32_bf16 v[114:117], v[178:181], v[186:189], 0
	v_mfma_f32_16x16x32_bf16 v[102:105], v[170:173], v[194:197], 0
	v_mfma_f32_16x16x32_bf16 v[98:101], v[178:181], v[194:197], 0
	v_mfma_f32_16x16x32_bf16 v[86:89], v[170:173], v[206:209], 0
	v_mfma_f32_16x16x32_bf16 v[82:85], v[178:181], v[206:209], 0
	v_mfma_f32_16x16x32_bf16 v[70:73], v[170:173], v[214:217], 0
	v_mfma_f32_16x16x32_bf16 v[66:69], v[178:181], v[214:217], 0
	v_mfma_f32_16x16x32_bf16 v[118:121], v[174:177], v[190:193], v[118:121]
	v_mfma_f32_16x16x32_bf16 v[114:117], v[182:185], v[190:193], v[114:117]
	v_mfma_f32_16x16x32_bf16 v[102:105], v[174:177], v[198:201], v[102:105]
	v_mfma_f32_16x16x32_bf16 v[98:101], v[182:185], v[198:201], v[98:101]
	v_mfma_f32_16x16x32_bf16 v[86:89], v[174:177], v[210:213], v[86:89]
	v_mfma_f32_16x16x32_bf16 v[82:85], v[182:185], v[210:213], v[82:85]
	v_mfma_f32_16x16x32_bf16 v[70:73], v[174:177], v[218:221], v[70:73]
	v_mfma_f32_16x16x32_bf16 v[66:69], v[182:185], v[218:221], v[66:69]
	s_setprio 0
	s_barrier
	ds_read_b128 v[186:189], v152 offset:16384
	ds_read_b128 v[190:193], v152 offset:17408
	ds_read_b128 v[194:197], v152 offset:18432
	ds_read_b128 v[198:201], v152 offset:19456
	ds_read_b128 v[206:209], v152 offset:20480
	ds_read_b128 v[210:213], v152 offset:21504
	ds_read_b128 v[214:217], v152 offset:22528
	ds_read_b128 v[218:221], v152 offset:23552
	global_load_lds_dwordx4 v[146:147], off
	s_add_i32 m0, s63, 0x2000
	s_add_u32 s64, s30, 0x40000
	v_lshl_add_u64 v[202:203], s[30:31], 0, v[130:131]
	s_addc_u32 s65, s31, 0
	s_add_i32 s63, s46, s12
	global_load_lds_dwordx4 v[202:203], off
	v_lshl_add_u64 v[222:223], s[64:65], 0, v[134:135]
	s_mov_b32 m0, s63
	v_lshl_add_u64 v[224:225], s[36:37], 0, v[132:133]
	global_load_lds_dwordx4 v[222:223], off
	v_lshl_add_u64 v[222:223], s[64:65], 0, v[130:131]
	s_add_i32 m0, s63, 0x2000
	s_nop 0
	global_load_lds_dwordx4 v[222:223], off
	v_lshl_add_u64 v[222:223], s[36:37], 0, v[136:137]
	s_mov_b32 m0, s19
	s_nop 0
	global_load_lds_dwordx4 v[222:223], off
	s_mov_b32 m0, s33
	s_nop 0
	global_load_lds_dwordx4 v[224:225], off
	s_waitcnt vmcnt(8)
	s_waitcnt lgkmcnt(0)
	s_setprio 1
	s_barrier
	v_mfma_f32_16x16x32_bf16 v[62:65], v[154:157], v[186:189], 0
	v_mfma_f32_16x16x32_bf16 v[58:61], v[162:165], v[186:189], 0
	s_add_i32 s63, 0, 0x18000
	v_add_u32_e32 v153, s63, v149
	s_add_i32 s64, 0, 0x1c000
	v_mfma_f32_16x16x32_bf16 v[46:49], v[154:157], v[194:197], 0
	v_mfma_f32_16x16x32_bf16 v[42:45], v[162:165], v[194:197], 0
	v_mfma_f32_16x16x32_bf16 v[30:33], v[154:157], v[206:209], 0
	v_mfma_f32_16x16x32_bf16 v[26:29], v[162:165], v[206:209], 0
	v_mfma_f32_16x16x32_bf16 v[14:17], v[154:157], v[214:217], 0
	v_mfma_f32_16x16x32_bf16 v[10:13], v[162:165], v[214:217], 0
	v_mfma_f32_16x16x32_bf16 v[62:65], v[158:161], v[190:193], v[62:65]
	v_mfma_f32_16x16x32_bf16 v[58:61], v[166:169], v[190:193], v[58:61]
	v_mfma_f32_16x16x32_bf16 v[46:49], v[158:161], v[198:201], v[46:49]
	v_mfma_f32_16x16x32_bf16 v[42:45], v[166:169], v[198:201], v[42:45]
	v_mfma_f32_16x16x32_bf16 v[30:33], v[158:161], v[210:213], v[30:33]
	v_mfma_f32_16x16x32_bf16 v[26:29], v[166:169], v[210:213], v[26:29]
	v_mfma_f32_16x16x32_bf16 v[14:17], v[158:161], v[218:221], v[14:17]
	v_mfma_f32_16x16x32_bf16 v[10:13], v[166:169], v[218:221], v[10:13]
	v_mfma_f32_16x16x32_bf16 v[54:57], v[170:173], v[186:189], 0
	v_mfma_f32_16x16x32_bf16 v[50:53], v[178:181], v[186:189], 0
	v_mfma_f32_16x16x32_bf16 v[38:41], v[170:173], v[194:197], 0
	v_mfma_f32_16x16x32_bf16 v[34:37], v[178:181], v[194:197], 0
	v_mfma_f32_16x16x32_bf16 v[22:25], v[170:173], v[206:209], 0
	v_mfma_f32_16x16x32_bf16 v[18:21], v[178:181], v[206:209], 0
	v_mfma_f32_16x16x32_bf16 v[6:9], v[170:173], v[214:217], 0
	v_mfma_f32_16x16x32_bf16 v[2:5], v[178:181], v[214:217], 0
	v_mfma_f32_16x16x32_bf16 v[54:57], v[174:177], v[190:193], v[54:57]
	v_mfma_f32_16x16x32_bf16 v[50:53], v[182:185], v[190:193], v[50:53]
	v_mfma_f32_16x16x32_bf16 v[38:41], v[174:177], v[198:201], v[38:41]
	v_mfma_f32_16x16x32_bf16 v[34:37], v[182:185], v[198:201], v[34:37]
	v_mfma_f32_16x16x32_bf16 v[22:25], v[174:177], v[210:213], v[22:25]
	v_mfma_f32_16x16x32_bf16 v[18:21], v[182:185], v[210:213], v[18:21]
	v_mfma_f32_16x16x32_bf16 v[6:9], v[174:177], v[218:221], v[6:9]
	v_mfma_f32_16x16x32_bf16 v[2:5], v[182:185], v[218:221], v[2:5]
	s_setprio 0
	s_barrier
	ds_read_b128 v[154:157], v153
	ds_read_b128 v[158:161], v153 offset:1024
	ds_read_b128 v[162:165], v153 offset:2048
	ds_read_b128 v[166:169], v153 offset:3072
	v_add_u32_e32 v153, s64, v149
	ds_read_b128 v[170:173], v153
	ds_read_b128 v[174:177], v153 offset:1024
	ds_read_b128 v[178:181], v153 offset:2048
	ds_read_b128 v[182:185], v153 offset:3072
	s_add_u32 s36, s36, 0x40000
	s_addc_u32 s37, s37, 0
	s_mov_b32 m0, s35
	v_lshl_add_u64 v[226:227], s[36:37], 0, v[136:137]
	ds_read_b128 v[186:189], v152 offset:32768
	ds_read_b128 v[190:193], v152 offset:33792
	ds_read_b128 v[194:197], v152 offset:34816
	ds_read_b128 v[198:201], v152 offset:35840
	ds_read_b128 v[206:209], v152 offset:36864
	ds_read_b128 v[210:213], v152 offset:37888
	ds_read_b128 v[214:217], v152 offset:38912
	ds_read_b128 v[218:221], v152 offset:39936
	global_load_lds_dwordx4 v[226:227], off
	v_lshl_add_u64 v[226:227], s[36:37], 0, v[132:133]
	s_mov_b32 m0, s38
	s_nop 0
	global_load_lds_dwordx4 v[226:227], off
	s_waitcnt vmcnt(8)
	s_waitcnt lgkmcnt(0)
	s_setprio 1
	s_barrier
	v_mfma_f32_16x16x32_bf16 v[126:129], v[154:157], v[186:189], v[126:129]
	v_mfma_f32_16x16x32_bf16 v[122:125], v[162:165], v[186:189], v[122:125]
	s_add_i32 s36, s63, s12
	v_lshl_add_u64 v[146:147], v[146:147], 0, s[8:9]
	s_mov_b32 m0, s36
	v_mfma_f32_16x16x32_bf16 v[110:113], v[154:157], v[194:197], v[110:113]
	v_mfma_f32_16x16x32_bf16 v[106:109], v[162:165], v[194:197], v[106:109]
	v_mfma_f32_16x16x32_bf16 v[94:97], v[154:157], v[206:209], v[94:97]
	v_mfma_f32_16x16x32_bf16 v[90:93], v[162:165], v[206:209], v[90:93]
	v_mfma_f32_16x16x32_bf16 v[78:81], v[154:157], v[214:217], v[78:81]
	v_mfma_f32_16x16x32_bf16 v[74:77], v[162:165], v[214:217], v[74:77]
	v_mfma_f32_16x16x32_bf16 v[126:129], v[158:161], v[190:193], v[126:129]
	v_mfma_f32_16x16x32_bf16 v[122:125], v[166:169], v[190:193], v[122:125]
	v_mfma_f32_16x16x32_bf16 v[110:113], v[158:161], v[198:201], v[110:113]
	v_mfma_f32_16x16x32_bf16 v[106:109], v[166:169], v[198:201], v[106:109]
	v_mfma_f32_16x16x32_bf16 v[94:97], v[158:161], v[210:213], v[94:97]
	v_mfma_f32_16x16x32_bf16 v[90:93], v[166:169], v[210:213], v[90:93]
	v_mfma_f32_16x16x32_bf16 v[78:81], v[158:161], v[218:221], v[78:81]
	v_mfma_f32_16x16x32_bf16 v[74:77], v[166:169], v[218:221], v[74:77]
	v_mfma_f32_16x16x32_bf16 v[118:121], v[170:173], v[186:189], v[118:121]
	v_mfma_f32_16x16x32_bf16 v[114:117], v[178:181], v[186:189], v[114:117]
	v_mfma_f32_16x16x32_bf16 v[102:105], v[170:173], v[194:197], v[102:105]
	v_mfma_f32_16x16x32_bf16 v[98:101], v[178:181], v[194:197], v[98:101]
	v_mfma_f32_16x16x32_bf16 v[86:89], v[170:173], v[206:209], v[86:89]
	v_mfma_f32_16x16x32_bf16 v[82:85], v[178:181], v[206:209], v[82:85]
	v_mfma_f32_16x16x32_bf16 v[70:73], v[170:173], v[214:217], v[70:73]
	v_mfma_f32_16x16x32_bf16 v[66:69], v[178:181], v[214:217], v[66:69]
	v_mfma_f32_16x16x32_bf16 v[118:121], v[174:177], v[190:193], v[118:121]
	v_mfma_f32_16x16x32_bf16 v[114:117], v[182:185], v[190:193], v[114:117]
	v_mfma_f32_16x16x32_bf16 v[102:105], v[174:177], v[198:201], v[102:105]
	v_mfma_f32_16x16x32_bf16 v[98:101], v[182:185], v[198:201], v[98:101]
	v_mfma_f32_16x16x32_bf16 v[86:89], v[174:177], v[210:213], v[86:89]
	v_mfma_f32_16x16x32_bf16 v[82:85], v[182:185], v[210:213], v[82:85]
	v_mfma_f32_16x16x32_bf16 v[70:73], v[174:177], v[218:221], v[70:73]
	v_mfma_f32_16x16x32_bf16 v[66:69], v[182:185], v[218:221], v[66:69]
	s_setprio 0
	s_barrier
	ds_read_b128 v[186:189], v152 offset:49152
	ds_read_b128 v[190:193], v152 offset:50176
	ds_read_b128 v[194:197], v152 offset:51200
	ds_read_b128 v[198:201], v152 offset:52224
	ds_read_b128 v[206:209], v152 offset:53248
	ds_read_b128 v[210:213], v152 offset:54272
	ds_read_b128 v[214:217], v152 offset:55296
	ds_read_b128 v[218:221], v152 offset:56320
	global_load_lds_dwordx4 v[146:147], off
	s_add_i32 m0, s36, 0x2000
	s_add_u32 s30, s30, 0x40080
	v_lshl_add_u64 v[146:147], v[202:203], 0, s[8:9]
	s_addc_u32 s31, s31, 0
	s_add_i32 s36, s64, s12
	global_load_lds_dwordx4 v[146:147], off
	v_lshl_add_u64 v[146:147], s[30:31], 0, v[134:135]
	s_mov_b32 m0, s36
	s_nop 0
	global_load_lds_dwordx4 v[146:147], off
	v_lshl_add_u64 v[146:147], s[30:31], 0, v[130:131]
	s_add_i32 m0, s36, 0x2000
	s_nop 0
	global_load_lds_dwordx4 v[146:147], off
	v_lshl_add_u64 v[146:147], v[222:223], 0, s[8:9]
	s_mov_b32 m0, s42
	s_nop 0
	global_load_lds_dwordx4 v[146:147], off
	v_lshl_add_u64 v[146:147], v[224:225], 0, s[8:9]
	s_mov_b32 m0, s43
	s_nop 0
	global_load_lds_dwordx4 v[146:147], off
	s_waitcnt vmcnt(8)
	s_waitcnt lgkmcnt(0)
	s_setprio 1
	s_barrier
	v_mfma_f32_16x16x32_bf16 v[62:65], v[154:157], v[186:189], v[62:65]
	v_mfma_f32_16x16x32_bf16 v[58:61], v[162:165], v[186:189], v[58:61]
	s_add_i32 s62, s62, 2
	s_add_u32 s28, s28, 0x100
	s_addc_u32 s29, s29, 0
	s_add_u32 s50, s50, 0x100
	s_addc_u32 s51, s51, 0
	s_cmp_gt_u32 s62, 13
	v_mfma_f32_16x16x32_bf16 v[46:49], v[154:157], v[194:197], v[46:49]
	v_mfma_f32_16x16x32_bf16 v[42:45], v[162:165], v[194:197], v[42:45]
	v_mfma_f32_16x16x32_bf16 v[30:33], v[154:157], v[206:209], v[30:33]
	v_mfma_f32_16x16x32_bf16 v[26:29], v[162:165], v[206:209], v[26:29]
	v_mfma_f32_16x16x32_bf16 v[14:17], v[154:157], v[214:217], v[14:17]
	v_mfma_f32_16x16x32_bf16 v[10:13], v[162:165], v[214:217], v[10:13]
	v_mfma_f32_16x16x32_bf16 v[62:65], v[158:161], v[190:193], v[62:65]
	v_mfma_f32_16x16x32_bf16 v[58:61], v[166:169], v[190:193], v[58:61]
	v_mfma_f32_16x16x32_bf16 v[46:49], v[158:161], v[198:201], v[46:49]
	v_mfma_f32_16x16x32_bf16 v[42:45], v[166:169], v[198:201], v[42:45]
	v_mfma_f32_16x16x32_bf16 v[30:33], v[158:161], v[210:213], v[30:33]
	v_mfma_f32_16x16x32_bf16 v[26:29], v[166:169], v[210:213], v[26:29]
	v_mfma_f32_16x16x32_bf16 v[14:17], v[158:161], v[218:221], v[14:17]
	v_mfma_f32_16x16x32_bf16 v[10:13], v[166:169], v[218:221], v[10:13]
	v_mfma_f32_16x16x32_bf16 v[54:57], v[170:173], v[186:189], v[54:57]
	v_mfma_f32_16x16x32_bf16 v[50:53], v[178:181], v[186:189], v[50:53]
	v_mfma_f32_16x16x32_bf16 v[38:41], v[170:173], v[194:197], v[38:41]
	v_mfma_f32_16x16x32_bf16 v[34:37], v[178:181], v[194:197], v[34:37]
	v_mfma_f32_16x16x32_bf16 v[22:25], v[170:173], v[206:209], v[22:25]
	v_mfma_f32_16x16x32_bf16 v[18:21], v[178:181], v[206:209], v[18:21]
	v_mfma_f32_16x16x32_bf16 v[6:9], v[170:173], v[214:217], v[6:9]
	v_mfma_f32_16x16x32_bf16 v[2:5], v[178:181], v[214:217], v[2:5]
	v_mfma_f32_16x16x32_bf16 v[54:57], v[174:177], v[190:193], v[54:57]
	v_mfma_f32_16x16x32_bf16 v[50:53], v[182:185], v[190:193], v[50:53]
	v_mfma_f32_16x16x32_bf16 v[38:41], v[174:177], v[198:201], v[38:41]
	v_mfma_f32_16x16x32_bf16 v[34:37], v[182:185], v[198:201], v[34:37]
	v_mfma_f32_16x16x32_bf16 v[22:25], v[174:177], v[210:213], v[22:25]
	v_mfma_f32_16x16x32_bf16 v[18:21], v[182:185], v[210:213], v[18:21]
	v_mfma_f32_16x16x32_bf16 v[6:9], v[174:177], v[218:221], v[6:9]
	v_mfma_f32_16x16x32_bf16 v[2:5], v[182:185], v[218:221], v[2:5]
	s_setprio 0
	s_barrier
.LBB0_1619:
	ds_read_b128 v[154:157], v150
	ds_read_b128 v[158:161], v150 offset:1024
	ds_read_b128 v[162:165], v150 offset:2048
	ds_read_b128 v[166:169], v150 offset:3072
	ds_read_b128 v[170:173], v151
	ds_read_b128 v[174:177], v151 offset:1024
	ds_read_b128 v[178:181], v151 offset:2048
	ds_read_b128 v[182:185], v151 offset:3072
	s_add_u32 s30, s28, 0xfffc0080
	s_addc_u32 s31, s29, -1
	s_cmp_eq_u32 s62, 12
	s_cselect_b32 s37, s14, s31
	s_cselect_b32 s36, s15, s30
	s_cselect_b32 s31, s17, s51
	s_cselect_b32 s30, s49, s50
	v_lshl_add_u64 v[146:147], s[28:29], 0, v[138:139]
	s_add_i32 m0, s19, 0xc000
	ds_read_b128 v[186:189], v152
	ds_read_b128 v[190:193], v152 offset:1024
	ds_read_b128 v[194:197], v152 offset:2048
	ds_read_b128 v[198:201], v152 offset:3072
	ds_read_b128 v[206:209], v152 offset:4096
	ds_read_b128 v[210:213], v152 offset:5120
	ds_read_b128 v[214:217], v152 offset:6144
	ds_read_b128 v[218:221], v152 offset:7168
	global_load_lds_dwordx4 v[146:147], off
	v_lshl_add_u64 v[146:147], s[28:29], 0, v[140:141]
	s_add_i32 m0, s19, 0xe000
	s_nop 0
	global_load_lds_dwordx4 v[146:147], off
	s_waitcnt vmcnt(8)
	s_waitcnt lgkmcnt(0)
	s_setprio 1
	s_barrier
	v_mfma_f32_16x16x32_bf16 v[126:129], v[154:157], v[186:189], v[126:129]
	v_mfma_f32_16x16x32_bf16 v[122:125], v[162:165], v[186:189], v[122:125]
	s_add_i32 s63, s45, s12
	v_lshl_add_u64 v[146:147], s[30:31], 0, v[134:135]
	s_mov_b32 m0, s63
	v_mfma_f32_16x16x32_bf16 v[110:113], v[154:157], v[194:197], v[110:113]
	v_mfma_f32_16x16x32_bf16 v[106:109], v[162:165], v[194:197], v[106:109]
	v_mfma_f32_16x16x32_bf16 v[94:97], v[154:157], v[206:209], v[94:97]
	v_mfma_f32_16x16x32_bf16 v[90:93], v[162:165], v[206:209], v[90:93]
	v_mfma_f32_16x16x32_bf16 v[78:81], v[154:157], v[214:217], v[78:81]
	v_mfma_f32_16x16x32_bf16 v[74:77], v[162:165], v[214:217], v[74:77]
	v_mfma_f32_16x16x32_bf16 v[126:129], v[158:161], v[190:193], v[126:129]
	v_mfma_f32_16x16x32_bf16 v[122:125], v[166:169], v[190:193], v[122:125]
	v_mfma_f32_16x16x32_bf16 v[110:113], v[158:161], v[198:201], v[110:113]
	v_mfma_f32_16x16x32_bf16 v[106:109], v[166:169], v[198:201], v[106:109]
	v_mfma_f32_16x16x32_bf16 v[94:97], v[158:161], v[210:213], v[94:97]
	v_mfma_f32_16x16x32_bf16 v[90:93], v[166:169], v[210:213], v[90:93]
	v_mfma_f32_16x16x32_bf16 v[78:81], v[158:161], v[218:221], v[78:81]
	v_mfma_f32_16x16x32_bf16 v[74:77], v[166:169], v[218:221], v[74:77]
	v_mfma_f32_16x16x32_bf16 v[118:121], v[170:173], v[186:189], v[118:121]
	v_mfma_f32_16x16x32_bf16 v[114:117], v[178:181], v[186:189], v[114:117]
	v_mfma_f32_16x16x32_bf16 v[102:105], v[170:173], v[194:197], v[102:105]
	v_mfma_f32_16x16x32_bf16 v[98:101], v[178:181], v[194:197], v[98:101]
	v_mfma_f32_16x16x32_bf16 v[86:89], v[170:173], v[206:209], v[86:89]
	v_mfma_f32_16x16x32_bf16 v[82:85], v[178:181], v[206:209], v[82:85]
	v_mfma_f32_16x16x32_bf16 v[70:73], v[170:173], v[214:217], v[70:73]
	v_mfma_f32_16x16x32_bf16 v[66:69], v[178:181], v[214:217], v[66:69]
	v_mfma_f32_16x16x32_bf16 v[118:121], v[174:177], v[190:193], v[118:121]
	v_mfma_f32_16x16x32_bf16 v[114:117], v[182:185], v[190:193], v[114:117]
	v_mfma_f32_16x16x32_bf16 v[102:105], v[174:177], v[198:201], v[102:105]
	v_mfma_f32_16x16x32_bf16 v[98:101], v[182:185], v[198:201], v[98:101]
	v_mfma_f32_16x16x32_bf16 v[86:89], v[174:177], v[210:213], v[86:89]
	v_mfma_f32_16x16x32_bf16 v[82:85], v[182:185], v[210:213], v[82:85]
	v_mfma_f32_16x16x32_bf16 v[70:73], v[174:177], v[218:221], v[70:73]
	v_mfma_f32_16x16x32_bf16 v[66:69], v[182:185], v[218:221], v[66:69]
	s_setprio 0
	s_barrier
	ds_read_b128 v[186:189], v152 offset:16384
	ds_read_b128 v[190:193], v152 offset:17408
	ds_read_b128 v[194:197], v152 offset:18432
	ds_read_b128 v[198:201], v152 offset:19456
	ds_read_b128 v[206:209], v152 offset:20480
	ds_read_b128 v[210:213], v152 offset:21504
	ds_read_b128 v[214:217], v152 offset:22528
	ds_read_b128 v[218:221], v152 offset:23552
	global_load_lds_dwordx4 v[146:147], off
	s_add_i32 m0, s63, 0x2000
	s_add_u32 s64, s30, 0x40000
	v_lshl_add_u64 v[202:203], s[30:31], 0, v[130:131]
	s_addc_u32 s65, s31, 0
	s_add_i32 s63, s46, s12
	global_load_lds_dwordx4 v[202:203], off
	v_lshl_add_u64 v[222:223], s[64:65], 0, v[134:135]
	s_mov_b32 m0, s63
	v_lshl_add_u64 v[224:225], s[36:37], 0, v[132:133]
	global_load_lds_dwordx4 v[222:223], off
	v_lshl_add_u64 v[222:223], s[64:65], 0, v[130:131]
	s_add_i32 m0, s63, 0x2000
	s_nop 0
	global_load_lds_dwordx4 v[222:223], off
	v_lshl_add_u64 v[222:223], s[36:37], 0, v[136:137]
	s_mov_b32 m0, s19
	s_nop 0
	global_load_lds_dwordx4 v[222:223], off
	s_mov_b32 m0, s33
	s_nop 0
	global_load_lds_dwordx4 v[224:225], off
	s_waitcnt vmcnt(8)
	s_waitcnt lgkmcnt(0)
	s_setprio 1
	s_barrier
	v_mfma_f32_16x16x32_bf16 v[62:65], v[154:157], v[186:189], v[62:65]
	v_mfma_f32_16x16x32_bf16 v[58:61], v[162:165], v[186:189], v[58:61]
	s_add_i32 s63, 0, 0x18000
	v_add_u32_e32 v153, s63, v149
	s_add_i32 s64, 0, 0x1c000
	v_mfma_f32_16x16x32_bf16 v[46:49], v[154:157], v[194:197], v[46:49]
	v_mfma_f32_16x16x32_bf16 v[42:45], v[162:165], v[194:197], v[42:45]
	v_mfma_f32_16x16x32_bf16 v[30:33], v[154:157], v[206:209], v[30:33]
	v_mfma_f32_16x16x32_bf16 v[26:29], v[162:165], v[206:209], v[26:29]
	v_mfma_f32_16x16x32_bf16 v[14:17], v[154:157], v[214:217], v[14:17]
	v_mfma_f32_16x16x32_bf16 v[10:13], v[162:165], v[214:217], v[10:13]
	v_mfma_f32_16x16x32_bf16 v[62:65], v[158:161], v[190:193], v[62:65]
	v_mfma_f32_16x16x32_bf16 v[58:61], v[166:169], v[190:193], v[58:61]
	v_mfma_f32_16x16x32_bf16 v[46:49], v[158:161], v[198:201], v[46:49]
	v_mfma_f32_16x16x32_bf16 v[42:45], v[166:169], v[198:201], v[42:45]
	v_mfma_f32_16x16x32_bf16 v[30:33], v[158:161], v[210:213], v[30:33]
	v_mfma_f32_16x16x32_bf16 v[26:29], v[166:169], v[210:213], v[26:29]
	v_mfma_f32_16x16x32_bf16 v[14:17], v[158:161], v[218:221], v[14:17]
	v_mfma_f32_16x16x32_bf16 v[10:13], v[166:169], v[218:221], v[10:13]
	v_mfma_f32_16x16x32_bf16 v[54:57], v[170:173], v[186:189], v[54:57]
	v_mfma_f32_16x16x32_bf16 v[50:53], v[178:181], v[186:189], v[50:53]
	v_mfma_f32_16x16x32_bf16 v[38:41], v[170:173], v[194:197], v[38:41]
	v_mfma_f32_16x16x32_bf16 v[34:37], v[178:181], v[194:197], v[34:37]
	v_mfma_f32_16x16x32_bf16 v[22:25], v[170:173], v[206:209], v[22:25]
	v_mfma_f32_16x16x32_bf16 v[18:21], v[178:181], v[206:209], v[18:21]
	v_mfma_f32_16x16x32_bf16 v[6:9], v[170:173], v[214:217], v[6:9]
	v_mfma_f32_16x16x32_bf16 v[2:5], v[178:181], v[214:217], v[2:5]
	v_mfma_f32_16x16x32_bf16 v[54:57], v[174:177], v[190:193], v[54:57]
	v_mfma_f32_16x16x32_bf16 v[50:53], v[182:185], v[190:193], v[50:53]
	v_mfma_f32_16x16x32_bf16 v[38:41], v[174:177], v[198:201], v[38:41]
	v_mfma_f32_16x16x32_bf16 v[34:37], v[182:185], v[198:201], v[34:37]
	v_mfma_f32_16x16x32_bf16 v[22:25], v[174:177], v[210:213], v[22:25]
	v_mfma_f32_16x16x32_bf16 v[18:21], v[182:185], v[210:213], v[18:21]
	v_mfma_f32_16x16x32_bf16 v[6:9], v[174:177], v[218:221], v[6:9]
	v_mfma_f32_16x16x32_bf16 v[2:5], v[182:185], v[218:221], v[2:5]
	s_setprio 0
	s_barrier
	ds_read_b128 v[154:157], v153
	ds_read_b128 v[158:161], v153 offset:1024
	ds_read_b128 v[162:165], v153 offset:2048
	ds_read_b128 v[166:169], v153 offset:3072
	v_add_u32_e32 v153, s64, v149
	ds_read_b128 v[170:173], v153
	ds_read_b128 v[174:177], v153 offset:1024
	ds_read_b128 v[178:181], v153 offset:2048
	ds_read_b128 v[182:185], v153 offset:3072
	s_add_u32 s36, s36, 0x40000
	s_addc_u32 s37, s37, 0
	s_mov_b32 m0, s35
	v_lshl_add_u64 v[226:227], s[36:37], 0, v[136:137]
	ds_read_b128 v[186:189], v152 offset:32768
	ds_read_b128 v[190:193], v152 offset:33792
	ds_read_b128 v[194:197], v152 offset:34816
	ds_read_b128 v[198:201], v152 offset:35840
	ds_read_b128 v[206:209], v152 offset:36864
	ds_read_b128 v[210:213], v152 offset:37888
	ds_read_b128 v[214:217], v152 offset:38912
	ds_read_b128 v[218:221], v152 offset:39936
	global_load_lds_dwordx4 v[226:227], off
	v_lshl_add_u64 v[226:227], s[36:37], 0, v[132:133]
	s_mov_b32 m0, s38
	s_nop 0
	global_load_lds_dwordx4 v[226:227], off
	s_waitcnt vmcnt(8)
	s_waitcnt lgkmcnt(0)
	s_setprio 1
	s_barrier
	v_mfma_f32_16x16x32_bf16 v[126:129], v[154:157], v[186:189], v[126:129]
	v_mfma_f32_16x16x32_bf16 v[122:125], v[162:165], v[186:189], v[122:125]
	s_add_i32 s36, s63, s12
	v_lshl_add_u64 v[146:147], v[146:147], 0, s[8:9]
	s_mov_b32 m0, s36
	v_mfma_f32_16x16x32_bf16 v[110:113], v[154:157], v[194:197], v[110:113]
	v_mfma_f32_16x16x32_bf16 v[106:109], v[162:165], v[194:197], v[106:109]
	v_mfma_f32_16x16x32_bf16 v[94:97], v[154:157], v[206:209], v[94:97]
	v_mfma_f32_16x16x32_bf16 v[90:93], v[162:165], v[206:209], v[90:93]
	v_mfma_f32_16x16x32_bf16 v[78:81], v[154:157], v[214:217], v[78:81]
	v_mfma_f32_16x16x32_bf16 v[74:77], v[162:165], v[214:217], v[74:77]
	v_mfma_f32_16x16x32_bf16 v[126:129], v[158:161], v[190:193], v[126:129]
	v_mfma_f32_16x16x32_bf16 v[122:125], v[166:169], v[190:193], v[122:125]
	v_mfma_f32_16x16x32_bf16 v[110:113], v[158:161], v[198:201], v[110:113]
	v_mfma_f32_16x16x32_bf16 v[106:109], v[166:169], v[198:201], v[106:109]
	v_mfma_f32_16x16x32_bf16 v[94:97], v[158:161], v[210:213], v[94:97]
	v_mfma_f32_16x16x32_bf16 v[90:93], v[166:169], v[210:213], v[90:93]
	v_mfma_f32_16x16x32_bf16 v[78:81], v[158:161], v[218:221], v[78:81]
	v_mfma_f32_16x16x32_bf16 v[74:77], v[166:169], v[218:221], v[74:77]
	v_mfma_f32_16x16x32_bf16 v[118:121], v[170:173], v[186:189], v[118:121]
	v_mfma_f32_16x16x32_bf16 v[114:117], v[178:181], v[186:189], v[114:117]
	v_mfma_f32_16x16x32_bf16 v[102:105], v[170:173], v[194:197], v[102:105]
	v_mfma_f32_16x16x32_bf16 v[98:101], v[178:181], v[194:197], v[98:101]
	v_mfma_f32_16x16x32_bf16 v[86:89], v[170:173], v[206:209], v[86:89]
	v_mfma_f32_16x16x32_bf16 v[82:85], v[178:181], v[206:209], v[82:85]
	v_mfma_f32_16x16x32_bf16 v[70:73], v[170:173], v[214:217], v[70:73]
	v_mfma_f32_16x16x32_bf16 v[66:69], v[178:181], v[214:217], v[66:69]
	v_mfma_f32_16x16x32_bf16 v[118:121], v[174:177], v[190:193], v[118:121]
	v_mfma_f32_16x16x32_bf16 v[114:117], v[182:185], v[190:193], v[114:117]
	v_mfma_f32_16x16x32_bf16 v[102:105], v[174:177], v[198:201], v[102:105]
	v_mfma_f32_16x16x32_bf16 v[98:101], v[182:185], v[198:201], v[98:101]
	v_mfma_f32_16x16x32_bf16 v[86:89], v[174:177], v[210:213], v[86:89]
	v_mfma_f32_16x16x32_bf16 v[82:85], v[182:185], v[210:213], v[82:85]
	v_mfma_f32_16x16x32_bf16 v[70:73], v[174:177], v[218:221], v[70:73]
	v_mfma_f32_16x16x32_bf16 v[66:69], v[182:185], v[218:221], v[66:69]
	s_setprio 0
	s_barrier
	ds_read_b128 v[186:189], v152 offset:49152
	ds_read_b128 v[190:193], v152 offset:50176
	ds_read_b128 v[194:197], v152 offset:51200
	ds_read_b128 v[198:201], v152 offset:52224
	ds_read_b128 v[206:209], v152 offset:53248
	ds_read_b128 v[210:213], v152 offset:54272
	ds_read_b128 v[214:217], v152 offset:55296
	ds_read_b128 v[218:221], v152 offset:56320
	global_load_lds_dwordx4 v[146:147], off
	s_add_i32 m0, s36, 0x2000
	s_add_u32 s30, s30, 0x40080
	v_lshl_add_u64 v[146:147], v[202:203], 0, s[8:9]
	s_addc_u32 s31, s31, 0
	s_add_i32 s36, s64, s12
	global_load_lds_dwordx4 v[146:147], off
	v_lshl_add_u64 v[146:147], s[30:31], 0, v[134:135]
	s_mov_b32 m0, s36
	s_nop 0
	global_load_lds_dwordx4 v[146:147], off
	v_lshl_add_u64 v[146:147], s[30:31], 0, v[130:131]
	s_add_i32 m0, s36, 0x2000
	s_nop 0
	global_load_lds_dwordx4 v[146:147], off
	v_lshl_add_u64 v[146:147], v[222:223], 0, s[8:9]
	s_mov_b32 m0, s42
	s_nop 0
	global_load_lds_dwordx4 v[146:147], off
	v_lshl_add_u64 v[146:147], v[224:225], 0, s[8:9]
	s_mov_b32 m0, s43
	s_nop 0
	global_load_lds_dwordx4 v[146:147], off
	s_waitcnt vmcnt(8)
	s_waitcnt lgkmcnt(0)
	s_setprio 1
	s_barrier
	v_mfma_f32_16x16x32_bf16 v[62:65], v[154:157], v[186:189], v[62:65]
	v_mfma_f32_16x16x32_bf16 v[58:61], v[162:165], v[186:189], v[58:61]
	s_add_i32 s62, s62, 2
	s_add_u32 s28, s28, 0x100
	s_addc_u32 s29, s29, 0
	s_add_u32 s50, s50, 0x100
	s_addc_u32 s51, s51, 0
	s_cmp_gt_u32 s62, 13
	v_mfma_f32_16x16x32_bf16 v[46:49], v[154:157], v[194:197], v[46:49]
	v_mfma_f32_16x16x32_bf16 v[42:45], v[162:165], v[194:197], v[42:45]
	v_mfma_f32_16x16x32_bf16 v[30:33], v[154:157], v[206:209], v[30:33]
	v_mfma_f32_16x16x32_bf16 v[26:29], v[162:165], v[206:209], v[26:29]
	v_mfma_f32_16x16x32_bf16 v[14:17], v[154:157], v[214:217], v[14:17]
	v_mfma_f32_16x16x32_bf16 v[10:13], v[162:165], v[214:217], v[10:13]
	v_mfma_f32_16x16x32_bf16 v[62:65], v[158:161], v[190:193], v[62:65]
	v_mfma_f32_16x16x32_bf16 v[58:61], v[166:169], v[190:193], v[58:61]
	v_mfma_f32_16x16x32_bf16 v[46:49], v[158:161], v[198:201], v[46:49]
	v_mfma_f32_16x16x32_bf16 v[42:45], v[166:169], v[198:201], v[42:45]
	v_mfma_f32_16x16x32_bf16 v[30:33], v[158:161], v[210:213], v[30:33]
	v_mfma_f32_16x16x32_bf16 v[26:29], v[166:169], v[210:213], v[26:29]
	v_mfma_f32_16x16x32_bf16 v[14:17], v[158:161], v[218:221], v[14:17]
	v_mfma_f32_16x16x32_bf16 v[10:13], v[166:169], v[218:221], v[10:13]
	v_mfma_f32_16x16x32_bf16 v[54:57], v[170:173], v[186:189], v[54:57]
	v_mfma_f32_16x16x32_bf16 v[50:53], v[178:181], v[186:189], v[50:53]
	v_mfma_f32_16x16x32_bf16 v[38:41], v[170:173], v[194:197], v[38:41]
	v_mfma_f32_16x16x32_bf16 v[34:37], v[178:181], v[194:197], v[34:37]
	v_mfma_f32_16x16x32_bf16 v[22:25], v[170:173], v[206:209], v[22:25]
	v_mfma_f32_16x16x32_bf16 v[18:21], v[178:181], v[206:209], v[18:21]
	v_mfma_f32_16x16x32_bf16 v[6:9], v[170:173], v[214:217], v[6:9]
	v_mfma_f32_16x16x32_bf16 v[2:5], v[178:181], v[214:217], v[2:5]
	v_mfma_f32_16x16x32_bf16 v[54:57], v[174:177], v[190:193], v[54:57]
	v_mfma_f32_16x16x32_bf16 v[50:53], v[182:185], v[190:193], v[50:53]
	v_mfma_f32_16x16x32_bf16 v[38:41], v[174:177], v[198:201], v[38:41]
	v_mfma_f32_16x16x32_bf16 v[34:37], v[182:185], v[198:201], v[34:37]
	v_mfma_f32_16x16x32_bf16 v[22:25], v[174:177], v[210:213], v[22:25]
	v_mfma_f32_16x16x32_bf16 v[18:21], v[182:185], v[210:213], v[18:21]
	v_mfma_f32_16x16x32_bf16 v[6:9], v[174:177], v[218:221], v[6:9]
	v_mfma_f32_16x16x32_bf16 v[2:5], v[182:185], v[218:221], v[2:5]
	s_setprio 0
	s_barrier
	s_cbranch_scc0 .LBB0_1619
	s_and_b64 vcc, exec, s[10:11]
	s_cbranch_vccz .LBB0_1622
	s_barrier

.LBB0_1707:
	v_readlane_b32 s46, v249, 32
	v_readlane_b32 s47, v249, 33
	s_add_u32 s46, s46, s42
	s_addc_u32 s47, s47, s43
	s_and_b64 s[48:49], s[44:45], exec
	s_cselect_b32 s34, s47, s51
	s_cselect_b32 s66, s46, s50
	s_add_u32 s48, s35, s40
	s_addc_u32 s49, s70, s41
	s_and_b64 s[64:65], s[44:45], exec
	s_cselect_b32 s67, s49, s63
	s_cselect_b32 s68, s48, s62
	s_add_i32 s69, s7, -2
	s_add_u32 s50, s50, 0x100080
	s_addc_u32 s51, s51, 0
	s_add_u32 s91, s62, 0x100
	s_addc_u32 s92, s63, 0
	s_mov_b32 s62, 0
	s_waitcnt vmcnt(0)
	ds_read_b128 v[130:133], v168
	ds_read_b128 v[134:137], v168 offset:1024
	ds_read_b128 v[138:141], v168 offset:2048
	ds_read_b128 v[142:145], v168 offset:3072
	ds_read_b128 v[162:165], v169
	ds_read_b128 v[172:175], v169 offset:1024
	ds_read_b128 v[176:179], v169 offset:2048
	ds_read_b128 v[180:183], v169 offset:3072
	s_add_i32 s93, s62, 2
	s_add_u32 s63, s50, 0xfff00080
	s_addc_u32 s64, s51, -1
	s_cmp_eq_u32 s69, s62
	s_cselect_b32 s62, s68, s91
	s_cselect_b32 s65, s34, s64
	s_cselect_b32 s64, s66, s63
	s_cselect_b32 s63, s67, s92
	v_lshl_add_u64 v[218:219], s[50:51], 0, v[156:157]
	s_add_i32 m0, s12, 0xc000
	ds_read_b128 v[184:187], v170
	ds_read_b128 v[188:191], v170 offset:1024
	ds_read_b128 v[192:195], v170 offset:2048
	ds_read_b128 v[196:199], v170 offset:3072
	ds_read_b128 v[200:203], v170 offset:4096
	ds_read_b128 v[206:209], v170 offset:5120
	ds_read_b128 v[210:213], v170 offset:6144
	ds_read_b128 v[214:217], v170 offset:7168
	global_load_lds_dwordx4 v[218:219], off
	v_lshl_add_u64 v[218:219], s[50:51], 0, v[158:159]
	s_add_i32 m0, s12, 0xe000
	s_nop 0
	global_load_lds_dwordx4 v[218:219], off
	s_waitcnt vmcnt(8)
	s_waitcnt lgkmcnt(0)
	s_setprio 1
	s_barrier
	v_mfma_f32_16x16x32_bf16 v[126:129], v[130:133], v[184:187], 0
	v_mfma_f32_16x16x32_bf16 v[122:125], v[138:141], v[184:187], 0
	s_add_i32 s94, s31, s2
	v_lshl_add_u64 v[218:219], s[62:63], 0, v[148:149]
	s_mov_b32 m0, s94
	v_mfma_f32_16x16x32_bf16 v[110:113], v[130:133], v[192:195], 0
	v_mfma_f32_16x16x32_bf16 v[106:109], v[138:141], v[192:195], 0
	v_mfma_f32_16x16x32_bf16 v[98:101], v[130:133], v[200:203], 0
	v_mfma_f32_16x16x32_bf16 v[90:93], v[138:141], v[200:203], 0
	v_mfma_f32_16x16x32_bf16 v[82:85], v[130:133], v[210:213], 0
	v_mfma_f32_16x16x32_bf16 v[74:77], v[138:141], v[210:213], 0
	v_mfma_f32_16x16x32_bf16 v[126:129], v[134:137], v[188:191], v[126:129]
	v_mfma_f32_16x16x32_bf16 v[122:125], v[142:145], v[188:191], v[122:125]
	v_mfma_f32_16x16x32_bf16 v[110:113], v[134:137], v[196:199], v[110:113]
	v_mfma_f32_16x16x32_bf16 v[106:109], v[142:145], v[196:199], v[106:109]
	v_mfma_f32_16x16x32_bf16 v[98:101], v[134:137], v[206:209], v[98:101]
	v_mfma_f32_16x16x32_bf16 v[90:93], v[142:145], v[206:209], v[90:93]
	v_mfma_f32_16x16x32_bf16 v[82:85], v[134:137], v[214:217], v[82:85]
	v_mfma_f32_16x16x32_bf16 v[74:77], v[142:145], v[214:217], v[74:77]
	v_mfma_f32_16x16x32_bf16 v[118:121], v[162:165], v[184:187], 0
	v_mfma_f32_16x16x32_bf16 v[114:117], v[176:179], v[184:187], 0
	v_mfma_f32_16x16x32_bf16 v[102:105], v[162:165], v[192:195], 0
	v_mfma_f32_16x16x32_bf16 v[94:97], v[176:179], v[192:195], 0
	v_mfma_f32_16x16x32_bf16 v[86:89], v[162:165], v[200:203], 0
	v_mfma_f32_16x16x32_bf16 v[78:81], v[176:179], v[200:203], 0
	v_mfma_f32_16x16x32_bf16 v[70:73], v[162:165], v[210:213], 0
	v_mfma_f32_16x16x32_bf16 v[66:69], v[176:179], v[210:213], 0
	v_mfma_f32_16x16x32_bf16 v[118:121], v[172:175], v[188:191], v[118:121]
	v_mfma_f32_16x16x32_bf16 v[114:117], v[180:183], v[188:191], v[114:117]
	v_mfma_f32_16x16x32_bf16 v[102:105], v[172:175], v[196:199], v[102:105]
	v_mfma_f32_16x16x32_bf16 v[94:97], v[180:183], v[196:199], v[94:97]
	v_mfma_f32_16x16x32_bf16 v[86:89], v[172:175], v[206:209], v[86:89]
	v_mfma_f32_16x16x32_bf16 v[78:81], v[180:183], v[206:209], v[78:81]
	v_mfma_f32_16x16x32_bf16 v[70:73], v[172:175], v[214:217], v[70:73]
	v_mfma_f32_16x16x32_bf16 v[66:69], v[180:183], v[214:217], v[66:69]
	s_setprio 0
	s_barrier
	ds_read_b128 v[184:187], v170 offset:16384
	ds_read_b128 v[188:191], v170 offset:17408
	ds_read_b128 v[192:195], v170 offset:18432
	ds_read_b128 v[196:199], v170 offset:19456
	ds_read_b128 v[200:203], v170 offset:20480
	ds_read_b128 v[206:209], v170 offset:21504
	ds_read_b128 v[210:213], v170 offset:22528
	ds_read_b128 v[214:217], v170 offset:23552
	global_load_lds_dwordx4 v[218:219], off
	s_add_i32 m0, s94, 0x2000
	s_add_u32 s94, s62, 0x100000
	v_lshl_add_u64 v[220:221], s[62:63], 0, v[152:153]
	s_addc_u32 s95, s63, 0
	s_add_i32 s96, s82, s2
	global_load_lds_dwordx4 v[220:221], off
	v_lshl_add_u64 v[222:223], s[94:95], 0, v[148:149]
	s_mov_b32 m0, s96
	v_lshl_add_u64 v[224:225], s[64:65], 0, v[150:151]
	global_load_lds_dwordx4 v[222:223], off
	v_lshl_add_u64 v[222:223], s[94:95], 0, v[152:153]
	s_add_i32 m0, s96, 0x2000
	s_nop 0
	global_load_lds_dwordx4 v[222:223], off
	v_lshl_add_u64 v[222:223], s[64:65], 0, v[146:147]
	s_mov_b32 m0, s12
	s_nop 0
	global_load_lds_dwordx4 v[222:223], off
	s_mov_b32 m0, s13
	s_nop 0
	global_load_lds_dwordx4 v[224:225], off
	s_waitcnt vmcnt(8)
	s_waitcnt lgkmcnt(0)
	s_setprio 1
	s_barrier
	v_mfma_f32_16x16x32_bf16 v[62:65], v[130:133], v[184:187], 0
	v_mfma_f32_16x16x32_bf16 v[58:61], v[138:141], v[184:187], 0
	v_mfma_f32_16x16x32_bf16 v[50:53], v[130:133], v[192:195], 0
	v_mfma_f32_16x16x32_bf16 v[42:45], v[138:141], v[192:195], 0
	v_mfma_f32_16x16x32_bf16 v[34:37], v[130:133], v[200:203], 0
	v_mfma_f32_16x16x32_bf16 v[26:29], v[138:141], v[200:203], 0
	v_mfma_f32_16x16x32_bf16 v[18:21], v[130:133], v[210:213], 0
	v_mfma_f32_16x16x32_bf16 v[10:13], v[138:141], v[210:213], 0
	v_mfma_f32_16x16x32_bf16 v[62:65], v[134:137], v[188:191], v[62:65]
	v_mfma_f32_16x16x32_bf16 v[58:61], v[142:145], v[188:191], v[58:61]
	v_mfma_f32_16x16x32_bf16 v[50:53], v[134:137], v[196:199], v[50:53]
	v_mfma_f32_16x16x32_bf16 v[42:45], v[142:145], v[196:199], v[42:45]
	v_mfma_f32_16x16x32_bf16 v[34:37], v[134:137], v[206:209], v[34:37]
	v_mfma_f32_16x16x32_bf16 v[26:29], v[142:145], v[206:209], v[26:29]
	v_mfma_f32_16x16x32_bf16 v[18:21], v[134:137], v[214:217], v[18:21]
	v_mfma_f32_16x16x32_bf16 v[10:13], v[142:145], v[214:217], v[10:13]
	v_mfma_f32_16x16x32_bf16 v[54:57], v[162:165], v[184:187], 0
	v_mfma_f32_16x16x32_bf16 v[46:49], v[176:179], v[184:187], 0
	v_mfma_f32_16x16x32_bf16 v[38:41], v[162:165], v[192:195], 0
	v_mfma_f32_16x16x32_bf16 v[30:33], v[176:179], v[192:195], 0
	v_mfma_f32_16x16x32_bf16 v[22:25], v[162:165], v[200:203], 0
	v_mfma_f32_16x16x32_bf16 v[14:17], v[176:179], v[200:203], 0
	v_mfma_f32_16x16x32_bf16 v[6:9], v[162:165], v[210:213], 0
	v_mfma_f32_16x16x32_bf16 v[2:5], v[176:179], v[210:213], 0
	v_mfma_f32_16x16x32_bf16 v[54:57], v[172:175], v[188:191], v[54:57]
	v_mfma_f32_16x16x32_bf16 v[46:49], v[180:183], v[188:191], v[46:49]
	v_mfma_f32_16x16x32_bf16 v[38:41], v[172:175], v[196:199], v[38:41]
	v_mfma_f32_16x16x32_bf16 v[30:33], v[180:183], v[196:199], v[30:33]
	v_mfma_f32_16x16x32_bf16 v[22:25], v[172:175], v[206:209], v[22:25]
	v_mfma_f32_16x16x32_bf16 v[14:17], v[180:183], v[206:209], v[14:17]
	v_mfma_f32_16x16x32_bf16 v[6:9], v[172:175], v[214:217], v[6:9]
	v_mfma_f32_16x16x32_bf16 v[2:5], v[180:183], v[214:217], v[2:5]
	s_setprio 0
	s_barrier
	s_add_i32 s94, 0, 0x18000
	s_add_i32 s95, 0, 0x1c000
	v_add_u32_e32 v142, s94, v167
	v_add_u32_e32 v154, s95, v167
	ds_read_b128 v[130:133], v142
	ds_read_b128 v[134:137], v142 offset:1024
	ds_read_b128 v[138:141], v142 offset:2048
	ds_read_b128 v[142:145], v142 offset:3072
	ds_read_b128 v[162:165], v154
	ds_read_b128 v[172:175], v154 offset:1024
	ds_read_b128 v[176:179], v154 offset:2048
	ds_read_b128 v[180:183], v154 offset:3072
	s_add_u32 s64, s64, 0x100000
	s_addc_u32 s65, s65, 0
	s_mov_b32 m0, s18
	v_lshl_add_u64 v[226:227], s[64:65], 0, v[146:147]
	ds_read_b128 v[184:187], v170 offset:32768
	ds_read_b128 v[188:191], v170 offset:33792
	ds_read_b128 v[192:195], v170 offset:34816
	ds_read_b128 v[196:199], v170 offset:35840
	ds_read_b128 v[200:203], v170 offset:36864
	ds_read_b128 v[206:209], v170 offset:37888
	ds_read_b128 v[210:213], v170 offset:38912
	ds_read_b128 v[214:217], v170 offset:39936
	global_load_lds_dwordx4 v[226:227], off
	v_lshl_add_u64 v[226:227], s[64:65], 0, v[150:151]
	s_mov_b32 m0, s19
	s_nop 0
	global_load_lds_dwordx4 v[226:227], off
	s_waitcnt vmcnt(8)
	s_waitcnt lgkmcnt(0)
	s_setprio 1
	s_barrier
	v_mfma_f32_16x16x32_bf16 v[126:129], v[130:133], v[184:187], v[126:129]
	v_mfma_f32_16x16x32_bf16 v[122:125], v[138:141], v[184:187], v[122:125]
	s_add_i32 s64, s94, s2
	v_lshl_add_u64 v[218:219], v[218:219], 0, s[16:17]
	s_mov_b32 m0, s64
	v_mfma_f32_16x16x32_bf16 v[110:113], v[130:133], v[192:195], v[110:113]
	v_mfma_f32_16x16x32_bf16 v[106:109], v[138:141], v[192:195], v[106:109]
	v_mfma_f32_16x16x32_bf16 v[98:101], v[130:133], v[200:203], v[98:101]
	v_mfma_f32_16x16x32_bf16 v[90:93], v[138:141], v[200:203], v[90:93]
	v_mfma_f32_16x16x32_bf16 v[82:85], v[130:133], v[210:213], v[82:85]
	v_mfma_f32_16x16x32_bf16 v[74:77], v[138:141], v[210:213], v[74:77]
	v_mfma_f32_16x16x32_bf16 v[126:129], v[134:137], v[188:191], v[126:129]
	v_mfma_f32_16x16x32_bf16 v[122:125], v[142:145], v[188:191], v[122:125]
	v_mfma_f32_16x16x32_bf16 v[110:113], v[134:137], v[196:199], v[110:113]
	v_mfma_f32_16x16x32_bf16 v[106:109], v[142:145], v[196:199], v[106:109]
	v_mfma_f32_16x16x32_bf16 v[98:101], v[134:137], v[206:209], v[98:101]
	v_mfma_f32_16x16x32_bf16 v[90:93], v[142:145], v[206:209], v[90:93]
	v_mfma_f32_16x16x32_bf16 v[82:85], v[134:137], v[214:217], v[82:85]
	v_mfma_f32_16x16x32_bf16 v[74:77], v[142:145], v[214:217], v[74:77]
	v_mfma_f32_16x16x32_bf16 v[118:121], v[162:165], v[184:187], v[118:121]
	v_mfma_f32_16x16x32_bf16 v[114:117], v[176:179], v[184:187], v[114:117]
	v_mfma_f32_16x16x32_bf16 v[102:105], v[162:165], v[192:195], v[102:105]
	v_mfma_f32_16x16x32_bf16 v[94:97], v[176:179], v[192:195], v[94:97]
	v_mfma_f32_16x16x32_bf16 v[86:89], v[162:165], v[200:203], v[86:89]
	v_mfma_f32_16x16x32_bf16 v[78:81], v[176:179], v[200:203], v[78:81]
	v_mfma_f32_16x16x32_bf16 v[70:73], v[162:165], v[210:213], v[70:73]
	v_mfma_f32_16x16x32_bf16 v[66:69], v[176:179], v[210:213], v[66:69]
	v_mfma_f32_16x16x32_bf16 v[118:121], v[172:175], v[188:191], v[118:121]
	v_mfma_f32_16x16x32_bf16 v[114:117], v[180:183], v[188:191], v[114:117]
	v_mfma_f32_16x16x32_bf16 v[102:105], v[172:175], v[196:199], v[102:105]
	v_mfma_f32_16x16x32_bf16 v[94:97], v[180:183], v[196:199], v[94:97]
	v_mfma_f32_16x16x32_bf16 v[86:89], v[172:175], v[206:209], v[86:89]
	v_mfma_f32_16x16x32_bf16 v[78:81], v[180:183], v[206:209], v[78:81]
	v_mfma_f32_16x16x32_bf16 v[70:73], v[172:175], v[214:217], v[70:73]
	v_mfma_f32_16x16x32_bf16 v[66:69], v[180:183], v[214:217], v[66:69]
	s_setprio 0
	s_barrier
	ds_read_b128 v[184:187], v170 offset:49152
	ds_read_b128 v[188:191], v170 offset:50176
	ds_read_b128 v[192:195], v170 offset:51200
	ds_read_b128 v[196:199], v170 offset:52224
	ds_read_b128 v[200:203], v170 offset:53248
	ds_read_b128 v[206:209], v170 offset:54272
	ds_read_b128 v[210:213], v170 offset:55296
	ds_read_b128 v[214:217], v170 offset:56320
	global_load_lds_dwordx4 v[218:219], off
	s_add_i32 m0, s64, 0x2000
	s_add_u32 s62, s62, 0x100080
	v_lshl_add_u64 v[218:219], v[220:221], 0, s[16:17]
	s_addc_u32 s63, s63, 0
	s_add_i32 s64, s95, s2
	global_load_lds_dwordx4 v[218:219], off
	v_lshl_add_u64 v[218:219], s[62:63], 0, v[148:149]
	s_mov_b32 m0, s64
	s_nop 0
	global_load_lds_dwordx4 v[218:219], off
	v_lshl_add_u64 v[218:219], s[62:63], 0, v[152:153]
	s_add_i32 m0, s64, 0x2000
	s_nop 0
	global_load_lds_dwordx4 v[218:219], off
	v_lshl_add_u64 v[218:219], v[222:223], 0, s[16:17]
	s_mov_b32 m0, s74
	s_nop 0
	global_load_lds_dwordx4 v[218:219], off
	v_lshl_add_u64 v[218:219], v[224:225], 0, s[16:17]
	s_mov_b32 m0, s75
	s_nop 0
	global_load_lds_dwordx4 v[218:219], off
	s_waitcnt vmcnt(8)
	s_waitcnt lgkmcnt(0)
	s_setprio 1
	s_barrier
	v_mfma_f32_16x16x32_bf16 v[62:65], v[130:133], v[184:187], v[62:65]
	v_mfma_f32_16x16x32_bf16 v[58:61], v[138:141], v[184:187], v[58:61]
	s_add_u32 s50, s50, 0x100
	s_addc_u32 s51, s51, 0
	s_add_u32 s91, s91, 0x100
	s_addc_u32 s92, s92, 0
	s_cmp_ge_i32 s93, s7
	s_mov_b32 s62, s93
	v_mfma_f32_16x16x32_bf16 v[50:53], v[130:133], v[192:195], v[50:53]
	v_mfma_f32_16x16x32_bf16 v[42:45], v[138:141], v[192:195], v[42:45]
	v_mfma_f32_16x16x32_bf16 v[34:37], v[130:133], v[200:203], v[34:37]
	v_mfma_f32_16x16x32_bf16 v[26:29], v[138:141], v[200:203], v[26:29]
	v_mfma_f32_16x16x32_bf16 v[18:21], v[130:133], v[210:213], v[18:21]
	v_mfma_f32_16x16x32_bf16 v[10:13], v[138:141], v[210:213], v[10:13]
	v_mfma_f32_16x16x32_bf16 v[62:65], v[134:137], v[188:191], v[62:65]
	v_mfma_f32_16x16x32_bf16 v[58:61], v[142:145], v[188:191], v[58:61]
	v_mfma_f32_16x16x32_bf16 v[50:53], v[134:137], v[196:199], v[50:53]
	v_mfma_f32_16x16x32_bf16 v[42:45], v[142:145], v[196:199], v[42:45]
	v_mfma_f32_16x16x32_bf16 v[34:37], v[134:137], v[206:209], v[34:37]
	v_mfma_f32_16x16x32_bf16 v[26:29], v[142:145], v[206:209], v[26:29]
	v_mfma_f32_16x16x32_bf16 v[18:21], v[134:137], v[214:217], v[18:21]
	v_mfma_f32_16x16x32_bf16 v[10:13], v[142:145], v[214:217], v[10:13]
	v_mfma_f32_16x16x32_bf16 v[54:57], v[162:165], v[184:187], v[54:57]
	v_mfma_f32_16x16x32_bf16 v[46:49], v[176:179], v[184:187], v[46:49]
	v_mfma_f32_16x16x32_bf16 v[38:41], v[162:165], v[192:195], v[38:41]
	v_mfma_f32_16x16x32_bf16 v[30:33], v[176:179], v[192:195], v[30:33]
	v_mfma_f32_16x16x32_bf16 v[22:25], v[162:165], v[200:203], v[22:25]
	v_mfma_f32_16x16x32_bf16 v[14:17], v[176:179], v[200:203], v[14:17]
	v_mfma_f32_16x16x32_bf16 v[6:9], v[162:165], v[210:213], v[6:9]
	v_mfma_f32_16x16x32_bf16 v[2:5], v[176:179], v[210:213], v[2:5]
	v_mfma_f32_16x16x32_bf16 v[54:57], v[172:175], v[188:191], v[54:57]
	v_mfma_f32_16x16x32_bf16 v[46:49], v[180:183], v[188:191], v[46:49]
	v_mfma_f32_16x16x32_bf16 v[38:41], v[172:175], v[196:199], v[38:41]
	v_mfma_f32_16x16x32_bf16 v[30:33], v[180:183], v[196:199], v[30:33]
	v_mfma_f32_16x16x32_bf16 v[22:25], v[172:175], v[206:209], v[22:25]
	v_mfma_f32_16x16x32_bf16 v[14:17], v[180:183], v[206:209], v[14:17]
	v_mfma_f32_16x16x32_bf16 v[6:9], v[172:175], v[214:217], v[6:9]
	v_mfma_f32_16x16x32_bf16 v[2:5], v[180:183], v[214:217], v[2:5]
	s_setprio 0
	s_barrier
.LBB0_1708:
	ds_read_b128 v[130:133], v168
	ds_read_b128 v[134:137], v168 offset:1024
	ds_read_b128 v[138:141], v168 offset:2048
	ds_read_b128 v[142:145], v168 offset:3072
	ds_read_b128 v[162:165], v169
	ds_read_b128 v[172:175], v169 offset:1024
	ds_read_b128 v[176:179], v169 offset:2048
	ds_read_b128 v[180:183], v169 offset:3072
	s_add_i32 s93, s62, 2
	s_add_u32 s63, s50, 0xfff00080
	s_addc_u32 s64, s51, -1
	s_cmp_eq_u32 s69, s62
	s_cselect_b32 s62, s68, s91
	s_cselect_b32 s65, s34, s64
	s_cselect_b32 s64, s66, s63
	s_cselect_b32 s63, s67, s92
	v_lshl_add_u64 v[218:219], s[50:51], 0, v[156:157]
	s_add_i32 m0, s12, 0xc000
	ds_read_b128 v[184:187], v170
	ds_read_b128 v[188:191], v170 offset:1024
	ds_read_b128 v[192:195], v170 offset:2048
	ds_read_b128 v[196:199], v170 offset:3072
	ds_read_b128 v[200:203], v170 offset:4096
	ds_read_b128 v[206:209], v170 offset:5120
	ds_read_b128 v[210:213], v170 offset:6144
	ds_read_b128 v[214:217], v170 offset:7168
	global_load_lds_dwordx4 v[218:219], off
	v_lshl_add_u64 v[218:219], s[50:51], 0, v[158:159]
	s_add_i32 m0, s12, 0xe000
	s_nop 0
	global_load_lds_dwordx4 v[218:219], off
	s_waitcnt vmcnt(8)
	s_waitcnt lgkmcnt(0)
	s_setprio 1
	s_barrier
	v_mfma_f32_16x16x32_bf16 v[126:129], v[130:133], v[184:187], v[126:129]
	v_mfma_f32_16x16x32_bf16 v[122:125], v[138:141], v[184:187], v[122:125]
	s_add_i32 s94, s31, s2
	v_lshl_add_u64 v[218:219], s[62:63], 0, v[148:149]
	s_mov_b32 m0, s94
	v_mfma_f32_16x16x32_bf16 v[110:113], v[130:133], v[192:195], v[110:113]
	v_mfma_f32_16x16x32_bf16 v[106:109], v[138:141], v[192:195], v[106:109]
	v_mfma_f32_16x16x32_bf16 v[98:101], v[130:133], v[200:203], v[98:101]
	v_mfma_f32_16x16x32_bf16 v[90:93], v[138:141], v[200:203], v[90:93]
	v_mfma_f32_16x16x32_bf16 v[82:85], v[130:133], v[210:213], v[82:85]
	v_mfma_f32_16x16x32_bf16 v[74:77], v[138:141], v[210:213], v[74:77]
	v_mfma_f32_16x16x32_bf16 v[126:129], v[134:137], v[188:191], v[126:129]
	v_mfma_f32_16x16x32_bf16 v[122:125], v[142:145], v[188:191], v[122:125]
	v_mfma_f32_16x16x32_bf16 v[110:113], v[134:137], v[196:199], v[110:113]
	v_mfma_f32_16x16x32_bf16 v[106:109], v[142:145], v[196:199], v[106:109]
	v_mfma_f32_16x16x32_bf16 v[98:101], v[134:137], v[206:209], v[98:101]
	v_mfma_f32_16x16x32_bf16 v[90:93], v[142:145], v[206:209], v[90:93]
	v_mfma_f32_16x16x32_bf16 v[82:85], v[134:137], v[214:217], v[82:85]
	v_mfma_f32_16x16x32_bf16 v[74:77], v[142:145], v[214:217], v[74:77]
	v_mfma_f32_16x16x32_bf16 v[118:121], v[162:165], v[184:187], v[118:121]
	v_mfma_f32_16x16x32_bf16 v[114:117], v[176:179], v[184:187], v[114:117]
	v_mfma_f32_16x16x32_bf16 v[102:105], v[162:165], v[192:195], v[102:105]
	v_mfma_f32_16x16x32_bf16 v[94:97], v[176:179], v[192:195], v[94:97]
	v_mfma_f32_16x16x32_bf16 v[86:89], v[162:165], v[200:203], v[86:89]
	v_mfma_f32_16x16x32_bf16 v[78:81], v[176:179], v[200:203], v[78:81]
	v_mfma_f32_16x16x32_bf16 v[70:73], v[162:165], v[210:213], v[70:73]
	v_mfma_f32_16x16x32_bf16 v[66:69], v[176:179], v[210:213], v[66:69]
	v_mfma_f32_16x16x32_bf16 v[118:121], v[172:175], v[188:191], v[118:121]
	v_mfma_f32_16x16x32_bf16 v[114:117], v[180:183], v[188:191], v[114:117]
	v_mfma_f32_16x16x32_bf16 v[102:105], v[172:175], v[196:199], v[102:105]
	v_mfma_f32_16x16x32_bf16 v[94:97], v[180:183], v[196:199], v[94:97]
	v_mfma_f32_16x16x32_bf16 v[86:89], v[172:175], v[206:209], v[86:89]
	v_mfma_f32_16x16x32_bf16 v[78:81], v[180:183], v[206:209], v[78:81]
	v_mfma_f32_16x16x32_bf16 v[70:73], v[172:175], v[214:217], v[70:73]
	v_mfma_f32_16x16x32_bf16 v[66:69], v[180:183], v[214:217], v[66:69]
	s_setprio 0
	s_barrier
	ds_read_b128 v[184:187], v170 offset:16384
	ds_read_b128 v[188:191], v170 offset:17408
	ds_read_b128 v[192:195], v170 offset:18432
	ds_read_b128 v[196:199], v170 offset:19456
	ds_read_b128 v[200:203], v170 offset:20480
	ds_read_b128 v[206:209], v170 offset:21504
	ds_read_b128 v[210:213], v170 offset:22528
	ds_read_b128 v[214:217], v170 offset:23552
	global_load_lds_dwordx4 v[218:219], off
	s_add_i32 m0, s94, 0x2000
	s_add_u32 s94, s62, 0x100000
	v_lshl_add_u64 v[220:221], s[62:63], 0, v[152:153]
	s_addc_u32 s95, s63, 0
	s_add_i32 s96, s82, s2
	global_load_lds_dwordx4 v[220:221], off
	v_lshl_add_u64 v[222:223], s[94:95], 0, v[148:149]
	s_mov_b32 m0, s96
	v_lshl_add_u64 v[224:225], s[64:65], 0, v[150:151]
	global_load_lds_dwordx4 v[222:223], off
	v_lshl_add_u64 v[222:223], s[94:95], 0, v[152:153]
	s_add_i32 m0, s96, 0x2000
	s_nop 0
	global_load_lds_dwordx4 v[222:223], off
	v_lshl_add_u64 v[222:223], s[64:65], 0, v[146:147]
	s_mov_b32 m0, s12
	s_nop 0
	global_load_lds_dwordx4 v[222:223], off
	s_mov_b32 m0, s13
	s_nop 0
	global_load_lds_dwordx4 v[224:225], off
	s_waitcnt vmcnt(8)
	s_waitcnt lgkmcnt(0)
	s_setprio 1
	s_barrier
	v_mfma_f32_16x16x32_bf16 v[62:65], v[130:133], v[184:187], v[62:65]
	v_mfma_f32_16x16x32_bf16 v[58:61], v[138:141], v[184:187], v[58:61]
	v_mfma_f32_16x16x32_bf16 v[50:53], v[130:133], v[192:195], v[50:53]
	v_mfma_f32_16x16x32_bf16 v[42:45], v[138:141], v[192:195], v[42:45]
	v_mfma_f32_16x16x32_bf16 v[34:37], v[130:133], v[200:203], v[34:37]
	v_mfma_f32_16x16x32_bf16 v[26:29], v[138:141], v[200:203], v[26:29]
	v_mfma_f32_16x16x32_bf16 v[18:21], v[130:133], v[210:213], v[18:21]
	v_mfma_f32_16x16x32_bf16 v[10:13], v[138:141], v[210:213], v[10:13]
	v_mfma_f32_16x16x32_bf16 v[62:65], v[134:137], v[188:191], v[62:65]
	v_mfma_f32_16x16x32_bf16 v[58:61], v[142:145], v[188:191], v[58:61]
	v_mfma_f32_16x16x32_bf16 v[50:53], v[134:137], v[196:199], v[50:53]
	v_mfma_f32_16x16x32_bf16 v[42:45], v[142:145], v[196:199], v[42:45]
	v_mfma_f32_16x16x32_bf16 v[34:37], v[134:137], v[206:209], v[34:37]
	v_mfma_f32_16x16x32_bf16 v[26:29], v[142:145], v[206:209], v[26:29]
	v_mfma_f32_16x16x32_bf16 v[18:21], v[134:137], v[214:217], v[18:21]
	v_mfma_f32_16x16x32_bf16 v[10:13], v[142:145], v[214:217], v[10:13]
	v_mfma_f32_16x16x32_bf16 v[54:57], v[162:165], v[184:187], v[54:57]
	v_mfma_f32_16x16x32_bf16 v[46:49], v[176:179], v[184:187], v[46:49]
	v_mfma_f32_16x16x32_bf16 v[38:41], v[162:165], v[192:195], v[38:41]
	v_mfma_f32_16x16x32_bf16 v[30:33], v[176:179], v[192:195], v[30:33]
	v_mfma_f32_16x16x32_bf16 v[22:25], v[162:165], v[200:203], v[22:25]
	v_mfma_f32_16x16x32_bf16 v[14:17], v[176:179], v[200:203], v[14:17]
	v_mfma_f32_16x16x32_bf16 v[6:9], v[162:165], v[210:213], v[6:9]
	v_mfma_f32_16x16x32_bf16 v[2:5], v[176:179], v[210:213], v[2:5]
	v_mfma_f32_16x16x32_bf16 v[54:57], v[172:175], v[188:191], v[54:57]
	v_mfma_f32_16x16x32_bf16 v[46:49], v[180:183], v[188:191], v[46:49]
	v_mfma_f32_16x16x32_bf16 v[38:41], v[172:175], v[196:199], v[38:41]
	v_mfma_f32_16x16x32_bf16 v[30:33], v[180:183], v[196:199], v[30:33]
	v_mfma_f32_16x16x32_bf16 v[22:25], v[172:175], v[206:209], v[22:25]
	v_mfma_f32_16x16x32_bf16 v[14:17], v[180:183], v[206:209], v[14:17]
	v_mfma_f32_16x16x32_bf16 v[6:9], v[172:175], v[214:217], v[6:9]
	v_mfma_f32_16x16x32_bf16 v[2:5], v[180:183], v[214:217], v[2:5]
	s_setprio 0
	s_barrier
	s_add_i32 s94, 0, 0x18000
	s_add_i32 s95, 0, 0x1c000
	v_add_u32_e32 v142, s94, v167
	v_add_u32_e32 v154, s95, v167
	ds_read_b128 v[130:133], v142
	ds_read_b128 v[134:137], v142 offset:1024
	ds_read_b128 v[138:141], v142 offset:2048
	ds_read_b128 v[142:145], v142 offset:3072
	ds_read_b128 v[162:165], v154
	ds_read_b128 v[172:175], v154 offset:1024
	ds_read_b128 v[176:179], v154 offset:2048
	ds_read_b128 v[180:183], v154 offset:3072
	s_add_u32 s64, s64, 0x100000
	s_addc_u32 s65, s65, 0
	s_mov_b32 m0, s18
	v_lshl_add_u64 v[226:227], s[64:65], 0, v[146:147]
	ds_read_b128 v[184:187], v170 offset:32768
	ds_read_b128 v[188:191], v170 offset:33792
	ds_read_b128 v[192:195], v170 offset:34816
	ds_read_b128 v[196:199], v170 offset:35840
	ds_read_b128 v[200:203], v170 offset:36864
	ds_read_b128 v[206:209], v170 offset:37888
	ds_read_b128 v[210:213], v170 offset:38912
	ds_read_b128 v[214:217], v170 offset:39936
	global_load_lds_dwordx4 v[226:227], off
	v_lshl_add_u64 v[226:227], s[64:65], 0, v[150:151]
	s_mov_b32 m0, s19
	s_nop 0
	global_load_lds_dwordx4 v[226:227], off
	s_waitcnt vmcnt(8)
	s_waitcnt lgkmcnt(0)
	s_setprio 1
	s_barrier
	v_mfma_f32_16x16x32_bf16 v[126:129], v[130:133], v[184:187], v[126:129]
	v_mfma_f32_16x16x32_bf16 v[122:125], v[138:141], v[184:187], v[122:125]
	s_add_i32 s64, s94, s2
	v_lshl_add_u64 v[218:219], v[218:219], 0, s[16:17]
	s_mov_b32 m0, s64
	v_mfma_f32_16x16x32_bf16 v[110:113], v[130:133], v[192:195], v[110:113]
	v_mfma_f32_16x16x32_bf16 v[106:109], v[138:141], v[192:195], v[106:109]
	v_mfma_f32_16x16x32_bf16 v[98:101], v[130:133], v[200:203], v[98:101]
	v_mfma_f32_16x16x32_bf16 v[90:93], v[138:141], v[200:203], v[90:93]
	v_mfma_f32_16x16x32_bf16 v[82:85], v[130:133], v[210:213], v[82:85]
	v_mfma_f32_16x16x32_bf16 v[74:77], v[138:141], v[210:213], v[74:77]
	v_mfma_f32_16x16x32_bf16 v[126:129], v[134:137], v[188:191], v[126:129]
	v_mfma_f32_16x16x32_bf16 v[122:125], v[142:145], v[188:191], v[122:125]
	v_mfma_f32_16x16x32_bf16 v[110:113], v[134:137], v[196:199], v[110:113]
	v_mfma_f32_16x16x32_bf16 v[106:109], v[142:145], v[196:199], v[106:109]
	v_mfma_f32_16x16x32_bf16 v[98:101], v[134:137], v[206:209], v[98:101]
	v_mfma_f32_16x16x32_bf16 v[90:93], v[142:145], v[206:209], v[90:93]
	v_mfma_f32_16x16x32_bf16 v[82:85], v[134:137], v[214:217], v[82:85]
	v_mfma_f32_16x16x32_bf16 v[74:77], v[142:145], v[214:217], v[74:77]
	v_mfma_f32_16x16x32_bf16 v[118:121], v[162:165], v[184:187], v[118:121]
	v_mfma_f32_16x16x32_bf16 v[114:117], v[176:179], v[184:187], v[114:117]
	v_mfma_f32_16x16x32_bf16 v[102:105], v[162:165], v[192:195], v[102:105]
	v_mfma_f32_16x16x32_bf16 v[94:97], v[176:179], v[192:195], v[94:97]
	v_mfma_f32_16x16x32_bf16 v[86:89], v[162:165], v[200:203], v[86:89]
	v_mfma_f32_16x16x32_bf16 v[78:81], v[176:179], v[200:203], v[78:81]
	v_mfma_f32_16x16x32_bf16 v[70:73], v[162:165], v[210:213], v[70:73]
	v_mfma_f32_16x16x32_bf16 v[66:69], v[176:179], v[210:213], v[66:69]
	v_mfma_f32_16x16x32_bf16 v[118:121], v[172:175], v[188:191], v[118:121]
	v_mfma_f32_16x16x32_bf16 v[114:117], v[180:183], v[188:191], v[114:117]
	v_mfma_f32_16x16x32_bf16 v[102:105], v[172:175], v[196:199], v[102:105]
	v_mfma_f32_16x16x32_bf16 v[94:97], v[180:183], v[196:199], v[94:97]
	v_mfma_f32_16x16x32_bf16 v[86:89], v[172:175], v[206:209], v[86:89]
	v_mfma_f32_16x16x32_bf16 v[78:81], v[180:183], v[206:209], v[78:81]
	v_mfma_f32_16x16x32_bf16 v[70:73], v[172:175], v[214:217], v[70:73]
	v_mfma_f32_16x16x32_bf16 v[66:69], v[180:183], v[214:217], v[66:69]
	s_setprio 0
	s_barrier
	ds_read_b128 v[184:187], v170 offset:49152
	ds_read_b128 v[188:191], v170 offset:50176
	ds_read_b128 v[192:195], v170 offset:51200
	ds_read_b128 v[196:199], v170 offset:52224
	ds_read_b128 v[200:203], v170 offset:53248
	ds_read_b128 v[206:209], v170 offset:54272
	ds_read_b128 v[210:213], v170 offset:55296
	ds_read_b128 v[214:217], v170 offset:56320
	global_load_lds_dwordx4 v[218:219], off
	s_add_i32 m0, s64, 0x2000
	s_add_u32 s62, s62, 0x100080
	v_lshl_add_u64 v[218:219], v[220:221], 0, s[16:17]
	s_addc_u32 s63, s63, 0
	s_add_i32 s64, s95, s2
	global_load_lds_dwordx4 v[218:219], off
	v_lshl_add_u64 v[218:219], s[62:63], 0, v[148:149]
	s_mov_b32 m0, s64
	s_nop 0
	global_load_lds_dwordx4 v[218:219], off
	v_lshl_add_u64 v[218:219], s[62:63], 0, v[152:153]
	s_add_i32 m0, s64, 0x2000
	s_nop 0
	global_load_lds_dwordx4 v[218:219], off
	v_lshl_add_u64 v[218:219], v[222:223], 0, s[16:17]
	s_mov_b32 m0, s74
	s_nop 0
	global_load_lds_dwordx4 v[218:219], off
	v_lshl_add_u64 v[218:219], v[224:225], 0, s[16:17]
	s_mov_b32 m0, s75
	s_nop 0
	global_load_lds_dwordx4 v[218:219], off
	s_waitcnt vmcnt(8)
	s_waitcnt lgkmcnt(0)
	s_setprio 1
	s_barrier
	v_mfma_f32_16x16x32_bf16 v[62:65], v[130:133], v[184:187], v[62:65]
	v_mfma_f32_16x16x32_bf16 v[58:61], v[138:141], v[184:187], v[58:61]
	s_add_u32 s50, s50, 0x100
	s_addc_u32 s51, s51, 0
	s_add_u32 s91, s91, 0x100
	s_addc_u32 s92, s92, 0
	s_cmp_ge_i32 s93, s7
	s_mov_b32 s62, s93
	v_mfma_f32_16x16x32_bf16 v[50:53], v[130:133], v[192:195], v[50:53]
	v_mfma_f32_16x16x32_bf16 v[42:45], v[138:141], v[192:195], v[42:45]
	v_mfma_f32_16x16x32_bf16 v[34:37], v[130:133], v[200:203], v[34:37]
	v_mfma_f32_16x16x32_bf16 v[26:29], v[138:141], v[200:203], v[26:29]
	v_mfma_f32_16x16x32_bf16 v[18:21], v[130:133], v[210:213], v[18:21]
	v_mfma_f32_16x16x32_bf16 v[10:13], v[138:141], v[210:213], v[10:13]
	v_mfma_f32_16x16x32_bf16 v[62:65], v[134:137], v[188:191], v[62:65]
	v_mfma_f32_16x16x32_bf16 v[58:61], v[142:145], v[188:191], v[58:61]
	v_mfma_f32_16x16x32_bf16 v[50:53], v[134:137], v[196:199], v[50:53]
	v_mfma_f32_16x16x32_bf16 v[42:45], v[142:145], v[196:199], v[42:45]
	v_mfma_f32_16x16x32_bf16 v[34:37], v[134:137], v[206:209], v[34:37]
	v_mfma_f32_16x16x32_bf16 v[26:29], v[142:145], v[206:209], v[26:29]
	v_mfma_f32_16x16x32_bf16 v[18:21], v[134:137], v[214:217], v[18:21]
	v_mfma_f32_16x16x32_bf16 v[10:13], v[142:145], v[214:217], v[10:13]
	v_mfma_f32_16x16x32_bf16 v[54:57], v[162:165], v[184:187], v[54:57]
	v_mfma_f32_16x16x32_bf16 v[46:49], v[176:179], v[184:187], v[46:49]
	v_mfma_f32_16x16x32_bf16 v[38:41], v[162:165], v[192:195], v[38:41]
	v_mfma_f32_16x16x32_bf16 v[30:33], v[176:179], v[192:195], v[30:33]
	v_mfma_f32_16x16x32_bf16 v[22:25], v[162:165], v[200:203], v[22:25]
	v_mfma_f32_16x16x32_bf16 v[14:17], v[176:179], v[200:203], v[14:17]
	v_mfma_f32_16x16x32_bf16 v[6:9], v[162:165], v[210:213], v[6:9]
	v_mfma_f32_16x16x32_bf16 v[2:5], v[176:179], v[210:213], v[2:5]
	v_mfma_f32_16x16x32_bf16 v[54:57], v[172:175], v[188:191], v[54:57]
	v_mfma_f32_16x16x32_bf16 v[46:49], v[180:183], v[188:191], v[46:49]
	v_mfma_f32_16x16x32_bf16 v[38:41], v[172:175], v[196:199], v[38:41]
	v_mfma_f32_16x16x32_bf16 v[30:33], v[180:183], v[196:199], v[30:33]
	v_mfma_f32_16x16x32_bf16 v[22:25], v[172:175], v[206:209], v[22:25]
	v_mfma_f32_16x16x32_bf16 v[14:17], v[180:183], v[206:209], v[14:17]
	v_mfma_f32_16x16x32_bf16 v[6:9], v[172:175], v[214:217], v[6:9]
	v_mfma_f32_16x16x32_bf16 v[2:5], v[180:183], v[214:217], v[2:5]
	s_setprio 0
	s_barrier
	s_cbranch_scc0 .LBB0_1708
	s_and_b64 vcc, exec, s[20:21]
	s_cbranch_vccz .LBB0_1711
	s_barrier
